# FLAT loads/stores converted to GLOBAL (no lgkmcnt increments, no aperture check)
# baseline (speedup 1.0000x reference)
; __device__ __forceinline__ unsigned pk2(float lo, float hi) { const f32x2_t f = {lo, hi}; const bf16x2_t b = __builtin_convertvector(f, bf16x2_t); return __builtin_bit_cast(unsigned, b); }
;   __device__ __forceinline__ void operator()(const f32x4 (&acc)[2][2][4][2], const pg8::Unit& u, int wr, int wc, int fr, int fq) const {
;     ...
;             u16* base = G + (size_t)(order * 1024 + c) * (size_t)(2 * L);
;             u32x4 o;
;             if (dir == 0) { o.x = pk2(v[7], v[6]); o.y = pk2(v[5], v[4]); o.z = pk2(v[3], v[2]); o.w = pk2(v[1], v[0]); *(u32x4*)(base + (L - 8 - p0)) = o; }
;             else { o.x = pk2(v[0], v[1]); o.y = pk2(v[2], v[3]); o.z = pk2(v[4], v[5]); o.w = pk2(v[6], v[7]); *(u32x4*)(base + (L + p0)) = o; }
.LBB0_49:
	s_or_b64 exec, exec, s[0:1]
	v_lshlrev_b64 v[4:5], v70, v[68:69]
	v_lshl_add_u64 v[4:5], v[4:5], 1, v[64:65]
	v_cvt_pk_bf16_f32 v3, v6, v7
	v_lshl_add_u64 v[4:5], v[60:61], 1, v[4:5]
	global_store_dwordx4 v[4:5], v[0:3], off

; #define PG8_STAGE(bufoff, gbase, voff) do { _Pragma("unroll") for (int _i = 0; _i < 2; ++_i) \
;     __builtin_amdgcn_global_load_lds((const unsigned*)((const char*)(gbase) + (voff)[_i]), (LAS unsigned*)(lds + (bufoff) + ldsw + _i * 8192), 16, 0, 0); } while (0)
; #define PG8_LDA(dst, b, h) do { _Pragma("unroll") for (int m = 0; m < 4; ++m) _Pragma("unroll") for (int k = 0; k < 2; ++k) dst[m][k] = *(const LAS bf16x8*)(lds + PG8_SA(b, h) + aoff + m * 2048 + k * 1024); } while (0)
; #define PG8_LDB(dst, b, h) do { _Pragma("unroll") for (int n = 0; n < 2; ++n) _Pragma("unroll") for (int k = 0; k < 2; ++k) dst[n][k] = *(const LAS bf16x8*)(lds + PG8_SB(b, h) + boff + n * 2048 + k * 1024); } while (0)
; #define PG8_MMA(ai, bj, At, Bt) do { __builtin_amdgcn_s_setprio(1); _Pragma("unroll") for (int m = 0; m < 4; ++m) _Pragma("unroll") for (int n = 0; n < 2; ++n) _Pragma("unroll") for (int k = 0; k < 2; ++k) \
;     acc[ai][bj][m][n] = __builtin_amdgcn_mfma_f32_16x16x32_bf16(Bt[n][k], At[m][k], acc[ai][bj][m][n], 0, 0, 0); __builtin_amdgcn_s_setprio(0); } while (0)
; #define PG8_WAIT_V(n) asm volatile("s_waitcnt vmcnt(" #n ")" ::: "memory")
; #define PG8_WAIT_L(n) asm volatile("s_waitcnt lgkmcnt(" #n ")" ::: "memory")
; #define PG8_BAR __builtin_amdgcn_s_barrier()
; #define PG8_SCHED __builtin_amdgcn_sched_barrier(0)
; template <class Epi>
; __device__ __forceinline__ void gemm_phase(LAS unsigned char* lds, const Gemm g, const StaticOrder& S, const Epi& E) {
;     ...
;       PG8_LDB(B0, 0, 0); PG8_SCHED; PG8_LDA(At, 0, 0); PG8_STAGE(PG8_SA(1, 1), a1 + hstep, voffA);
;       PG8_WAIT_L(8); PG8_BAR; PG8_WAIT_L(0); PG8_MMA(0, 0, At, B0); PG8_BAR; PG8_SCHED;
;       PG8_LDB(B1, 0, 1); PG8_STAGE(PG8_SB(0, 0), b2, voffB);
;       PG8_BAR; PG8_WAIT_L(0); PG8_MMA(0, 1, At, B1); PG8_BAR;
;       PG8_LDA(At, 0, 1); PG8_STAGE(PG8_SA(0, 0), a2, voffA);
;       PG8_BAR; PG8_WAIT_L(0); PG8_MMA(1, 0, At, B0); PG8_BAR; PG8_SCHED;
;       PG8_STAGE(PG8_SB(0, 1), b2 + hstep, voffB);
;       PG8_WAIT_V(6); PG8_BAR; PG8_MMA(1, 1, At, B1); PG8_BAR;
.LBB0_56:
	s_add_i32 s76, s10, 2
	s_add_u32 s12, s0, 0x80
	s_addc_u32 s11, s1, 0
	s_add_i32 s77, 0, 0x10000
	s_waitcnt lgkmcnt(0)
	v_add_u32_e32 v80, s77, v187
	ds_read_b128 v[130:133], v80
	ds_read_b128 v[134:137], v80 offset:1024
	ds_read_b128 v[138:141], v80 offset:2048
	ds_read_b128 v[142:145], v80 offset:3072
	s_cmp_eq_u32 s21, s10
	s_cselect_b32 s10, s18, s12
	s_cselect_b32 s11, s19, s11
	s_cselect_b32 s13, s17, s75
	s_cselect_b32 s12, s16, s74
	v_lshl_add_u64 v[194:195], s[0:1], 0, v[172:173]
	s_add_i32 m0, s15, 0xc000
	ds_read_b128 v[146:149], v189
	ds_read_b128 v[150:153], v189 offset:1024
	ds_read_b128 v[154:157], v189 offset:2048
	ds_read_b128 v[158:161], v189 offset:3072
	ds_read_b128 v[174:177], v189 offset:4096
	ds_read_b128 v[178:181], v189 offset:5120
	ds_read_b128 v[182:185], v189 offset:6144
	ds_read_b128 v[190:193], v189 offset:7168
	global_load_lds_dwordx4 v[194:195], off
	v_lshl_add_u64 v[194:195], s[0:1], 0, v[170:171]
	s_add_i32 m0, s15, 0xe000
	s_nop 0
	global_load_lds_dwordx4 v[194:195], off
	s_waitcnt lgkmcnt(8)
	s_barrier
	s_waitcnt lgkmcnt(0)
	s_waitcnt lgkmcnt(0)
	v_mfma_f32_16x16x32_bf16 v[126:129], v[130:133], v[146:149], v[126:129]
	v_mfma_f32_16x16x32_bf16 v[122:125], v[138:141], v[146:149], v[122:125]
	v_mfma_f32_16x16x32_bf16 v[118:121], v[130:133], v[154:157], v[118:121]
	v_mfma_f32_16x16x32_bf16 v[114:117], v[138:141], v[154:157], v[114:117]
	v_mfma_f32_16x16x32_bf16 v[110:113], v[130:133], v[174:177], v[110:113]
	v_mfma_f32_16x16x32_bf16 v[106:109], v[138:141], v[174:177], v[106:109]
	v_mfma_f32_16x16x32_bf16 v[102:105], v[130:133], v[182:185], v[102:105]
	v_mfma_f32_16x16x32_bf16 v[98:101], v[138:141], v[182:185], v[98:101]
	v_mfma_f32_16x16x32_bf16 v[126:129], v[134:137], v[150:153], v[126:129]
	v_mfma_f32_16x16x32_bf16 v[122:125], v[142:145], v[150:153], v[122:125]
	v_mfma_f32_16x16x32_bf16 v[118:121], v[134:137], v[158:161], v[118:121]
	v_mfma_f32_16x16x32_bf16 v[114:117], v[142:145], v[158:161], v[114:117]
	v_mfma_f32_16x16x32_bf16 v[110:113], v[134:137], v[178:181], v[110:113]
	v_mfma_f32_16x16x32_bf16 v[106:109], v[142:145], v[178:181], v[106:109]
	v_mfma_f32_16x16x32_bf16 v[102:105], v[134:137], v[190:193], v[102:105]
	v_mfma_f32_16x16x32_bf16 v[98:101], v[142:145], v[190:193], v[98:101]
	s_barrier
	s_add_i32 s78, 0, 0x14000
	s_add_i32 s77, s77, s14
	v_add_u32_e32 v80, s78, v187
	v_lshl_add_u64 v[210:211], s[12:13], 0, v[164:165]
	s_mov_b32 m0, s77
	ds_read_b128 v[194:197], v80
	ds_read_b128 v[198:201], v80 offset:1024
	ds_read_b128 v[202:205], v80 offset:2048
	ds_read_b128 v[206:209], v80 offset:3072
	global_load_lds_dwordx4 v[210:211], off
	v_lshl_add_u64 v[212:213], s[12:13], 0, v[168:169]
	s_add_i32 m0, s77, 0x2000
	s_nop 0
	global_load_lds_dwordx4 v[212:213], off
	s_barrier
	s_waitcnt lgkmcnt(0)
	s_waitcnt lgkmcnt(0)
	v_mfma_f32_16x16x32_bf16 v[60:63], v[194:197], v[146:149], v[60:63]
	v_mfma_f32_16x16x32_bf16 v[56:59], v[202:205], v[146:149], v[56:59]
	v_mfma_f32_16x16x32_bf16 v[52:55], v[194:197], v[154:157], v[52:55]
	v_mfma_f32_16x16x32_bf16 v[48:51], v[202:205], v[154:157], v[48:51]
	v_mfma_f32_16x16x32_bf16 v[44:47], v[194:197], v[174:177], v[44:47]
	v_mfma_f32_16x16x32_bf16 v[40:43], v[202:205], v[174:177], v[40:43]
	v_mfma_f32_16x16x32_bf16 v[36:39], v[194:197], v[182:185], v[36:39]
	v_mfma_f32_16x16x32_bf16 v[32:35], v[202:205], v[182:185], v[32:35]
	v_mfma_f32_16x16x32_bf16 v[60:63], v[198:201], v[150:153], v[60:63]
	v_mfma_f32_16x16x32_bf16 v[56:59], v[206:209], v[150:153], v[56:59]
	v_mfma_f32_16x16x32_bf16 v[52:55], v[198:201], v[158:161], v[52:55]
	v_mfma_f32_16x16x32_bf16 v[48:51], v[206:209], v[158:161], v[48:51]
	v_mfma_f32_16x16x32_bf16 v[44:47], v[198:201], v[178:181], v[44:47]
	v_mfma_f32_16x16x32_bf16 v[40:43], v[206:209], v[178:181], v[40:43]
	v_mfma_f32_16x16x32_bf16 v[36:39], v[198:201], v[190:193], v[36:39]
	v_mfma_f32_16x16x32_bf16 v[32:35], v[206:209], v[190:193], v[32:35]
	s_mov_b32 m0, s15
	v_lshl_add_u64 v[216:217], s[10:11], 0, v[162:163]
	s_barrier
	ds_read_b128 v[146:149], v189 offset:16384
	ds_read_b128 v[150:153], v189 offset:17408
	ds_read_b128 v[154:157], v189 offset:18432
	ds_read_b128 v[158:161], v189 offset:19456
	ds_read_b128 v[174:177], v189 offset:20480
	ds_read_b128 v[178:181], v189 offset:21504
	ds_read_b128 v[182:185], v189 offset:22528
	ds_read_b128 v[190:193], v189 offset:23552
	global_load_lds_dwordx4 v[216:217], off
	v_lshl_add_u64 v[232:233], s[10:11], 0, v[166:167]
	s_mov_b32 m0, s84
	s_nop 0
	global_load_lds_dwordx4 v[232:233], off
	s_barrier
	s_waitcnt lgkmcnt(0)
	s_waitcnt lgkmcnt(0)
	v_mfma_f32_16x16x32_bf16 v[94:97], v[130:133], v[146:149], v[94:97]
	v_mfma_f32_16x16x32_bf16 v[90:93], v[138:141], v[146:149], v[90:93]
	v_mfma_f32_16x16x32_bf16 v[86:89], v[130:133], v[154:157], v[86:89]
	v_mfma_f32_16x16x32_bf16 v[82:85], v[138:141], v[154:157], v[82:85]
	v_mfma_f32_16x16x32_bf16 v[76:79], v[130:133], v[174:177], v[76:79]
	v_mfma_f32_16x16x32_bf16 v[72:75], v[138:141], v[174:177], v[72:75]
	v_mfma_f32_16x16x32_bf16 v[68:71], v[130:133], v[182:185], v[68:71]
	v_mfma_f32_16x16x32_bf16 v[64:67], v[138:141], v[182:185], v[64:67]
	v_mfma_f32_16x16x32_bf16 v[94:97], v[134:137], v[150:153], v[94:97]
	v_mfma_f32_16x16x32_bf16 v[90:93], v[142:145], v[150:153], v[90:93]
	v_mfma_f32_16x16x32_bf16 v[86:89], v[134:137], v[158:161], v[86:89]
	v_mfma_f32_16x16x32_bf16 v[82:85], v[142:145], v[158:161], v[82:85]
	v_mfma_f32_16x16x32_bf16 v[76:79], v[134:137], v[178:181], v[76:79]
	v_mfma_f32_16x16x32_bf16 v[72:75], v[142:145], v[178:181], v[72:75]
	v_mfma_f32_16x16x32_bf16 v[68:71], v[134:137], v[190:193], v[68:71]
	v_mfma_f32_16x16x32_bf16 v[64:67], v[142:145], v[190:193], v[64:67]
	s_barrier
; #define PG8_STAGE(bufoff, gbase, voff) do { _Pragma("unroll") for (int _i = 0; _i < 2; ++_i) \
;     __builtin_amdgcn_global_load_lds((const unsigned*)((const char*)(gbase) + (voff)[_i]), (LAS unsigned*)(lds + (bufoff) + ldsw + _i * 8192), 16, 0, 0); } while (0)
; #define PG8_LDA(dst, b, h) do { _Pragma("unroll") for (int m = 0; m < 4; ++m) _Pragma("unroll") for (int k = 0; k < 2; ++k) dst[m][k] = *(const LAS bf16x8*)(lds + PG8_SA(b, h) + aoff + m * 2048 + k * 1024); } while (0)
; #define PG8_LDB(dst, b, h) do { _Pragma("unroll") for (int n = 0; n < 2; ++n) _Pragma("unroll") for (int k = 0; k < 2; ++k) dst[n][k] = *(const LAS bf16x8*)(lds + PG8_SB(b, h) + boff + n * 2048 + k * 1024); } while (0)
; #define PG8_MMA(ai, bj, At, Bt) do { __builtin_amdgcn_s_setprio(1); _Pragma("unroll") for (int m = 0; m < 4; ++m) _Pragma("unroll") for (int n = 0; n < 2; ++n) _Pragma("unroll") for (int k = 0; k < 2; ++k) \
;     acc[ai][bj][m][n] = __builtin_amdgcn_mfma_f32_16x16x32_bf16(Bt[n][k], At[m][k], acc[ai][bj][m][n], 0, 0, 0); __builtin_amdgcn_s_setprio(0); } while (0)
; #define PG8_WAIT_V(n) asm volatile("s_waitcnt vmcnt(" #n ")" ::: "memory")
; #define PG8_WAIT_L(n) asm volatile("s_waitcnt lgkmcnt(" #n ")" ::: "memory")
; #define PG8_BAR __builtin_amdgcn_s_barrier()
; #define PG8_SCHED __builtin_amdgcn_sched_barrier(0)
; template <class Epi>
; __device__ __forceinline__ void gemm_phase(LAS unsigned char* lds, const Gemm g, const StaticOrder& S, const Epi& E) {
;     ...
;       PG8_WAIT_V(6); PG8_BAR; PG8_MMA(1, 1, At, B1); PG8_BAR;
;       PG8_LDB(B0, 1, 0); PG8_SCHED; PG8_LDA(At, 1, 0); PG8_STAGE(PG8_SA(0, 1), a2 + hstep, voffA);
;       PG8_WAIT_L(8); PG8_BAR; PG8_WAIT_L(0); PG8_MMA(0, 0, At, B0); PG8_BAR; PG8_SCHED;
;       PG8_LDB(B1, 1, 1); PG8_STAGE(PG8_SB(1, 0), b3, voffB);
;       PG8_BAR; PG8_WAIT_L(0); PG8_MMA(0, 1, At, B1); PG8_BAR;
;       PG8_LDA(At, 1, 1); PG8_STAGE(PG8_SA(1, 0), a3, voffA);
;       PG8_BAR; PG8_WAIT_L(0); PG8_MMA(1, 0, At, B0); PG8_BAR; PG8_SCHED;
;       PG8_STAGE(PG8_SB(1, 1), b3 + hstep, voffB);
;       PG8_WAIT_V(6); PG8_BAR; PG8_MMA(1, 1, At, B1); PG8_BAR;
	s_add_u32 s12, s12, s64
	s_addc_u32 s13, s13, 0
	s_add_i32 s77, s78, s14
	v_lshl_add_u64 v[236:237], s[12:13], 0, v[164:165]
	s_mov_b32 m0, s77
	v_lshl_add_u64 v[242:243], s[12:13], 0, v[168:169]
	global_load_lds_dwordx4 v[236:237], off
	s_add_i32 m0, s77, 0x2000
	s_nop 0
	global_load_lds_dwordx4 v[242:243], off
	s_waitcnt vmcnt(6)
	s_barrier
	v_mfma_f32_16x16x32_bf16 v[28:31], v[194:197], v[146:149], v[28:31]
	v_mfma_f32_16x16x32_bf16 v[24:27], v[202:205], v[146:149], v[24:27]
	v_mfma_f32_16x16x32_bf16 v[20:23], v[194:197], v[154:157], v[20:23]
	v_mfma_f32_16x16x32_bf16 v[16:19], v[202:205], v[154:157], v[16:19]
	v_mfma_f32_16x16x32_bf16 v[12:15], v[194:197], v[174:177], v[12:15]
	v_mfma_f32_16x16x32_bf16 v[8:11], v[202:205], v[174:177], v[8:11]
	v_mfma_f32_16x16x32_bf16 v[4:7], v[194:197], v[182:185], v[4:7]
	v_mfma_f32_16x16x32_bf16 v[0:3], v[202:205], v[182:185], v[0:3]
	v_mfma_f32_16x16x32_bf16 v[28:31], v[198:201], v[150:153], v[28:31]
	v_mfma_f32_16x16x32_bf16 v[24:27], v[206:209], v[150:153], v[24:27]
	v_mfma_f32_16x16x32_bf16 v[20:23], v[198:201], v[158:161], v[20:23]
	v_mfma_f32_16x16x32_bf16 v[16:19], v[206:209], v[158:161], v[16:19]
	v_mfma_f32_16x16x32_bf16 v[12:15], v[198:201], v[178:181], v[12:15]
	v_mfma_f32_16x16x32_bf16 v[8:11], v[206:209], v[178:181], v[8:11]
	v_mfma_f32_16x16x32_bf16 v[4:7], v[198:201], v[190:193], v[4:7]
	v_mfma_f32_16x16x32_bf16 v[0:3], v[206:209], v[190:193], v[0:3]
	s_add_i32 s12, 0, 0x18000
	v_add_u32_e32 v80, s12, v187
	s_barrier
	ds_read_b128 v[130:133], v80
	ds_read_b128 v[134:137], v80 offset:1024
	ds_read_b128 v[138:141], v80 offset:2048
	ds_read_b128 v[142:145], v80 offset:3072
	s_add_u32 s10, s10, s64
	s_addc_u32 s11, s11, 0
	s_mov_b32 m0, s99
	v_lshl_add_u64 v[194:195], s[10:11], 0, v[162:163]
	ds_read_b128 v[146:149], v189 offset:32768
	ds_read_b128 v[150:153], v189 offset:33792
	ds_read_b128 v[154:157], v189 offset:34816
	ds_read_b128 v[158:161], v189 offset:35840
	ds_read_b128 v[174:177], v189 offset:36864
	ds_read_b128 v[178:181], v189 offset:37888
	ds_read_b128 v[182:185], v189 offset:38912
	ds_read_b128 v[190:193], v189 offset:39936
	global_load_lds_dwordx4 v[194:195], off
	v_lshl_add_u64 v[194:195], s[10:11], 0, v[166:167]
	s_mov_b32 m0, s33
	s_nop 0
	global_load_lds_dwordx4 v[194:195], off
	s_waitcnt lgkmcnt(8)
	s_barrier
	s_waitcnt lgkmcnt(0)
	s_waitcnt lgkmcnt(0)
	v_mfma_f32_16x16x32_bf16 v[126:129], v[130:133], v[146:149], v[126:129]
	v_mfma_f32_16x16x32_bf16 v[122:125], v[138:141], v[146:149], v[122:125]
	v_mfma_f32_16x16x32_bf16 v[118:121], v[130:133], v[154:157], v[118:121]
	v_mfma_f32_16x16x32_bf16 v[114:117], v[138:141], v[154:157], v[114:117]
	v_mfma_f32_16x16x32_bf16 v[110:113], v[130:133], v[174:177], v[110:113]
	v_mfma_f32_16x16x32_bf16 v[106:109], v[138:141], v[174:177], v[106:109]
	v_mfma_f32_16x16x32_bf16 v[102:105], v[130:133], v[182:185], v[102:105]
	v_mfma_f32_16x16x32_bf16 v[98:101], v[138:141], v[182:185], v[98:101]
	v_mfma_f32_16x16x32_bf16 v[126:129], v[134:137], v[150:153], v[126:129]
	v_mfma_f32_16x16x32_bf16 v[122:125], v[142:145], v[150:153], v[122:125]
	v_mfma_f32_16x16x32_bf16 v[118:121], v[134:137], v[158:161], v[118:121]
	v_mfma_f32_16x16x32_bf16 v[114:117], v[142:145], v[158:161], v[114:117]
	v_mfma_f32_16x16x32_bf16 v[110:113], v[134:137], v[178:181], v[110:113]
	v_mfma_f32_16x16x32_bf16 v[106:109], v[142:145], v[178:181], v[106:109]
	v_mfma_f32_16x16x32_bf16 v[102:105], v[134:137], v[190:193], v[102:105]
	v_mfma_f32_16x16x32_bf16 v[98:101], v[142:145], v[190:193], v[98:101]
	s_barrier
	s_add_i32 s10, 0, 0x1c000
	s_add_i32 s11, s12, s14
	v_add_u32_e32 v80, s10, v187
	v_lshl_add_u64 v[210:211], v[210:211], 0, s[90:91]
	s_mov_b32 m0, s11
	ds_read_b128 v[194:197], v80
	ds_read_b128 v[198:201], v80 offset:1024
	ds_read_b128 v[202:205], v80 offset:2048
	ds_read_b128 v[206:209], v80 offset:3072
	global_load_lds_dwordx4 v[210:211], off
	v_lshl_add_u64 v[210:211], v[212:213], 0, s[90:91]
	s_add_i32 m0, s11, 0x2000
	s_nop 0
	global_load_lds_dwordx4 v[210:211], off
	s_barrier
	s_waitcnt lgkmcnt(0)
	s_waitcnt lgkmcnt(0)
	v_mfma_f32_16x16x32_bf16 v[60:63], v[194:197], v[146:149], v[60:63]
	v_mfma_f32_16x16x32_bf16 v[56:59], v[202:205], v[146:149], v[56:59]
	v_mfma_f32_16x16x32_bf16 v[52:55], v[194:197], v[154:157], v[52:55]
	v_mfma_f32_16x16x32_bf16 v[48:51], v[202:205], v[154:157], v[48:51]
	v_mfma_f32_16x16x32_bf16 v[44:47], v[194:197], v[174:177], v[44:47]
	v_mfma_f32_16x16x32_bf16 v[40:43], v[202:205], v[174:177], v[40:43]
	v_mfma_f32_16x16x32_bf16 v[36:39], v[194:197], v[182:185], v[36:39]
	v_mfma_f32_16x16x32_bf16 v[32:35], v[202:205], v[182:185], v[32:35]
	v_mfma_f32_16x16x32_bf16 v[60:63], v[198:201], v[150:153], v[60:63]
	v_mfma_f32_16x16x32_bf16 v[56:59], v[206:209], v[150:153], v[56:59]
	v_mfma_f32_16x16x32_bf16 v[52:55], v[198:201], v[158:161], v[52:55]
	v_mfma_f32_16x16x32_bf16 v[48:51], v[206:209], v[158:161], v[48:51]
	v_mfma_f32_16x16x32_bf16 v[44:47], v[198:201], v[178:181], v[44:47]
	v_mfma_f32_16x16x32_bf16 v[40:43], v[206:209], v[178:181], v[40:43]
	v_mfma_f32_16x16x32_bf16 v[36:39], v[198:201], v[190:193], v[36:39]
	v_mfma_f32_16x16x32_bf16 v[32:35], v[206:209], v[190:193], v[32:35]
	s_mov_b32 m0, s29
	v_lshl_add_u64 v[210:211], v[216:217], 0, s[90:91]
	s_barrier
	ds_read_b128 v[146:149], v189 offset:49152
	ds_read_b128 v[150:153], v189 offset:50176
	ds_read_b128 v[154:157], v189 offset:51200
	ds_read_b128 v[158:161], v189 offset:52224
	ds_read_b128 v[174:177], v189 offset:53248
	ds_read_b128 v[178:181], v189 offset:54272
	ds_read_b128 v[182:185], v189 offset:55296
	ds_read_b128 v[190:193], v189 offset:56320
	global_load_lds_dwordx4 v[210:211], off
	v_lshl_add_u64 v[210:211], v[232:233], 0, s[90:91]
	s_mov_b32 m0, s20
	s_nop 0
	global_load_lds_dwordx4 v[210:211], off
	s_barrier
; #define PG8_STAGE(bufoff, gbase, voff) do { _Pragma("unroll") for (int _i = 0; _i < 2; ++_i) \
;     __builtin_amdgcn_global_load_lds((const unsigned*)((const char*)(gbase) + (voff)[_i]), (LAS unsigned*)(lds + (bufoff) + ldsw + _i * 8192), 16, 0, 0); } while (0)
; #define PG8_MMA(ai, bj, At, Bt) do { __builtin_amdgcn_s_setprio(1); _Pragma("unroll") for (int m = 0; m < 4; ++m) _Pragma("unroll") for (int n = 0; n < 2; ++n) _Pragma("unroll") for (int k = 0; k < 2; ++k) \
;     acc[ai][bj][m][n] = __builtin_amdgcn_mfma_f32_16x16x32_bf16(Bt[n][k], At[m][k], acc[ai][bj][m][n], 0, 0, 0); __builtin_amdgcn_s_setprio(0); } while (0)
; #define PG8_WAIT_V(n) asm volatile("s_waitcnt vmcnt(" #n ")" ::: "memory")
; #define PG8_WAIT_L(n) asm volatile("s_waitcnt lgkmcnt(" #n ")" ::: "memory")
; #define PG8_BAR __builtin_amdgcn_s_barrier()
; #define PG8_SCHED __builtin_amdgcn_sched_barrier(0)
; template <class Epi>
; __device__ __forceinline__ void gemm_phase(LAS unsigned char* lds, const Gemm g, const StaticOrder& S, const Epi& E) {
;     ...
;       PG8_BAR; PG8_WAIT_L(0); PG8_MMA(1, 0, At, B0); PG8_BAR; PG8_SCHED;
;       PG8_STAGE(PG8_SB(1, 1), b3 + hstep, voffB);
;       PG8_WAIT_V(6); PG8_BAR; PG8_MMA(1, 1, At, B1); PG8_BAR;
;     }
;     E(acc, cur, wr, wc, fr, fq);
;     if (!has_next) break;
;   __device__ __forceinline__ void operator()(const f32x4 (&acc)[2][2][4][2], const pg8::Unit& u, int wr, int wc, int fr, int fq) const {
;     ...
;     } else {
;       float* xo = P->out + (size_t)slice * TS * DM; const u16* x2b = (const u16*)(ws + O_X2B) + (size_t)slice * TS * DM;
; #pragma unroll
;       for (int ai = 0; ai < 2; ++ai) {
;         u32x4 xv[4][2];
; #pragma unroll
;         for (int m = 0; m < 4; ++m)
; #pragma unroll
;           for (int bj = 0; bj < 2; ++bj) xv[m][bj] = *(const u32x4*)(x2b + (size_t)(row0 + ai * 128 + m * 16) * DM + col0 + bj * 128);
	s_waitcnt lgkmcnt(0)
	s_waitcnt lgkmcnt(0)
	v_mfma_f32_16x16x32_bf16 v[94:97], v[130:133], v[146:149], v[94:97]
	v_mfma_f32_16x16x32_bf16 v[90:93], v[138:141], v[146:149], v[90:93]
	v_mfma_f32_16x16x32_bf16 v[86:89], v[130:133], v[154:157], v[86:89]
	v_mfma_f32_16x16x32_bf16 v[82:85], v[138:141], v[154:157], v[82:85]
	v_mfma_f32_16x16x32_bf16 v[76:79], v[130:133], v[174:177], v[76:79]
	v_mfma_f32_16x16x32_bf16 v[72:75], v[138:141], v[174:177], v[72:75]
	v_mfma_f32_16x16x32_bf16 v[68:71], v[130:133], v[182:185], v[68:71]
	v_mfma_f32_16x16x32_bf16 v[64:67], v[138:141], v[182:185], v[64:67]
	v_mfma_f32_16x16x32_bf16 v[94:97], v[134:137], v[150:153], v[94:97]
	v_mfma_f32_16x16x32_bf16 v[90:93], v[142:145], v[150:153], v[90:93]
	v_mfma_f32_16x16x32_bf16 v[86:89], v[134:137], v[158:161], v[86:89]
	v_mfma_f32_16x16x32_bf16 v[82:85], v[142:145], v[158:161], v[82:85]
	v_mfma_f32_16x16x32_bf16 v[76:79], v[134:137], v[178:181], v[76:79]
	v_mfma_f32_16x16x32_bf16 v[72:75], v[142:145], v[178:181], v[72:75]
	v_mfma_f32_16x16x32_bf16 v[68:71], v[134:137], v[190:193], v[68:71]
	v_mfma_f32_16x16x32_bf16 v[64:67], v[142:145], v[190:193], v[64:67]
	s_barrier
	s_add_i32 s10, s10, s14
	v_lshl_add_u64 v[130:131], v[236:237], 0, s[90:91]
	s_mov_b32 m0, s10
	s_nop 0
	global_load_lds_dwordx4 v[130:131], off
	v_lshl_add_u64 v[130:131], v[242:243], 0, s[90:91]
	s_add_i32 m0, s10, 0x2000
	s_nop 0
	global_load_lds_dwordx4 v[130:131], off
	s_waitcnt vmcnt(6)
	s_barrier
	v_mfma_f32_16x16x32_bf16 v[28:31], v[194:197], v[146:149], v[28:31]
	v_mfma_f32_16x16x32_bf16 v[24:27], v[202:205], v[146:149], v[24:27]
	v_mfma_f32_16x16x32_bf16 v[20:23], v[194:197], v[154:157], v[20:23]
	v_mfma_f32_16x16x32_bf16 v[16:19], v[202:205], v[154:157], v[16:19]
	v_mfma_f32_16x16x32_bf16 v[12:15], v[194:197], v[174:177], v[12:15]
	v_mfma_f32_16x16x32_bf16 v[8:11], v[202:205], v[174:177], v[8:11]
	v_mfma_f32_16x16x32_bf16 v[4:7], v[194:197], v[182:185], v[4:7]
	v_mfma_f32_16x16x32_bf16 v[0:3], v[202:205], v[182:185], v[0:3]
	v_mfma_f32_16x16x32_bf16 v[28:31], v[198:201], v[150:153], v[28:31]
	v_mfma_f32_16x16x32_bf16 v[24:27], v[206:209], v[150:153], v[24:27]
	v_mfma_f32_16x16x32_bf16 v[20:23], v[198:201], v[158:161], v[20:23]
	v_mfma_f32_16x16x32_bf16 v[16:19], v[206:209], v[158:161], v[16:19]
	v_mfma_f32_16x16x32_bf16 v[12:15], v[198:201], v[178:181], v[12:15]
	v_mfma_f32_16x16x32_bf16 v[8:11], v[206:209], v[178:181], v[8:11]
	v_mfma_f32_16x16x32_bf16 v[4:7], v[198:201], v[190:193], v[4:7]
	v_mfma_f32_16x16x32_bf16 v[0:3], v[206:209], v[190:193], v[0:3]
	s_add_u32 s74, s74, 0x100
	s_addc_u32 s75, s75, 0
	s_add_u32 s0, s0, 0x100
	s_addc_u32 s1, s1, 0
	s_cmp_ge_u32 s76, s2
	s_mov_b32 s10, s76
	s_barrier
	s_cbranch_scc0 .LBB0_56
	s_cmp_lg_u32 s71, 0
	s_cselect_b64 s[0:1], -1, 0
	s_cmp_eq_u32 s71, 0
	s_cselect_b32 s10, s73, s72
	s_cselect_b32 s11, s72, s73
	s_lshl_b32 s71, s10, 8
	s_add_i32 s71, s71, s28
	v_or_b32_e32 v176, s71, v186
	v_lshl_or_b32 v174, s11, 8, v188
	s_cmp_lt_i32 s98, 2
	s_mov_b64 s[10:11], -1
	s_cbranch_scc1 .LBB0_151
	s_cmp_lt_i32 s98, 4
	s_cbranch_scc1 .LBB0_84
	s_cmp_lt_i32 s98, 5
	s_cbranch_scc1 .LBB0_65
	s_cmp_lg_u32 s98, 5
	s_cbranch_scc0 .LBB0_62
	v_readlane_b32 s10, v254, 18
	v_ashrrev_i32_e32 v175, 31, v174
	v_readlane_b32 s11, v254, 19
	v_ashrrev_i32_e32 v177, 31, v176
	v_lshlrev_b64 v[130:131], 11, v[176:177]
	v_lshl_add_u64 v[136:137], v[174:175], 1, s[10:11]
	v_or_b32_e32 v190, 16, v176
	v_lshl_add_u64 v[130:131], v[136:137], 0, v[130:131]
	v_ashrrev_i32_e32 v191, 31, v190
	global_load_dwordx4 v[138:141], v[130:131], off
	global_load_dwordx4 v[142:145], v[130:131], off offset:256
	v_lshlrev_b64 v[130:131], 11, v[190:191]
	v_or_b32_e32 v192, 32, v176
	v_lshl_add_u64 v[130:131], v[136:137], 0, v[130:131]
	v_ashrrev_i32_e32 v193, 31, v192
	global_load_dwordx4 v[146:149], v[130:131], off
	global_load_dwordx4 v[150:153], v[130:131], off offset:256
	v_lshlrev_b64 v[130:131], 11, v[192:193]
	v_or_b32_e32 v194, 48, v176
	v_lshl_add_u64 v[130:131], v[136:137], 0, v[130:131]
	v_ashrrev_i32_e32 v195, 31, v194
	global_load_dwordx4 v[154:157], v[130:131], off
	global_load_dwordx4 v[158:161], v[130:131], off offset:256
	v_lshlrev_b64 v[130:131], 11, v[194:195]
	v_lshl_add_u64 v[130:131], v[136:137], 0, v[130:131]
	global_load_dwordx4 v[178:181], v[130:131], off
	s_nop 0
	global_load_dwordx4 v[130:133], v[130:131], off offset:256
	v_readlane_b32 s10, v254, 20
	v_readlane_b32 s11, v254, 21
	s_nop 1
	v_lshl_add_u64 v[134:135], v[174:175], 2, s[10:11]
	v_lshlrev_b64 v[182:183], 12, v[176:177]
	v_lshl_add_u64 v[196:197], v[134:135], 0, v[182:183]
	s_waitcnt vmcnt(0) lgkmcnt(0)
; __device__ __forceinline__ float lo16(unsigned v) { return __uint_as_float(v << 16); }
; __device__ __forceinline__ float hi16(unsigned v) { return __uint_as_float(v & 0xffff0000u); }
;   __device__ __forceinline__ void operator()(const f32x4 (&acc)[2][2][4][2], const pg8::Unit& u, int wr, int wc, int fr, int fq) const {
;     ...
;       float* xo = P->out + (size_t)slice * TS * DM; const u16* x2b = (const u16*)(ws + O_X2B) + (size_t)slice * TS * DM;
; #pragma unroll
;       for (int ai = 0; ai < 2; ++ai) {
;         u32x4 xv[4][2];
; #pragma unroll
;         for (int m = 0; m < 4; ++m)
; #pragma unroll
;           for (int bj = 0; bj < 2; ++bj) xv[m][bj] = *(const u32x4*)(x2b + (size_t)(row0 + ai * 128 + m * 16) * DM + col0 + bj * 128);
;         __builtin_amdgcn_sched_barrier(0);
; #pragma unroll
;         for (int m = 0; m < 4; ++m) {
;           const int row = row0 + ai * 128 + m * 16;
; #pragma unroll
;           for (int bj = 0; bj < 2; ++bj) {
;             float* d = xo + (size_t)row * DM + col0 + bj * 128;
;             const u32x4 x4 = xv[m][bj];
;             f32x4 o0 = acc[ai][bj][m][0], o1 = acc[ai][bj][m][1];
;             o0[0] += lo16(x4.x); o0[1] += hi16(x4.x); o0[2] += lo16(x4.y); o0[3] += hi16(x4.y); o1[0] += lo16(x4.z); o1[1] += hi16(x4.z); o1[2] += lo16(x4.w); o1[3] += hi16(x4.w);
;             *(f32x4*)d = o0; *(f32x4*)(d + 4) = o1;
;           }
;         }
	v_lshlrev_b32_e32 v182, 16, v138
	v_and_b32_e32 v183, 0xffff0000, v138
	v_lshlrev_b32_e32 v138, 16, v139
	v_and_b32_e32 v139, 0xffff0000, v139
	v_pk_add_f32 v[184:185], v[128:129], v[138:139]
	v_lshlrev_b32_e32 v138, 16, v140
	v_and_b32_e32 v139, 0xffff0000, v140
	v_lshlrev_b32_e32 v140, 16, v141
	v_and_b32_e32 v141, 0xffff0000, v141
	v_pk_add_f32 v[182:183], v[126:127], v[182:183]
	v_pk_add_f32 v[138:139], v[122:123], v[138:139]
	v_pk_add_f32 v[140:141], v[124:125], v[140:141]
	global_store_dwordx4 v[196:197], v[182:185], off
	global_store_dwordx4 v[196:197], v[138:141], off offset:16
	s_nop 1
	v_lshlrev_b32_e32 v138, 16, v142
	v_and_b32_e32 v139, 0xffff0000, v142
	v_lshlrev_b32_e32 v140, 16, v143
	v_and_b32_e32 v141, 0xffff0000, v143
	v_pk_add_f32 v[138:139], v[60:61], v[138:139]
	v_pk_add_f32 v[140:141], v[62:63], v[140:141]
	v_lshlrev_b32_e32 v142, 16, v144
	v_and_b32_e32 v143, 0xffff0000, v144
	v_lshlrev_b32_e32 v144, 16, v145
	v_and_b32_e32 v145, 0xffff0000, v145
	v_pk_add_f32 v[142:143], v[56:57], v[142:143]
	v_pk_add_f32 v[144:145], v[58:59], v[144:145]
	global_store_dwordx4 v[196:197], v[138:141], off offset:512
	global_store_dwordx4 v[196:197], v[142:145], off offset:528
	s_nop 0
	v_lshlrev_b64 v[138:139], 12, v[190:191]
	v_lshl_add_u64 v[182:183], v[134:135], 0, v[138:139]
	v_lshlrev_b32_e32 v138, 16, v146
	v_and_b32_e32 v139, 0xffff0000, v146
	v_lshlrev_b32_e32 v140, 16, v147
	v_and_b32_e32 v141, 0xffff0000, v147
	v_pk_add_f32 v[138:139], v[118:119], v[138:139]
	v_pk_add_f32 v[140:141], v[120:121], v[140:141]
	v_lshlrev_b32_e32 v142, 16, v148
	v_and_b32_e32 v143, 0xffff0000, v148
	v_lshlrev_b32_e32 v144, 16, v149
	v_and_b32_e32 v145, 0xffff0000, v149
	v_pk_add_f32 v[142:143], v[114:115], v[142:143]
	v_pk_add_f32 v[144:145], v[116:117], v[144:145]
	global_store_dwordx4 v[182:183], v[138:141], off
	global_store_dwordx4 v[182:183], v[142:145], off offset:16
	s_nop 0
	v_lshlrev_b32_e32 v138, 16, v150
	v_and_b32_e32 v139, 0xffff0000, v150
	v_lshlrev_b32_e32 v140, 16, v151
	v_and_b32_e32 v141, 0xffff0000, v151
	v_pk_add_f32 v[138:139], v[52:53], v[138:139]
	v_pk_add_f32 v[140:141], v[54:55], v[140:141]
	v_lshlrev_b32_e32 v142, 16, v152
	v_and_b32_e32 v143, 0xffff0000, v152
	v_lshlrev_b32_e32 v144, 16, v153
	v_and_b32_e32 v145, 0xffff0000, v153
	v_pk_add_f32 v[142:143], v[48:49], v[142:143]
	v_pk_add_f32 v[144:145], v[50:51], v[144:145]
	global_store_dwordx4 v[182:183], v[138:141], off offset:512
	global_store_dwordx4 v[182:183], v[142:145], off offset:528
	s_nop 0
	v_lshlrev_b64 v[138:139], 12, v[192:193]
	v_lshl_add_u64 v[146:147], v[134:135], 0, v[138:139]
	v_lshlrev_b32_e32 v138, 16, v154
	v_and_b32_e32 v139, 0xffff0000, v154
	v_lshlrev_b32_e32 v140, 16, v155
	v_and_b32_e32 v141, 0xffff0000, v155
	v_pk_add_f32 v[138:139], v[110:111], v[138:139]
	v_pk_add_f32 v[140:141], v[112:113], v[140:141]
	v_lshlrev_b32_e32 v142, 16, v156
	v_and_b32_e32 v143, 0xffff0000, v156
	v_lshlrev_b32_e32 v144, 16, v157
	v_and_b32_e32 v145, 0xffff0000, v157
	v_pk_add_f32 v[142:143], v[106:107], v[142:143]
	v_pk_add_f32 v[144:145], v[108:109], v[144:145]
	global_store_dwordx4 v[146:147], v[138:141], off
	global_store_dwordx4 v[146:147], v[142:145], off offset:16
	s_nop 0
	v_lshlrev_b32_e32 v138, 16, v158
	v_and_b32_e32 v139, 0xffff0000, v158
	v_lshlrev_b32_e32 v140, 16, v159
	v_and_b32_e32 v141, 0xffff0000, v159
	v_pk_add_f32 v[138:139], v[44:45], v[138:139]
	v_pk_add_f32 v[140:141], v[46:47], v[140:141]
	v_lshlrev_b32_e32 v142, 16, v160
	v_and_b32_e32 v143, 0xffff0000, v160
	v_lshlrev_b32_e32 v144, 16, v161
	v_and_b32_e32 v145, 0xffff0000, v161
	v_pk_add_f32 v[142:143], v[40:41], v[142:143]
	v_pk_add_f32 v[144:145], v[42:43], v[144:145]
	global_store_dwordx4 v[146:147], v[138:141], off offset:512
	global_store_dwordx4 v[146:147], v[142:145], off offset:528
	s_nop 0
	v_lshlrev_b64 v[138:139], 12, v[194:195]
	v_lshl_add_u64 v[146:147], v[134:135], 0, v[138:139]
	v_lshlrev_b32_e32 v138, 16, v178
	v_and_b32_e32 v139, 0xffff0000, v178
	v_lshlrev_b32_e32 v140, 16, v179
	v_and_b32_e32 v141, 0xffff0000, v179
	v_pk_add_f32 v[138:139], v[102:103], v[138:139]
	v_pk_add_f32 v[140:141], v[104:105], v[140:141]
	v_lshlrev_b32_e32 v142, 16, v180
	v_and_b32_e32 v143, 0xffff0000, v180
	v_lshlrev_b32_e32 v144, 16, v181
	v_and_b32_e32 v145, 0xffff0000, v181
	v_pk_add_f32 v[142:143], v[98:99], v[142:143]
	v_pk_add_f32 v[144:145], v[100:101], v[144:145]
	global_store_dwordx4 v[146:147], v[138:141], off
	global_store_dwordx4 v[146:147], v[142:145], off offset:16
	s_nop 0
	v_lshlrev_b32_e32 v138, 16, v130
	v_and_b32_e32 v139, 0xffff0000, v130
	v_lshlrev_b32_e32 v130, 16, v131
	v_and_b32_e32 v131, 0xffff0000, v131
	v_pk_add_f32 v[138:139], v[36:37], v[138:139]
	v_pk_add_f32 v[140:141], v[38:39], v[130:131]
	v_lshlrev_b32_e32 v130, 16, v132
	v_and_b32_e32 v131, 0xffff0000, v132
	v_lshlrev_b32_e32 v132, 16, v133
	v_and_b32_e32 v133, 0xffff0000, v133
	v_pk_add_f32 v[130:131], v[32:33], v[130:131]
	v_pk_add_f32 v[132:133], v[34:35], v[132:133]
	global_store_dwordx4 v[146:147], v[138:141], off offset:512
	global_store_dwordx4 v[146:147], v[130:133], off offset:528
	v_add_u32_e32 v182, 0x80, v176
	v_ashrrev_i32_e32 v183, 31, v182
	v_lshlrev_b64 v[130:131], 11, v[182:183]
	v_add_u32_e32 v190, 0x90, v176
	v_lshl_add_u64 v[130:131], v[136:137], 0, v[130:131]
	v_ashrrev_i32_e32 v191, 31, v190
	global_load_dwordx4 v[138:141], v[130:131], off
	global_load_dwordx4 v[142:145], v[130:131], off offset:256
	v_lshlrev_b64 v[130:131], 11, v[190:191]
	v_add_u32_e32 v192, 0xa0, v176
	v_lshl_add_u64 v[130:131], v[136:137], 0, v[130:131]
	v_ashrrev_i32_e32 v193, 31, v192
	global_load_dwordx4 v[146:149], v[130:131], off
	global_load_dwordx4 v[150:153], v[130:131], off offset:256
	v_lshlrev_b64 v[130:131], 11, v[192:193]
	v_add_u32_e32 v194, 0xb0, v176
	v_lshl_add_u64 v[130:131], v[136:137], 0, v[130:131]
	v_ashrrev_i32_e32 v195, 31, v194
	global_load_dwordx4 v[154:157], v[130:131], off
	global_load_dwordx4 v[158:161], v[130:131], off offset:256
	v_lshlrev_b64 v[130:131], 11, v[194:195]
	v_lshl_add_u64 v[130:131], v[136:137], 0, v[130:131]
	global_load_dwordx4 v[178:181], v[130:131], off
	s_nop 0
	global_load_dwordx4 v[130:133], v[130:131], off offset:256
	v_lshlrev_b64 v[136:137], 12, v[182:183]
	v_lshl_add_u64 v[196:197], v[134:135], 0, v[136:137]
	s_waitcnt vmcnt(0) lgkmcnt(0)
; __device__ __forceinline__ float lo16(unsigned v) { return __uint_as_float(v << 16); }
; __device__ __forceinline__ float hi16(unsigned v) { return __uint_as_float(v & 0xffff0000u); }
;   __device__ __forceinline__ void operator()(const f32x4 (&acc)[2][2][4][2], const pg8::Unit& u, int wr, int wc, int fr, int fq) const {
;     ...
; #pragma unroll
;         for (int m = 0; m < 4; ++m) {
;           const int row = row0 + ai * 128 + m * 16;
; #pragma unroll
;           for (int bj = 0; bj < 2; ++bj) {
;             float* d = xo + (size_t)row * DM + col0 + bj * 128;
;             const u32x4 x4 = xv[m][bj];
;             f32x4 o0 = acc[ai][bj][m][0], o1 = acc[ai][bj][m][1];
;             o0[0] += lo16(x4.x); o0[1] += hi16(x4.x); o0[2] += lo16(x4.y); o0[3] += hi16(x4.y); o1[0] += lo16(x4.z); o1[1] += hi16(x4.z); o1[2] += lo16(x4.w); o1[3] += hi16(x4.w);
;             *(f32x4*)d = o0; *(f32x4*)(d + 4) = o1;
;           }
;         }
	v_lshlrev_b32_e32 v136, 16, v138
	v_and_b32_e32 v137, 0xffff0000, v138
	v_lshlrev_b32_e32 v138, 16, v139
	v_and_b32_e32 v139, 0xffff0000, v139
	v_pk_add_f32 v[136:137], v[94:95], v[136:137]
	v_pk_add_f32 v[138:139], v[96:97], v[138:139]
	v_lshlrev_b32_e32 v182, 16, v140
	v_and_b32_e32 v183, 0xffff0000, v140
	v_lshlrev_b32_e32 v140, 16, v141
	v_and_b32_e32 v141, 0xffff0000, v141
	v_pk_add_f32 v[182:183], v[90:91], v[182:183]
	v_pk_add_f32 v[184:185], v[92:93], v[140:141]
	global_store_dwordx4 v[196:197], v[136:139], off
	global_store_dwordx4 v[196:197], v[182:185], off offset:16
	v_lshlrev_b32_e32 v140, 16, v144
	v_lshlrev_b32_e32 v136, 16, v142
	v_and_b32_e32 v137, 0xffff0000, v142
	v_lshlrev_b32_e32 v138, 16, v143
	v_and_b32_e32 v139, 0xffff0000, v143
	v_pk_add_f32 v[136:137], v[28:29], v[136:137]
	v_pk_add_f32 v[138:139], v[30:31], v[138:139]
	v_and_b32_e32 v141, 0xffff0000, v144
	v_lshlrev_b32_e32 v142, 16, v145
	v_and_b32_e32 v143, 0xffff0000, v145
	v_pk_add_f32 v[140:141], v[24:25], v[140:141]
	v_pk_add_f32 v[142:143], v[26:27], v[142:143]
	global_store_dwordx4 v[196:197], v[136:139], off offset:512
	global_store_dwordx4 v[196:197], v[140:143], off offset:528
	s_nop 0
	v_lshlrev_b64 v[136:137], 12, v[190:191]
	v_lshl_add_u64 v[144:145], v[134:135], 0, v[136:137]
	v_lshlrev_b32_e32 v136, 16, v146
	v_and_b32_e32 v137, 0xffff0000, v146
	v_lshlrev_b32_e32 v138, 16, v147
	v_and_b32_e32 v139, 0xffff0000, v147
	v_pk_add_f32 v[136:137], v[86:87], v[136:137]
	v_pk_add_f32 v[138:139], v[88:89], v[138:139]
	v_lshlrev_b32_e32 v140, 16, v148
	v_and_b32_e32 v141, 0xffff0000, v148
	v_lshlrev_b32_e32 v142, 16, v149
	v_and_b32_e32 v143, 0xffff0000, v149
	v_pk_add_f32 v[140:141], v[82:83], v[140:141]
	v_pk_add_f32 v[142:143], v[84:85], v[142:143]
	global_store_dwordx4 v[144:145], v[136:139], off
	global_store_dwordx4 v[144:145], v[140:143], off offset:16
	s_nop 0
	v_lshlrev_b32_e32 v136, 16, v150
	v_and_b32_e32 v137, 0xffff0000, v150
	v_lshlrev_b32_e32 v138, 16, v151
	v_and_b32_e32 v139, 0xffff0000, v151
	v_pk_add_f32 v[136:137], v[20:21], v[136:137]
	v_pk_add_f32 v[138:139], v[22:23], v[138:139]
	v_lshlrev_b32_e32 v140, 16, v152
	v_and_b32_e32 v141, 0xffff0000, v152
	v_lshlrev_b32_e32 v142, 16, v153
	v_and_b32_e32 v143, 0xffff0000, v153
	v_pk_add_f32 v[140:141], v[16:17], v[140:141]
	v_pk_add_f32 v[142:143], v[18:19], v[142:143]
	global_store_dwordx4 v[144:145], v[136:139], off offset:512
	global_store_dwordx4 v[144:145], v[140:143], off offset:528
	s_nop 0
	v_lshlrev_b64 v[136:137], 12, v[192:193]
	v_lshl_add_u64 v[144:145], v[134:135], 0, v[136:137]
	v_lshlrev_b32_e32 v136, 16, v154
	v_and_b32_e32 v137, 0xffff0000, v154
	v_lshlrev_b32_e32 v138, 16, v155
	v_and_b32_e32 v139, 0xffff0000, v155
	v_pk_add_f32 v[136:137], v[76:77], v[136:137]
	v_pk_add_f32 v[138:139], v[78:79], v[138:139]
	v_lshlrev_b32_e32 v140, 16, v156
	v_and_b32_e32 v141, 0xffff0000, v156
	v_lshlrev_b32_e32 v142, 16, v157
	v_and_b32_e32 v143, 0xffff0000, v157
	v_pk_add_f32 v[140:141], v[72:73], v[140:141]
	v_pk_add_f32 v[142:143], v[74:75], v[142:143]
	global_store_dwordx4 v[144:145], v[136:139], off
	global_store_dwordx4 v[144:145], v[140:143], off offset:16
	s_nop 0
	v_lshlrev_b32_e32 v136, 16, v158
	v_and_b32_e32 v137, 0xffff0000, v158
	v_lshlrev_b32_e32 v138, 16, v159
	v_and_b32_e32 v139, 0xffff0000, v159
	v_pk_add_f32 v[136:137], v[12:13], v[136:137]
	v_pk_add_f32 v[138:139], v[14:15], v[138:139]
	v_lshlrev_b32_e32 v140, 16, v160
	v_and_b32_e32 v141, 0xffff0000, v160
	v_lshlrev_b32_e32 v142, 16, v161
	v_and_b32_e32 v143, 0xffff0000, v161
	v_pk_add_f32 v[140:141], v[8:9], v[140:141]
	v_pk_add_f32 v[142:143], v[10:11], v[142:143]
	global_store_dwordx4 v[144:145], v[136:139], off offset:512
	global_store_dwordx4 v[144:145], v[140:143], off offset:528
	s_nop 0
	v_lshlrev_b64 v[136:137], 12, v[194:195]
	v_lshl_add_u64 v[142:143], v[134:135], 0, v[136:137]
	v_lshlrev_b32_e32 v134, 16, v178
	v_and_b32_e32 v135, 0xffff0000, v178
	v_lshlrev_b32_e32 v136, 16, v179
	v_and_b32_e32 v137, 0xffff0000, v179
	v_pk_add_f32 v[134:135], v[68:69], v[134:135]
	v_pk_add_f32 v[136:137], v[70:71], v[136:137]
	v_lshlrev_b32_e32 v138, 16, v180
	v_and_b32_e32 v139, 0xffff0000, v180
	v_lshlrev_b32_e32 v140, 16, v181
	v_and_b32_e32 v141, 0xffff0000, v181
	v_pk_add_f32 v[138:139], v[64:65], v[138:139]
	v_pk_add_f32 v[140:141], v[66:67], v[140:141]
	global_store_dwordx4 v[142:143], v[134:137], off
	global_store_dwordx4 v[142:143], v[138:141], off offset:16
	s_nop 0
	v_lshlrev_b32_e32 v134, 16, v130
	v_and_b32_e32 v135, 0xffff0000, v130
	v_lshlrev_b32_e32 v130, 16, v131
	v_and_b32_e32 v131, 0xffff0000, v131
	v_pk_add_f32 v[134:135], v[4:5], v[134:135]
	v_pk_add_f32 v[136:137], v[6:7], v[130:131]
	v_lshlrev_b32_e32 v130, 16, v132
	v_and_b32_e32 v131, 0xffff0000, v132
	v_lshlrev_b32_e32 v132, 16, v133
	v_and_b32_e32 v133, 0xffff0000, v133
	v_pk_add_f32 v[130:131], v[0:1], v[130:131]
	v_pk_add_f32 v[132:133], v[2:3], v[132:133]
	global_store_dwordx4 v[142:143], v[134:137], off offset:512
	global_store_dwordx4 v[142:143], v[130:133], off offset:528
	s_mov_b64 s[10:11], 0
; __device__ __forceinline__ unsigned pk2(float lo, float hi) { const f32x2_t f = {lo, hi}; const bf16x2_t b = __builtin_convertvector(f, bf16x2_t); return __builtin_bit_cast(unsigned, b); }
;   __device__ __forceinline__ void operator()(const f32x4 (&acc)[2][2][4][2], const pg8::Unit& u, int wr, int wc, int fr, int fq) const {
;     ...
;       const float* rs2 = (const float*)(ws + O_RSTD2) + (size_t)slice * TS; u16* hb = (u16*)(ws + O_HB + (size_t)(slice & 1) * HB_BYTES);
;       float rsv[2][4];
; #pragma unroll
;       for (int ai = 0; ai < 2; ++ai)
; #pragma unroll
;         for (int m = 0; m < 4; ++m) rsv[ai][m] = rs2[row0 + ai * 128 + m * 16];
;       __builtin_amdgcn_sched_barrier(0);
; #pragma unroll
;       for (int ai = 0; ai < 2; ++ai)
; #pragma unroll
;         for (int m = 0; m < 4; ++m) {
;           const int row = row0 + ai * 128 + m * 16; const float rs = rsv[ai][m];
; #pragma unroll
;           for (int bj = 0; bj < 2; ++bj) {
;             const int c = col0 + bj * 128;
;             f32x4 a = acc[ai][bj][m][0] * rs, b = acc[ai][bj][m][1] * rs;
; #pragma unroll
;             for (int e = 0; e < 4; ++e) { a[e] = fmaxf(a[e], 0.f); a[e] *= a[e]; b[e] = fmaxf(b[e], 0.f); b[e] *= b[e]; }
;             u32x4 o; o.x = pk2(a[0], a[1]); o.y = pk2(a[2], a[3]); o.z = pk2(b[0], b[1]); o.w = pk2(b[2], b[3]);
;             *(u32x4*)(hb + (size_t)row * DFF + c) = o;
;           }
.LBB0_62:
	s_andn2_b64 vcc, exec, s[10:11]
	s_cbranch_vccnz .LBB0_64
	v_readlane_b32 s10, v254, 16
	v_ashrrev_i32_e32 v177, 31, v176
	v_readlane_b32 s11, v254, 17
	v_or_b32_e32 v150, 16, v176
	v_or_b32_e32 v152, 32, v176
	v_lshl_add_u64 v[130:131], v[176:177], 2, s[10:11]
	global_load_dword v144, v[130:131], off
	global_load_dword v146, v[130:131], off offset:64
	global_load_dword v148, v[130:131], off offset:128
	global_load_dword v138, v[130:131], off offset:192
	global_load_dword v136, v[130:131], off offset:512
	global_load_dword v134, v[130:131], off offset:576
	global_load_dword v132, v[130:131], off offset:640
	global_load_dword v80, v[130:131], off offset:704
	v_or_b32_e32 v154, 48, v176
	v_ashrrev_i32_e32 v151, 31, v150
	v_ashrrev_i32_e32 v153, 31, v152
	v_ashrrev_i32_e32 v155, 31, v154
	s_waitcnt vmcnt(0) lgkmcnt(0)
	v_pk_mul_f32 v[142:143], v[126:127], v[144:145] op_sel_hi:[1,0]
	v_pk_mul_f32 v[156:157], v[124:125], v[144:145] op_sel_hi:[1,0]
	v_readlane_b32 s10, v254, 23
	v_pk_mul_f32 v[140:141], v[128:129], v[144:145] op_sel_hi:[1,0]
	v_pk_mul_f32 v[158:159], v[122:123], v[144:145] op_sel_hi:[1,0]
	v_max_f32_e32 v142, 0, v142
	v_max_f32_e32 v143, 0, v143
	v_max_f32_e32 v156, 0, v156
	v_max_f32_e32 v157, 0, v157
	v_lshlrev_b64 v[130:131], 13, v[176:177]
	v_readlane_b32 s11, v254, 24
	v_max_f32_e32 v158, 0, v158
	v_pk_mul_f32 v[142:143], v[142:143], v[142:143]
	v_max_f32_e32 v159, 0, v159
	v_max_f32_e32 v140, 0, v140
	v_max_f32_e32 v141, 0, v141
	v_pk_mul_f32 v[156:157], v[156:157], v[156:157]
	v_ashrrev_i32_e32 v175, 31, v174
	v_lshl_add_u64 v[130:131], s[10:11], 0, v[130:131]
	v_pk_mul_f32 v[158:159], v[158:159], v[158:159]
	v_pk_mul_f32 v[160:161], v[140:141], v[140:141]
	v_cvt_pk_bf16_f32 v140, v142, v143
	v_cvt_pk_bf16_f32 v143, v156, v157
	v_lshlrev_b64 v[156:157], 1, v[174:175]
	v_cvt_pk_bf16_f32 v141, v160, v161
	v_cvt_pk_bf16_f32 v142, v158, v159
	v_lshl_add_u64 v[130:131], v[130:131], 0, v[156:157]
	global_store_dwordx4 v[130:131], v[140:143], off
	v_pk_mul_f32 v[158:159], v[58:59], v[144:145] op_sel_hi:[1,0]
	s_nop 0
	v_pk_mul_f32 v[140:141], v[62:63], v[144:145] op_sel_hi:[1,0]
	v_pk_mul_f32 v[142:143], v[60:61], v[144:145] op_sel_hi:[1,0]
	v_pk_mul_f32 v[144:145], v[56:57], v[144:145] op_sel_hi:[1,0]
	v_max_f32_e32 v142, 0, v142
	v_max_f32_e32 v144, 0, v144
	v_max_f32_e32 v143, 0, v143
	v_max_f32_e32 v145, 0, v145
	v_max_f32_e32 v140, 0, v140
	v_max_f32_e32 v158, 0, v158
	v_max_f32_e32 v141, 0, v141
	v_max_f32_e32 v159, 0, v159
	v_pk_mul_f32 v[142:143], v[142:143], v[142:143]
	v_pk_mul_f32 v[144:145], v[144:145], v[144:145]
	v_pk_mul_f32 v[160:161], v[140:141], v[140:141]
	v_pk_mul_f32 v[158:159], v[158:159], v[158:159]
	v_cvt_pk_bf16_f32 v140, v142, v143
	v_cvt_pk_bf16_f32 v141, v160, v161
	v_cvt_pk_bf16_f32 v142, v144, v145
	v_cvt_pk_bf16_f32 v143, v158, v159
	global_store_dwordx4 v[130:131], v[140:143], off offset:256
	v_pk_mul_f32 v[158:159], v[114:115], v[146:147] op_sel_hi:[1,0]
	s_nop 0
	v_lshlrev_b64 v[140:141], 13, v[150:151]
	v_lshl_add_u64 v[144:145], s[10:11], 0, v[140:141]
	v_pk_mul_f32 v[140:141], v[120:121], v[146:147] op_sel_hi:[1,0]
	v_pk_mul_f32 v[142:143], v[118:119], v[146:147] op_sel_hi:[1,0]
	v_pk_mul_f32 v[150:151], v[116:117], v[146:147] op_sel_hi:[1,0]
	v_max_f32_e32 v142, 0, v142
	v_max_f32_e32 v158, 0, v158
	v_max_f32_e32 v143, 0, v143
	v_max_f32_e32 v159, 0, v159
	v_max_f32_e32 v140, 0, v140
	v_max_f32_e32 v150, 0, v150
	v_max_f32_e32 v141, 0, v141
	v_max_f32_e32 v151, 0, v151
	v_pk_mul_f32 v[142:143], v[142:143], v[142:143]
	v_pk_mul_f32 v[158:159], v[158:159], v[158:159]
	v_pk_mul_f32 v[160:161], v[140:141], v[140:141]
	v_pk_mul_f32 v[150:151], v[150:151], v[150:151]
	v_cvt_pk_bf16_f32 v140, v142, v143
	v_cvt_pk_bf16_f32 v141, v160, v161
	v_cvt_pk_bf16_f32 v142, v158, v159
	v_cvt_pk_bf16_f32 v143, v150, v151
	v_lshl_add_u64 v[144:145], v[144:145], 0, v[156:157]
	global_store_dwordx4 v[144:145], v[140:143], off
	v_pk_mul_f32 v[150:151], v[50:51], v[146:147] op_sel_hi:[1,0]
	s_nop 0
	v_pk_mul_f32 v[140:141], v[54:55], v[146:147] op_sel_hi:[1,0]
	v_pk_mul_f32 v[142:143], v[52:53], v[146:147] op_sel_hi:[1,0]
	v_pk_mul_f32 v[146:147], v[48:49], v[146:147] op_sel_hi:[1,0]
	v_max_f32_e32 v142, 0, v142
	v_max_f32_e32 v146, 0, v146
	v_max_f32_e32 v143, 0, v143
	v_max_f32_e32 v147, 0, v147
	v_max_f32_e32 v140, 0, v140
	v_max_f32_e32 v150, 0, v150
	v_max_f32_e32 v141, 0, v141
	v_max_f32_e32 v151, 0, v151
	v_pk_mul_f32 v[142:143], v[142:143], v[142:143]
	v_pk_mul_f32 v[146:147], v[146:147], v[146:147]
	v_pk_mul_f32 v[158:159], v[140:141], v[140:141]
	v_pk_mul_f32 v[150:151], v[150:151], v[150:151]
	v_cvt_pk_bf16_f32 v140, v142, v143
	v_cvt_pk_bf16_f32 v141, v158, v159
	v_cvt_pk_bf16_f32 v142, v146, v147
	v_cvt_pk_bf16_f32 v143, v150, v151
	global_store_dwordx4 v[144:145], v[140:143], off offset:256
	v_pk_mul_f32 v[146:147], v[108:109], v[148:149] op_sel_hi:[1,0]
	v_pk_mul_f32 v[150:151], v[106:107], v[148:149] op_sel_hi:[1,0]
	v_lshlrev_b64 v[140:141], 13, v[152:153]
	v_lshl_add_u64 v[144:145], s[10:11], 0, v[140:141]
	v_pk_mul_f32 v[140:141], v[112:113], v[148:149] op_sel_hi:[1,0]
	v_pk_mul_f32 v[142:143], v[110:111], v[148:149] op_sel_hi:[1,0]
	v_max_f32_e32 v150, 0, v150
	v_max_f32_e32 v142, 0, v142
	v_max_f32_e32 v143, 0, v143
	v_max_f32_e32 v151, 0, v151
	v_max_f32_e32 v140, 0, v140
	v_max_f32_e32 v146, 0, v146
	v_max_f32_e32 v141, 0, v141
	v_max_f32_e32 v147, 0, v147
	v_pk_mul_f32 v[142:143], v[142:143], v[142:143]
	v_pk_mul_f32 v[150:151], v[150:151], v[150:151]
	v_pk_mul_f32 v[152:153], v[140:141], v[140:141]
	v_pk_mul_f32 v[146:147], v[146:147], v[146:147]
	v_cvt_pk_bf16_f32 v140, v142, v143
; __device__ __forceinline__ unsigned pk2(float lo, float hi) { const f32x2_t f = {lo, hi}; const bf16x2_t b = __builtin_convertvector(f, bf16x2_t); return __builtin_bit_cast(unsigned, b); }
;   __device__ __forceinline__ void operator()(const f32x4 (&acc)[2][2][4][2], const pg8::Unit& u, int wr, int wc, int fr, int fq) const {
;     ...
; #pragma unroll
;       for (int ai = 0; ai < 2; ++ai)
; #pragma unroll
;         for (int m = 0; m < 4; ++m) {
;           const int row = row0 + ai * 128 + m * 16; const float rs = rsv[ai][m];
; #pragma unroll
;           for (int bj = 0; bj < 2; ++bj) {
;             const int c = col0 + bj * 128;
;             f32x4 a = acc[ai][bj][m][0] * rs, b = acc[ai][bj][m][1] * rs;
; #pragma unroll
;             for (int e = 0; e < 4; ++e) { a[e] = fmaxf(a[e], 0.f); a[e] *= a[e]; b[e] = fmaxf(b[e], 0.f); b[e] *= b[e]; }
;             u32x4 o; o.x = pk2(a[0], a[1]); o.y = pk2(a[2], a[3]); o.z = pk2(b[0], b[1]); o.w = pk2(b[2], b[3]);
;             *(u32x4*)(hb + (size_t)row * DFF + c) = o;
;           }
	v_cvt_pk_bf16_f32 v141, v152, v153
	v_cvt_pk_bf16_f32 v142, v150, v151
	v_cvt_pk_bf16_f32 v143, v146, v147
	v_lshl_add_u64 v[144:145], v[144:145], 0, v[156:157]
	global_store_dwordx4 v[144:145], v[140:143], off
	v_pk_mul_f32 v[146:147], v[42:43], v[148:149] op_sel_hi:[1,0]
	s_nop 0
	v_pk_mul_f32 v[140:141], v[46:47], v[148:149] op_sel_hi:[1,0]
	v_pk_mul_f32 v[142:143], v[44:45], v[148:149] op_sel_hi:[1,0]
	v_pk_mul_f32 v[148:149], v[40:41], v[148:149] op_sel_hi:[1,0]
	v_max_f32_e32 v142, 0, v142
	v_max_f32_e32 v148, 0, v148
	v_max_f32_e32 v143, 0, v143
	v_max_f32_e32 v149, 0, v149
	v_max_f32_e32 v140, 0, v140
	v_max_f32_e32 v146, 0, v146
	v_max_f32_e32 v141, 0, v141
	v_max_f32_e32 v147, 0, v147
	v_pk_mul_f32 v[142:143], v[142:143], v[142:143]
	v_pk_mul_f32 v[148:149], v[148:149], v[148:149]
	v_pk_mul_f32 v[150:151], v[140:141], v[140:141]
	v_pk_mul_f32 v[146:147], v[146:147], v[146:147]
	v_cvt_pk_bf16_f32 v140, v142, v143
	v_cvt_pk_bf16_f32 v141, v150, v151
	v_cvt_pk_bf16_f32 v142, v148, v149
	v_cvt_pk_bf16_f32 v143, v146, v147
	global_store_dwordx4 v[144:145], v[140:143], off offset:256
	v_pk_mul_f32 v[146:147], v[100:101], v[138:139] op_sel_hi:[1,0]
	v_pk_mul_f32 v[148:149], v[98:99], v[138:139] op_sel_hi:[1,0]
	v_lshlrev_b64 v[140:141], 13, v[154:155]
	v_lshl_add_u64 v[144:145], s[10:11], 0, v[140:141]
	v_pk_mul_f32 v[140:141], v[104:105], v[138:139] op_sel_hi:[1,0]
	v_pk_mul_f32 v[142:143], v[102:103], v[138:139] op_sel_hi:[1,0]
	v_max_f32_e32 v148, 0, v148
	v_max_f32_e32 v142, 0, v142
	v_max_f32_e32 v143, 0, v143
	v_max_f32_e32 v149, 0, v149
	v_max_f32_e32 v140, 0, v140
	v_max_f32_e32 v146, 0, v146
	v_max_f32_e32 v141, 0, v141
	v_max_f32_e32 v147, 0, v147
	v_pk_mul_f32 v[142:143], v[142:143], v[142:143]
	v_pk_mul_f32 v[148:149], v[148:149], v[148:149]
	v_pk_mul_f32 v[150:151], v[140:141], v[140:141]
	v_pk_mul_f32 v[146:147], v[146:147], v[146:147]
	v_cvt_pk_bf16_f32 v140, v142, v143
	v_cvt_pk_bf16_f32 v141, v150, v151
	v_cvt_pk_bf16_f32 v142, v148, v149
	v_cvt_pk_bf16_f32 v143, v146, v147
	v_lshl_add_u64 v[144:145], v[144:145], 0, v[156:157]
	global_store_dwordx4 v[144:145], v[140:143], off
	v_pk_mul_f32 v[146:147], v[34:35], v[138:139] op_sel_hi:[1,0]
	s_mov_b64 s[10:11], 0x100000
	v_pk_mul_f32 v[140:141], v[38:39], v[138:139] op_sel_hi:[1,0]
	v_pk_mul_f32 v[142:143], v[36:37], v[138:139] op_sel_hi:[1,0]
	v_pk_mul_f32 v[138:139], v[32:33], v[138:139] op_sel_hi:[1,0]
	v_max_f32_e32 v142, 0, v142
	v_max_f32_e32 v138, 0, v138
	v_max_f32_e32 v139, 0, v139
	v_max_f32_e32 v143, 0, v143
	v_pk_mul_f32 v[148:149], v[138:139], v[138:139]
	v_max_f32_e32 v138, 0, v140
	v_max_f32_e32 v140, 0, v146
	v_max_f32_e32 v139, 0, v141
	v_max_f32_e32 v141, 0, v147
	v_pk_mul_f32 v[142:143], v[142:143], v[142:143]
	v_pk_mul_f32 v[150:151], v[138:139], v[138:139]
	v_pk_mul_f32 v[146:147], v[140:141], v[140:141]
	v_cvt_pk_bf16_f32 v138, v142, v143
	v_cvt_pk_bf16_f32 v139, v150, v151
	v_cvt_pk_bf16_f32 v140, v148, v149
	v_cvt_pk_bf16_f32 v141, v146, v147
	global_store_dwordx4 v[144:145], v[138:141], off offset:256
	v_pk_mul_f32 v[142:143], v[92:93], v[136:137] op_sel_hi:[1,0]
	v_pk_mul_f32 v[144:145], v[90:91], v[136:137] op_sel_hi:[1,0]
	v_pk_mul_f32 v[140:141], v[94:95], v[136:137] op_sel_hi:[1,0]
	v_pk_mul_f32 v[138:139], v[96:97], v[136:137] op_sel_hi:[1,0]
	v_max_f32_e32 v140, 0, v140
	v_max_f32_e32 v141, 0, v141
	v_max_f32_e32 v142, 0, v142
	v_max_f32_e32 v143, 0, v143
	v_max_f32_e32 v144, 0, v144
	v_pk_mul_f32 v[140:141], v[140:141], v[140:141]
	v_max_f32_e32 v145, 0, v145
	v_max_f32_e32 v138, 0, v138
	v_max_f32_e32 v139, 0, v139
	v_pk_mul_f32 v[142:143], v[142:143], v[142:143]
	v_pk_mul_f32 v[144:145], v[144:145], v[144:145]
	v_pk_mul_f32 v[146:147], v[138:139], v[138:139]
	v_cvt_pk_bf16_f32 v138, v140, v141
	v_cvt_pk_bf16_f32 v141, v142, v143
	v_lshl_add_u64 v[142:143], v[130:131], 0, s[10:11]
	s_mov_b32 s10, 0x100000
	v_cvt_pk_bf16_f32 v140, v144, v145
	v_add_co_u32_e32 v144, vcc, s10, v130
	v_cvt_pk_bf16_f32 v139, v146, v147
	s_nop 0
	v_addc_co_u32_e32 v145, vcc, 0, v131, vcc
	global_store_dwordx4 v[144:145], v[138:141], off
	v_pk_mul_f32 v[144:145], v[26:27], v[136:137] op_sel_hi:[1,0]
	s_mov_b64 s[10:11], 0x120000
	v_pk_mul_f32 v[138:139], v[30:31], v[136:137] op_sel_hi:[1,0]
	v_pk_mul_f32 v[140:141], v[28:29], v[136:137] op_sel_hi:[1,0]
	v_pk_mul_f32 v[136:137], v[24:25], v[136:137] op_sel_hi:[1,0]
	v_max_f32_e32 v140, 0, v140
	v_max_f32_e32 v136, 0, v136
	v_max_f32_e32 v137, 0, v137
	v_max_f32_e32 v141, 0, v141
	v_pk_mul_f32 v[146:147], v[136:137], v[136:137]
	v_max_f32_e32 v136, 0, v138
	v_max_f32_e32 v138, 0, v144
	v_max_f32_e32 v137, 0, v139
	v_max_f32_e32 v139, 0, v145
	v_pk_mul_f32 v[140:141], v[140:141], v[140:141]
	v_pk_mul_f32 v[148:149], v[136:137], v[136:137]
	v_pk_mul_f32 v[144:145], v[138:139], v[138:139]
	v_cvt_pk_bf16_f32 v136, v140, v141
	v_cvt_pk_bf16_f32 v137, v148, v149
	v_cvt_pk_bf16_f32 v138, v146, v147
	v_cvt_pk_bf16_f32 v139, v144, v145
	global_store_dwordx4 v[142:143], v[136:139], off offset:256
	v_pk_mul_f32 v[140:141], v[84:85], v[134:135] op_sel_hi:[1,0]
	v_pk_mul_f32 v[142:143], v[82:83], v[134:135] op_sel_hi:[1,0]
	v_pk_mul_f32 v[138:139], v[86:87], v[134:135] op_sel_hi:[1,0]
	v_pk_mul_f32 v[136:137], v[88:89], v[134:135] op_sel_hi:[1,0]
	v_max_f32_e32 v138, 0, v138
	v_max_f32_e32 v139, 0, v139
	v_max_f32_e32 v140, 0, v140
	v_max_f32_e32 v141, 0, v141
	v_max_f32_e32 v142, 0, v142
; __device__ __forceinline__ unsigned pk2(float lo, float hi) { const f32x2_t f = {lo, hi}; const bf16x2_t b = __builtin_convertvector(f, bf16x2_t); return __builtin_bit_cast(unsigned, b); }
;   __device__ __forceinline__ void operator()(const f32x4 (&acc)[2][2][4][2], const pg8::Unit& u, int wr, int wc, int fr, int fq) const {
;     ...
; #pragma unroll
;       for (int ai = 0; ai < 2; ++ai)
; #pragma unroll
;         for (int m = 0; m < 4; ++m) {
;           const int row = row0 + ai * 128 + m * 16; const float rs = rsv[ai][m];
; #pragma unroll
;           for (int bj = 0; bj < 2; ++bj) {
;             const int c = col0 + bj * 128;
;             f32x4 a = acc[ai][bj][m][0] * rs, b = acc[ai][bj][m][1] * rs;
; #pragma unroll
;             for (int e = 0; e < 4; ++e) { a[e] = fmaxf(a[e], 0.f); a[e] *= a[e]; b[e] = fmaxf(b[e], 0.f); b[e] *= b[e]; }
;             u32x4 o; o.x = pk2(a[0], a[1]); o.y = pk2(a[2], a[3]); o.z = pk2(b[0], b[1]); o.w = pk2(b[2], b[3]);
;             *(u32x4*)(hb + (size_t)row * DFF + c) = o;
;           }
	v_pk_mul_f32 v[138:139], v[138:139], v[138:139]
	v_max_f32_e32 v143, 0, v143
	v_max_f32_e32 v136, 0, v136
	v_max_f32_e32 v137, 0, v137
	v_pk_mul_f32 v[140:141], v[140:141], v[140:141]
	v_pk_mul_f32 v[142:143], v[142:143], v[142:143]
	v_pk_mul_f32 v[144:145], v[136:137], v[136:137]
	v_cvt_pk_bf16_f32 v136, v138, v139
	v_cvt_pk_bf16_f32 v139, v140, v141
	v_lshl_add_u64 v[140:141], v[130:131], 0, s[10:11]
	s_mov_b32 s10, 0x120000
	v_cvt_pk_bf16_f32 v138, v142, v143
	v_add_co_u32_e32 v142, vcc, s10, v130
	v_cvt_pk_bf16_f32 v137, v144, v145
	s_nop 0
	v_addc_co_u32_e32 v143, vcc, 0, v131, vcc
	global_store_dwordx4 v[142:143], v[136:139], off
	v_pk_mul_f32 v[142:143], v[18:19], v[134:135] op_sel_hi:[1,0]
	s_mov_b64 s[10:11], 0x140000
	v_pk_mul_f32 v[136:137], v[22:23], v[134:135] op_sel_hi:[1,0]
	v_pk_mul_f32 v[138:139], v[20:21], v[134:135] op_sel_hi:[1,0]
	v_pk_mul_f32 v[134:135], v[16:17], v[134:135] op_sel_hi:[1,0]
	v_max_f32_e32 v138, 0, v138
	v_max_f32_e32 v134, 0, v134
	v_max_f32_e32 v135, 0, v135
	v_max_f32_e32 v139, 0, v139
	v_pk_mul_f32 v[144:145], v[134:135], v[134:135]
	v_max_f32_e32 v134, 0, v136
	v_max_f32_e32 v136, 0, v142
	v_max_f32_e32 v135, 0, v137
	v_max_f32_e32 v137, 0, v143
	v_pk_mul_f32 v[138:139], v[138:139], v[138:139]
	v_pk_mul_f32 v[146:147], v[134:135], v[134:135]
	v_pk_mul_f32 v[142:143], v[136:137], v[136:137]
	v_cvt_pk_bf16_f32 v134, v138, v139
	v_cvt_pk_bf16_f32 v135, v146, v147
	v_cvt_pk_bf16_f32 v136, v144, v145
	v_cvt_pk_bf16_f32 v137, v142, v143
	global_store_dwordx4 v[140:141], v[134:137], off offset:256
	v_pk_mul_f32 v[138:139], v[74:75], v[132:133] op_sel_hi:[1,0]
	v_pk_mul_f32 v[140:141], v[72:73], v[132:133] op_sel_hi:[1,0]
	v_pk_mul_f32 v[136:137], v[76:77], v[132:133] op_sel_hi:[1,0]
	v_pk_mul_f32 v[134:135], v[78:79], v[132:133] op_sel_hi:[1,0]
	v_max_f32_e32 v136, 0, v136
	v_max_f32_e32 v137, 0, v137
	v_max_f32_e32 v138, 0, v138
	v_max_f32_e32 v139, 0, v139
	v_max_f32_e32 v140, 0, v140
	v_pk_mul_f32 v[136:137], v[136:137], v[136:137]
	v_max_f32_e32 v141, 0, v141
	v_max_f32_e32 v134, 0, v134
	v_max_f32_e32 v135, 0, v135
	v_pk_mul_f32 v[138:139], v[138:139], v[138:139]
	v_pk_mul_f32 v[140:141], v[140:141], v[140:141]
	v_pk_mul_f32 v[142:143], v[134:135], v[134:135]
	v_cvt_pk_bf16_f32 v134, v136, v137
	v_cvt_pk_bf16_f32 v137, v138, v139
	v_lshl_add_u64 v[138:139], v[130:131], 0, s[10:11]
	s_mov_b32 s10, 0x140000
	v_cvt_pk_bf16_f32 v136, v140, v141
	v_add_co_u32_e32 v140, vcc, s10, v130
	v_cvt_pk_bf16_f32 v135, v142, v143
	s_nop 0
	v_addc_co_u32_e32 v141, vcc, 0, v131, vcc
	global_store_dwordx4 v[140:141], v[134:137], off
	v_pk_mul_f32 v[140:141], v[10:11], v[132:133] op_sel_hi:[1,0]
	s_mov_b64 s[10:11], 0x160000
	v_pk_mul_f32 v[134:135], v[14:15], v[132:133] op_sel_hi:[1,0]
	v_pk_mul_f32 v[136:137], v[12:13], v[132:133] op_sel_hi:[1,0]
	v_pk_mul_f32 v[132:133], v[8:9], v[132:133] op_sel_hi:[1,0]
	v_max_f32_e32 v136, 0, v136
	v_max_f32_e32 v132, 0, v132
	v_max_f32_e32 v133, 0, v133
	v_max_f32_e32 v137, 0, v137
	v_pk_mul_f32 v[142:143], v[132:133], v[132:133]
	v_max_f32_e32 v132, 0, v134
	v_max_f32_e32 v134, 0, v140
	v_max_f32_e32 v133, 0, v135
	v_max_f32_e32 v135, 0, v141
	v_pk_mul_f32 v[136:137], v[136:137], v[136:137]
	v_pk_mul_f32 v[144:145], v[132:133], v[132:133]
	v_pk_mul_f32 v[140:141], v[134:135], v[134:135]
	v_cvt_pk_bf16_f32 v132, v136, v137
	v_cvt_pk_bf16_f32 v133, v144, v145
	v_cvt_pk_bf16_f32 v134, v142, v143
	v_cvt_pk_bf16_f32 v135, v140, v141
	global_store_dwordx4 v[138:139], v[132:135], off offset:256
	v_pk_mul_f32 v[136:137], v[66:67], v[80:81] op_sel_hi:[1,0]
	v_pk_mul_f32 v[138:139], v[64:65], v[80:81] op_sel_hi:[1,0]
	v_pk_mul_f32 v[134:135], v[68:69], v[80:81] op_sel_hi:[1,0]
	v_pk_mul_f32 v[132:133], v[70:71], v[80:81] op_sel_hi:[1,0]
	v_max_f32_e32 v134, 0, v134
	v_max_f32_e32 v135, 0, v135
	v_max_f32_e32 v136, 0, v136
	v_max_f32_e32 v137, 0, v137
	v_pk_mul_f32 v[134:135], v[134:135], v[134:135]
	v_max_f32_e32 v132, 0, v132
	v_max_f32_e32 v133, 0, v133
	v_pk_mul_f32 v[136:137], v[136:137], v[136:137]
	v_max_f32_e32 v138, 0, v138
	v_max_f32_e32 v139, 0, v139
	v_pk_mul_f32 v[140:141], v[132:133], v[132:133]
	v_cvt_pk_bf16_f32 v132, v134, v135
	v_cvt_pk_bf16_f32 v135, v136, v137
	v_lshl_add_u64 v[136:137], v[130:131], 0, s[10:11]
	s_mov_b32 s10, 0x160000
	v_pk_mul_f32 v[138:139], v[138:139], v[138:139]
	v_add_co_u32_e32 v130, vcc, s10, v130
	v_cvt_pk_bf16_f32 v133, v140, v141
	v_cvt_pk_bf16_f32 v134, v138, v139
	v_addc_co_u32_e32 v131, vcc, 0, v131, vcc
	global_store_dwordx4 v[130:131], v[132:135], off
	v_pk_mul_f32 v[130:131], v[6:7], v[80:81] op_sel_hi:[1,0]
	v_pk_mul_f32 v[138:139], v[0:1], v[80:81] op_sel_hi:[1,0]
	v_pk_mul_f32 v[132:133], v[4:5], v[80:81] op_sel_hi:[1,0]
	v_pk_mul_f32 v[134:135], v[2:3], v[80:81] op_sel_hi:[1,0]
	v_max_f32_e32 v132, 0, v132
	v_max_f32_e32 v138, 0, v138
	v_max_f32_e32 v133, 0, v133
	v_max_f32_e32 v139, 0, v139
	v_max_f32_e32 v130, 0, v130
	v_max_f32_e32 v134, 0, v134
	v_max_f32_e32 v131, 0, v131
	v_max_f32_e32 v135, 0, v135
	v_pk_mul_f32 v[132:133], v[132:133], v[132:133]
	v_pk_mul_f32 v[138:139], v[138:139], v[138:139]
	v_pk_mul_f32 v[140:141], v[130:131], v[130:131]
	v_pk_mul_f32 v[134:135], v[134:135], v[134:135]
	v_cvt_pk_bf16_f32 v130, v132, v133
	v_cvt_pk_bf16_f32 v131, v140, v141
	v_cvt_pk_bf16_f32 v132, v138, v139
	v_cvt_pk_bf16_f32 v133, v134, v135
	global_store_dwordx4 v[136:137], v[130:133], off offset:256

; __device__ __forceinline__ unsigned pk2(float lo, float hi) { const f32x2_t f = {lo, hi}; const bf16x2_t b = __builtin_convertvector(f, bf16x2_t); return __builtin_bit_cast(unsigned, b); }
;   __device__ __forceinline__ void operator()(const f32x4 (&acc)[2][2][4][2], const pg8::Unit& u, int wr, int wc, int fr, int fq) const {
;     ...
;       const float* xin = (u.pm < 256) ? P->in[I_XP] : P->in[I_XS] - (size_t)65536 * DM;
;       u16* x2b = (u16*)(ws + O_X2B);
;       float* ssq = (float*)(ws + O_SSQ2);
; #pragma unroll
;       for (int g8 = 0; g8 < 4; ++g8) {
;         const int ai = g8 >> 1, m0 = (g8 & 1) * 2;
;         f32x4 xa[2][2][2];
; #pragma unroll
;         for (int mm = 0; mm < 2; ++mm)
; #pragma unroll
;           for (int bj = 0; bj < 2; ++bj) {
;             const float* xp = xin + (size_t)(row0 + ai * 128 + (m0 + mm) * 16) * DM + col0 + bj * 128;
;             xa[mm][bj][0] = *(const f32x4*)xp; xa[mm][bj][1] = *(const f32x4*)(xp + 4);
;           }
;         __builtin_amdgcn_sched_barrier(0);
; #pragma unroll
;         for (int mm = 0; mm < 2; ++mm) {
;           const int m = m0 + mm, row = row0 + ai * 128 + m * 16; float sq = 0.f;
; #pragma unroll
;           for (int bj = 0; bj < 2; ++bj) {
;             const int c = col0 + bj * 128;
;             const f32x4 a = acc[ai][bj][m][0] + xa[mm][bj][0], b = acc[ai][bj][m][1] + xa[mm][bj][1];
;             u32x4 o; o.x = pk2(a[0], a[1]); o.y = pk2(a[2], a[3]); o.z = pk2(b[0], b[1]); o.w = pk2(b[2], b[3]);
;             *(u32x4*)(x2b + (size_t)row * DM + c) = o;
;             sq += a[0] * a[0] + a[1] * a[1] + a[2] * a[2] + a[3] * a[3] + b[0] * b[0] + b[1] * b[1] + b[2] * b[2] + b[3] * b[3];
;           }
;           sq += __shfl_xor(sq, 16); sq += __shfl_xor(sq, 32);
;           if (fq == 0) ssq[(size_t)(u.pn * 4 + wc) * TALL + row] = sq;
.LBB0_65:
	s_andn2_b64 vcc, exec, s[10:11]
	s_cbranch_vccnz .LBB0_83
	s_cmpk_lt_i32 s73, 0x100
	v_readlane_b32 s10, v253, 17
	v_readlane_b32 s11, v253, 16
	s_cselect_b32 s10, s37, s10
	s_cselect_b32 s11, s36, s11
	v_mov_b32_e32 v130, s11
	v_mov_b32_e32 v131, s10
	v_ashrrev_i32_e32 v175, 31, v174
	v_ashrrev_i32_e32 v177, 31, v176
	v_lshl_add_u64 v[146:147], v[174:175], 2, v[130:131]
	v_lshlrev_b64 v[130:131], 12, v[176:177]
	v_or_b32_e32 v148, 16, v176
	v_lshl_add_u64 v[130:131], v[146:147], 0, v[130:131]
	v_ashrrev_i32_e32 v149, 31, v148
	global_load_dwordx4 v[152:155], v[130:131], off offset:16
	global_load_dwordx4 v[156:159], v[130:131], off
	global_load_dwordx4 v[178:181], v[130:131], off offset:528
	global_load_dwordx4 v[182:185], v[130:131], off offset:512
	v_lshlrev_b64 v[130:131], 12, v[148:149]
	v_lshl_add_u64 v[134:135], v[146:147], 0, v[130:131]
	global_load_dwordx4 v[138:141], v[134:135], off offset:16
	global_load_dwordx4 v[142:145], v[134:135], off
	global_load_dwordx4 v[130:133], v[134:135], off offset:528
	s_nop 0
	global_load_dwordx4 v[134:137], v[134:135], off offset:512
	v_and_b32_e32 v150, 64, v225
	v_xor_b32_e32 v80, 16, v225
	v_add_u32_e32 v151, 64, v150
	v_cmp_lt_i32_e32 vcc, v80, v151
	s_nop 1
	v_cndmask_b32_e32 v80, v225, v80, vcc
	v_lshlrev_b32_e32 v150, 2, v80
	v_xor_b32_e32 v80, 32, v225
	v_cmp_lt_i32_e32 vcc, v80, v151
	s_nop 1
	v_cndmask_b32_e32 v80, v225, v80, vcc
	v_lshlrev_b32_e32 v80, 2, v80
	s_waitcnt vmcnt(0)
	v_pk_add_f32 v[156:157], v[126:127], v[156:157]
	v_pk_add_f32 v[158:159], v[128:129], v[158:159]
	v_mul_f32_e32 v151, v157, v157
	v_fmac_f32_e32 v151, v156, v156
	v_fmac_f32_e32 v151, v158, v158
	v_pk_add_f32 v[192:193], v[122:123], v[152:153]
	v_cvt_pk_bf16_f32 v153, v158, v159
	v_fmac_f32_e32 v151, v159, v159
	v_pk_add_f32 v[158:159], v[60:61], v[182:183]
	v_pk_add_f32 v[190:191], v[124:125], v[154:155]
	v_mul_f32_e32 v155, v159, v159
	v_cvt_pk_bf16_f32 v152, v156, v157
	v_pk_add_f32 v[156:157], v[62:63], v[184:185]
	v_fmac_f32_e32 v155, v158, v158
	v_fmac_f32_e32 v155, v156, v156
	v_pk_add_f32 v[178:179], v[56:57], v[178:179]
	v_fmac_f32_e32 v155, v157, v157
	v_fmac_f32_e32 v151, v192, v192
	v_fmac_f32_e32 v155, v178, v178
	v_fmac_f32_e32 v151, v193, v193
	v_pk_add_f32 v[180:181], v[58:59], v[180:181]
	v_fmac_f32_e32 v155, v179, v179
	v_fmac_f32_e32 v151, v190, v190
	v_fmac_f32_e32 v155, v180, v180
	v_fmac_f32_e32 v151, v191, v191
	v_fmac_f32_e32 v155, v181, v181
	v_add_f32_e32 v151, v151, v155
	ds_bpermute_b32 v182, v150, v151
	v_lshlrev_b64 v[160:161], 11, v[176:177]
	v_lshl_add_u64 v[160:161], s[34:35], 0, v[160:161]
	v_cvt_pk_bf16_f32 v154, v192, v193
	v_cvt_pk_bf16_f32 v155, v190, v191
	v_lshl_add_u64 v[160:161], v[174:175], 1, v[160:161]
	s_waitcnt lgkmcnt(0)
	v_add_f32_e32 v151, v151, v182
	global_store_dwordx4 v[160:161], v[152:155], off
	ds_bpermute_b32 v152, v80, v151
	s_nop 0
	v_cvt_pk_bf16_f32 v154, v158, v159
	v_cvt_pk_bf16_f32 v155, v156, v157
	v_cvt_pk_bf16_f32 v156, v178, v179
	v_cvt_pk_bf16_f32 v157, v180, v181
	global_store_dwordx4 v[160:161], v[154:157], off offset:256
	s_and_saveexec_b64 s[10:11], s[6:7]
	v_readlane_b32 s73, v254, 15
	v_readlane_b32 s74, v254, 41
	v_readlane_b32 s75, v254, 14
	s_cbranch_execz .LBB0_68
	s_lshl_b32 s12, s72, 2
	s_or_b32 s12, s12, s73
	s_mul_hi_i32 s13, s12, 0x50000
	s_mul_i32 s12, s12, 0x50000
	s_add_u32 s12, s74, s12
	s_addc_u32 s13, s75, s13
	s_waitcnt lgkmcnt(0)
	v_add_f32_e32 v151, v151, v152
	v_lshl_add_u64 v[152:153], v[176:177], 2, s[12:13]
	global_store_dword v[152:153], v151, off
.LBB0_68:
	s_or_b64 exec, exec, s[10:11]
	v_pk_add_f32 v[142:143], v[118:119], v[142:143]
	s_waitcnt lgkmcnt(0)
	v_pk_add_f32 v[152:153], v[116:117], v[140:141]
	v_mul_f32_e32 v141, v143, v143
	v_pk_add_f32 v[144:145], v[120:121], v[144:145]
	v_fmac_f32_e32 v141, v142, v142
	v_fmac_f32_e32 v141, v144, v144
	v_pk_add_f32 v[134:135], v[52:53], v[134:135]
	v_pk_add_f32 v[154:155], v[114:115], v[138:139]
	v_cvt_pk_bf16_f32 v139, v144, v145
	v_fmac_f32_e32 v141, v145, v145
	v_pk_add_f32 v[144:145], v[48:49], v[130:131]
	v_mul_f32_e32 v130, v135, v135
	v_pk_add_f32 v[136:137], v[54:55], v[136:137]
	v_fmac_f32_e32 v130, v134, v134
	v_fmac_f32_e32 v130, v136, v136
	v_fmac_f32_e32 v130, v137, v137
	v_fmac_f32_e32 v141, v154, v154
	v_fmac_f32_e32 v130, v144, v144
	v_cvt_pk_bf16_f32 v138, v142, v143
	v_fmac_f32_e32 v141, v155, v155
	v_pk_add_f32 v[142:143], v[50:51], v[132:133]
	v_fmac_f32_e32 v130, v145, v145
	v_fmac_f32_e32 v141, v152, v152
	v_fmac_f32_e32 v130, v142, v142
	v_fmac_f32_e32 v141, v153, v153
	v_fmac_f32_e32 v130, v143, v143
	v_add_f32_e32 v130, v141, v130
	ds_bpermute_b32 v131, v150, v130
	v_lshlrev_b64 v[148:149], 11, v[148:149]
	v_lshl_add_u64 v[148:149], s[34:35], 0, v[148:149]
	v_cvt_pk_bf16_f32 v140, v154, v155
	v_cvt_pk_bf16_f32 v141, v152, v153
	s_waitcnt lgkmcnt(0)
	v_add_f32_e32 v130, v130, v131
	ds_bpermute_b32 v131, v80, v130
	v_lshl_add_u64 v[148:149], v[174:175], 1, v[148:149]
	v_cvt_pk_bf16_f32 v132, v134, v135
	v_cvt_pk_bf16_f32 v133, v136, v137
	v_cvt_pk_bf16_f32 v134, v144, v145
	v_cvt_pk_bf16_f32 v135, v142, v143
	global_store_dwordx4 v[148:149], v[138:141], off
	global_store_dwordx4 v[148:149], v[132:135], off offset:256
	s_and_saveexec_b64 s[10:11], s[6:7]
	s_cbranch_execz .LBB0_70
	s_lshl_b32 s12, s72, 2
	s_or_b32 s12, s12, s73
	s_mul_hi_i32 s13, s12, 0x50000
	s_mul_i32 s12, s12, 0x50000
	s_add_u32 s12, s74, s12
	s_addc_u32 s13, s75, s13
	s_waitcnt lgkmcnt(0)
	v_add_f32_e32 v132, v130, v131
	v_lshl_add_u64 v[130:131], v[176:177], 2, s[12:13]
	global_store_dword v[130:131], v132, off offset:64
; __device__ __forceinline__ unsigned pk2(float lo, float hi) { const f32x2_t f = {lo, hi}; const bf16x2_t b = __builtin_convertvector(f, bf16x2_t); return __builtin_bit_cast(unsigned, b); }
;   __device__ __forceinline__ void operator()(const f32x4 (&acc)[2][2][4][2], const pg8::Unit& u, int wr, int wc, int fr, int fq) const {
;     ...
;       for (int g8 = 0; g8 < 4; ++g8) {
;         const int ai = g8 >> 1, m0 = (g8 & 1) * 2;
;         f32x4 xa[2][2][2];
; #pragma unroll
;         for (int mm = 0; mm < 2; ++mm)
; #pragma unroll
;           for (int bj = 0; bj < 2; ++bj) {
;             const float* xp = xin + (size_t)(row0 + ai * 128 + (m0 + mm) * 16) * DM + col0 + bj * 128;
;             xa[mm][bj][0] = *(const f32x4*)xp; xa[mm][bj][1] = *(const f32x4*)(xp + 4);
;           }
;         __builtin_amdgcn_sched_barrier(0);
; #pragma unroll
;         for (int mm = 0; mm < 2; ++mm) {
;           const int m = m0 + mm, row = row0 + ai * 128 + m * 16; float sq = 0.f;
; #pragma unroll
;           for (int bj = 0; bj < 2; ++bj) {
;             const int c = col0 + bj * 128;
;             const f32x4 a = acc[ai][bj][m][0] + xa[mm][bj][0], b = acc[ai][bj][m][1] + xa[mm][bj][1];
;             u32x4 o; o.x = pk2(a[0], a[1]); o.y = pk2(a[2], a[3]); o.z = pk2(b[0], b[1]); o.w = pk2(b[2], b[3]);
;             *(u32x4*)(x2b + (size_t)row * DM + c) = o;
;             sq += a[0] * a[0] + a[1] * a[1] + a[2] * a[2] + a[3] * a[3] + b[0] * b[0] + b[1] * b[1] + b[2] * b[2] + b[3] * b[3];
;           }
;           sq += __shfl_xor(sq, 16); sq += __shfl_xor(sq, 32);
;           if (fq == 0) ssq[(size_t)(u.pn * 4 + wc) * TALL + row] = sq;
;         }
;         __builtin_amdgcn_sched_barrier(0);
;       }
.LBB0_70:
	s_or_b64 exec, exec, s[10:11]
	v_or_b32_e32 v160, 32, v176
	v_ashrrev_i32_e32 v161, 31, v160
	s_waitcnt lgkmcnt(0)
	v_lshlrev_b64 v[130:131], 12, v[160:161]
	v_or_b32_e32 v148, 48, v176
	v_lshl_add_u64 v[130:131], v[146:147], 0, v[130:131]
	v_ashrrev_i32_e32 v149, 31, v148
	global_load_dwordx4 v[152:155], v[130:131], off offset:16
	global_load_dwordx4 v[156:159], v[130:131], off
	global_load_dwordx4 v[178:181], v[130:131], off offset:528
	global_load_dwordx4 v[182:185], v[130:131], off offset:512
	v_lshlrev_b64 v[130:131], 12, v[148:149]
	v_lshl_add_u64 v[134:135], v[146:147], 0, v[130:131]
	global_load_dwordx4 v[138:141], v[134:135], off offset:16
	global_load_dwordx4 v[142:145], v[134:135], off
	global_load_dwordx4 v[130:133], v[134:135], off offset:528
	s_nop 0
	global_load_dwordx4 v[134:137], v[134:135], off offset:512
	s_waitcnt vmcnt(0)
	v_pk_add_f32 v[156:157], v[110:111], v[156:157]
	v_pk_add_f32 v[158:159], v[112:113], v[158:159]
	v_mul_f32_e32 v151, v157, v157
	v_fmac_f32_e32 v151, v156, v156
	v_fmac_f32_e32 v151, v158, v158
	v_pk_add_f32 v[192:193], v[106:107], v[152:153]
	v_cvt_pk_bf16_f32 v153, v158, v159
	v_fmac_f32_e32 v151, v159, v159
	v_pk_add_f32 v[158:159], v[44:45], v[182:183]
	v_pk_add_f32 v[190:191], v[108:109], v[154:155]
	v_mul_f32_e32 v155, v159, v159
	v_cvt_pk_bf16_f32 v152, v156, v157
	v_pk_add_f32 v[156:157], v[46:47], v[184:185]
	v_fmac_f32_e32 v155, v158, v158
	v_fmac_f32_e32 v155, v156, v156
	v_pk_add_f32 v[178:179], v[40:41], v[178:179]
	v_fmac_f32_e32 v155, v157, v157
	v_fmac_f32_e32 v151, v192, v192
	v_fmac_f32_e32 v155, v178, v178
	v_fmac_f32_e32 v151, v193, v193
	v_pk_add_f32 v[180:181], v[42:43], v[180:181]
	v_fmac_f32_e32 v155, v179, v179
	v_fmac_f32_e32 v151, v190, v190
	v_fmac_f32_e32 v155, v180, v180
	v_fmac_f32_e32 v151, v191, v191
	v_fmac_f32_e32 v155, v181, v181
	v_add_f32_e32 v151, v151, v155
	ds_bpermute_b32 v182, v150, v151
	v_lshlrev_b64 v[160:161], 11, v[160:161]
	v_lshl_add_u64 v[160:161], s[34:35], 0, v[160:161]
	v_cvt_pk_bf16_f32 v154, v192, v193
	v_cvt_pk_bf16_f32 v155, v190, v191
	v_lshl_add_u64 v[160:161], v[174:175], 1, v[160:161]
	s_waitcnt lgkmcnt(0)
	v_add_f32_e32 v151, v151, v182
	global_store_dwordx4 v[160:161], v[152:155], off
	ds_bpermute_b32 v152, v80, v151
	s_nop 0
	v_cvt_pk_bf16_f32 v154, v158, v159
	v_cvt_pk_bf16_f32 v155, v156, v157
	v_cvt_pk_bf16_f32 v156, v178, v179
	v_cvt_pk_bf16_f32 v157, v180, v181
	global_store_dwordx4 v[160:161], v[154:157], off offset:256
	s_and_saveexec_b64 s[10:11], s[6:7]
	s_cbranch_execz .LBB0_72
	s_lshl_b32 s12, s72, 2
	s_or_b32 s12, s12, s73
	s_mul_hi_i32 s13, s12, 0x50000
	s_mul_i32 s12, s12, 0x50000
	s_add_u32 s12, s74, s12
	s_addc_u32 s13, s75, s13
	s_waitcnt lgkmcnt(0)
	v_add_f32_e32 v151, v151, v152
	v_lshl_add_u64 v[152:153], v[176:177], 2, s[12:13]
	global_store_dword v[152:153], v151, off offset:128
.LBB0_72:
	s_or_b64 exec, exec, s[10:11]
	v_pk_add_f32 v[142:143], v[102:103], v[142:143]
	s_waitcnt lgkmcnt(0)
	v_pk_add_f32 v[152:153], v[100:101], v[140:141]
	v_mul_f32_e32 v141, v143, v143
	v_pk_add_f32 v[144:145], v[104:105], v[144:145]
	v_fmac_f32_e32 v141, v142, v142
	v_fmac_f32_e32 v141, v144, v144
	v_pk_add_f32 v[134:135], v[36:37], v[134:135]
	v_pk_add_f32 v[154:155], v[98:99], v[138:139]
	v_cvt_pk_bf16_f32 v139, v144, v145
	v_fmac_f32_e32 v141, v145, v145
	v_pk_add_f32 v[144:145], v[32:33], v[130:131]
	v_mul_f32_e32 v130, v135, v135
	v_pk_add_f32 v[136:137], v[38:39], v[136:137]
	v_fmac_f32_e32 v130, v134, v134
	v_fmac_f32_e32 v130, v136, v136
	v_fmac_f32_e32 v130, v137, v137
	v_fmac_f32_e32 v141, v154, v154
	v_fmac_f32_e32 v130, v144, v144
	v_cvt_pk_bf16_f32 v138, v142, v143
	v_fmac_f32_e32 v141, v155, v155
	v_pk_add_f32 v[142:143], v[34:35], v[132:133]
	v_fmac_f32_e32 v130, v145, v145
	v_fmac_f32_e32 v141, v152, v152
	v_fmac_f32_e32 v130, v142, v142
	v_fmac_f32_e32 v141, v153, v153
	v_fmac_f32_e32 v130, v143, v143
	v_add_f32_e32 v130, v141, v130
	ds_bpermute_b32 v131, v150, v130
	v_lshlrev_b64 v[148:149], 11, v[148:149]
	v_lshl_add_u64 v[148:149], s[34:35], 0, v[148:149]
	v_cvt_pk_bf16_f32 v140, v154, v155
	v_cvt_pk_bf16_f32 v141, v152, v153
	s_waitcnt lgkmcnt(0)
	v_add_f32_e32 v130, v130, v131
	ds_bpermute_b32 v131, v80, v130
	v_lshl_add_u64 v[148:149], v[174:175], 1, v[148:149]
	v_cvt_pk_bf16_f32 v132, v134, v135
	v_cvt_pk_bf16_f32 v133, v136, v137
	v_cvt_pk_bf16_f32 v134, v144, v145
	v_cvt_pk_bf16_f32 v135, v142, v143
	global_store_dwordx4 v[148:149], v[138:141], off
	global_store_dwordx4 v[148:149], v[132:135], off offset:256
	s_and_saveexec_b64 s[10:11], s[6:7]
	s_cbranch_execz .LBB0_74
	s_lshl_b32 s12, s72, 2
	s_or_b32 s12, s12, s73
	s_mul_hi_i32 s13, s12, 0x50000
	s_mul_i32 s12, s12, 0x50000
	s_add_u32 s12, s74, s12
	s_addc_u32 s13, s75, s13
	s_waitcnt lgkmcnt(0)
	v_add_f32_e32 v132, v130, v131
	v_lshl_add_u64 v[130:131], v[176:177], 2, s[12:13]
	global_store_dword v[130:131], v132, off offset:192
; __device__ __forceinline__ unsigned pk2(float lo, float hi) { const f32x2_t f = {lo, hi}; const bf16x2_t b = __builtin_convertvector(f, bf16x2_t); return __builtin_bit_cast(unsigned, b); }
;   __device__ __forceinline__ void operator()(const f32x4 (&acc)[2][2][4][2], const pg8::Unit& u, int wr, int wc, int fr, int fq) const {
;     ...
;       for (int g8 = 0; g8 < 4; ++g8) {
;         const int ai = g8 >> 1, m0 = (g8 & 1) * 2;
;         f32x4 xa[2][2][2];
; #pragma unroll
;         for (int mm = 0; mm < 2; ++mm)
; #pragma unroll
;           for (int bj = 0; bj < 2; ++bj) {
;             const float* xp = xin + (size_t)(row0 + ai * 128 + (m0 + mm) * 16) * DM + col0 + bj * 128;
;             xa[mm][bj][0] = *(const f32x4*)xp; xa[mm][bj][1] = *(const f32x4*)(xp + 4);
;           }
;         __builtin_amdgcn_sched_barrier(0);
; #pragma unroll
;         for (int mm = 0; mm < 2; ++mm) {
;           const int m = m0 + mm, row = row0 + ai * 128 + m * 16; float sq = 0.f;
; #pragma unroll
;           for (int bj = 0; bj < 2; ++bj) {
;             const int c = col0 + bj * 128;
;             const f32x4 a = acc[ai][bj][m][0] + xa[mm][bj][0], b = acc[ai][bj][m][1] + xa[mm][bj][1];
;             u32x4 o; o.x = pk2(a[0], a[1]); o.y = pk2(a[2], a[3]); o.z = pk2(b[0], b[1]); o.w = pk2(b[2], b[3]);
;             *(u32x4*)(x2b + (size_t)row * DM + c) = o;
;             sq += a[0] * a[0] + a[1] * a[1] + a[2] * a[2] + a[3] * a[3] + b[0] * b[0] + b[1] * b[1] + b[2] * b[2] + b[3] * b[3];
;           }
;           sq += __shfl_xor(sq, 16); sq += __shfl_xor(sq, 32);
;           if (fq == 0) ssq[(size_t)(u.pn * 4 + wc) * TALL + row] = sq;
;         }
;         __builtin_amdgcn_sched_barrier(0);
;       }
.LBB0_74:
	s_or_b64 exec, exec, s[10:11]
	v_add_u32_e32 v160, 0x80, v176
	v_ashrrev_i32_e32 v161, 31, v160
	s_waitcnt lgkmcnt(0)
	v_lshlrev_b64 v[130:131], 12, v[160:161]
	v_add_u32_e32 v148, 0x90, v176
	v_lshl_add_u64 v[130:131], v[146:147], 0, v[130:131]
	v_ashrrev_i32_e32 v149, 31, v148
	global_load_dwordx4 v[152:155], v[130:131], off offset:16
	global_load_dwordx4 v[156:159], v[130:131], off
	global_load_dwordx4 v[178:181], v[130:131], off offset:528
	global_load_dwordx4 v[182:185], v[130:131], off offset:512
	v_lshlrev_b64 v[130:131], 12, v[148:149]
	v_lshl_add_u64 v[134:135], v[146:147], 0, v[130:131]
	global_load_dwordx4 v[138:141], v[134:135], off offset:16
	global_load_dwordx4 v[142:145], v[134:135], off
	global_load_dwordx4 v[130:133], v[134:135], off offset:528
	s_nop 0
	global_load_dwordx4 v[134:137], v[134:135], off offset:512
	s_waitcnt vmcnt(0)
	v_pk_add_f32 v[156:157], v[94:95], v[156:157]
	v_pk_add_f32 v[158:159], v[96:97], v[158:159]
	v_mul_f32_e32 v151, v157, v157
	v_fmac_f32_e32 v151, v156, v156
	v_fmac_f32_e32 v151, v158, v158
	v_pk_add_f32 v[192:193], v[90:91], v[152:153]
	v_cvt_pk_bf16_f32 v153, v158, v159
	v_fmac_f32_e32 v151, v159, v159
	v_pk_add_f32 v[158:159], v[28:29], v[182:183]
	v_pk_add_f32 v[190:191], v[92:93], v[154:155]
	v_mul_f32_e32 v155, v159, v159
	v_cvt_pk_bf16_f32 v152, v156, v157
	v_pk_add_f32 v[156:157], v[30:31], v[184:185]
	v_fmac_f32_e32 v155, v158, v158
	v_fmac_f32_e32 v155, v156, v156
	v_pk_add_f32 v[178:179], v[24:25], v[178:179]
	v_fmac_f32_e32 v155, v157, v157
	v_fmac_f32_e32 v151, v192, v192
	v_fmac_f32_e32 v155, v178, v178
	v_fmac_f32_e32 v151, v193, v193
	v_pk_add_f32 v[180:181], v[26:27], v[180:181]
	v_fmac_f32_e32 v155, v179, v179
	v_fmac_f32_e32 v151, v190, v190
	v_fmac_f32_e32 v155, v180, v180
	v_fmac_f32_e32 v151, v191, v191
	v_fmac_f32_e32 v155, v181, v181
	v_add_f32_e32 v151, v151, v155
	ds_bpermute_b32 v182, v150, v151
	v_lshlrev_b64 v[160:161], 11, v[160:161]
	v_lshl_add_u64 v[160:161], s[34:35], 0, v[160:161]
	v_cvt_pk_bf16_f32 v154, v192, v193
	v_cvt_pk_bf16_f32 v155, v190, v191
	v_lshl_add_u64 v[160:161], v[174:175], 1, v[160:161]
	s_waitcnt lgkmcnt(0)
	v_add_f32_e32 v151, v151, v182
	global_store_dwordx4 v[160:161], v[152:155], off
	ds_bpermute_b32 v152, v80, v151
	s_nop 0
	v_cvt_pk_bf16_f32 v154, v158, v159
	v_cvt_pk_bf16_f32 v155, v156, v157
	v_cvt_pk_bf16_f32 v156, v178, v179
	v_cvt_pk_bf16_f32 v157, v180, v181
	global_store_dwordx4 v[160:161], v[154:157], off offset:256
	s_and_saveexec_b64 s[10:11], s[6:7]
	s_cbranch_execz .LBB0_76
	s_lshl_b32 s12, s72, 2
	s_or_b32 s12, s12, s73
	s_mul_hi_i32 s13, s12, 0x50000
	s_mul_i32 s12, s12, 0x50000
	s_add_u32 s12, s74, s12
	s_addc_u32 s13, s75, s13
	s_waitcnt lgkmcnt(0)
	v_add_f32_e32 v151, v151, v152
	v_lshl_add_u64 v[152:153], v[176:177], 2, s[12:13]
	global_store_dword v[152:153], v151, off offset:512
.LBB0_76:
	s_or_b64 exec, exec, s[10:11]
	v_pk_add_f32 v[142:143], v[86:87], v[142:143]
	s_waitcnt lgkmcnt(0)
	v_pk_add_f32 v[152:153], v[84:85], v[140:141]
	v_mul_f32_e32 v141, v143, v143
	v_pk_add_f32 v[144:145], v[88:89], v[144:145]
	v_fmac_f32_e32 v141, v142, v142
	v_fmac_f32_e32 v141, v144, v144
	v_pk_add_f32 v[134:135], v[20:21], v[134:135]
	v_pk_add_f32 v[154:155], v[82:83], v[138:139]
	v_cvt_pk_bf16_f32 v139, v144, v145
	v_fmac_f32_e32 v141, v145, v145
	v_pk_add_f32 v[144:145], v[16:17], v[130:131]
	v_mul_f32_e32 v130, v135, v135
	v_pk_add_f32 v[136:137], v[22:23], v[136:137]
	v_fmac_f32_e32 v130, v134, v134
	v_fmac_f32_e32 v130, v136, v136
	v_fmac_f32_e32 v130, v137, v137
	v_fmac_f32_e32 v141, v154, v154
	v_fmac_f32_e32 v130, v144, v144
	v_cvt_pk_bf16_f32 v138, v142, v143
	v_fmac_f32_e32 v141, v155, v155
	v_pk_add_f32 v[142:143], v[18:19], v[132:133]
	v_fmac_f32_e32 v130, v145, v145
	v_fmac_f32_e32 v141, v152, v152
	v_fmac_f32_e32 v130, v142, v142
	v_fmac_f32_e32 v141, v153, v153
	v_fmac_f32_e32 v130, v143, v143
	v_add_f32_e32 v130, v141, v130
	ds_bpermute_b32 v131, v150, v130
	v_lshlrev_b64 v[148:149], 11, v[148:149]
	v_lshl_add_u64 v[148:149], s[34:35], 0, v[148:149]
	v_cvt_pk_bf16_f32 v140, v154, v155
	v_cvt_pk_bf16_f32 v141, v152, v153
	s_waitcnt lgkmcnt(0)
	v_add_f32_e32 v130, v130, v131
	ds_bpermute_b32 v131, v80, v130
	v_lshl_add_u64 v[148:149], v[174:175], 1, v[148:149]
	v_cvt_pk_bf16_f32 v132, v134, v135
	v_cvt_pk_bf16_f32 v133, v136, v137
	v_cvt_pk_bf16_f32 v134, v144, v145
	v_cvt_pk_bf16_f32 v135, v142, v143
	global_store_dwordx4 v[148:149], v[138:141], off
	global_store_dwordx4 v[148:149], v[132:135], off offset:256
	s_and_saveexec_b64 s[10:11], s[6:7]
	s_cbranch_execz .LBB0_78
	s_lshl_b32 s12, s72, 2
	s_or_b32 s12, s12, s73
	s_mul_hi_i32 s13, s12, 0x50000
	s_mul_i32 s12, s12, 0x50000
	s_add_u32 s12, s74, s12
	s_addc_u32 s13, s75, s13
	s_waitcnt lgkmcnt(0)
	v_add_f32_e32 v132, v130, v131
	v_lshl_add_u64 v[130:131], v[176:177], 2, s[12:13]
	global_store_dword v[130:131], v132, off offset:576
; __device__ __forceinline__ unsigned pk2(float lo, float hi) { const f32x2_t f = {lo, hi}; const bf16x2_t b = __builtin_convertvector(f, bf16x2_t); return __builtin_bit_cast(unsigned, b); }
;   __device__ __forceinline__ void operator()(const f32x4 (&acc)[2][2][4][2], const pg8::Unit& u, int wr, int wc, int fr, int fq) const {
;     ...
;       for (int g8 = 0; g8 < 4; ++g8) {
;         const int ai = g8 >> 1, m0 = (g8 & 1) * 2;
;         f32x4 xa[2][2][2];
; #pragma unroll
;         for (int mm = 0; mm < 2; ++mm)
; #pragma unroll
;           for (int bj = 0; bj < 2; ++bj) {
;             const float* xp = xin + (size_t)(row0 + ai * 128 + (m0 + mm) * 16) * DM + col0 + bj * 128;
;             xa[mm][bj][0] = *(const f32x4*)xp; xa[mm][bj][1] = *(const f32x4*)(xp + 4);
;           }
;         __builtin_amdgcn_sched_barrier(0);
; #pragma unroll
;         for (int mm = 0; mm < 2; ++mm) {
;           const int m = m0 + mm, row = row0 + ai * 128 + m * 16; float sq = 0.f;
; #pragma unroll
;           for (int bj = 0; bj < 2; ++bj) {
;             const int c = col0 + bj * 128;
;             const f32x4 a = acc[ai][bj][m][0] + xa[mm][bj][0], b = acc[ai][bj][m][1] + xa[mm][bj][1];
;             u32x4 o; o.x = pk2(a[0], a[1]); o.y = pk2(a[2], a[3]); o.z = pk2(b[0], b[1]); o.w = pk2(b[2], b[3]);
;             *(u32x4*)(x2b + (size_t)row * DM + c) = o;
;             sq += a[0] * a[0] + a[1] * a[1] + a[2] * a[2] + a[3] * a[3] + b[0] * b[0] + b[1] * b[1] + b[2] * b[2] + b[3] * b[3];
;           }
;           sq += __shfl_xor(sq, 16); sq += __shfl_xor(sq, 32);
;           if (fq == 0) ssq[(size_t)(u.pn * 4 + wc) * TALL + row] = sq;
;         }
;         __builtin_amdgcn_sched_barrier(0);
;       }
.LBB0_78:
	s_or_b64 exec, exec, s[10:11]
	v_add_u32_e32 v160, 0xa0, v176
	v_ashrrev_i32_e32 v161, 31, v160
	s_waitcnt lgkmcnt(0)
	v_lshlrev_b64 v[130:131], 12, v[160:161]
	v_add_u32_e32 v148, 0xb0, v176
	v_lshl_add_u64 v[130:131], v[146:147], 0, v[130:131]
	v_ashrrev_i32_e32 v149, 31, v148
	global_load_dwordx4 v[152:155], v[130:131], off offset:16
	global_load_dwordx4 v[156:159], v[130:131], off
	global_load_dwordx4 v[178:181], v[130:131], off offset:528
	global_load_dwordx4 v[182:185], v[130:131], off offset:512
	v_lshlrev_b64 v[130:131], 12, v[148:149]
	v_lshl_add_u64 v[134:135], v[146:147], 0, v[130:131]
	global_load_dwordx4 v[138:141], v[134:135], off offset:16
	global_load_dwordx4 v[142:145], v[134:135], off
	global_load_dwordx4 v[130:133], v[134:135], off offset:528
	s_nop 0
	global_load_dwordx4 v[134:137], v[134:135], off offset:512
	s_waitcnt vmcnt(0)
	v_pk_add_f32 v[156:157], v[76:77], v[156:157]
	v_pk_add_f32 v[158:159], v[78:79], v[158:159]
	v_mul_f32_e32 v151, v157, v157
	v_fmac_f32_e32 v151, v156, v156
	v_fmac_f32_e32 v151, v158, v158
	v_pk_add_f32 v[190:191], v[72:73], v[152:153]
	v_cvt_pk_bf16_f32 v153, v158, v159
	v_fmac_f32_e32 v151, v159, v159
	v_pk_add_f32 v[158:159], v[12:13], v[182:183]
	v_lshlrev_b64 v[146:147], 11, v[160:161]
	v_pk_add_f32 v[160:161], v[74:75], v[154:155]
	v_mul_f32_e32 v155, v159, v159
	v_cvt_pk_bf16_f32 v152, v156, v157
	v_pk_add_f32 v[156:157], v[14:15], v[184:185]
	v_fmac_f32_e32 v155, v158, v158
	v_fmac_f32_e32 v155, v156, v156
	v_pk_add_f32 v[178:179], v[8:9], v[178:179]
	v_fmac_f32_e32 v155, v157, v157
	v_fmac_f32_e32 v151, v190, v190
	v_fmac_f32_e32 v155, v178, v178
	v_fmac_f32_e32 v151, v191, v191
	v_pk_add_f32 v[180:181], v[10:11], v[180:181]
	v_fmac_f32_e32 v155, v179, v179
	v_fmac_f32_e32 v151, v160, v160
	v_fmac_f32_e32 v155, v180, v180
	v_fmac_f32_e32 v151, v161, v161
	v_fmac_f32_e32 v155, v181, v181
	v_add_f32_e32 v151, v151, v155
	ds_bpermute_b32 v182, v150, v151
	v_lshl_add_u64 v[146:147], s[34:35], 0, v[146:147]
	v_cvt_pk_bf16_f32 v155, v160, v161
	v_lshl_add_u64 v[160:161], v[174:175], 1, v[146:147]
	v_cvt_pk_bf16_f32 v154, v190, v191
	s_waitcnt lgkmcnt(0)
	v_add_f32_e32 v146, v151, v182
	ds_bpermute_b32 v147, v80, v146
	global_store_dwordx4 v[160:161], v[152:155], off
	s_nop 1
	v_cvt_pk_bf16_f32 v152, v158, v159
	v_cvt_pk_bf16_f32 v153, v156, v157
	v_cvt_pk_bf16_f32 v154, v178, v179
	v_cvt_pk_bf16_f32 v155, v180, v181
	global_store_dwordx4 v[160:161], v[152:155], off offset:256
	s_and_saveexec_b64 s[10:11], s[6:7]
	s_cbranch_execz .LBB0_80
	s_lshl_b32 s12, s72, 2
	s_or_b32 s12, s12, s73
	s_mul_hi_i32 s13, s12, 0x50000
	s_mul_i32 s12, s12, 0x50000
	s_add_u32 s12, s74, s12
	s_addc_u32 s13, s75, s13
	s_waitcnt lgkmcnt(0)
	v_add_f32_e32 v151, v146, v147
	v_lshl_add_u64 v[146:147], v[176:177], 2, s[12:13]
	global_store_dword v[146:147], v151, off offset:640
.LBB0_80:
	s_or_b64 exec, exec, s[10:11]
	v_pk_add_f32 v[142:143], v[68:69], v[142:143]
	s_waitcnt lgkmcnt(0)
	v_lshlrev_b64 v[146:147], 11, v[148:149]
	v_pk_add_f32 v[148:149], v[66:67], v[140:141]
	v_mul_f32_e32 v141, v143, v143
	v_pk_add_f32 v[144:145], v[70:71], v[144:145]
	v_fmac_f32_e32 v141, v142, v142
	v_fmac_f32_e32 v141, v144, v144
	v_pk_add_f32 v[134:135], v[4:5], v[134:135]
	v_pk_add_f32 v[152:153], v[64:65], v[138:139]
	v_cvt_pk_bf16_f32 v139, v144, v145
	v_fmac_f32_e32 v141, v145, v145
	v_pk_add_f32 v[144:145], v[0:1], v[130:131]
	v_mul_f32_e32 v130, v135, v135
	v_pk_add_f32 v[136:137], v[6:7], v[136:137]
	v_fmac_f32_e32 v130, v134, v134
	v_fmac_f32_e32 v130, v136, v136
	v_fmac_f32_e32 v130, v137, v137
	v_fmac_f32_e32 v141, v152, v152
	v_fmac_f32_e32 v130, v144, v144
	v_cvt_pk_bf16_f32 v138, v142, v143
	v_fmac_f32_e32 v141, v153, v153
	v_pk_add_f32 v[142:143], v[2:3], v[132:133]
	v_fmac_f32_e32 v130, v145, v145
	v_fmac_f32_e32 v141, v148, v148
	v_fmac_f32_e32 v130, v142, v142
	v_fmac_f32_e32 v141, v149, v149
	v_fmac_f32_e32 v130, v143, v143
	v_add_f32_e32 v130, v141, v130
	ds_bpermute_b32 v131, v150, v130
	v_lshl_add_u64 v[146:147], s[34:35], 0, v[146:147]
	v_cvt_pk_bf16_f32 v140, v152, v153
	v_cvt_pk_bf16_f32 v141, v148, v149
	v_lshl_add_u64 v[146:147], v[174:175], 1, v[146:147]
	s_waitcnt lgkmcnt(0)
	v_add_f32_e32 v130, v130, v131
	ds_bpermute_b32 v80, v80, v130
	v_cvt_pk_bf16_f32 v132, v134, v135
	v_cvt_pk_bf16_f32 v133, v136, v137
	v_cvt_pk_bf16_f32 v134, v144, v145
	v_cvt_pk_bf16_f32 v135, v142, v143
	global_store_dwordx4 v[146:147], v[138:141], off
	global_store_dwordx4 v[146:147], v[132:135], off offset:256
	s_and_saveexec_b64 s[10:11], s[6:7]
	s_cbranch_execz .LBB0_82
	s_lshl_b32 s12, s72, 2
	s_or_b32 s12, s12, s73
	s_mul_hi_i32 s13, s12, 0x50000
	s_mul_i32 s12, s12, 0x50000
	s_add_u32 s12, s74, s12
	s_addc_u32 s13, s75, s13
	s_waitcnt lgkmcnt(0)
	v_add_f32_e32 v80, v130, v80
	v_lshl_add_u64 v[130:131], v[176:177], 2, s[12:13]
	global_store_dword v[130:131], v80, off offset:704

;   __device__ __forceinline__ void operator()(const f32x4 (&acc)[2][2][4][2], const pg8::Unit& u, int wr, int wc, int fr, int fq) const {
;     ...
;       const u16* sg = (const u16*)(ws + O_SG + (size_t)(slice & 1) * SG_BYTES) + (mode == EM_HBR ? 1024 : 0); u16* mg = (u16*)(ws + O_MG) + (size_t)slice * TS * 1024;
; #pragma unroll
;       for (int g8 = 0; g8 < 4; ++g8) {
;         const int ai = g8 >> 1, m0 = (g8 & 1) * 2;
;         u32x4 sv[2][2], pv[2][2];
; #pragma unroll
;         for (int mm = 0; mm < 2; ++mm)
; #pragma unroll
;           for (int bj = 0; bj < 2; ++bj) {
;             const int row = row0 + ai * 128 + (m0 + mm) * 16, c = col0 + bj * 128;
;             sv[mm][bj] = *(const u32x4*)(sg + (size_t)row * 2048 + c);
;             if (mode == EM_HBR) pv[mm][bj] = *(const u32x4*)(mg + (size_t)row * 1024 + c);
;           }
.LBB0_84:
	s_andn2_b64 vcc, exec, s[10:11]
	s_cbranch_vccnz .LBB0_150
	v_ashrrev_i32_e32 v177, 31, v176
	v_lshlrev_b64 v[130:131], 12, v[176:177]
	v_lshl_add_u64 v[130:131], s[60:61], 0, v[130:131]
	v_ashrrev_i32_e32 v175, 31, v174
	v_lshl_add_u64 v[130:131], v[174:175], 1, v[130:131]
	global_load_dwordx4 v[158:161], v[130:131], off
	v_readlane_b32 s12, v254, 39
	v_lshlrev_b64 v[132:133], 11, v[176:177]
	v_readlane_b32 s13, v254, 40
	v_lshl_add_u64 v[132:133], s[4:5], 0, v[132:133]
	s_andn2_b64 vcc, exec, s[12:13]
	s_waitcnt lgkmcnt(0)
	v_cndmask_b32_e64 v80, 0, 1, s[12:13]
	v_cmp_ne_u32_e64 s[10:11], 1, v80
	v_lshl_add_u64 v[180:181], v[174:175], 1, v[132:133]
	s_cbranch_vccnz .LBB0_87
	global_load_dwordx4 v[142:145], v[180:181], off
.LBB0_87:
	global_load_dwordx4 v[154:157], v[130:131], off offset:256
	s_and_b64 vcc, exec, s[10:11]
	s_cbranch_vccnz .LBB0_89
	global_load_dwordx4 v[138:141], v[180:181], off offset:256
.LBB0_89:
	v_or_b32_e32 v132, 16, v176
	v_ashrrev_i32_e32 v133, 31, v132
	v_lshlrev_b64 v[130:131], 12, v[132:133]
	v_lshl_add_u64 v[130:131], s[60:61], 0, v[130:131]
	v_lshl_add_u64 v[130:131], v[174:175], 1, v[130:131]
	global_load_dwordx4 v[150:153], v[130:131], off
	v_lshlrev_b64 v[132:133], 11, v[132:133]
	v_lshl_add_u64 v[132:133], s[4:5], 0, v[132:133]
	s_and_b64 vcc, exec, s[10:11]
	v_lshl_add_u64 v[178:179], v[174:175], 1, v[132:133]
	s_cbranch_vccnz .LBB0_91
	global_load_dwordx4 v[134:137], v[178:179], off
.LBB0_91:
	global_load_dwordx4 v[146:149], v[130:131], off offset:256
	s_and_b64 vcc, exec, s[10:11]
	s_cbranch_vccnz .LBB0_93
	global_load_dwordx4 v[130:133], v[178:179], off offset:256

; __device__ __forceinline__ unsigned pk2(float lo, float hi) { const f32x2_t f = {lo, hi}; const bf16x2_t b = __builtin_convertvector(f, bf16x2_t); return __builtin_bit_cast(unsigned, b); }
; __device__ __forceinline__ float lo16(unsigned v) { return __uint_as_float(v << 16); }
; __device__ __forceinline__ float hi16(unsigned v) { return __uint_as_float(v & 0xffff0000u); }
;   __device__ __forceinline__ void operator()(const f32x4 (&acc)[2][2][4][2], const pg8::Unit& u, int wr, int wc, int fr, int fq) const {
;     ...
;       for (int g8 = 0; g8 < 4; ++g8) {
;         const int ai = g8 >> 1, m0 = (g8 & 1) * 2;
;         u32x4 sv[2][2], pv[2][2];
; #pragma unroll
;         for (int mm = 0; mm < 2; ++mm)
; #pragma unroll
;           for (int bj = 0; bj < 2; ++bj) {
;             const int row = row0 + ai * 128 + (m0 + mm) * 16, c = col0 + bj * 128;
;             sv[mm][bj] = *(const u32x4*)(sg + (size_t)row * 2048 + c);
;             if (mode == EM_HBR) pv[mm][bj] = *(const u32x4*)(mg + (size_t)row * 1024 + c);
;           }
;         __builtin_amdgcn_sched_barrier(0);
; #pragma unroll
;         for (int mm = 0; mm < 2; ++mm)
; #pragma unroll
;           for (int bj = 0; bj < 2; ++bj) {
;             const int m = m0 + mm, row = row0 + ai * 128 + m * 16, c = col0 + bj * 128;
;             const u32x4 sx = sv[mm][bj];
;             const f32x4 a = acc[ai][bj][m][0], b = acc[ai][bj][m][1];
;             float v[8] = {a[0] * lo16(sx.x), a[1] * hi16(sx.x), a[2] * lo16(sx.y), a[3] * hi16(sx.y), b[0] * lo16(sx.z), b[1] * hi16(sx.z), b[2] * lo16(sx.w), b[3] * hi16(sx.w)};
;             if (mode == EM_HBR) { const u32x4 p = pv[mm][bj];
;               v[0] += lo16(p.x); v[1] += hi16(p.x); v[2] += lo16(p.y); v[3] += hi16(p.y); v[4] += lo16(p.z); v[5] += hi16(p.z); v[6] += lo16(p.w); v[7] += hi16(p.w); }
;             u32x4 o; o.x = pk2(v[0], v[1]); o.y = pk2(v[2], v[3]); o.z = pk2(v[4], v[5]); o.w = pk2(v[6], v[7]);
;             *(u32x4*)(mg + (size_t)row * 1024 + c) = o;
;           }
;         __builtin_amdgcn_sched_barrier(0);
.LBB0_95:
	v_cvt_pk_bf16_f32 v182, v182, v183
	v_cvt_pk_bf16_f32 v183, v158, v159
	v_cvt_pk_bf16_f32 v184, v184, v185
	v_cvt_pk_bf16_f32 v185, v160, v161
	s_waitcnt lgkmcnt(0)
	v_and_b32_e32 v161, 0xffff0000, v155
	v_lshlrev_b32_e32 v160, 16, v155
	global_store_dwordx4 v[180:181], v[182:185], off
	v_and_b32_e32 v159, 0xffff0000, v154
	v_lshlrev_b32_e32 v158, 16, v154
	v_pk_mul_f32 v[154:155], v[62:63], v[160:161]
	v_and_b32_e32 v161, 0xffff0000, v156
	v_lshlrev_b32_e32 v160, 16, v156
	v_and_b32_e32 v183, 0xffff0000, v157
	v_lshlrev_b32_e32 v182, 16, v157
	v_pk_mul_f32 v[158:159], v[60:61], v[158:159]
	v_pk_mul_f32 v[160:161], v[56:57], v[160:161]
	s_and_b64 vcc, exec, s[10:11]
	v_pk_mul_f32 v[156:157], v[58:59], v[182:183]
	s_cbranch_vccnz .LBB0_97
	v_and_b32_e32 v183, 0xffff0000, v138
	v_lshlrev_b32_e32 v182, 16, v138
	v_pk_add_f32 v[158:159], v[158:159], v[182:183]
	v_and_b32_e32 v183, 0xffff0000, v139
	v_lshlrev_b32_e32 v182, 16, v139
	v_pk_add_f32 v[154:155], v[154:155], v[182:183]
	v_and_b32_e32 v183, 0xffff0000, v140
	v_lshlrev_b32_e32 v182, 16, v140
	v_pk_add_f32 v[160:161], v[160:161], v[182:183]
	v_and_b32_e32 v183, 0xffff0000, v141
	v_lshlrev_b32_e32 v182, 16, v141
	v_pk_add_f32 v[156:157], v[156:157], v[182:183]
.LBB0_97:
	v_cvt_pk_bf16_f32 v158, v158, v159
	v_cvt_pk_bf16_f32 v159, v154, v155
	v_cvt_pk_bf16_f32 v160, v160, v161
	v_cvt_pk_bf16_f32 v161, v156, v157
	v_and_b32_e32 v157, 0xffff0000, v151
	v_lshlrev_b32_e32 v156, 16, v151
	global_store_dwordx4 v[180:181], v[158:161], off offset:256
	v_and_b32_e32 v155, 0xffff0000, v150
	v_lshlrev_b32_e32 v154, 16, v150
	v_pk_mul_f32 v[150:151], v[120:121], v[156:157]
	v_and_b32_e32 v157, 0xffff0000, v152
	v_lshlrev_b32_e32 v156, 16, v152
	v_and_b32_e32 v159, 0xffff0000, v153
	v_lshlrev_b32_e32 v158, 16, v153
	v_pk_mul_f32 v[154:155], v[118:119], v[154:155]
	v_pk_mul_f32 v[156:157], v[114:115], v[156:157]
	s_and_b64 vcc, exec, s[10:11]
	v_pk_mul_f32 v[152:153], v[116:117], v[158:159]
	s_cbranch_vccnz .LBB0_99
	v_and_b32_e32 v159, 0xffff0000, v134
	v_lshlrev_b32_e32 v158, 16, v134
	v_pk_add_f32 v[154:155], v[154:155], v[158:159]
	v_and_b32_e32 v159, 0xffff0000, v135
	v_lshlrev_b32_e32 v158, 16, v135
	v_pk_add_f32 v[150:151], v[150:151], v[158:159]
	v_and_b32_e32 v159, 0xffff0000, v136
	v_lshlrev_b32_e32 v158, 16, v136
	v_pk_add_f32 v[156:157], v[156:157], v[158:159]
	v_and_b32_e32 v159, 0xffff0000, v137
	v_lshlrev_b32_e32 v158, 16, v137
	v_pk_add_f32 v[152:153], v[152:153], v[158:159]
.LBB0_99:
	v_cvt_pk_bf16_f32 v154, v154, v155
	v_cvt_pk_bf16_f32 v155, v150, v151
	v_cvt_pk_bf16_f32 v156, v156, v157
	v_cvt_pk_bf16_f32 v157, v152, v153
	v_and_b32_e32 v153, 0xffff0000, v147
	v_lshlrev_b32_e32 v152, 16, v147
	global_store_dwordx4 v[178:179], v[154:157], off
	v_and_b32_e32 v151, 0xffff0000, v146
	v_lshlrev_b32_e32 v150, 16, v146
	v_pk_mul_f32 v[146:147], v[54:55], v[152:153]
	v_and_b32_e32 v153, 0xffff0000, v148
	v_lshlrev_b32_e32 v152, 16, v148
	v_and_b32_e32 v155, 0xffff0000, v149
	v_lshlrev_b32_e32 v154, 16, v149
	v_pk_mul_f32 v[150:151], v[52:53], v[150:151]
	v_pk_mul_f32 v[152:153], v[48:49], v[152:153]
	s_and_b64 vcc, exec, s[10:11]
	v_pk_mul_f32 v[148:149], v[50:51], v[154:155]
	s_cbranch_vccnz .LBB0_101
	v_and_b32_e32 v155, 0xffff0000, v130
	v_lshlrev_b32_e32 v154, 16, v130
	v_pk_add_f32 v[150:151], v[150:151], v[154:155]
	v_and_b32_e32 v155, 0xffff0000, v131
	v_lshlrev_b32_e32 v154, 16, v131
	v_pk_add_f32 v[146:147], v[146:147], v[154:155]
	v_and_b32_e32 v155, 0xffff0000, v132
	v_lshlrev_b32_e32 v154, 16, v132
	v_pk_add_f32 v[152:153], v[152:153], v[154:155]
	v_and_b32_e32 v155, 0xffff0000, v133
	v_lshlrev_b32_e32 v154, 16, v133
	v_pk_add_f32 v[148:149], v[148:149], v[154:155]
.LBB0_101:
	v_cvt_pk_bf16_f32 v150, v150, v151
	v_cvt_pk_bf16_f32 v151, v146, v147
	v_cvt_pk_bf16_f32 v152, v152, v153
	v_cvt_pk_bf16_f32 v153, v148, v149
	global_store_dwordx4 v[178:179], v[150:153], off offset:256
	v_or_b32_e32 v148, 32, v176
	v_ashrrev_i32_e32 v149, 31, v148
	v_lshlrev_b64 v[146:147], 12, v[148:149]
	v_lshl_add_u64 v[146:147], s[60:61], 0, v[146:147]
	v_lshl_add_u64 v[146:147], v[174:175], 1, v[146:147]
	global_load_dwordx4 v[158:161], v[146:147], off
	v_lshlrev_b64 v[148:149], 11, v[148:149]
	v_lshl_add_u64 v[148:149], s[4:5], 0, v[148:149]
	s_and_b64 vcc, exec, s[10:11]
	v_lshl_add_u64 v[180:181], v[174:175], 1, v[148:149]
	s_cbranch_vccnz .LBB0_103
	global_load_dwordx4 v[142:145], v[180:181], off
.LBB0_103:
	global_load_dwordx4 v[154:157], v[146:147], off offset:256
	s_and_b64 vcc, exec, s[10:11]
	s_cbranch_vccnz .LBB0_105
	global_load_dwordx4 v[138:141], v[180:181], off offset:256
.LBB0_105:
	v_or_b32_e32 v148, 48, v176
	v_ashrrev_i32_e32 v149, 31, v148
	v_lshlrev_b64 v[146:147], 12, v[148:149]
	v_lshl_add_u64 v[146:147], s[60:61], 0, v[146:147]
	v_lshl_add_u64 v[146:147], v[174:175], 1, v[146:147]
	global_load_dwordx4 v[150:153], v[146:147], off
	v_lshlrev_b64 v[148:149], 11, v[148:149]
	v_lshl_add_u64 v[148:149], s[4:5], 0, v[148:149]
	s_and_b64 vcc, exec, s[10:11]
	v_lshl_add_u64 v[178:179], v[174:175], 1, v[148:149]
	s_cbranch_vccnz .LBB0_107
	global_load_dwordx4 v[134:137], v[178:179], off
.LBB0_107:
	s_nop 0
	global_load_dwordx4 v[146:149], v[146:147], off offset:256
	s_and_b64 vcc, exec, s[10:11]
	s_cbranch_vccnz .LBB0_109
	global_load_dwordx4 v[130:133], v[178:179], off offset:256

; __device__ __forceinline__ unsigned pk2(float lo, float hi) { const f32x2_t f = {lo, hi}; const bf16x2_t b = __builtin_convertvector(f, bf16x2_t); return __builtin_bit_cast(unsigned, b); }
; __device__ __forceinline__ float lo16(unsigned v) { return __uint_as_float(v << 16); }
; __device__ __forceinline__ float hi16(unsigned v) { return __uint_as_float(v & 0xffff0000u); }
;   __device__ __forceinline__ void operator()(const f32x4 (&acc)[2][2][4][2], const pg8::Unit& u, int wr, int wc, int fr, int fq) const {
;     ...
;       for (int g8 = 0; g8 < 4; ++g8) {
;         const int ai = g8 >> 1, m0 = (g8 & 1) * 2;
;         u32x4 sv[2][2], pv[2][2];
; #pragma unroll
;         for (int mm = 0; mm < 2; ++mm)
; #pragma unroll
;           for (int bj = 0; bj < 2; ++bj) {
;             const int row = row0 + ai * 128 + (m0 + mm) * 16, c = col0 + bj * 128;
;             sv[mm][bj] = *(const u32x4*)(sg + (size_t)row * 2048 + c);
;             if (mode == EM_HBR) pv[mm][bj] = *(const u32x4*)(mg + (size_t)row * 1024 + c);
;           }
;         __builtin_amdgcn_sched_barrier(0);
; #pragma unroll
;         for (int mm = 0; mm < 2; ++mm)
; #pragma unroll
;           for (int bj = 0; bj < 2; ++bj) {
;             const int m = m0 + mm, row = row0 + ai * 128 + m * 16, c = col0 + bj * 128;
;             const u32x4 sx = sv[mm][bj];
;             const f32x4 a = acc[ai][bj][m][0], b = acc[ai][bj][m][1];
;             float v[8] = {a[0] * lo16(sx.x), a[1] * hi16(sx.x), a[2] * lo16(sx.y), a[3] * hi16(sx.y), b[0] * lo16(sx.z), b[1] * hi16(sx.z), b[2] * lo16(sx.w), b[3] * hi16(sx.w)};
;             if (mode == EM_HBR) { const u32x4 p = pv[mm][bj];
;               v[0] += lo16(p.x); v[1] += hi16(p.x); v[2] += lo16(p.y); v[3] += hi16(p.y); v[4] += lo16(p.z); v[5] += hi16(p.z); v[6] += lo16(p.w); v[7] += hi16(p.w); }
;             u32x4 o; o.x = pk2(v[0], v[1]); o.y = pk2(v[2], v[3]); o.z = pk2(v[4], v[5]); o.w = pk2(v[6], v[7]);
;             *(u32x4*)(mg + (size_t)row * 1024 + c) = o;
;           }
;         __builtin_amdgcn_sched_barrier(0);
.LBB0_111:
	v_cvt_pk_bf16_f32 v182, v182, v183
	v_cvt_pk_bf16_f32 v183, v158, v159
	v_cvt_pk_bf16_f32 v184, v184, v185
	v_cvt_pk_bf16_f32 v185, v160, v161
	v_and_b32_e32 v161, 0xffff0000, v155
	v_lshlrev_b32_e32 v160, 16, v155
	global_store_dwordx4 v[180:181], v[182:185], off
	v_and_b32_e32 v159, 0xffff0000, v154
	v_lshlrev_b32_e32 v158, 16, v154
	v_pk_mul_f32 v[154:155], v[46:47], v[160:161]
	v_and_b32_e32 v161, 0xffff0000, v156
	v_lshlrev_b32_e32 v160, 16, v156
	v_and_b32_e32 v183, 0xffff0000, v157
	v_lshlrev_b32_e32 v182, 16, v157
	v_pk_mul_f32 v[158:159], v[44:45], v[158:159]
	v_pk_mul_f32 v[160:161], v[40:41], v[160:161]
	s_and_b64 vcc, exec, s[10:11]
	v_pk_mul_f32 v[156:157], v[42:43], v[182:183]
	s_cbranch_vccnz .LBB0_113
	v_and_b32_e32 v183, 0xffff0000, v138
	v_lshlrev_b32_e32 v182, 16, v138
	v_pk_add_f32 v[158:159], v[158:159], v[182:183]
	v_and_b32_e32 v183, 0xffff0000, v139
	v_lshlrev_b32_e32 v182, 16, v139
	v_pk_add_f32 v[154:155], v[154:155], v[182:183]
	v_and_b32_e32 v183, 0xffff0000, v140
	v_lshlrev_b32_e32 v182, 16, v140
	v_pk_add_f32 v[160:161], v[160:161], v[182:183]
	v_and_b32_e32 v183, 0xffff0000, v141
	v_lshlrev_b32_e32 v182, 16, v141
	v_pk_add_f32 v[156:157], v[156:157], v[182:183]
.LBB0_113:
	v_cvt_pk_bf16_f32 v158, v158, v159
	v_cvt_pk_bf16_f32 v159, v154, v155
	v_cvt_pk_bf16_f32 v160, v160, v161
	v_cvt_pk_bf16_f32 v161, v156, v157
	v_and_b32_e32 v157, 0xffff0000, v151
	v_lshlrev_b32_e32 v156, 16, v151
	global_store_dwordx4 v[180:181], v[158:161], off offset:256
	v_and_b32_e32 v155, 0xffff0000, v150
	v_lshlrev_b32_e32 v154, 16, v150
	v_pk_mul_f32 v[150:151], v[104:105], v[156:157]
	v_and_b32_e32 v157, 0xffff0000, v152
	v_lshlrev_b32_e32 v156, 16, v152
	v_and_b32_e32 v159, 0xffff0000, v153
	v_lshlrev_b32_e32 v158, 16, v153
	v_pk_mul_f32 v[154:155], v[102:103], v[154:155]
	v_pk_mul_f32 v[156:157], v[98:99], v[156:157]
	s_and_b64 vcc, exec, s[10:11]
	v_pk_mul_f32 v[152:153], v[100:101], v[158:159]
	s_cbranch_vccnz .LBB0_115
	v_and_b32_e32 v159, 0xffff0000, v134
	v_lshlrev_b32_e32 v158, 16, v134
	v_pk_add_f32 v[154:155], v[154:155], v[158:159]
	v_and_b32_e32 v159, 0xffff0000, v135
	v_lshlrev_b32_e32 v158, 16, v135
	v_pk_add_f32 v[150:151], v[150:151], v[158:159]
	v_and_b32_e32 v159, 0xffff0000, v136
	v_lshlrev_b32_e32 v158, 16, v136
	v_pk_add_f32 v[156:157], v[156:157], v[158:159]
	v_and_b32_e32 v159, 0xffff0000, v137
	v_lshlrev_b32_e32 v158, 16, v137
	v_pk_add_f32 v[152:153], v[152:153], v[158:159]
.LBB0_115:
	v_cvt_pk_bf16_f32 v154, v154, v155
	v_cvt_pk_bf16_f32 v155, v150, v151
	v_cvt_pk_bf16_f32 v156, v156, v157
	v_cvt_pk_bf16_f32 v157, v152, v153
	v_and_b32_e32 v153, 0xffff0000, v147
	v_lshlrev_b32_e32 v152, 16, v147
	global_store_dwordx4 v[178:179], v[154:157], off
	v_and_b32_e32 v151, 0xffff0000, v146
	v_lshlrev_b32_e32 v150, 16, v146
	v_pk_mul_f32 v[146:147], v[38:39], v[152:153]
	v_and_b32_e32 v153, 0xffff0000, v148
	v_lshlrev_b32_e32 v152, 16, v148
	v_and_b32_e32 v155, 0xffff0000, v149
	v_lshlrev_b32_e32 v154, 16, v149
	v_pk_mul_f32 v[150:151], v[36:37], v[150:151]
	v_pk_mul_f32 v[152:153], v[32:33], v[152:153]
	s_and_b64 vcc, exec, s[10:11]
	v_pk_mul_f32 v[148:149], v[34:35], v[154:155]
	s_cbranch_vccnz .LBB0_117
	v_and_b32_e32 v155, 0xffff0000, v130
	v_lshlrev_b32_e32 v154, 16, v130
	v_pk_add_f32 v[150:151], v[150:151], v[154:155]
	v_and_b32_e32 v155, 0xffff0000, v131
	v_lshlrev_b32_e32 v154, 16, v131
	v_pk_add_f32 v[146:147], v[146:147], v[154:155]
	v_and_b32_e32 v155, 0xffff0000, v132
	v_lshlrev_b32_e32 v154, 16, v132
	v_pk_add_f32 v[152:153], v[152:153], v[154:155]
	v_and_b32_e32 v155, 0xffff0000, v133
	v_lshlrev_b32_e32 v154, 16, v133
	v_pk_add_f32 v[148:149], v[148:149], v[154:155]
.LBB0_117:
	v_cvt_pk_bf16_f32 v150, v150, v151
	v_cvt_pk_bf16_f32 v151, v146, v147
	v_cvt_pk_bf16_f32 v152, v152, v153
	v_cvt_pk_bf16_f32 v153, v148, v149
	global_store_dwordx4 v[178:179], v[150:153], off offset:256
	v_add_u32_e32 v148, 0x80, v176
	v_ashrrev_i32_e32 v149, 31, v148
	v_lshlrev_b64 v[146:147], 12, v[148:149]
	v_lshl_add_u64 v[146:147], s[60:61], 0, v[146:147]
	v_lshl_add_u64 v[146:147], v[174:175], 1, v[146:147]
	global_load_dwordx4 v[158:161], v[146:147], off
	v_lshlrev_b64 v[148:149], 11, v[148:149]
	v_lshl_add_u64 v[148:149], s[4:5], 0, v[148:149]
	s_and_b64 vcc, exec, s[10:11]
	v_lshl_add_u64 v[180:181], v[174:175], 1, v[148:149]
	s_cbranch_vccnz .LBB0_119
	global_load_dwordx4 v[142:145], v[180:181], off

;   __device__ __forceinline__ void operator()(const f32x4 (&acc)[2][2][4][2], const pg8::Unit& u, int wr, int wc, int fr, int fq) const {
;     ...
; #pragma unroll
;         for (int mm = 0; mm < 2; ++mm)
; #pragma unroll
;           for (int bj = 0; bj < 2; ++bj) {
;             const int row = row0 + ai * 128 + (m0 + mm) * 16, c = col0 + bj * 128;
;             sv[mm][bj] = *(const u32x4*)(sg + (size_t)row * 2048 + c);
;             if (mode == EM_HBR) pv[mm][bj] = *(const u32x4*)(mg + (size_t)row * 1024 + c);
;           }
.LBB0_121:
	v_add_u32_e32 v148, 0x90, v176
	v_ashrrev_i32_e32 v149, 31, v148
	v_lshlrev_b64 v[146:147], 12, v[148:149]
	v_lshl_add_u64 v[146:147], s[60:61], 0, v[146:147]
	v_lshl_add_u64 v[146:147], v[174:175], 1, v[146:147]
	global_load_dwordx4 v[150:153], v[146:147], off
	v_lshlrev_b64 v[148:149], 11, v[148:149]
	v_lshl_add_u64 v[148:149], s[4:5], 0, v[148:149]
	s_and_b64 vcc, exec, s[10:11]
	v_lshl_add_u64 v[178:179], v[174:175], 1, v[148:149]
	s_cbranch_vccnz .LBB0_123
	global_load_dwordx4 v[134:137], v[178:179], off

; __device__ __forceinline__ unsigned pk2(float lo, float hi) { const f32x2_t f = {lo, hi}; const bf16x2_t b = __builtin_convertvector(f, bf16x2_t); return __builtin_bit_cast(unsigned, b); }
; __device__ __forceinline__ float lo16(unsigned v) { return __uint_as_float(v << 16); }
; __device__ __forceinline__ float hi16(unsigned v) { return __uint_as_float(v & 0xffff0000u); }
;   __device__ __forceinline__ void operator()(const f32x4 (&acc)[2][2][4][2], const pg8::Unit& u, int wr, int wc, int fr, int fq) const {
;     ...
;       for (int g8 = 0; g8 < 4; ++g8) {
;         const int ai = g8 >> 1, m0 = (g8 & 1) * 2;
;         u32x4 sv[2][2], pv[2][2];
; #pragma unroll
;         for (int mm = 0; mm < 2; ++mm)
; #pragma unroll
;           for (int bj = 0; bj < 2; ++bj) {
;             const int row = row0 + ai * 128 + (m0 + mm) * 16, c = col0 + bj * 128;
;             sv[mm][bj] = *(const u32x4*)(sg + (size_t)row * 2048 + c);
;             if (mode == EM_HBR) pv[mm][bj] = *(const u32x4*)(mg + (size_t)row * 1024 + c);
;           }
;         __builtin_amdgcn_sched_barrier(0);
; #pragma unroll
;         for (int mm = 0; mm < 2; ++mm)
; #pragma unroll
;           for (int bj = 0; bj < 2; ++bj) {
;             const int m = m0 + mm, row = row0 + ai * 128 + m * 16, c = col0 + bj * 128;
;             const u32x4 sx = sv[mm][bj];
;             const f32x4 a = acc[ai][bj][m][0], b = acc[ai][bj][m][1];
;             float v[8] = {a[0] * lo16(sx.x), a[1] * hi16(sx.x), a[2] * lo16(sx.y), a[3] * hi16(sx.y), b[0] * lo16(sx.z), b[1] * hi16(sx.z), b[2] * lo16(sx.w), b[3] * hi16(sx.w)};
;             if (mode == EM_HBR) { const u32x4 p = pv[mm][bj];
;               v[0] += lo16(p.x); v[1] += hi16(p.x); v[2] += lo16(p.y); v[3] += hi16(p.y); v[4] += lo16(p.z); v[5] += hi16(p.z); v[6] += lo16(p.w); v[7] += hi16(p.w); }
;             u32x4 o; o.x = pk2(v[0], v[1]); o.y = pk2(v[2], v[3]); o.z = pk2(v[4], v[5]); o.w = pk2(v[6], v[7]);
;             *(u32x4*)(mg + (size_t)row * 1024 + c) = o;
;           }
;         __builtin_amdgcn_sched_barrier(0);
.LBB0_127:
	v_cvt_pk_bf16_f32 v182, v182, v183
	v_cvt_pk_bf16_f32 v183, v158, v159
	v_cvt_pk_bf16_f32 v184, v184, v185
	v_cvt_pk_bf16_f32 v185, v160, v161
	v_and_b32_e32 v161, 0xffff0000, v155
	v_lshlrev_b32_e32 v160, 16, v155
	global_store_dwordx4 v[180:181], v[182:185], off
	v_and_b32_e32 v159, 0xffff0000, v154
	v_lshlrev_b32_e32 v158, 16, v154
	v_pk_mul_f32 v[154:155], v[30:31], v[160:161]
	v_and_b32_e32 v161, 0xffff0000, v156
	v_lshlrev_b32_e32 v160, 16, v156
	v_and_b32_e32 v183, 0xffff0000, v157
	v_lshlrev_b32_e32 v182, 16, v157
	v_pk_mul_f32 v[158:159], v[28:29], v[158:159]
	v_pk_mul_f32 v[160:161], v[24:25], v[160:161]
	s_and_b64 vcc, exec, s[10:11]
	v_pk_mul_f32 v[156:157], v[26:27], v[182:183]
	s_cbranch_vccnz .LBB0_129
	v_and_b32_e32 v183, 0xffff0000, v138
	v_lshlrev_b32_e32 v182, 16, v138
	v_pk_add_f32 v[158:159], v[158:159], v[182:183]
	v_and_b32_e32 v183, 0xffff0000, v139
	v_lshlrev_b32_e32 v182, 16, v139
	v_pk_add_f32 v[154:155], v[154:155], v[182:183]
	v_and_b32_e32 v183, 0xffff0000, v140
	v_lshlrev_b32_e32 v182, 16, v140
	v_pk_add_f32 v[160:161], v[160:161], v[182:183]
	v_and_b32_e32 v183, 0xffff0000, v141
	v_lshlrev_b32_e32 v182, 16, v141
	v_pk_add_f32 v[156:157], v[156:157], v[182:183]
.LBB0_129:
	v_cvt_pk_bf16_f32 v158, v158, v159
	v_cvt_pk_bf16_f32 v159, v154, v155
	v_cvt_pk_bf16_f32 v160, v160, v161
	v_cvt_pk_bf16_f32 v161, v156, v157
	v_and_b32_e32 v157, 0xffff0000, v151
	v_lshlrev_b32_e32 v156, 16, v151
	global_store_dwordx4 v[180:181], v[158:161], off offset:256
	v_and_b32_e32 v155, 0xffff0000, v150
	v_lshlrev_b32_e32 v154, 16, v150
	v_pk_mul_f32 v[150:151], v[88:89], v[156:157]
	v_and_b32_e32 v157, 0xffff0000, v152
	v_lshlrev_b32_e32 v156, 16, v152
	v_and_b32_e32 v159, 0xffff0000, v153
	v_lshlrev_b32_e32 v158, 16, v153
	v_pk_mul_f32 v[154:155], v[86:87], v[154:155]
	v_pk_mul_f32 v[156:157], v[82:83], v[156:157]
	s_and_b64 vcc, exec, s[10:11]
	v_pk_mul_f32 v[152:153], v[84:85], v[158:159]
	s_cbranch_vccnz .LBB0_131
	v_and_b32_e32 v159, 0xffff0000, v134
	v_lshlrev_b32_e32 v158, 16, v134
	v_pk_add_f32 v[154:155], v[154:155], v[158:159]
	v_and_b32_e32 v159, 0xffff0000, v135
	v_lshlrev_b32_e32 v158, 16, v135
	v_pk_add_f32 v[150:151], v[150:151], v[158:159]
	v_and_b32_e32 v159, 0xffff0000, v136
	v_lshlrev_b32_e32 v158, 16, v136
	v_pk_add_f32 v[156:157], v[156:157], v[158:159]
	v_and_b32_e32 v159, 0xffff0000, v137
	v_lshlrev_b32_e32 v158, 16, v137
	v_pk_add_f32 v[152:153], v[152:153], v[158:159]
.LBB0_131:
	v_cvt_pk_bf16_f32 v154, v154, v155
	v_cvt_pk_bf16_f32 v155, v150, v151
	v_cvt_pk_bf16_f32 v156, v156, v157
	v_cvt_pk_bf16_f32 v157, v152, v153
	v_and_b32_e32 v153, 0xffff0000, v147
	v_lshlrev_b32_e32 v152, 16, v147
	global_store_dwordx4 v[178:179], v[154:157], off
	v_and_b32_e32 v151, 0xffff0000, v146
	v_lshlrev_b32_e32 v150, 16, v146
	v_pk_mul_f32 v[146:147], v[22:23], v[152:153]
	v_and_b32_e32 v153, 0xffff0000, v148
	v_lshlrev_b32_e32 v152, 16, v148
	v_and_b32_e32 v155, 0xffff0000, v149
	v_lshlrev_b32_e32 v154, 16, v149
	v_pk_mul_f32 v[150:151], v[20:21], v[150:151]
	v_pk_mul_f32 v[152:153], v[16:17], v[152:153]
	s_and_b64 vcc, exec, s[10:11]
	v_pk_mul_f32 v[148:149], v[18:19], v[154:155]
	s_cbranch_vccnz .LBB0_133
	v_and_b32_e32 v155, 0xffff0000, v130
	v_lshlrev_b32_e32 v154, 16, v130
	v_pk_add_f32 v[150:151], v[150:151], v[154:155]
	v_and_b32_e32 v155, 0xffff0000, v131
	v_lshlrev_b32_e32 v154, 16, v131
	v_pk_add_f32 v[146:147], v[146:147], v[154:155]
	v_and_b32_e32 v155, 0xffff0000, v132
	v_lshlrev_b32_e32 v154, 16, v132
	v_pk_add_f32 v[152:153], v[152:153], v[154:155]
	v_and_b32_e32 v155, 0xffff0000, v133
	v_lshlrev_b32_e32 v154, 16, v133
	v_pk_add_f32 v[148:149], v[148:149], v[154:155]
.LBB0_133:
	v_cvt_pk_bf16_f32 v150, v150, v151
	v_cvt_pk_bf16_f32 v151, v146, v147
	v_cvt_pk_bf16_f32 v152, v152, v153
	v_cvt_pk_bf16_f32 v153, v148, v149
	global_store_dwordx4 v[178:179], v[150:153], off offset:256
	v_add_u32_e32 v148, 0xa0, v176
	v_ashrrev_i32_e32 v149, 31, v148
	v_lshlrev_b64 v[146:147], 12, v[148:149]
	v_lshl_add_u64 v[146:147], s[60:61], 0, v[146:147]
	v_lshl_add_u64 v[146:147], v[174:175], 1, v[146:147]
	global_load_dwordx4 v[158:161], v[146:147], off
	v_lshlrev_b64 v[148:149], 11, v[148:149]
	v_lshl_add_u64 v[148:149], s[4:5], 0, v[148:149]
	s_and_b64 vcc, exec, s[10:11]
	v_lshl_add_u64 v[180:181], v[174:175], 1, v[148:149]
	s_cbranch_vccnz .LBB0_135
	global_load_dwordx4 v[142:145], v[180:181], off

;   __device__ __forceinline__ void operator()(const f32x4 (&acc)[2][2][4][2], const pg8::Unit& u, int wr, int wc, int fr, int fq) const {
;     ...
; #pragma unroll
;         for (int mm = 0; mm < 2; ++mm)
; #pragma unroll
;           for (int bj = 0; bj < 2; ++bj) {
;             const int row = row0 + ai * 128 + (m0 + mm) * 16, c = col0 + bj * 128;
;             sv[mm][bj] = *(const u32x4*)(sg + (size_t)row * 2048 + c);
;             if (mode == EM_HBR) pv[mm][bj] = *(const u32x4*)(mg + (size_t)row * 1024 + c);
;           }
.LBB0_137:
	v_add_u32_e32 v148, 0xb0, v176
	v_ashrrev_i32_e32 v149, 31, v148
	v_lshlrev_b64 v[146:147], 12, v[148:149]
	v_lshl_add_u64 v[146:147], s[60:61], 0, v[146:147]
	v_lshl_add_u64 v[146:147], v[174:175], 1, v[146:147]
	global_load_dwordx4 v[150:153], v[146:147], off
	v_lshlrev_b64 v[148:149], 11, v[148:149]
	v_lshl_add_u64 v[148:149], s[4:5], 0, v[148:149]
	s_and_b64 vcc, exec, s[10:11]
	v_lshl_add_u64 v[178:179], v[174:175], 1, v[148:149]
	s_cbranch_vccnz .LBB0_139
	global_load_dwordx4 v[134:137], v[178:179], off

; __device__ __forceinline__ unsigned pk2(float lo, float hi) { const f32x2_t f = {lo, hi}; const bf16x2_t b = __builtin_convertvector(f, bf16x2_t); return __builtin_bit_cast(unsigned, b); }
; __device__ __forceinline__ float lo16(unsigned v) { return __uint_as_float(v << 16); }
; __device__ __forceinline__ float hi16(unsigned v) { return __uint_as_float(v & 0xffff0000u); }
;   __device__ __forceinline__ void operator()(const f32x4 (&acc)[2][2][4][2], const pg8::Unit& u, int wr, int wc, int fr, int fq) const {
;     ...
; #pragma unroll
;         for (int mm = 0; mm < 2; ++mm)
; #pragma unroll
;           for (int bj = 0; bj < 2; ++bj) {
;             const int m = m0 + mm, row = row0 + ai * 128 + m * 16, c = col0 + bj * 128;
;             const u32x4 sx = sv[mm][bj];
;             const f32x4 a = acc[ai][bj][m][0], b = acc[ai][bj][m][1];
;             float v[8] = {a[0] * lo16(sx.x), a[1] * hi16(sx.x), a[2] * lo16(sx.y), a[3] * hi16(sx.y), b[0] * lo16(sx.z), b[1] * hi16(sx.z), b[2] * lo16(sx.w), b[3] * hi16(sx.w)};
;             if (mode == EM_HBR) { const u32x4 p = pv[mm][bj];
;               v[0] += lo16(p.x); v[1] += hi16(p.x); v[2] += lo16(p.y); v[3] += hi16(p.y); v[4] += lo16(p.z); v[5] += hi16(p.z); v[6] += lo16(p.w); v[7] += hi16(p.w); }
;             u32x4 o; o.x = pk2(v[0], v[1]); o.y = pk2(v[2], v[3]); o.z = pk2(v[4], v[5]); o.w = pk2(v[6], v[7]);
;             *(u32x4*)(mg + (size_t)row * 1024 + c) = o;
;           }
;         __builtin_amdgcn_sched_barrier(0);
.LBB0_143:
	v_cvt_pk_bf16_f32 v142, v182, v183
	v_cvt_pk_bf16_f32 v143, v158, v159
	v_cvt_pk_bf16_f32 v144, v184, v185
	v_cvt_pk_bf16_f32 v145, v160, v161
	global_store_dwordx4 v[180:181], v[142:145], off
	v_and_b32_e32 v159, 0xffff0000, v157
	v_lshlrev_b32_e32 v158, 16, v157
	v_and_b32_e32 v143, 0xffff0000, v154
	v_lshlrev_b32_e32 v142, 16, v154
	v_and_b32_e32 v145, 0xffff0000, v155
	v_lshlrev_b32_e32 v144, 16, v155
	v_and_b32_e32 v155, 0xffff0000, v156
	v_lshlrev_b32_e32 v154, 16, v156
	v_pk_mul_f32 v[142:143], v[12:13], v[142:143]
	v_pk_mul_f32 v[144:145], v[14:15], v[144:145]
	v_pk_mul_f32 v[154:155], v[8:9], v[154:155]
	s_and_b64 vcc, exec, s[10:11]
	v_pk_mul_f32 v[156:157], v[10:11], v[158:159]
	s_cbranch_vccnz .LBB0_145
	v_and_b32_e32 v159, 0xffff0000, v138
	v_lshlrev_b32_e32 v158, 16, v138
	v_pk_add_f32 v[142:143], v[142:143], v[158:159]
	v_and_b32_e32 v159, 0xffff0000, v139
	v_lshlrev_b32_e32 v158, 16, v139
	v_and_b32_e32 v139, 0xffff0000, v140
	v_lshlrev_b32_e32 v138, 16, v140
	v_pk_add_f32 v[154:155], v[154:155], v[138:139]
	v_and_b32_e32 v139, 0xffff0000, v141
	v_lshlrev_b32_e32 v138, 16, v141
	v_pk_add_f32 v[144:145], v[144:145], v[158:159]
	v_pk_add_f32 v[156:157], v[156:157], v[138:139]
.LBB0_145:
	v_cvt_pk_bf16_f32 v138, v142, v143
	v_cvt_pk_bf16_f32 v139, v144, v145
	v_cvt_pk_bf16_f32 v140, v154, v155
	v_cvt_pk_bf16_f32 v141, v156, v157
	global_store_dwordx4 v[180:181], v[138:141], off offset:256
	v_and_b32_e32 v143, 0xffff0000, v152
	v_lshlrev_b32_e32 v142, 16, v152
	v_and_b32_e32 v139, 0xffff0000, v150
	v_lshlrev_b32_e32 v138, 16, v150
	v_and_b32_e32 v141, 0xffff0000, v151
	v_lshlrev_b32_e32 v140, 16, v151
	v_and_b32_e32 v145, 0xffff0000, v153
	v_lshlrev_b32_e32 v144, 16, v153
	v_pk_mul_f32 v[138:139], v[68:69], v[138:139]
	v_pk_mul_f32 v[140:141], v[70:71], v[140:141]
	v_pk_mul_f32 v[142:143], v[64:65], v[142:143]
	s_and_b64 vcc, exec, s[10:11]
	v_pk_mul_f32 v[144:145], v[66:67], v[144:145]
	s_cbranch_vccnz .LBB0_147
	v_and_b32_e32 v151, 0xffff0000, v134
	v_lshlrev_b32_e32 v150, 16, v134
	v_pk_add_f32 v[138:139], v[138:139], v[150:151]
	v_and_b32_e32 v151, 0xffff0000, v135
	v_lshlrev_b32_e32 v150, 16, v135
	v_and_b32_e32 v135, 0xffff0000, v136
	v_lshlrev_b32_e32 v134, 16, v136
	v_pk_add_f32 v[142:143], v[142:143], v[134:135]
	v_and_b32_e32 v135, 0xffff0000, v137
	v_lshlrev_b32_e32 v134, 16, v137
	v_pk_add_f32 v[140:141], v[140:141], v[150:151]
	v_pk_add_f32 v[144:145], v[144:145], v[134:135]
.LBB0_147:
	v_cvt_pk_bf16_f32 v134, v138, v139
	v_cvt_pk_bf16_f32 v135, v140, v141
	v_cvt_pk_bf16_f32 v136, v142, v143
	v_cvt_pk_bf16_f32 v137, v144, v145
	global_store_dwordx4 v[178:179], v[134:137], off
	v_and_b32_e32 v139, 0xffff0000, v148
	v_lshlrev_b32_e32 v138, 16, v148
	v_and_b32_e32 v135, 0xffff0000, v146
	v_lshlrev_b32_e32 v134, 16, v146
	v_and_b32_e32 v137, 0xffff0000, v147
	v_lshlrev_b32_e32 v136, 16, v147
	v_and_b32_e32 v141, 0xffff0000, v149
	v_lshlrev_b32_e32 v140, 16, v149
	v_pk_mul_f32 v[134:135], v[4:5], v[134:135]
	v_pk_mul_f32 v[136:137], v[6:7], v[136:137]
	v_pk_mul_f32 v[138:139], v[0:1], v[138:139]
	s_and_b64 vcc, exec, s[10:11]
	v_pk_mul_f32 v[140:141], v[2:3], v[140:141]
	s_cbranch_vccnz .LBB0_149
	v_and_b32_e32 v143, 0xffff0000, v130
	v_lshlrev_b32_e32 v142, 16, v130
	v_pk_add_f32 v[134:135], v[134:135], v[142:143]
	v_and_b32_e32 v143, 0xffff0000, v131
	v_lshlrev_b32_e32 v142, 16, v131
	v_and_b32_e32 v131, 0xffff0000, v132
	v_lshlrev_b32_e32 v130, 16, v132
	v_pk_add_f32 v[138:139], v[138:139], v[130:131]
	v_and_b32_e32 v131, 0xffff0000, v133
	v_lshlrev_b32_e32 v130, 16, v133
	v_pk_add_f32 v[136:137], v[136:137], v[142:143]
	v_pk_add_f32 v[140:141], v[140:141], v[130:131]
.LBB0_149:
	v_cvt_pk_bf16_f32 v130, v134, v135
	v_cvt_pk_bf16_f32 v131, v136, v137
	v_cvt_pk_bf16_f32 v132, v138, v139
	v_cvt_pk_bf16_f32 v133, v140, v141
	global_store_dwordx4 v[178:179], v[130:133], off offset:256

; __device__ __forceinline__ unsigned pk2(float lo, float hi) { const f32x2_t f = {lo, hi}; const bf16x2_t b = __builtin_convertvector(f, bf16x2_t); return __builtin_bit_cast(unsigned, b); }
;   __device__ __forceinline__ void operator()(const f32x4 (&acc)[2][2][4][2], const pg8::Unit& u, int wr, int wc, int fr, int fq) const {
;     ...
;       const float* rstd1 = (const float*)(ws + O_RSTD1) + (size_t)slice * TS;
;       if (u.swap) {
;         u16* hyT = (u16*)(ws + O_HYT);
;         f32x4 rr[2][2];
; #pragma unroll
;         for (int bj = 0; bj < 2; ++bj) { rr[bj][0] = *(const f32x4*)(rstd1 + col0 + bj * 128); rr[bj][1] = *(const f32x4*)(rstd1 + col0 + bj * 128 + 4); }
;         __builtin_amdgcn_sched_barrier(0);
; #pragma unroll
;         for (int bj = 0; bj < 2; ++bj) {
;           const int tok0 = col0 + bj * 128;
; #pragma unroll
;           for (int ai = 0; ai < 2; ++ai)
; #pragma unroll
;             for (int m = 0; m < 4; ++m) {
;               const int ch = row0 + ai * 128 + m * 16 - 4608;
;               const f32x4 a = acc[ai][bj][m][0] * rr[bj][0], b = acc[ai][bj][m][1] * rr[bj][1];
;               u32x4 o; o.x = pk2(a[0], a[1]); o.y = pk2(a[2], a[3]); o.z = pk2(b[0], b[1]); o.w = pk2(b[2], b[3]);
;               *(u32x4*)(hyT + (size_t)ch * TS + tok0) = o;
;             }
;         }
.LBB0_151:
	s_andn2_b64 vcc, exec, s[10:11]
	s_cbranch_vccnz .LBB0_50
	s_cmp_gt_i32 s98, 0
	s_mov_b64 s[10:11], -1
	s_cbranch_scc0 .LBB0_285
	s_andn2_b64 vcc, exec, s[0:1]
	v_ashrrev_i32_e32 v175, 31, v174
	s_cbranch_vccnz .LBB0_155
	v_lshl_add_u64 v[130:131], v[174:175], 2, s[82:83]
	global_load_dwordx4 v[138:141], v[130:131], off
	global_load_dwordx4 v[142:145], v[130:131], off offset:16
	global_load_dwordx4 v[134:137], v[130:131], off offset:512
	s_nop 0
	global_load_dwordx4 v[130:133], v[130:131], off offset:528
	v_add_u32_e32 v150, 0xffffee00, v176
	v_readlane_b32 s0, v254, 30
	v_readlane_b32 s1, v254, 31
	v_ashrrev_i32_e32 v151, 31, v150
	s_waitcnt vmcnt(0) lgkmcnt(0)
	v_pk_mul_f32 v[148:149], v[128:129], v[140:141]
	v_lshl_add_u64 v[152:153], v[174:175], 1, s[0:1]
	v_pk_mul_f32 v[146:147], v[126:127], v[138:139]
	v_pk_mul_f32 v[154:155], v[124:125], v[144:145]
	v_pk_mul_f32 v[156:157], v[122:123], v[142:143]
	v_lshlrev_b64 v[150:151], 15, v[150:151]
	v_cvt_pk_bf16_f32 v146, v146, v147
	v_cvt_pk_bf16_f32 v147, v148, v149
	v_cvt_pk_bf16_f32 v148, v156, v157
	v_cvt_pk_bf16_f32 v149, v154, v155
	v_lshl_add_u64 v[150:151], v[152:153], 0, v[150:151]
	v_add_u32_e32 v154, 0xffffee10, v176
	global_store_dwordx4 v[150:151], v[146:149], off
	v_pk_mul_f32 v[156:157], v[116:117], v[144:145]
	v_ashrrev_i32_e32 v155, 31, v154
	v_pk_mul_f32 v[148:149], v[120:121], v[140:141]
	v_pk_mul_f32 v[146:147], v[118:119], v[138:139]
	v_pk_mul_f32 v[158:159], v[114:115], v[142:143]
	v_cvt_pk_bf16_f32 v146, v146, v147
	v_cvt_pk_bf16_f32 v147, v148, v149
	v_cvt_pk_bf16_f32 v149, v156, v157
	v_lshlrev_b64 v[154:155], 15, v[154:155]
	v_add_u32_e32 v156, 0xffffee20, v176
	v_cvt_pk_bf16_f32 v148, v158, v159
	v_lshl_add_u64 v[154:155], v[152:153], 0, v[154:155]
	v_ashrrev_i32_e32 v157, 31, v156
	global_store_dwordx4 v[154:155], v[146:149], off
	v_pk_mul_f32 v[158:159], v[108:109], v[144:145]
	v_pk_mul_f32 v[160:161], v[106:107], v[142:143]
	v_pk_mul_f32 v[148:149], v[112:113], v[140:141]
	v_pk_mul_f32 v[146:147], v[110:111], v[138:139]
	v_lshlrev_b64 v[156:157], 15, v[156:157]
	v_cvt_pk_bf16_f32 v146, v146, v147
	v_cvt_pk_bf16_f32 v147, v148, v149
	v_cvt_pk_bf16_f32 v148, v160, v161
	v_cvt_pk_bf16_f32 v149, v158, v159
	v_lshl_add_u64 v[156:157], v[152:153], 0, v[156:157]
	v_add_u32_e32 v158, 0xffffee30, v176
	global_store_dwordx4 v[156:157], v[146:149], off
	v_pk_mul_f32 v[160:161], v[100:101], v[144:145]
	v_ashrrev_i32_e32 v159, 31, v158
	v_pk_mul_f32 v[148:149], v[104:105], v[140:141]
	v_pk_mul_f32 v[146:147], v[102:103], v[138:139]
	v_pk_mul_f32 v[178:179], v[98:99], v[142:143]
	v_cvt_pk_bf16_f32 v146, v146, v147
	v_cvt_pk_bf16_f32 v147, v148, v149
	v_cvt_pk_bf16_f32 v149, v160, v161
	v_lshlrev_b64 v[158:159], 15, v[158:159]
	v_add_u32_e32 v160, 0xffffee80, v176
	v_cvt_pk_bf16_f32 v148, v178, v179
	v_lshl_add_u64 v[158:159], v[152:153], 0, v[158:159]
	v_ashrrev_i32_e32 v161, 31, v160
	global_store_dwordx4 v[158:159], v[146:149], off
	v_pk_mul_f32 v[178:179], v[92:93], v[144:145]
	v_pk_mul_f32 v[180:181], v[90:91], v[142:143]
	v_pk_mul_f32 v[148:149], v[96:97], v[140:141]
	v_pk_mul_f32 v[146:147], v[94:95], v[138:139]
	v_lshlrev_b64 v[160:161], 15, v[160:161]
	v_cvt_pk_bf16_f32 v146, v146, v147
	v_cvt_pk_bf16_f32 v147, v148, v149
	v_cvt_pk_bf16_f32 v148, v180, v181
	v_cvt_pk_bf16_f32 v149, v178, v179
	v_lshl_add_u64 v[160:161], v[152:153], 0, v[160:161]
	v_add_u32_e32 v178, 0xffffee90, v176
	global_store_dwordx4 v[160:161], v[146:149], off
	v_pk_mul_f32 v[180:181], v[84:85], v[144:145]
	v_ashrrev_i32_e32 v179, 31, v178
	v_pk_mul_f32 v[148:149], v[88:89], v[140:141]
	v_pk_mul_f32 v[146:147], v[86:87], v[138:139]
	v_pk_mul_f32 v[182:183], v[82:83], v[142:143]
	v_cvt_pk_bf16_f32 v146, v146, v147
	v_cvt_pk_bf16_f32 v147, v148, v149
	v_cvt_pk_bf16_f32 v149, v180, v181
	v_lshlrev_b64 v[178:179], 15, v[178:179]
	v_add_u32_e32 v180, 0xffffeea0, v176
	v_cvt_pk_bf16_f32 v148, v182, v183
	v_lshl_add_u64 v[178:179], v[152:153], 0, v[178:179]
	v_ashrrev_i32_e32 v181, 31, v180
	global_store_dwordx4 v[178:179], v[146:149], off
	v_pk_mul_f32 v[182:183], v[74:75], v[144:145]
	v_pk_mul_f32 v[184:185], v[72:73], v[142:143]
	v_pk_mul_f32 v[148:149], v[78:79], v[140:141]
	v_pk_mul_f32 v[146:147], v[76:77], v[138:139]
	v_lshlrev_b64 v[180:181], 15, v[180:181]
	v_cvt_pk_bf16_f32 v146, v146, v147
	v_cvt_pk_bf16_f32 v147, v148, v149
	v_cvt_pk_bf16_f32 v148, v184, v185
	v_cvt_pk_bf16_f32 v149, v182, v183
	v_lshl_add_u64 v[180:181], v[152:153], 0, v[180:181]
	global_store_dwordx4 v[180:181], v[146:149], off
	v_pk_mul_f32 v[140:141], v[70:71], v[140:141]
	v_pk_mul_f32 v[138:139], v[68:69], v[138:139]
; __device__ __forceinline__ unsigned pk2(float lo, float hi) { const f32x2_t f = {lo, hi}; const bf16x2_t b = __builtin_convertvector(f, bf16x2_t); return __builtin_bit_cast(unsigned, b); }
;   __device__ __forceinline__ void operator()(const f32x4 (&acc)[2][2][4][2], const pg8::Unit& u, int wr, int wc, int fr, int fq) const {
;     ...
;       if (u.swap) {
;         u16* hyT = (u16*)(ws + O_HYT);
;         f32x4 rr[2][2];
; #pragma unroll
;         for (int bj = 0; bj < 2; ++bj) { rr[bj][0] = *(const f32x4*)(rstd1 + col0 + bj * 128); rr[bj][1] = *(const f32x4*)(rstd1 + col0 + bj * 128 + 4); }
;         __builtin_amdgcn_sched_barrier(0);
; #pragma unroll
;         for (int bj = 0; bj < 2; ++bj) {
;           const int tok0 = col0 + bj * 128;
; #pragma unroll
;           for (int ai = 0; ai < 2; ++ai)
; #pragma unroll
;             for (int m = 0; m < 4; ++m) {
;               const int ch = row0 + ai * 128 + m * 16 - 4608;
;               const f32x4 a = acc[ai][bj][m][0] * rr[bj][0], b = acc[ai][bj][m][1] * rr[bj][1];
;               u32x4 o; o.x = pk2(a[0], a[1]); o.y = pk2(a[2], a[3]); o.z = pk2(b[0], b[1]); o.w = pk2(b[2], b[3]);
;               *(u32x4*)(hyT + (size_t)ch * TS + tok0) = o;
;             }
;         }
;       } else {
;         u16* qkv = (u16*)(ws + O_QKV); u16* sg = (u16*)(ws + O_SG + (size_t)(slice & 1) * SG_BYTES);
;         const bool isg = (u.pn >= 30);
;         float rsv[2][4];
; #pragma unroll
;         for (int ai = 0; ai < 2; ++ai)
; #pragma unroll
;           for (int m = 0; m < 4; ++m) rsv[ai][m] = rstd1[row0 + ai * 128 + m * 16];
	v_add_u32_e32 v146, 0xffffeeb0, v176
	v_pk_mul_f32 v[142:143], v[64:65], v[142:143]
	v_ashrrev_i32_e32 v147, 31, v146
	v_pk_mul_f32 v[144:145], v[66:67], v[144:145]
	v_cvt_pk_bf16_f32 v138, v138, v139
	v_cvt_pk_bf16_f32 v139, v140, v141
	v_cvt_pk_bf16_f32 v140, v142, v143
	v_lshlrev_b64 v[142:143], 15, v[146:147]
	v_cvt_pk_bf16_f32 v141, v144, v145
	v_lshl_add_u64 v[142:143], v[152:153], 0, v[142:143]
	global_store_dwordx4 v[142:143], v[138:141], off
	v_pk_mul_f32 v[144:145], v[58:59], v[132:133]
	v_pk_mul_f32 v[146:147], v[56:57], v[130:131]
	v_pk_mul_f32 v[140:141], v[62:63], v[136:137]
	v_pk_mul_f32 v[138:139], v[60:61], v[134:135]
	s_mov_b64 s[10:11], 0
	v_cvt_pk_bf16_f32 v138, v138, v139
	v_cvt_pk_bf16_f32 v139, v140, v141
	v_cvt_pk_bf16_f32 v140, v146, v147
	v_cvt_pk_bf16_f32 v141, v144, v145
	global_store_dwordx4 v[150:151], v[138:141], off offset:256
	v_pk_mul_f32 v[144:145], v[50:51], v[132:133]
	v_pk_mul_f32 v[146:147], v[48:49], v[130:131]
	v_pk_mul_f32 v[140:141], v[54:55], v[136:137]
	v_pk_mul_f32 v[138:139], v[52:53], v[134:135]
	s_nop 0
	v_cvt_pk_bf16_f32 v138, v138, v139
	v_cvt_pk_bf16_f32 v139, v140, v141
	v_cvt_pk_bf16_f32 v140, v146, v147
	v_cvt_pk_bf16_f32 v141, v144, v145
	global_store_dwordx4 v[154:155], v[138:141], off offset:256
	v_pk_mul_f32 v[144:145], v[42:43], v[132:133]
	v_pk_mul_f32 v[146:147], v[40:41], v[130:131]
	v_pk_mul_f32 v[140:141], v[46:47], v[136:137]
	v_pk_mul_f32 v[138:139], v[44:45], v[134:135]
	s_nop 0
	v_cvt_pk_bf16_f32 v138, v138, v139
	v_cvt_pk_bf16_f32 v139, v140, v141
	v_cvt_pk_bf16_f32 v140, v146, v147
	v_cvt_pk_bf16_f32 v141, v144, v145
	global_store_dwordx4 v[156:157], v[138:141], off offset:256
	v_pk_mul_f32 v[144:145], v[34:35], v[132:133]
	v_pk_mul_f32 v[146:147], v[32:33], v[130:131]
	v_pk_mul_f32 v[140:141], v[38:39], v[136:137]
	v_pk_mul_f32 v[138:139], v[36:37], v[134:135]
	s_nop 0
	v_cvt_pk_bf16_f32 v138, v138, v139
	v_cvt_pk_bf16_f32 v139, v140, v141
	v_cvt_pk_bf16_f32 v140, v146, v147
	v_cvt_pk_bf16_f32 v141, v144, v145
	global_store_dwordx4 v[158:159], v[138:141], off offset:256
	v_pk_mul_f32 v[144:145], v[26:27], v[132:133]
	v_pk_mul_f32 v[146:147], v[24:25], v[130:131]
	v_pk_mul_f32 v[140:141], v[30:31], v[136:137]
	v_pk_mul_f32 v[138:139], v[28:29], v[134:135]
	s_nop 0
	v_cvt_pk_bf16_f32 v138, v138, v139
	v_cvt_pk_bf16_f32 v139, v140, v141
	v_cvt_pk_bf16_f32 v140, v146, v147
	v_cvt_pk_bf16_f32 v141, v144, v145
	global_store_dwordx4 v[160:161], v[138:141], off offset:256
	v_pk_mul_f32 v[144:145], v[18:19], v[132:133]
	v_pk_mul_f32 v[146:147], v[16:17], v[130:131]
	v_pk_mul_f32 v[140:141], v[22:23], v[136:137]
	v_pk_mul_f32 v[138:139], v[20:21], v[134:135]
	s_nop 0
	v_cvt_pk_bf16_f32 v138, v138, v139
	v_cvt_pk_bf16_f32 v139, v140, v141
	v_cvt_pk_bf16_f32 v140, v146, v147
	v_cvt_pk_bf16_f32 v141, v144, v145
	global_store_dwordx4 v[178:179], v[138:141], off offset:256
	v_pk_mul_f32 v[144:145], v[10:11], v[132:133]
	v_pk_mul_f32 v[146:147], v[8:9], v[130:131]
	v_pk_mul_f32 v[140:141], v[14:15], v[136:137]
	v_pk_mul_f32 v[138:139], v[12:13], v[134:135]
	v_pk_mul_f32 v[136:137], v[6:7], v[136:137]
	v_cvt_pk_bf16_f32 v138, v138, v139
	v_cvt_pk_bf16_f32 v139, v140, v141
	v_cvt_pk_bf16_f32 v140, v146, v147
	v_cvt_pk_bf16_f32 v141, v144, v145
	global_store_dwordx4 v[180:181], v[138:141], off offset:256
	v_pk_mul_f32 v[134:135], v[4:5], v[134:135]
	s_nop 0
	v_pk_mul_f32 v[138:139], v[2:3], v[132:133]
	v_pk_mul_f32 v[132:133], v[0:1], v[130:131]
	v_cvt_pk_bf16_f32 v130, v134, v135
	v_cvt_pk_bf16_f32 v131, v136, v137
	v_cvt_pk_bf16_f32 v132, v132, v133
	v_cvt_pk_bf16_f32 v133, v138, v139
	global_store_dwordx4 v[142:143], v[130:133], off offset:256
.LBB0_155:
	s_andn2_b64 vcc, exec, s[10:11]
	s_cbranch_vccnz .LBB0_284
	v_ashrrev_i32_e32 v177, 31, v176
	v_lshl_add_u64 v[130:131], v[176:177], 2, s[82:83]
	global_load_dword v148, v[130:131], off
	global_load_dword v146, v[130:131], off offset:64
	global_load_dword v144, v[130:131], off offset:128
	global_load_dword v142, v[130:131], off offset:192
	global_load_dword v140, v[130:131], off offset:512
	global_load_dword v138, v[130:131], off offset:576
	global_load_dword v136, v[130:131], off offset:640
	global_load_dword v134, v[130:131], off offset:704
	s_cmp_lt_i32 s72, 30
	s_cselect_b64 s[0:1], -1, 0
	s_cmp_gt_i32 s72, 29
	s_waitcnt vmcnt(0) lgkmcnt(0)
	v_pk_mul_f32 v[132:133], v[128:129], v[148:149] op_sel_hi:[1,0]
	v_pk_mul_f32 v[130:131], v[126:127], v[148:149] op_sel_hi:[1,0]
	v_pk_mul_f32 v[150:151], v[124:125], v[148:149] op_sel_hi:[1,0]
	v_pk_mul_f32 v[152:153], v[122:123], v[148:149] op_sel_hi:[1,0]
	s_mov_b64 s[10:11], -1
	s_cbranch_scc1 .LBB0_158
	s_mov_b64 s[10:11], 0

; __device__ __forceinline__ unsigned pk2(float lo, float hi) { const f32x2_t f = {lo, hi}; const bf16x2_t b = __builtin_convertvector(f, bf16x2_t); return __builtin_bit_cast(unsigned, b); }
;   __device__ __forceinline__ void operator()(const f32x4 (&acc)[2][2][4][2], const pg8::Unit& u, int wr, int wc, int fr, int fq) const {
;     ...
;             const int row = row0 + ai * 128 + m * 16; const float rs = rsv[ai][m];
; #pragma unroll
;             for (int bj = 0; bj < 2; ++bj) {
;               const int c = col0 + bj * 128;
;               f32x4 a = acc[ai][bj][m][0] * rs, b = acc[ai][bj][m][1] * rs;
;               if (isg) {
; #pragma unroll
;                 for (int e = 0; e < 4; ++e) { a[e] = __builtin_amdgcn_rcpf(1.0f + __expf(-a[e])); b[e] = __builtin_amdgcn_rcpf(1.0f + __expf(-b[e])); }
;               }
;               u32x4 o; o.x = pk2(a[0], a[1]); o.y = pk2(a[2], a[3]); o.z = pk2(b[0], b[1]); o.w = pk2(b[2], b[3]);
;               if (isg) *(u32x4*)(sg + (size_t)row * 2048 + (c - 7680)) = o; else *(u32x4*)(qkv + (size_t)row * 4608 + c) = o;
.LBB0_160:
	v_mov_b64_e32 v[154:155], s[30:31]
	s_movk_i32 s10, 0x2400
	v_mad_i64_i32 v[154:155], s[10:11], v176, s10, v[154:155]
	v_cvt_pk_bf16_f32 v130, v130, v131
	v_cvt_pk_bf16_f32 v131, v132, v133
	v_cvt_pk_bf16_f32 v132, v152, v153
	v_cvt_pk_bf16_f32 v133, v150, v151
	s_mov_b64 s[10:11], -1
	s_and_b64 vcc, exec, s[0:1]
	v_lshl_add_u64 v[152:153], v[174:175], 1, v[154:155]
	s_cbranch_vccz .LBB0_162
	global_store_dwordx4 v[152:153], v[130:133], off
	s_mov_b64 s[10:11], 0
.LBB0_162:
	v_lshlrev_b64 v[150:151], 12, v[176:177]
	v_lshl_add_u64 v[150:151], s[56:57], 0, v[150:151]
	s_andn2_b64 vcc, exec, s[10:11]
	v_lshl_add_u64 v[150:151], v[174:175], 1, v[150:151]
	s_cbranch_vccnz .LBB0_164
	v_add_co_u32_e32 v154, vcc, 0x2584e000, v150
	s_nop 1
	v_addc_co_u32_e32 v155, vcc, 0, v151, vcc
	global_store_dwordx4 v[154:155], v[130:133], off offset:1024

; __device__ __forceinline__ unsigned pk2(float lo, float hi) { const f32x2_t f = {lo, hi}; const bf16x2_t b = __builtin_convertvector(f, bf16x2_t); return __builtin_bit_cast(unsigned, b); }
;   __device__ __forceinline__ void operator()(const f32x4 (&acc)[2][2][4][2], const pg8::Unit& u, int wr, int wc, int fr, int fq) const {
;     ...
;             const int row = row0 + ai * 128 + m * 16; const float rs = rsv[ai][m];
; #pragma unroll
;             for (int bj = 0; bj < 2; ++bj) {
;               const int c = col0 + bj * 128;
;               f32x4 a = acc[ai][bj][m][0] * rs, b = acc[ai][bj][m][1] * rs;
;               if (isg) {
; #pragma unroll
;                 for (int e = 0; e < 4; ++e) { a[e] = __builtin_amdgcn_rcpf(1.0f + __expf(-a[e])); b[e] = __builtin_amdgcn_rcpf(1.0f + __expf(-b[e])); }
;               }
;               u32x4 o; o.x = pk2(a[0], a[1]); o.y = pk2(a[2], a[3]); o.z = pk2(b[0], b[1]); o.w = pk2(b[2], b[3]);
;               if (isg) *(u32x4*)(sg + (size_t)row * 2048 + (c - 7680)) = o; else *(u32x4*)(qkv + (size_t)row * 4608 + c) = o;
.LBB0_168:
	v_cvt_pk_bf16_f32 v130, v130, v131
	v_cvt_pk_bf16_f32 v131, v132, v133
	v_cvt_pk_bf16_f32 v132, v148, v149
	v_cvt_pk_bf16_f32 v133, v154, v155
	s_and_b64 vcc, exec, s[10:11]
	s_mov_b64 s[0:1], -1
	s_cbranch_vccnz .LBB0_170
	s_mov_b64 s[0:1], 0
	global_store_dwordx4 v[152:153], v[130:133], off offset:256
.LBB0_170:
	s_andn2_b64 vcc, exec, s[0:1]
	s_cbranch_vccnz .LBB0_172
	v_add_co_u32_e32 v148, vcc, 0x2584e000, v150
	s_nop 1
	v_addc_co_u32_e32 v149, vcc, 0, v151, vcc
	global_store_dwordx4 v[148:149], v[130:133], off offset:1280

; __device__ __forceinline__ unsigned pk2(float lo, float hi) { const f32x2_t f = {lo, hi}; const bf16x2_t b = __builtin_convertvector(f, bf16x2_t); return __builtin_bit_cast(unsigned, b); }
;   __device__ __forceinline__ void operator()(const f32x4 (&acc)[2][2][4][2], const pg8::Unit& u, int wr, int wc, int fr, int fq) const {
;     ...
;             const int row = row0 + ai * 128 + m * 16; const float rs = rsv[ai][m];
; #pragma unroll
;             for (int bj = 0; bj < 2; ++bj) {
;               const int c = col0 + bj * 128;
;               f32x4 a = acc[ai][bj][m][0] * rs, b = acc[ai][bj][m][1] * rs;
;               if (isg) {
; #pragma unroll
;                 for (int e = 0; e < 4; ++e) { a[e] = __builtin_amdgcn_rcpf(1.0f + __expf(-a[e])); b[e] = __builtin_amdgcn_rcpf(1.0f + __expf(-b[e])); }
;               }
;               u32x4 o; o.x = pk2(a[0], a[1]); o.y = pk2(a[2], a[3]); o.z = pk2(b[0], b[1]); o.w = pk2(b[2], b[3]);
;               if (isg) *(u32x4*)(sg + (size_t)row * 2048 + (c - 7680)) = o; else *(u32x4*)(qkv + (size_t)row * 4608 + c) = o;
.LBB0_176:
	v_or_b32_e32 v152, 16, v176
	v_mov_b64_e32 v[154:155], s[30:31]
	s_movk_i32 s0, 0x2400
	v_mad_i64_i32 v[154:155], s[0:1], v152, s0, v[154:155]
	v_cvt_pk_bf16_f32 v130, v130, v131
	v_cvt_pk_bf16_f32 v131, v132, v133
	v_cvt_pk_bf16_f32 v132, v150, v151
	v_cvt_pk_bf16_f32 v133, v148, v149
	s_mov_b64 s[0:1], -1
	s_and_b64 vcc, exec, s[10:11]
	v_lshl_add_u64 v[148:149], v[174:175], 1, v[154:155]
	s_cbranch_vccnz .LBB0_178
	s_mov_b64 s[0:1], 0
	global_store_dwordx4 v[148:149], v[130:133], off
.LBB0_178:
	v_ashrrev_i32_e32 v153, 31, v152
	v_lshlrev_b64 v[150:151], 12, v[152:153]
	v_lshl_add_u64 v[150:151], s[56:57], 0, v[150:151]
	s_andn2_b64 vcc, exec, s[0:1]
	v_lshl_add_u64 v[150:151], v[174:175], 1, v[150:151]
	s_cbranch_vccnz .LBB0_180
	v_add_co_u32_e32 v152, vcc, 0x2584e000, v150
	s_nop 1
	v_addc_co_u32_e32 v153, vcc, 0, v151, vcc
	global_store_dwordx4 v[152:153], v[130:133], off offset:1024

; __device__ __forceinline__ unsigned pk2(float lo, float hi) { const f32x2_t f = {lo, hi}; const bf16x2_t b = __builtin_convertvector(f, bf16x2_t); return __builtin_bit_cast(unsigned, b); }
;   __device__ __forceinline__ void operator()(const f32x4 (&acc)[2][2][4][2], const pg8::Unit& u, int wr, int wc, int fr, int fq) const {
;     ...
;             const int row = row0 + ai * 128 + m * 16; const float rs = rsv[ai][m];
; #pragma unroll
;             for (int bj = 0; bj < 2; ++bj) {
;               const int c = col0 + bj * 128;
;               f32x4 a = acc[ai][bj][m][0] * rs, b = acc[ai][bj][m][1] * rs;
;               if (isg) {
; #pragma unroll
;                 for (int e = 0; e < 4; ++e) { a[e] = __builtin_amdgcn_rcpf(1.0f + __expf(-a[e])); b[e] = __builtin_amdgcn_rcpf(1.0f + __expf(-b[e])); }
;               }
;               u32x4 o; o.x = pk2(a[0], a[1]); o.y = pk2(a[2], a[3]); o.z = pk2(b[0], b[1]); o.w = pk2(b[2], b[3]);
;               if (isg) *(u32x4*)(sg + (size_t)row * 2048 + (c - 7680)) = o; else *(u32x4*)(qkv + (size_t)row * 4608 + c) = o;
.LBB0_184:
	v_cvt_pk_bf16_f32 v130, v130, v131
	v_cvt_pk_bf16_f32 v131, v132, v133
	v_cvt_pk_bf16_f32 v132, v146, v147
	v_cvt_pk_bf16_f32 v133, v152, v153
	s_and_b64 vcc, exec, s[10:11]
	s_mov_b64 s[0:1], -1
	s_cbranch_vccnz .LBB0_186
	s_mov_b64 s[0:1], 0
	global_store_dwordx4 v[148:149], v[130:133], off offset:256
.LBB0_186:
	s_andn2_b64 vcc, exec, s[0:1]
	s_cbranch_vccnz .LBB0_188
	v_add_co_u32_e32 v146, vcc, 0x2584e000, v150
	s_nop 1
	v_addc_co_u32_e32 v147, vcc, 0, v151, vcc
	global_store_dwordx4 v[146:147], v[130:133], off offset:1280

; __device__ __forceinline__ unsigned pk2(float lo, float hi) { const f32x2_t f = {lo, hi}; const bf16x2_t b = __builtin_convertvector(f, bf16x2_t); return __builtin_bit_cast(unsigned, b); }
;   __device__ __forceinline__ void operator()(const f32x4 (&acc)[2][2][4][2], const pg8::Unit& u, int wr, int wc, int fr, int fq) const {
;     ...
;             const int row = row0 + ai * 128 + m * 16; const float rs = rsv[ai][m];
; #pragma unroll
;             for (int bj = 0; bj < 2; ++bj) {
;               const int c = col0 + bj * 128;
;               f32x4 a = acc[ai][bj][m][0] * rs, b = acc[ai][bj][m][1] * rs;
;               if (isg) {
; #pragma unroll
;                 for (int e = 0; e < 4; ++e) { a[e] = __builtin_amdgcn_rcpf(1.0f + __expf(-a[e])); b[e] = __builtin_amdgcn_rcpf(1.0f + __expf(-b[e])); }
;               }
;               u32x4 o; o.x = pk2(a[0], a[1]); o.y = pk2(a[2], a[3]); o.z = pk2(b[0], b[1]); o.w = pk2(b[2], b[3]);
;               if (isg) *(u32x4*)(sg + (size_t)row * 2048 + (c - 7680)) = o; else *(u32x4*)(qkv + (size_t)row * 4608 + c) = o;
.LBB0_192:
	v_or_b32_e32 v150, 32, v176
	v_mov_b64_e32 v[152:153], s[30:31]
	s_movk_i32 s0, 0x2400
	v_mad_i64_i32 v[152:153], s[0:1], v150, s0, v[152:153]
	v_cvt_pk_bf16_f32 v130, v130, v131
	v_cvt_pk_bf16_f32 v131, v132, v133
	v_cvt_pk_bf16_f32 v132, v148, v149
	v_cvt_pk_bf16_f32 v133, v146, v147
	s_mov_b64 s[0:1], -1
	s_and_b64 vcc, exec, s[10:11]
	v_lshl_add_u64 v[146:147], v[174:175], 1, v[152:153]
	s_cbranch_vccnz .LBB0_194
	s_mov_b64 s[0:1], 0
	global_store_dwordx4 v[146:147], v[130:133], off
.LBB0_194:
	v_ashrrev_i32_e32 v151, 31, v150
	v_lshlrev_b64 v[148:149], 12, v[150:151]
	v_lshl_add_u64 v[148:149], s[56:57], 0, v[148:149]
	s_andn2_b64 vcc, exec, s[0:1]
	v_lshl_add_u64 v[148:149], v[174:175], 1, v[148:149]
	s_cbranch_vccnz .LBB0_196
	v_add_co_u32_e32 v150, vcc, 0x2584e000, v148
	s_nop 1
	v_addc_co_u32_e32 v151, vcc, 0, v149, vcc
	global_store_dwordx4 v[150:151], v[130:133], off offset:1024

; __device__ __forceinline__ unsigned pk2(float lo, float hi) { const f32x2_t f = {lo, hi}; const bf16x2_t b = __builtin_convertvector(f, bf16x2_t); return __builtin_bit_cast(unsigned, b); }
;   __device__ __forceinline__ void operator()(const f32x4 (&acc)[2][2][4][2], const pg8::Unit& u, int wr, int wc, int fr, int fq) const {
;     ...
;             const int row = row0 + ai * 128 + m * 16; const float rs = rsv[ai][m];
; #pragma unroll
;             for (int bj = 0; bj < 2; ++bj) {
;               const int c = col0 + bj * 128;
;               f32x4 a = acc[ai][bj][m][0] * rs, b = acc[ai][bj][m][1] * rs;
;               if (isg) {
; #pragma unroll
;                 for (int e = 0; e < 4; ++e) { a[e] = __builtin_amdgcn_rcpf(1.0f + __expf(-a[e])); b[e] = __builtin_amdgcn_rcpf(1.0f + __expf(-b[e])); }
;               }
;               u32x4 o; o.x = pk2(a[0], a[1]); o.y = pk2(a[2], a[3]); o.z = pk2(b[0], b[1]); o.w = pk2(b[2], b[3]);
;               if (isg) *(u32x4*)(sg + (size_t)row * 2048 + (c - 7680)) = o; else *(u32x4*)(qkv + (size_t)row * 4608 + c) = o;
.LBB0_200:
	v_cvt_pk_bf16_f32 v130, v130, v131
	v_cvt_pk_bf16_f32 v131, v132, v133
	v_cvt_pk_bf16_f32 v132, v144, v145
	v_cvt_pk_bf16_f32 v133, v150, v151
	s_and_b64 vcc, exec, s[10:11]
	s_mov_b64 s[0:1], -1
	s_cbranch_vccnz .LBB0_202
	s_mov_b64 s[0:1], 0
	global_store_dwordx4 v[146:147], v[130:133], off offset:256
.LBB0_202:
	s_andn2_b64 vcc, exec, s[0:1]
	s_cbranch_vccnz .LBB0_204
	v_add_co_u32_e32 v144, vcc, 0x2584e000, v148
	s_nop 1
	v_addc_co_u32_e32 v145, vcc, 0, v149, vcc
	global_store_dwordx4 v[144:145], v[130:133], off offset:1280

; __device__ __forceinline__ unsigned pk2(float lo, float hi) { const f32x2_t f = {lo, hi}; const bf16x2_t b = __builtin_convertvector(f, bf16x2_t); return __builtin_bit_cast(unsigned, b); }
;   __device__ __forceinline__ void operator()(const f32x4 (&acc)[2][2][4][2], const pg8::Unit& u, int wr, int wc, int fr, int fq) const {
;     ...
;             const int row = row0 + ai * 128 + m * 16; const float rs = rsv[ai][m];
; #pragma unroll
;             for (int bj = 0; bj < 2; ++bj) {
;               const int c = col0 + bj * 128;
;               f32x4 a = acc[ai][bj][m][0] * rs, b = acc[ai][bj][m][1] * rs;
;               if (isg) {
; #pragma unroll
;                 for (int e = 0; e < 4; ++e) { a[e] = __builtin_amdgcn_rcpf(1.0f + __expf(-a[e])); b[e] = __builtin_amdgcn_rcpf(1.0f + __expf(-b[e])); }
;               }
;               u32x4 o; o.x = pk2(a[0], a[1]); o.y = pk2(a[2], a[3]); o.z = pk2(b[0], b[1]); o.w = pk2(b[2], b[3]);
;               if (isg) *(u32x4*)(sg + (size_t)row * 2048 + (c - 7680)) = o; else *(u32x4*)(qkv + (size_t)row * 4608 + c) = o;
.LBB0_208:
	v_or_b32_e32 v148, 48, v176
	v_mov_b64_e32 v[150:151], s[30:31]
	s_movk_i32 s0, 0x2400
	v_mad_i64_i32 v[150:151], s[0:1], v148, s0, v[150:151]
	v_cvt_pk_bf16_f32 v130, v130, v131
	v_cvt_pk_bf16_f32 v131, v132, v133
	v_cvt_pk_bf16_f32 v132, v146, v147
	v_cvt_pk_bf16_f32 v133, v144, v145
	s_mov_b64 s[0:1], -1
	s_and_b64 vcc, exec, s[10:11]
	v_lshl_add_u64 v[144:145], v[174:175], 1, v[150:151]
	s_cbranch_vccnz .LBB0_210
	s_mov_b64 s[0:1], 0
	global_store_dwordx4 v[144:145], v[130:133], off
.LBB0_210:
	v_ashrrev_i32_e32 v149, 31, v148
	v_lshlrev_b64 v[146:147], 12, v[148:149]
	v_lshl_add_u64 v[146:147], s[56:57], 0, v[146:147]
	s_andn2_b64 vcc, exec, s[0:1]
	v_lshl_add_u64 v[146:147], v[174:175], 1, v[146:147]
	s_cbranch_vccnz .LBB0_212
	v_add_co_u32_e32 v148, vcc, 0x2584e000, v146
	s_nop 1
	v_addc_co_u32_e32 v149, vcc, 0, v147, vcc
	global_store_dwordx4 v[148:149], v[130:133], off offset:1024

; __device__ __forceinline__ unsigned pk2(float lo, float hi) { const f32x2_t f = {lo, hi}; const bf16x2_t b = __builtin_convertvector(f, bf16x2_t); return __builtin_bit_cast(unsigned, b); }
;   __device__ __forceinline__ void operator()(const f32x4 (&acc)[2][2][4][2], const pg8::Unit& u, int wr, int wc, int fr, int fq) const {
;     ...
;             const int row = row0 + ai * 128 + m * 16; const float rs = rsv[ai][m];
; #pragma unroll
;             for (int bj = 0; bj < 2; ++bj) {
;               const int c = col0 + bj * 128;
;               f32x4 a = acc[ai][bj][m][0] * rs, b = acc[ai][bj][m][1] * rs;
;               if (isg) {
; #pragma unroll
;                 for (int e = 0; e < 4; ++e) { a[e] = __builtin_amdgcn_rcpf(1.0f + __expf(-a[e])); b[e] = __builtin_amdgcn_rcpf(1.0f + __expf(-b[e])); }
;               }
;               u32x4 o; o.x = pk2(a[0], a[1]); o.y = pk2(a[2], a[3]); o.z = pk2(b[0], b[1]); o.w = pk2(b[2], b[3]);
;               if (isg) *(u32x4*)(sg + (size_t)row * 2048 + (c - 7680)) = o; else *(u32x4*)(qkv + (size_t)row * 4608 + c) = o;
.LBB0_216:
	v_cvt_pk_bf16_f32 v130, v130, v131
	v_cvt_pk_bf16_f32 v131, v132, v133
	v_cvt_pk_bf16_f32 v132, v142, v143
	v_cvt_pk_bf16_f32 v133, v148, v149
	s_and_b64 vcc, exec, s[10:11]
	s_mov_b64 s[0:1], -1
	s_cbranch_vccnz .LBB0_218
	s_mov_b64 s[0:1], 0
	global_store_dwordx4 v[144:145], v[130:133], off offset:256
.LBB0_218:
	s_andn2_b64 vcc, exec, s[0:1]
	s_cbranch_vccnz .LBB0_220
	v_add_co_u32_e32 v142, vcc, 0x2584e000, v146
	s_nop 1
	v_addc_co_u32_e32 v143, vcc, 0, v147, vcc
	global_store_dwordx4 v[142:143], v[130:133], off offset:1280

; __device__ __forceinline__ unsigned pk2(float lo, float hi) { const f32x2_t f = {lo, hi}; const bf16x2_t b = __builtin_convertvector(f, bf16x2_t); return __builtin_bit_cast(unsigned, b); }
;   __device__ __forceinline__ void operator()(const f32x4 (&acc)[2][2][4][2], const pg8::Unit& u, int wr, int wc, int fr, int fq) const {
;     ...
;             const int row = row0 + ai * 128 + m * 16; const float rs = rsv[ai][m];
; #pragma unroll
;             for (int bj = 0; bj < 2; ++bj) {
;               const int c = col0 + bj * 128;
;               f32x4 a = acc[ai][bj][m][0] * rs, b = acc[ai][bj][m][1] * rs;
;               if (isg) {
; #pragma unroll
;                 for (int e = 0; e < 4; ++e) { a[e] = __builtin_amdgcn_rcpf(1.0f + __expf(-a[e])); b[e] = __builtin_amdgcn_rcpf(1.0f + __expf(-b[e])); }
;               }
;               u32x4 o; o.x = pk2(a[0], a[1]); o.y = pk2(a[2], a[3]); o.z = pk2(b[0], b[1]); o.w = pk2(b[2], b[3]);
;               if (isg) *(u32x4*)(sg + (size_t)row * 2048 + (c - 7680)) = o; else *(u32x4*)(qkv + (size_t)row * 4608 + c) = o;
.LBB0_224:
	v_add_u32_e32 v146, 0x80, v176
	v_mov_b64_e32 v[148:149], s[30:31]
	s_movk_i32 s0, 0x2400
	v_mad_i64_i32 v[148:149], s[0:1], v146, s0, v[148:149]
	v_cvt_pk_bf16_f32 v130, v130, v131
	v_cvt_pk_bf16_f32 v131, v132, v133
	v_cvt_pk_bf16_f32 v132, v144, v145
	v_cvt_pk_bf16_f32 v133, v142, v143
	s_mov_b64 s[0:1], -1
	s_and_b64 vcc, exec, s[10:11]
	v_lshl_add_u64 v[142:143], v[174:175], 1, v[148:149]
	s_cbranch_vccnz .LBB0_226
	s_mov_b64 s[0:1], 0
	global_store_dwordx4 v[142:143], v[130:133], off
.LBB0_226:
	v_ashrrev_i32_e32 v147, 31, v146
	v_lshlrev_b64 v[144:145], 12, v[146:147]
	v_lshl_add_u64 v[144:145], s[56:57], 0, v[144:145]
	s_andn2_b64 vcc, exec, s[0:1]
	v_lshl_add_u64 v[144:145], v[174:175], 1, v[144:145]
	s_cbranch_vccnz .LBB0_228
	v_add_co_u32_e32 v146, vcc, 0x2584e000, v144
	s_nop 1
	v_addc_co_u32_e32 v147, vcc, 0, v145, vcc
	global_store_dwordx4 v[146:147], v[130:133], off offset:1024

; __device__ __forceinline__ unsigned pk2(float lo, float hi) { const f32x2_t f = {lo, hi}; const bf16x2_t b = __builtin_convertvector(f, bf16x2_t); return __builtin_bit_cast(unsigned, b); }
;   __device__ __forceinline__ void operator()(const f32x4 (&acc)[2][2][4][2], const pg8::Unit& u, int wr, int wc, int fr, int fq) const {
;     ...
;             const int row = row0 + ai * 128 + m * 16; const float rs = rsv[ai][m];
; #pragma unroll
;             for (int bj = 0; bj < 2; ++bj) {
;               const int c = col0 + bj * 128;
;               f32x4 a = acc[ai][bj][m][0] * rs, b = acc[ai][bj][m][1] * rs;
;               if (isg) {
; #pragma unroll
;                 for (int e = 0; e < 4; ++e) { a[e] = __builtin_amdgcn_rcpf(1.0f + __expf(-a[e])); b[e] = __builtin_amdgcn_rcpf(1.0f + __expf(-b[e])); }
;               }
;               u32x4 o; o.x = pk2(a[0], a[1]); o.y = pk2(a[2], a[3]); o.z = pk2(b[0], b[1]); o.w = pk2(b[2], b[3]);
;               if (isg) *(u32x4*)(sg + (size_t)row * 2048 + (c - 7680)) = o; else *(u32x4*)(qkv + (size_t)row * 4608 + c) = o;
.LBB0_232:
	v_cvt_pk_bf16_f32 v130, v130, v131
	v_cvt_pk_bf16_f32 v131, v132, v133
	v_cvt_pk_bf16_f32 v132, v140, v141
	v_cvt_pk_bf16_f32 v133, v146, v147
	s_and_b64 vcc, exec, s[10:11]
	s_mov_b64 s[0:1], -1
	s_cbranch_vccnz .LBB0_234
	s_mov_b64 s[0:1], 0
	global_store_dwordx4 v[142:143], v[130:133], off offset:256
.LBB0_234:
	s_andn2_b64 vcc, exec, s[0:1]
	s_cbranch_vccnz .LBB0_236
	v_add_co_u32_e32 v140, vcc, 0x2584e000, v144
	s_nop 1
	v_addc_co_u32_e32 v141, vcc, 0, v145, vcc
	global_store_dwordx4 v[140:141], v[130:133], off offset:1280

; __device__ __forceinline__ unsigned pk2(float lo, float hi) { const f32x2_t f = {lo, hi}; const bf16x2_t b = __builtin_convertvector(f, bf16x2_t); return __builtin_bit_cast(unsigned, b); }
;   __device__ __forceinline__ void operator()(const f32x4 (&acc)[2][2][4][2], const pg8::Unit& u, int wr, int wc, int fr, int fq) const {
;     ...
;             const int row = row0 + ai * 128 + m * 16; const float rs = rsv[ai][m];
; #pragma unroll
;             for (int bj = 0; bj < 2; ++bj) {
;               const int c = col0 + bj * 128;
;               f32x4 a = acc[ai][bj][m][0] * rs, b = acc[ai][bj][m][1] * rs;
;               if (isg) {
; #pragma unroll
;                 for (int e = 0; e < 4; ++e) { a[e] = __builtin_amdgcn_rcpf(1.0f + __expf(-a[e])); b[e] = __builtin_amdgcn_rcpf(1.0f + __expf(-b[e])); }
;               }
;               u32x4 o; o.x = pk2(a[0], a[1]); o.y = pk2(a[2], a[3]); o.z = pk2(b[0], b[1]); o.w = pk2(b[2], b[3]);
;               if (isg) *(u32x4*)(sg + (size_t)row * 2048 + (c - 7680)) = o; else *(u32x4*)(qkv + (size_t)row * 4608 + c) = o;
.LBB0_240:
	v_add_u32_e32 v144, 0x90, v176
	v_mov_b64_e32 v[146:147], s[30:31]
	s_movk_i32 s0, 0x2400
	v_mad_i64_i32 v[146:147], s[0:1], v144, s0, v[146:147]
	v_cvt_pk_bf16_f32 v130, v130, v131
	v_cvt_pk_bf16_f32 v131, v132, v133
	v_cvt_pk_bf16_f32 v132, v142, v143
	v_cvt_pk_bf16_f32 v133, v140, v141
	s_mov_b64 s[0:1], -1
	s_and_b64 vcc, exec, s[10:11]
	v_lshl_add_u64 v[140:141], v[174:175], 1, v[146:147]
	s_cbranch_vccnz .LBB0_242
	s_mov_b64 s[0:1], 0
	global_store_dwordx4 v[140:141], v[130:133], off
.LBB0_242:
	v_ashrrev_i32_e32 v145, 31, v144
	v_lshlrev_b64 v[142:143], 12, v[144:145]
	v_lshl_add_u64 v[142:143], s[56:57], 0, v[142:143]
	s_andn2_b64 vcc, exec, s[0:1]
	v_lshl_add_u64 v[142:143], v[174:175], 1, v[142:143]
	s_cbranch_vccnz .LBB0_244
	v_add_co_u32_e32 v144, vcc, 0x2584e000, v142
	s_nop 1
	v_addc_co_u32_e32 v145, vcc, 0, v143, vcc
	global_store_dwordx4 v[144:145], v[130:133], off offset:1024

; __device__ __forceinline__ unsigned pk2(float lo, float hi) { const f32x2_t f = {lo, hi}; const bf16x2_t b = __builtin_convertvector(f, bf16x2_t); return __builtin_bit_cast(unsigned, b); }
;   __device__ __forceinline__ void operator()(const f32x4 (&acc)[2][2][4][2], const pg8::Unit& u, int wr, int wc, int fr, int fq) const {
;     ...
;             const int row = row0 + ai * 128 + m * 16; const float rs = rsv[ai][m];
; #pragma unroll
;             for (int bj = 0; bj < 2; ++bj) {
;               const int c = col0 + bj * 128;
;               f32x4 a = acc[ai][bj][m][0] * rs, b = acc[ai][bj][m][1] * rs;
;               if (isg) {
; #pragma unroll
;                 for (int e = 0; e < 4; ++e) { a[e] = __builtin_amdgcn_rcpf(1.0f + __expf(-a[e])); b[e] = __builtin_amdgcn_rcpf(1.0f + __expf(-b[e])); }
;               }
;               u32x4 o; o.x = pk2(a[0], a[1]); o.y = pk2(a[2], a[3]); o.z = pk2(b[0], b[1]); o.w = pk2(b[2], b[3]);
;               if (isg) *(u32x4*)(sg + (size_t)row * 2048 + (c - 7680)) = o; else *(u32x4*)(qkv + (size_t)row * 4608 + c) = o;
.LBB0_248:
	v_cvt_pk_bf16_f32 v130, v130, v131
	v_cvt_pk_bf16_f32 v131, v132, v133
	v_cvt_pk_bf16_f32 v132, v138, v139
	v_cvt_pk_bf16_f32 v133, v144, v145
	s_and_b64 vcc, exec, s[10:11]
	s_mov_b64 s[0:1], -1
	s_cbranch_vccnz .LBB0_250
	s_mov_b64 s[0:1], 0
	global_store_dwordx4 v[140:141], v[130:133], off offset:256
.LBB0_250:
	s_andn2_b64 vcc, exec, s[0:1]
	s_cbranch_vccnz .LBB0_252
	v_add_co_u32_e32 v138, vcc, 0x2584e000, v142
	s_nop 1
	v_addc_co_u32_e32 v139, vcc, 0, v143, vcc
	global_store_dwordx4 v[138:139], v[130:133], off offset:1280

; __device__ __forceinline__ unsigned pk2(float lo, float hi) { const f32x2_t f = {lo, hi}; const bf16x2_t b = __builtin_convertvector(f, bf16x2_t); return __builtin_bit_cast(unsigned, b); }
;   __device__ __forceinline__ void operator()(const f32x4 (&acc)[2][2][4][2], const pg8::Unit& u, int wr, int wc, int fr, int fq) const {
;     ...
;             const int row = row0 + ai * 128 + m * 16; const float rs = rsv[ai][m];
; #pragma unroll
;             for (int bj = 0; bj < 2; ++bj) {
;               const int c = col0 + bj * 128;
;               f32x4 a = acc[ai][bj][m][0] * rs, b = acc[ai][bj][m][1] * rs;
;               if (isg) {
; #pragma unroll
;                 for (int e = 0; e < 4; ++e) { a[e] = __builtin_amdgcn_rcpf(1.0f + __expf(-a[e])); b[e] = __builtin_amdgcn_rcpf(1.0f + __expf(-b[e])); }
;               }
;               u32x4 o; o.x = pk2(a[0], a[1]); o.y = pk2(a[2], a[3]); o.z = pk2(b[0], b[1]); o.w = pk2(b[2], b[3]);
;               if (isg) *(u32x4*)(sg + (size_t)row * 2048 + (c - 7680)) = o; else *(u32x4*)(qkv + (size_t)row * 4608 + c) = o;
.LBB0_256:
	v_add_u32_e32 v142, 0xa0, v176
	v_mov_b64_e32 v[144:145], s[30:31]
	s_movk_i32 s0, 0x2400
	v_mad_i64_i32 v[144:145], s[0:1], v142, s0, v[144:145]
	v_cvt_pk_bf16_f32 v130, v130, v131
	v_cvt_pk_bf16_f32 v131, v132, v133
	v_cvt_pk_bf16_f32 v132, v140, v141
	v_cvt_pk_bf16_f32 v133, v138, v139
	s_mov_b64 s[0:1], -1
	s_and_b64 vcc, exec, s[10:11]
	v_lshl_add_u64 v[138:139], v[174:175], 1, v[144:145]
	s_cbranch_vccnz .LBB0_258
	s_mov_b64 s[0:1], 0
	global_store_dwordx4 v[138:139], v[130:133], off
.LBB0_258:
	v_ashrrev_i32_e32 v143, 31, v142
	v_lshlrev_b64 v[140:141], 12, v[142:143]
	v_lshl_add_u64 v[140:141], s[56:57], 0, v[140:141]
	s_andn2_b64 vcc, exec, s[0:1]
	v_lshl_add_u64 v[140:141], v[174:175], 1, v[140:141]
	s_cbranch_vccnz .LBB0_260
	v_add_co_u32_e32 v142, vcc, 0x2584e000, v140
	s_nop 1
	v_addc_co_u32_e32 v143, vcc, 0, v141, vcc
	global_store_dwordx4 v[142:143], v[130:133], off offset:1024

; __device__ __forceinline__ unsigned pk2(float lo, float hi) { const f32x2_t f = {lo, hi}; const bf16x2_t b = __builtin_convertvector(f, bf16x2_t); return __builtin_bit_cast(unsigned, b); }
;   __device__ __forceinline__ void operator()(const f32x4 (&acc)[2][2][4][2], const pg8::Unit& u, int wr, int wc, int fr, int fq) const {
;     ...
;             const int row = row0 + ai * 128 + m * 16; const float rs = rsv[ai][m];
; #pragma unroll
;             for (int bj = 0; bj < 2; ++bj) {
;               const int c = col0 + bj * 128;
;               f32x4 a = acc[ai][bj][m][0] * rs, b = acc[ai][bj][m][1] * rs;
;               if (isg) {
; #pragma unroll
;                 for (int e = 0; e < 4; ++e) { a[e] = __builtin_amdgcn_rcpf(1.0f + __expf(-a[e])); b[e] = __builtin_amdgcn_rcpf(1.0f + __expf(-b[e])); }
;               }
;               u32x4 o; o.x = pk2(a[0], a[1]); o.y = pk2(a[2], a[3]); o.z = pk2(b[0], b[1]); o.w = pk2(b[2], b[3]);
;               if (isg) *(u32x4*)(sg + (size_t)row * 2048 + (c - 7680)) = o; else *(u32x4*)(qkv + (size_t)row * 4608 + c) = o;
.LBB0_264:
	v_cvt_pk_bf16_f32 v130, v130, v131
	v_cvt_pk_bf16_f32 v131, v132, v133
	v_cvt_pk_bf16_f32 v132, v136, v137
	v_cvt_pk_bf16_f32 v133, v142, v143
	s_and_b64 vcc, exec, s[10:11]
	s_mov_b64 s[0:1], -1
	s_cbranch_vccnz .LBB0_266
	s_mov_b64 s[0:1], 0
	global_store_dwordx4 v[138:139], v[130:133], off offset:256
.LBB0_266:
	s_andn2_b64 vcc, exec, s[0:1]
	s_cbranch_vccnz .LBB0_268
	v_add_co_u32_e32 v136, vcc, 0x2584e000, v140
	s_nop 1
	v_addc_co_u32_e32 v137, vcc, 0, v141, vcc
	global_store_dwordx4 v[136:137], v[130:133], off offset:1280

; __device__ __forceinline__ unsigned pk2(float lo, float hi) { const f32x2_t f = {lo, hi}; const bf16x2_t b = __builtin_convertvector(f, bf16x2_t); return __builtin_bit_cast(unsigned, b); }
;   __device__ __forceinline__ void operator()(const f32x4 (&acc)[2][2][4][2], const pg8::Unit& u, int wr, int wc, int fr, int fq) const {
;     ...
;             const int row = row0 + ai * 128 + m * 16; const float rs = rsv[ai][m];
; #pragma unroll
;             for (int bj = 0; bj < 2; ++bj) {
;               const int c = col0 + bj * 128;
;               f32x4 a = acc[ai][bj][m][0] * rs, b = acc[ai][bj][m][1] * rs;
;               if (isg) {
; #pragma unroll
;                 for (int e = 0; e < 4; ++e) { a[e] = __builtin_amdgcn_rcpf(1.0f + __expf(-a[e])); b[e] = __builtin_amdgcn_rcpf(1.0f + __expf(-b[e])); }
;               }
;               u32x4 o; o.x = pk2(a[0], a[1]); o.y = pk2(a[2], a[3]); o.z = pk2(b[0], b[1]); o.w = pk2(b[2], b[3]);
;               if (isg) *(u32x4*)(sg + (size_t)row * 2048 + (c - 7680)) = o; else *(u32x4*)(qkv + (size_t)row * 4608 + c) = o;
.LBB0_272:
	v_add_u32_e32 v140, 0xb0, v176
	v_mov_b64_e32 v[142:143], s[30:31]
	s_movk_i32 s0, 0x2400
	v_mad_i64_i32 v[142:143], s[0:1], v140, s0, v[142:143]
	v_cvt_pk_bf16_f32 v130, v130, v131
	v_cvt_pk_bf16_f32 v131, v132, v133
	v_cvt_pk_bf16_f32 v132, v138, v139
	v_cvt_pk_bf16_f32 v133, v136, v137
	s_mov_b64 s[0:1], -1
	s_and_b64 vcc, exec, s[10:11]
	v_lshl_add_u64 v[136:137], v[174:175], 1, v[142:143]
	s_cbranch_vccnz .LBB0_274
	s_mov_b64 s[0:1], 0
	global_store_dwordx4 v[136:137], v[130:133], off
.LBB0_274:
	v_ashrrev_i32_e32 v141, 31, v140
	v_lshlrev_b64 v[138:139], 12, v[140:141]
	v_lshl_add_u64 v[138:139], s[56:57], 0, v[138:139]
	s_andn2_b64 vcc, exec, s[0:1]
	v_lshl_add_u64 v[138:139], v[174:175], 1, v[138:139]
	s_cbranch_vccnz .LBB0_276
	v_add_co_u32_e32 v140, vcc, 0x2584e000, v138
	s_nop 1
	v_addc_co_u32_e32 v141, vcc, 0, v139, vcc
	global_store_dwordx4 v[140:141], v[130:133], off offset:1024

; __device__ __forceinline__ unsigned pk2(float lo, float hi) { const f32x2_t f = {lo, hi}; const bf16x2_t b = __builtin_convertvector(f, bf16x2_t); return __builtin_bit_cast(unsigned, b); }
;   __device__ __forceinline__ void operator()(const f32x4 (&acc)[2][2][4][2], const pg8::Unit& u, int wr, int wc, int fr, int fq) const {
;     ...
;             const int row = row0 + ai * 128 + m * 16; const float rs = rsv[ai][m];
; #pragma unroll
;             for (int bj = 0; bj < 2; ++bj) {
;               const int c = col0 + bj * 128;
;               f32x4 a = acc[ai][bj][m][0] * rs, b = acc[ai][bj][m][1] * rs;
;               if (isg) {
; #pragma unroll
;                 for (int e = 0; e < 4; ++e) { a[e] = __builtin_amdgcn_rcpf(1.0f + __expf(-a[e])); b[e] = __builtin_amdgcn_rcpf(1.0f + __expf(-b[e])); }
;               }
;               u32x4 o; o.x = pk2(a[0], a[1]); o.y = pk2(a[2], a[3]); o.z = pk2(b[0], b[1]); o.w = pk2(b[2], b[3]);
;               if (isg) *(u32x4*)(sg + (size_t)row * 2048 + (c - 7680)) = o; else *(u32x4*)(qkv + (size_t)row * 4608 + c) = o;
.LBB0_280:
	v_cvt_pk_bf16_f32 v130, v130, v131
	v_cvt_pk_bf16_f32 v131, v132, v133
	v_cvt_pk_bf16_f32 v132, v134, v135
	v_cvt_pk_bf16_f32 v133, v140, v141
	s_and_b64 vcc, exec, s[10:11]
	s_mov_b64 s[0:1], -1
	s_cbranch_vccnz .LBB0_282
	s_mov_b64 s[0:1], 0
	global_store_dwordx4 v[136:137], v[130:133], off offset:256
.LBB0_282:
	s_andn2_b64 vcc, exec, s[0:1]
	s_cbranch_vccnz .LBB0_284
	v_add_co_u32_e32 v134, vcc, 0x2584e000, v138
	s_nop 1
	v_addc_co_u32_e32 v135, vcc, 0, v139, vcc
	global_store_dwordx4 v[134:135], v[130:133], off offset:1280

; __device__ __forceinline__ unsigned pk2(float lo, float hi) { const f32x2_t f = {lo, hi}; const bf16x2_t b = __builtin_convertvector(f, bf16x2_t); return __builtin_bit_cast(unsigned, b); }
;   __device__ __forceinline__ void operator()(const f32x4 (&acc)[2][2][4][2], const pg8::Unit& u, int wr, int wc, int fr, int fq) const {
;     ...
; #pragma unroll
;         for (int ai = 0; ai < 2; ++ai)
; #pragma unroll
;           for (int m = 0; m < 4; ++m) {
;             const int fc = row0 + ai * 128 + m * 16; const int order = fc >> 11, dir = (fc >> 10) & 1, c = fc & 1023;
;             const float dl = dmin + (dmax - dmin) * ((float)c * (1.0f / 1023.0f));
;             float v[8]; float dk = __expf(-(float)p0 * tinv * dl); const float dstep = __expf(-tinv * dl);
; #pragma unroll
;             for (int e = 0; e < 8; ++e) { v[e] = acc[ai][bj][m][e >> 2][e & 3] * dk; dk *= dstep; }
;             u16* base = G + (size_t)(order * 1024 + c) * (size_t)(2 * L);
;             u32x4 o;
;             if (dir == 0) { o.x = pk2(v[7], v[6]); o.y = pk2(v[5], v[4]); o.z = pk2(v[3], v[2]); o.w = pk2(v[1], v[0]); *(u32x4*)(base + (L - 8 - p0)) = o; }
;             else { o.x = pk2(v[0], v[1]); o.y = pk2(v[2], v[3]); o.z = pk2(v[4], v[5]); o.w = pk2(v[6], v[7]); *(u32x4*)(base + (L + p0)) = o; }
.LBB0_290:
	v_cndmask_b32_e64 v80, v228, v229, s[0:1]
	v_lshl_add_u64 v[132:133], s[88:89], 0, v[80:81]
	v_cndmask_b32_e64 v80, 15, 12, s[0:1]
	s_ashr_i32 s0, s71, 1
	s_and_b32 s71, s0, 0xfffffc00
	v_or_b32_e32 v126, s71, v143
	v_ashrrev_i32_e32 v127, 31, v126
	v_lshlrev_b64 v[136:137], v80, v[126:127]
	v_lshl_add_u64 v[136:137], v[136:137], 1, v[132:133]
	v_cvt_pk_bf16_f32 v125, v134, v135
	v_lshl_add_u64 v[134:135], v[138:139], 1, v[136:137]
	v_or_b32_e32 v137, 16, v143
	v_lshl_add_u64 v[146:147], v[148:149], 0, v[134:135]
	global_store_dwordx2 v[134:135], v[124:125], off offset:8
	global_store_dword v[134:135], v123, off offset:4
	global_store_short_d16_hi v[134:135], v122, off offset:2
	global_store_short v[146:147], v122, off
	s_mov_b64 s[0:1], -1
	s_andn2_b64 vcc, exec, s[10:11]
	v_cvt_f32_u32_e32 v122, v137
	v_mul_f32_e32 v122, 0x3a802008, v122
	v_fmamk_f32 v136, v122, 0x41447cbd, v219
	v_mul_f32_e32 v122, v142, v136
	v_mul_f32_e64 v123, v136, -v141
	v_mul_f32_e32 v122, 0x3fb8aa3b, v122
	v_mul_f32_e32 v123, 0x3fb8aa3b, v123
	v_exp_f32_e32 v122, v122
	v_exp_f32_e32 v134, v123
	s_nop 0
	v_mul_f32_e32 v123, v134, v122
	v_pk_mul_f32 v[118:119], v[122:123], v[118:119]
	v_mul_f32_e32 v122, v134, v123
	v_mul_f32_e32 v123, v134, v122
	v_pk_mul_f32 v[120:121], v[122:123], v[120:121]
	v_mul_f32_e32 v122, v134, v123
	v_mul_f32_e32 v123, v134, v122
	v_pk_mul_f32 v[124:125], v[122:123], v[114:115]
	v_mul_f32_e32 v114, v134, v123
	v_mul_f32_e32 v115, v134, v114
	v_pk_mul_f32 v[122:123], v[114:115], v[116:117]
	v_cndmask_b32_e64 v114, 0, 1, s[10:11]
	v_cmp_ne_u32_e64 s[12:13], 1, v114
	s_cbranch_vccnz .LBB0_292
	v_cvt_pk_bf16_f32 v114, v118, v119
	v_cvt_pk_bf16_f32 v115, v120, v121
	v_cvt_pk_bf16_f32 v116, v124, v125
	s_mov_b64 s[0:1], 0

; __device__ __forceinline__ unsigned pk2(float lo, float hi) { const f32x2_t f = {lo, hi}; const bf16x2_t b = __builtin_convertvector(f, bf16x2_t); return __builtin_bit_cast(unsigned, b); }
;   __device__ __forceinline__ void operator()(const f32x4 (&acc)[2][2][4][2], const pg8::Unit& u, int wr, int wc, int fr, int fq) const {
;     ...
; #pragma unroll
;         for (int ai = 0; ai < 2; ++ai)
; #pragma unroll
;           for (int m = 0; m < 4; ++m) {
;             const int fc = row0 + ai * 128 + m * 16; const int order = fc >> 11, dir = (fc >> 10) & 1, c = fc & 1023;
;             const float dl = dmin + (dmax - dmin) * ((float)c * (1.0f / 1023.0f));
;             float v[8]; float dk = __expf(-(float)p0 * tinv * dl); const float dstep = __expf(-tinv * dl);
; #pragma unroll
;             for (int e = 0; e < 8; ++e) { v[e] = acc[ai][bj][m][e >> 2][e & 3] * dk; dk *= dstep; }
;             u16* base = G + (size_t)(order * 1024 + c) * (size_t)(2 * L);
;             u32x4 o;
;             if (dir == 0) { o.x = pk2(v[7], v[6]); o.y = pk2(v[5], v[4]); o.z = pk2(v[3], v[2]); o.w = pk2(v[1], v[0]); *(u32x4*)(base + (L - 8 - p0)) = o; }
;             else { o.x = pk2(v[0], v[1]); o.y = pk2(v[2], v[3]); o.z = pk2(v[4], v[5]); o.w = pk2(v[6], v[7]); *(u32x4*)(base + (L + p0)) = o; }
.LBB0_294:
	v_or_b32_e32 v118, s71, v137
	v_ashrrev_i32_e32 v119, 31, v118
	v_lshlrev_b64 v[120:121], v80, v[118:119]
	v_lshl_add_u64 v[120:121], v[120:121], 1, v[132:133]
	v_cvt_pk_bf16_f32 v117, v122, v123
	v_lshl_add_u64 v[120:121], v[134:135], 1, v[120:121]
	v_or_b32_e32 v123, 32, v143
	v_lshl_add_u64 v[146:147], v[148:149], 0, v[120:121]
	global_store_dwordx2 v[120:121], v[116:117], off offset:8
	global_store_dword v[120:121], v115, off offset:4
	global_store_short_d16_hi v[120:121], v114, off offset:2
	global_store_short v[146:147], v114, off
	s_mov_b64 s[0:1], -1
	s_and_b64 vcc, exec, s[12:13]
	v_cvt_f32_u32_e32 v114, v123
	v_mul_f32_e32 v114, 0x3a802008, v114
	v_fmamk_f32 v122, v114, 0x41447cbd, v219
	v_mul_f32_e32 v114, v142, v122
	v_mul_f32_e64 v115, v122, -v141
	v_mul_f32_e32 v114, 0x3fb8aa3b, v114
	v_mul_f32_e32 v115, 0x3fb8aa3b, v115
	v_exp_f32_e32 v114, v114
	v_exp_f32_e32 v120, v115
	s_nop 0
	v_mul_f32_e32 v115, v120, v114
	v_pk_mul_f32 v[110:111], v[114:115], v[110:111]
	v_mul_f32_e32 v114, v120, v115
	v_mul_f32_e32 v115, v120, v114
	v_pk_mul_f32 v[112:113], v[114:115], v[112:113]
	v_mul_f32_e32 v114, v120, v115
	v_mul_f32_e32 v115, v120, v114
	v_pk_mul_f32 v[116:117], v[114:115], v[106:107]
	v_mul_f32_e32 v106, v120, v115
	v_mul_f32_e32 v107, v120, v106
	v_pk_mul_f32 v[114:115], v[106:107], v[108:109]
	s_cbranch_vccnz .LBB0_296
	v_cvt_pk_bf16_f32 v106, v110, v111
	v_cvt_pk_bf16_f32 v107, v112, v113
	v_cvt_pk_bf16_f32 v108, v116, v117
	s_mov_b64 s[0:1], 0

; __device__ __forceinline__ unsigned pk2(float lo, float hi) { const f32x2_t f = {lo, hi}; const bf16x2_t b = __builtin_convertvector(f, bf16x2_t); return __builtin_bit_cast(unsigned, b); }
;   __device__ __forceinline__ void operator()(const f32x4 (&acc)[2][2][4][2], const pg8::Unit& u, int wr, int wc, int fr, int fq) const {
;     ...
; #pragma unroll
;         for (int ai = 0; ai < 2; ++ai)
; #pragma unroll
;           for (int m = 0; m < 4; ++m) {
;             const int fc = row0 + ai * 128 + m * 16; const int order = fc >> 11, dir = (fc >> 10) & 1, c = fc & 1023;
;             const float dl = dmin + (dmax - dmin) * ((float)c * (1.0f / 1023.0f));
;             float v[8]; float dk = __expf(-(float)p0 * tinv * dl); const float dstep = __expf(-tinv * dl);
; #pragma unroll
;             for (int e = 0; e < 8; ++e) { v[e] = acc[ai][bj][m][e >> 2][e & 3] * dk; dk *= dstep; }
;             u16* base = G + (size_t)(order * 1024 + c) * (size_t)(2 * L);
;             u32x4 o;
;             if (dir == 0) { o.x = pk2(v[7], v[6]); o.y = pk2(v[5], v[4]); o.z = pk2(v[3], v[2]); o.w = pk2(v[1], v[0]); *(u32x4*)(base + (L - 8 - p0)) = o; }
;             else { o.x = pk2(v[0], v[1]); o.y = pk2(v[2], v[3]); o.z = pk2(v[4], v[5]); o.w = pk2(v[6], v[7]); *(u32x4*)(base + (L + p0)) = o; }
.LBB0_298:
	v_or_b32_e32 v110, s71, v123
	v_ashrrev_i32_e32 v111, 31, v110
	v_lshlrev_b64 v[112:113], v80, v[110:111]
	v_lshl_add_u64 v[112:113], v[112:113], 1, v[132:133]
	v_cvt_pk_bf16_f32 v109, v114, v115
	v_lshl_add_u64 v[112:113], v[120:121], 1, v[112:113]
	v_or_b32_e32 v115, 48, v143
	v_lshl_add_u64 v[146:147], v[148:149], 0, v[112:113]
	global_store_dwordx2 v[112:113], v[108:109], off offset:8
	global_store_dword v[112:113], v107, off offset:4
	global_store_short_d16_hi v[112:113], v106, off offset:2
	global_store_short v[146:147], v106, off
	s_mov_b64 s[0:1], -1
	s_and_b64 vcc, exec, s[12:13]
	v_cvt_f32_u32_e32 v106, v115
	v_mul_f32_e32 v106, 0x3a802008, v106
	v_fmamk_f32 v114, v106, 0x41447cbd, v219
	v_mul_f32_e32 v106, v142, v114
	v_mul_f32_e64 v107, v114, -v141
	v_mul_f32_e32 v106, 0x3fb8aa3b, v106
	v_mul_f32_e32 v107, 0x3fb8aa3b, v107
	v_exp_f32_e32 v106, v106
	v_exp_f32_e32 v112, v107
	s_nop 0
	v_mul_f32_e32 v107, v112, v106
	v_mul_f32_e32 v108, v112, v107
	v_mul_f32_e32 v109, v112, v108
	v_pk_mul_f32 v[102:103], v[106:107], v[102:103]
	v_pk_mul_f32 v[106:107], v[108:109], v[104:105]
	v_mul_f32_e32 v104, v112, v109
	v_mul_f32_e32 v105, v112, v104
	v_pk_mul_f32 v[108:109], v[104:105], v[98:99]
	v_mul_f32_e32 v98, v112, v105
	v_mul_f32_e32 v99, v112, v98
	v_pk_mul_f32 v[104:105], v[98:99], v[100:101]
	s_cbranch_vccnz .LBB0_300
	v_cvt_pk_bf16_f32 v98, v102, v103
	v_cvt_pk_bf16_f32 v99, v106, v107
	v_cvt_pk_bf16_f32 v100, v108, v109
	s_mov_b64 s[0:1], 0

; __device__ __forceinline__ unsigned pk2(float lo, float hi) { const f32x2_t f = {lo, hi}; const bf16x2_t b = __builtin_convertvector(f, bf16x2_t); return __builtin_bit_cast(unsigned, b); }
;   __device__ __forceinline__ void operator()(const f32x4 (&acc)[2][2][4][2], const pg8::Unit& u, int wr, int wc, int fr, int fq) const {
;     ...
;         for (int ai = 0; ai < 2; ++ai)
; #pragma unroll
;           for (int m = 0; m < 4; ++m) {
;             const int fc = row0 + ai * 128 + m * 16; const int order = fc >> 11, dir = (fc >> 10) & 1, c = fc & 1023;
;             const float dl = dmin + (dmax - dmin) * ((float)c * (1.0f / 1023.0f));
;             float v[8]; float dk = __expf(-(float)p0 * tinv * dl); const float dstep = __expf(-tinv * dl);
; #pragma unroll
;             for (int e = 0; e < 8; ++e) { v[e] = acc[ai][bj][m][e >> 2][e & 3] * dk; dk *= dstep; }
;             u16* base = G + (size_t)(order * 1024 + c) * (size_t)(2 * L);
;             u32x4 o;
;             if (dir == 0) { o.x = pk2(v[7], v[6]); o.y = pk2(v[5], v[4]); o.z = pk2(v[3], v[2]); o.w = pk2(v[1], v[0]); *(u32x4*)(base + (L - 8 - p0)) = o; }
;             else { o.x = pk2(v[0], v[1]); o.y = pk2(v[2], v[3]); o.z = pk2(v[4], v[5]); o.w = pk2(v[6], v[7]); *(u32x4*)(base + (L + p0)) = o; }
.LBB0_302:
	v_add_u32_e32 v108, 0x80, v176
	v_and_b32_e32 v107, 0x3cf, v108
	v_cvt_f32_u32_e32 v106, v107
	v_or_b32_e32 v102, s71, v115
	v_ashrrev_i32_e32 v103, 31, v102
	v_lshlrev_b64 v[116:117], v80, v[102:103]
	v_mul_f32_e32 v106, 0x3a802008, v106
	v_fmamk_f32 v106, v106, 0x41447cbd, v219
	v_mul_f32_e32 v109, v142, v106
	v_lshl_add_u64 v[116:117], v[116:117], 1, v[132:133]
	v_mul_f32_e32 v109, 0x3fb8aa3b, v109
	v_cvt_pk_bf16_f32 v101, v104, v105
	v_lshl_add_u64 v[104:105], v[112:113], 1, v[116:117]
	v_exp_f32_e32 v112, v109
	v_mul_f32_e64 v109, v106, -v141
	v_mul_f32_e32 v109, 0x3fb8aa3b, v109
	v_exp_f32_e32 v109, v109
	v_lshl_add_u64 v[146:147], v[148:149], 0, v[104:105]
	global_store_dwordx2 v[104:105], v[100:101], off offset:8
	global_store_dword v[104:105], v99, off offset:4
	global_store_short_d16_hi v[104:105], v98, off offset:2
	global_store_short v[146:147], v98, off
	v_mul_f32_e32 v113, v109, v112
	s_nop 0
	v_mul_f32_e32 v100, v109, v113
	v_and_b32_e32 v98, 0x400, v108
	v_mul_f32_e32 v101, v109, v100
	v_cmp_ne_u32_e64 s[10:11], 0, v98
	v_pk_mul_f32 v[98:99], v[100:101], v[96:97]
	v_mul_f32_e32 v96, v109, v101
	v_mul_f32_e32 v97, v109, v96
	v_pk_mul_f32 v[100:101], v[96:97], v[90:91]
	v_mul_f32_e32 v90, v109, v97
	v_mul_f32_e32 v91, v109, v90
	v_pk_mul_f32 v[94:95], v[112:113], v[94:95]
	v_pk_mul_f32 v[96:97], v[90:91], v[92:93]
	s_and_saveexec_b64 s[0:1], s[10:11]
	s_xor_b64 s[0:1], exec, s[0:1]
	v_cvt_pk_bf16_f32 v90, v94, v95
	v_cvt_pk_bf16_f32 v91, v98, v99
	v_cvt_pk_bf16_f32 v92, v100, v101
	s_or_saveexec_b64 s[0:1], s[0:1]
	v_mov_b64_e32 v[104:105], v[128:129]
	s_xor_b64 exec, exec, s[0:1]
	v_pk_mov_b32 v[90:91], v[96:97], v[96:97] op_sel:[1,0]
	v_pk_mov_b32 v[92:93], v[100:101], v[100:101] op_sel:[1,0]
	v_cvt_pk_bf16_f32 v90, v90, v91
	v_cvt_pk_bf16_f32 v91, v92, v93
	v_pk_mov_b32 v[92:93], v[98:99], v[98:99] op_sel:[1,0]
	v_mov_b64_e32 v[104:105], v[130:131]
	v_cvt_pk_bf16_f32 v92, v92, v93
	v_mov_b32_e32 v96, v95
	v_mov_b32_e32 v97, v94
	s_or_b64 exec, exec, s[0:1]
	v_ashrrev_i32_e32 v93, 1, v108
	v_and_b32_e32 v99, 0xfffffc00, v93
	v_or_b32_e32 v94, v99, v107
	v_ashrrev_i32_e32 v95, 31, v94
	v_lshlrev_b64 v[100:101], v80, v[94:95]
	v_lshl_add_u64 v[100:101], v[100:101], 1, v[132:133]
	v_cvt_pk_bf16_f32 v93, v96, v97
	v_lshl_add_u64 v[96:97], v[104:105], 1, v[100:101]
	v_or_b32_e32 v100, 16, v107
	v_lshl_add_u64 v[146:147], v[148:149], 0, v[96:97]
	global_store_dwordx2 v[96:97], v[92:93], off offset:8
	global_store_dword v[96:97], v91, off offset:4
	global_store_short_d16_hi v[96:97], v90, off offset:2
	global_store_short v[146:147], v90, off
	s_nop 1
	v_cvt_f32_u32_e32 v90, v100
	v_mul_f32_e32 v90, 0x3a802008, v90
	v_fmamk_f32 v98, v90, 0x41447cbd, v219
	v_mul_f32_e32 v90, v142, v98
	v_mul_f32_e64 v91, v98, -v141
	v_mul_f32_e32 v90, 0x3fb8aa3b, v90
	v_mul_f32_e32 v91, 0x3fb8aa3b, v91
	v_exp_f32_e32 v90, v90
	v_exp_f32_e32 v96, v91
	s_nop 0
	v_mul_f32_e32 v91, v96, v90
	v_mul_f32_e32 v92, v96, v91
	v_mul_f32_e32 v93, v96, v92
	v_pk_mul_f32 v[86:87], v[90:91], v[86:87]
	v_pk_mul_f32 v[90:91], v[92:93], v[88:89]
	v_mul_f32_e32 v88, v96, v93
	v_mul_f32_e32 v89, v96, v88
	v_pk_mul_f32 v[92:93], v[88:89], v[82:83]
	v_mul_f32_e32 v82, v96, v89
	v_mul_f32_e32 v83, v96, v82
	v_pk_mul_f32 v[88:89], v[82:83], v[84:85]
	s_and_saveexec_b64 s[0:1], s[10:11]
	s_xor_b64 s[0:1], exec, s[0:1]
	v_cvt_pk_bf16_f32 v82, v86, v87
	v_cvt_pk_bf16_f32 v83, v90, v91
	v_cvt_pk_bf16_f32 v84, v92, v93
	s_or_saveexec_b64 s[0:1], s[0:1]
	v_mov_b64_e32 v[96:97], v[128:129]
	s_xor_b64 exec, exec, s[0:1]
	v_pk_mov_b32 v[82:83], v[88:89], v[88:89] op_sel:[1,0]
	v_pk_mov_b32 v[84:85], v[92:93], v[92:93] op_sel:[1,0]
	v_cvt_pk_bf16_f32 v82, v82, v83
	v_cvt_pk_bf16_f32 v83, v84, v85
	v_pk_mov_b32 v[84:85], v[90:91], v[90:91] op_sel:[1,0]
	v_mov_b64_e32 v[96:97], v[130:131]
	v_cvt_pk_bf16_f32 v84, v84, v85
	v_mov_b32_e32 v88, v87
	v_mov_b32_e32 v89, v86
	s_or_b64 exec, exec, s[0:1]
	v_or_b32_e32 v86, v100, v99
	v_ashrrev_i32_e32 v87, 31, v86
	v_lshlrev_b64 v[90:91], v80, v[86:87]
	v_lshl_add_u64 v[90:91], v[90:91], 1, v[132:133]
	v_cvt_pk_bf16_f32 v85, v88, v89
	v_lshl_add_u64 v[88:89], v[96:97], 1, v[90:91]
	v_or_b32_e32 v91, 32, v107
	v_lshl_add_u64 v[146:147], v[148:149], 0, v[88:89]
	global_store_dwordx2 v[88:89], v[84:85], off offset:8
	global_store_dword v[88:89], v83, off offset:4
	global_store_short_d16_hi v[88:89], v82, off offset:2
	global_store_short v[146:147], v82, off
	s_nop 1
	v_cvt_f32_u32_e32 v82, v91
	v_mul_f32_e32 v82, 0x3a802008, v82
	v_fmamk_f32 v90, v82, 0x41447cbd, v219
	v_mul_f32_e32 v82, v142, v90
	v_mul_f32_e64 v83, v90, -v141
	v_mul_f32_e32 v82, 0x3fb8aa3b, v82
	v_mul_f32_e32 v83, 0x3fb8aa3b, v83
	v_exp_f32_e32 v82, v82
	v_exp_f32_e32 v88, v83
; __device__ __forceinline__ unsigned pk2(float lo, float hi) { const f32x2_t f = {lo, hi}; const bf16x2_t b = __builtin_convertvector(f, bf16x2_t); return __builtin_bit_cast(unsigned, b); }
;   __device__ __forceinline__ void operator()(const f32x4 (&acc)[2][2][4][2], const pg8::Unit& u, int wr, int wc, int fr, int fq) const {
;     ...
;       for (int bj = 0; bj < 2; ++bj) {
;         const int pr = col0 + bj * 128; const int L = pr < 2048 ? 2048 : 16384; const int p0 = pr < 2048 ? pr : pr - 2048;
;         u16* G = (u16*)(ws + (L == 2048 ? O_G2K : O_G16K));
;         const float tinv = 1.0f / (float)(L - 1);
; #pragma unroll
;         for (int ai = 0; ai < 2; ++ai)
; #pragma unroll
;           for (int m = 0; m < 4; ++m) {
;             const int fc = row0 + ai * 128 + m * 16; const int order = fc >> 11, dir = (fc >> 10) & 1, c = fc & 1023;
;             const float dl = dmin + (dmax - dmin) * ((float)c * (1.0f / 1023.0f));
;             float v[8]; float dk = __expf(-(float)p0 * tinv * dl); const float dstep = __expf(-tinv * dl);
; #pragma unroll
;             for (int e = 0; e < 8; ++e) { v[e] = acc[ai][bj][m][e >> 2][e & 3] * dk; dk *= dstep; }
;             u16* base = G + (size_t)(order * 1024 + c) * (size_t)(2 * L);
;             u32x4 o;
;             if (dir == 0) { o.x = pk2(v[7], v[6]); o.y = pk2(v[5], v[4]); o.z = pk2(v[3], v[2]); o.w = pk2(v[1], v[0]); *(u32x4*)(base + (L - 8 - p0)) = o; }
;             else { o.x = pk2(v[0], v[1]); o.y = pk2(v[2], v[3]); o.z = pk2(v[4], v[5]); o.w = pk2(v[6], v[7]); *(u32x4*)(base + (L + p0)) = o; }
	s_nop 0
	v_mul_f32_e32 v83, v88, v82
	v_mul_f32_e32 v84, v88, v83
	v_mul_f32_e32 v85, v88, v84
	v_pk_mul_f32 v[76:77], v[82:83], v[76:77]
	v_pk_mul_f32 v[82:83], v[84:85], v[78:79]
	v_mul_f32_e32 v78, v88, v85
	v_mul_f32_e32 v79, v88, v78
	v_pk_mul_f32 v[84:85], v[78:79], v[72:73]
	v_mul_f32_e32 v72, v88, v79
	v_mul_f32_e32 v73, v88, v72
	v_pk_mul_f32 v[78:79], v[72:73], v[74:75]
	s_and_saveexec_b64 s[0:1], s[10:11]
	s_xor_b64 s[0:1], exec, s[0:1]
	v_cvt_pk_bf16_f32 v72, v76, v77
	v_cvt_pk_bf16_f32 v73, v82, v83
	v_cvt_pk_bf16_f32 v74, v84, v85
	s_or_saveexec_b64 s[0:1], s[0:1]
	v_mov_b64_e32 v[88:89], v[128:129]
	s_xor_b64 exec, exec, s[0:1]
	v_pk_mov_b32 v[72:73], v[78:79], v[78:79] op_sel:[1,0]
	v_pk_mov_b32 v[74:75], v[84:85], v[84:85] op_sel:[1,0]
	v_cvt_pk_bf16_f32 v72, v72, v73
	v_cvt_pk_bf16_f32 v73, v74, v75
	v_pk_mov_b32 v[74:75], v[82:83], v[82:83] op_sel:[1,0]
	v_mov_b64_e32 v[88:89], v[130:131]
	v_cvt_pk_bf16_f32 v74, v74, v75
	v_mov_b32_e32 v78, v77
	v_mov_b32_e32 v79, v76
	s_or_b64 exec, exec, s[0:1]
	v_or_b32_e32 v76, v91, v99
	v_ashrrev_i32_e32 v77, 31, v76
	v_lshlrev_b64 v[82:83], v80, v[76:77]
	v_lshl_add_u64 v[82:83], v[82:83], 1, v[132:133]
	v_cvt_pk_bf16_f32 v75, v78, v79
	v_lshl_add_u64 v[78:79], v[88:89], 1, v[82:83]
	v_lshl_add_u64 v[146:147], v[148:149], 0, v[78:79]
	global_store_dwordx2 v[78:79], v[74:75], off offset:8
	global_store_dword v[78:79], v73, off offset:4
	global_store_short_d16_hi v[78:79], v72, off offset:2
	global_store_short v[146:147], v72, off
	v_or_b32_e32 v79, 48, v107
	s_nop 0
	v_cvt_f32_u32_e32 v72, v79
	v_mul_f32_e32 v72, 0x3a802008, v72
	v_fmamk_f32 v78, v72, 0x41447cbd, v219
	v_mul_f32_e32 v72, v142, v78
	v_mul_f32_e64 v73, v78, -v141
	v_mul_f32_e32 v72, 0x3fb8aa3b, v72
	v_mul_f32_e32 v73, 0x3fb8aa3b, v73
	v_exp_f32_e32 v72, v72
	v_exp_f32_e32 v82, v73
	s_nop 0
	v_mul_f32_e32 v73, v82, v72
	v_mul_f32_e32 v74, v82, v73
	v_mul_f32_e32 v75, v82, v74
	v_pk_mul_f32 v[68:69], v[72:73], v[68:69]
	v_pk_mul_f32 v[72:73], v[74:75], v[70:71]
	v_mul_f32_e32 v70, v82, v75
	v_mul_f32_e32 v71, v82, v70
	v_pk_mul_f32 v[74:75], v[70:71], v[64:65]
	v_mul_f32_e32 v64, v82, v71
	v_mul_f32_e32 v65, v82, v64
	v_pk_mul_f32 v[70:71], v[64:65], v[66:67]
	s_and_saveexec_b64 s[0:1], s[10:11]
	s_xor_b64 s[0:1], exec, s[0:1]
	v_cvt_pk_bf16_f32 v64, v68, v69
	v_cvt_pk_bf16_f32 v65, v72, v73
	v_cvt_pk_bf16_f32 v66, v74, v75
	s_andn2_saveexec_b64 s[0:1], s[0:1]
	v_pk_mov_b32 v[64:65], v[70:71], v[70:71] op_sel:[1,0]
	v_pk_mov_b32 v[66:67], v[74:75], v[74:75] op_sel:[1,0]
	v_cvt_pk_bf16_f32 v64, v64, v65
	v_cvt_pk_bf16_f32 v65, v66, v67
	v_pk_mov_b32 v[66:67], v[72:73], v[72:73] op_sel:[1,0]
	v_mov_b64_e32 v[128:129], v[130:131]
	v_cvt_pk_bf16_f32 v66, v66, v67
	v_mov_b32_e32 v70, v69
	v_mov_b32_e32 v71, v68
	s_or_b64 exec, exec, s[0:1]
	v_or_b32_e32 v68, v79, v99
	v_ashrrev_i32_e32 v69, 31, v68
	v_lshlrev_b64 v[72:73], v80, v[68:69]
	v_lshl_add_u64 v[72:73], v[72:73], 1, v[132:133]
	v_cvt_pk_bf16_f32 v67, v70, v71
	v_lshl_add_u64 v[70:71], v[128:129], 1, v[72:73]
	v_lshl_add_u64 v[146:147], v[148:149], 0, v[70:71]
	global_store_dwordx2 v[70:71], v[66:67], off offset:8
	global_store_dword v[70:71], v65, off offset:4
	global_store_short_d16_hi v[70:71], v64, off offset:2
	global_store_short v[146:147], v64, off
	s_nop 1
	v_or_b32_e32 v64, 0x80, v174
	v_cmp_gt_i32_e64 s[0:1], s94, v64
	v_add_u32_e32 v65, 0xfffff880, v174
	s_mov_b64 s[94:95], -1
	v_cndmask_b32_e64 v74, v226, v227, s[0:1]
	v_cndmask_b32_e64 v75, v65, v64, s[0:1]
	v_add_u32_e32 v64, -1, v74
	v_cvt_f32_u32_e32 v64, v64
	v_div_scale_f32 v65, s[72:73], v64, v64, 1.0
	v_rcp_f32_e32 v66, v65
	s_nop 0
	v_fma_f32 v67, -v65, v66, 1.0
	v_fmac_f32_e32 v66, v67, v66
	v_div_scale_f32 v67, vcc, 1.0, v64, 1.0
	v_mul_f32_e32 v70, v67, v66
	v_fma_f32 v71, -v65, v70, v67
	v_fmac_f32_e32 v70, v71, v66
	v_fma_f32 v65, -v65, v70, v67
	v_div_fmas_f32 v65, v65, v66, v70
	v_div_fixup_f32 v79, v65, v64, 1.0
	v_cvt_f32_i32_e32 v64, v75
	s_and_b64 vcc, exec, s[12:13]
	v_mul_f32_e64 v82, v79, -v64
	v_mul_f32_e32 v64, v140, v82
	v_mul_f32_e32 v64, 0x3fb8aa3b, v64
	v_exp_f32_e32 v66, v64
	v_mul_f32_e64 v64, v140, -v79
	v_mul_f32_e32 v64, 0x3fb8aa3b, v64
	v_exp_f32_e32 v80, v64
	s_nop 0
	v_mul_f32_e32 v67, v80, v66
	v_pk_mul_f32 v[64:65], v[66:67], v[60:61]
	v_mul_f32_e32 v60, v80, v67
	v_mul_f32_e32 v61, v80, v60
	v_pk_mul_f32 v[70:71], v[60:61], v[62:63]
	v_mul_f32_e32 v60, v80, v61
	v_mul_f32_e32 v61, v80, v60
	v_pk_mul_f32 v[72:73], v[60:61], v[56:57]
	v_mul_f32_e32 v56, v80, v61
	v_mul_f32_e32 v57, v80, v56
	v_pk_mul_f32 v[66:67], v[56:57], v[58:59]
	s_cbranch_vccnz .LBB0_320
	v_cvt_pk_bf16_f32 v56, v64, v65
	v_cvt_pk_bf16_f32 v57, v70, v71
	v_cvt_pk_bf16_f32 v58, v72, v73
	s_mov_b64 s[94:95], 0

; __device__ __forceinline__ unsigned pk2(float lo, float hi) { const f32x2_t f = {lo, hi}; const bf16x2_t b = __builtin_convertvector(f, bf16x2_t); return __builtin_bit_cast(unsigned, b); }
;   __device__ __forceinline__ void operator()(const f32x4 (&acc)[2][2][4][2], const pg8::Unit& u, int wr, int wc, int fr, int fq) const {
;     ...
;           for (int m = 0; m < 4; ++m) {
;             const int fc = row0 + ai * 128 + m * 16; const int order = fc >> 11, dir = (fc >> 10) & 1, c = fc & 1023;
;             const float dl = dmin + (dmax - dmin) * ((float)c * (1.0f / 1023.0f));
;             float v[8]; float dk = __expf(-(float)p0 * tinv * dl); const float dstep = __expf(-tinv * dl);
; #pragma unroll
;             for (int e = 0; e < 8; ++e) { v[e] = acc[ai][bj][m][e >> 2][e & 3] * dk; dk *= dstep; }
;             u16* base = G + (size_t)(order * 1024 + c) * (size_t)(2 * L);
;             u32x4 o;
;             if (dir == 0) { o.x = pk2(v[7], v[6]); o.y = pk2(v[5], v[4]); o.z = pk2(v[3], v[2]); o.w = pk2(v[1], v[0]); *(u32x4*)(base + (L - 8 - p0)) = o; }
;             else { o.x = pk2(v[0], v[1]); o.y = pk2(v[2], v[3]); o.z = pk2(v[4], v[5]); o.w = pk2(v[6], v[7]); *(u32x4*)(base + (L + p0)) = o; }
.LBB0_322:
	v_mul_f32_e32 v59, v136, v82
	v_mul_f32_e32 v59, 0x3fb8aa3b, v59
	v_exp_f32_e32 v84, v59
	v_mul_f32_e64 v59, v136, -v79
	v_mul_f32_e32 v59, 0x3fb8aa3b, v59
	v_exp_f32_e32 v71, v59
	v_cndmask_b32_e64 v80, v228, v229, s[0:1]
	v_cndmask_b32_e64 v70, 15, 12, s[0:1]
	v_lshl_add_u64 v[64:65], s[88:89], 0, v[80:81]
	v_lshlrev_b64 v[72:73], v70, v[126:127]
	v_lshl_add_u64 v[72:73], v[72:73], 1, v[64:65]
	v_cvt_pk_bf16_f32 v59, v66, v67
	v_lshl_add_u64 v[66:67], v[74:75], 1, v[72:73]
	v_mul_f32_e32 v85, v71, v84
	global_store_dwordx4 v[66:67], v[56:59], off
	v_pk_mul_f32 v[52:53], v[84:85], v[52:53]
	s_and_b64 vcc, exec, s[12:13]
	v_mul_f32_e32 v58, v71, v85
	v_mul_f32_e32 v59, v71, v58
	v_pk_mul_f32 v[56:57], v[58:59], v[54:55]
	v_mul_f32_e32 v54, v71, v59
	v_mul_f32_e32 v55, v71, v54
	v_pk_mul_f32 v[58:59], v[54:55], v[48:49]
	v_mul_f32_e32 v48, v71, v55
	v_mul_f32_e32 v49, v71, v48
	v_pk_mul_f32 v[54:55], v[48:49], v[50:51]
	s_mov_b64 s[0:1], -1
	s_movk_i32 s94, 0x800
	s_cbranch_vccnz .LBB0_324
	v_cvt_pk_bf16_f32 v48, v52, v53
	v_cvt_pk_bf16_f32 v49, v56, v57
	v_cvt_pk_bf16_f32 v50, v58, v59
	s_mov_b64 s[0:1], 0

; __device__ __forceinline__ unsigned pk2(float lo, float hi) { const f32x2_t f = {lo, hi}; const bf16x2_t b = __builtin_convertvector(f, bf16x2_t); return __builtin_bit_cast(unsigned, b); }
;   __device__ __forceinline__ void operator()(const f32x4 (&acc)[2][2][4][2], const pg8::Unit& u, int wr, int wc, int fr, int fq) const {
;     ...
;           for (int m = 0; m < 4; ++m) {
;             const int fc = row0 + ai * 128 + m * 16; const int order = fc >> 11, dir = (fc >> 10) & 1, c = fc & 1023;
;             const float dl = dmin + (dmax - dmin) * ((float)c * (1.0f / 1023.0f));
;             float v[8]; float dk = __expf(-(float)p0 * tinv * dl); const float dstep = __expf(-tinv * dl);
; #pragma unroll
;             for (int e = 0; e < 8; ++e) { v[e] = acc[ai][bj][m][e >> 2][e & 3] * dk; dk *= dstep; }
;             u16* base = G + (size_t)(order * 1024 + c) * (size_t)(2 * L);
;             u32x4 o;
;             if (dir == 0) { o.x = pk2(v[7], v[6]); o.y = pk2(v[5], v[4]); o.z = pk2(v[3], v[2]); o.w = pk2(v[1], v[0]); *(u32x4*)(base + (L - 8 - p0)) = o; }
;             else { o.x = pk2(v[0], v[1]); o.y = pk2(v[2], v[3]); o.z = pk2(v[4], v[5]); o.w = pk2(v[6], v[7]); *(u32x4*)(base + (L + p0)) = o; }
.LBB0_326:
	v_mul_f32_e32 v51, v122, v82
	v_mul_f32_e32 v51, 0x3fb8aa3b, v51
	v_exp_f32_e32 v56, v51
	v_mul_f32_e64 v51, v122, -v79
	v_mul_f32_e32 v51, 0x3fb8aa3b, v51
	v_exp_f32_e32 v58, v51
	v_lshlrev_b64 v[52:53], v70, v[118:119]
	v_lshl_add_u64 v[52:53], v[52:53], 1, v[64:65]
	v_cvt_pk_bf16_f32 v51, v54, v55
	v_lshl_add_u64 v[52:53], v[66:67], 1, v[52:53]
	v_mul_f32_e32 v57, v58, v56
	global_store_dwordx4 v[52:53], v[48:51], off
	v_pk_mul_f32 v[44:45], v[56:57], v[44:45]
	s_and_b64 vcc, exec, s[12:13]
	v_mul_f32_e32 v50, v58, v57
	v_mul_f32_e32 v51, v58, v50
	v_pk_mul_f32 v[48:49], v[50:51], v[46:47]
	v_mul_f32_e32 v46, v58, v51
	v_mul_f32_e32 v47, v58, v46
	v_pk_mul_f32 v[50:51], v[46:47], v[40:41]
	v_mul_f32_e32 v40, v58, v47
	v_mul_f32_e32 v41, v58, v40
	v_pk_mul_f32 v[46:47], v[40:41], v[42:43]
	s_mov_b64 s[0:1], -1
	s_cbranch_vccnz .LBB0_328
	v_cvt_pk_bf16_f32 v40, v44, v45
	v_cvt_pk_bf16_f32 v41, v48, v49
	v_cvt_pk_bf16_f32 v42, v50, v51
	s_mov_b64 s[0:1], 0

; __device__ __forceinline__ unsigned pk2(float lo, float hi) { const f32x2_t f = {lo, hi}; const bf16x2_t b = __builtin_convertvector(f, bf16x2_t); return __builtin_bit_cast(unsigned, b); }
;   __device__ __forceinline__ void operator()(const f32x4 (&acc)[2][2][4][2], const pg8::Unit& u, int wr, int wc, int fr, int fq) const {
;     ...
;           for (int m = 0; m < 4; ++m) {
;             const int fc = row0 + ai * 128 + m * 16; const int order = fc >> 11, dir = (fc >> 10) & 1, c = fc & 1023;
;             const float dl = dmin + (dmax - dmin) * ((float)c * (1.0f / 1023.0f));
;             float v[8]; float dk = __expf(-(float)p0 * tinv * dl); const float dstep = __expf(-tinv * dl);
; #pragma unroll
;             for (int e = 0; e < 8; ++e) { v[e] = acc[ai][bj][m][e >> 2][e & 3] * dk; dk *= dstep; }
;             u16* base = G + (size_t)(order * 1024 + c) * (size_t)(2 * L);
;             u32x4 o;
;             if (dir == 0) { o.x = pk2(v[7], v[6]); o.y = pk2(v[5], v[4]); o.z = pk2(v[3], v[2]); o.w = pk2(v[1], v[0]); *(u32x4*)(base + (L - 8 - p0)) = o; }
;             else { o.x = pk2(v[0], v[1]); o.y = pk2(v[2], v[3]); o.z = pk2(v[4], v[5]); o.w = pk2(v[6], v[7]); *(u32x4*)(base + (L + p0)) = o; }
.LBB0_330:
	v_mul_f32_e32 v43, v114, v82
	v_mul_f32_e32 v43, 0x3fb8aa3b, v43
	v_exp_f32_e32 v48, v43
	v_mul_f32_e64 v43, v114, -v79
	v_mul_f32_e32 v43, 0x3fb8aa3b, v43
	v_exp_f32_e32 v50, v43
	v_lshlrev_b64 v[44:45], v70, v[110:111]
	v_lshl_add_u64 v[44:45], v[44:45], 1, v[64:65]
	v_cvt_pk_bf16_f32 v43, v46, v47
	v_lshl_add_u64 v[44:45], v[52:53], 1, v[44:45]
	v_mul_f32_e32 v49, v50, v48
	global_store_dwordx4 v[44:45], v[40:43], off
	v_pk_mul_f32 v[36:37], v[48:49], v[36:37]
	s_and_b64 vcc, exec, s[12:13]
	v_mul_f32_e32 v42, v50, v49
	v_mul_f32_e32 v43, v50, v42
	v_pk_mul_f32 v[40:41], v[42:43], v[38:39]
	v_mul_f32_e32 v38, v50, v43
	v_mul_f32_e32 v39, v50, v38
	v_pk_mul_f32 v[42:43], v[38:39], v[32:33]
	v_mul_f32_e32 v32, v50, v39
	v_mul_f32_e32 v33, v50, v32
	v_pk_mul_f32 v[38:39], v[32:33], v[34:35]
	s_mov_b64 s[0:1], -1
	s_cbranch_vccnz .LBB0_332
	v_cvt_pk_bf16_f32 v32, v36, v37
	v_cvt_pk_bf16_f32 v33, v40, v41
	v_cvt_pk_bf16_f32 v34, v42, v43
	s_mov_b64 s[0:1], 0

; __device__ __forceinline__ unsigned pk2(float lo, float hi) { const f32x2_t f = {lo, hi}; const bf16x2_t b = __builtin_convertvector(f, bf16x2_t); return __builtin_bit_cast(unsigned, b); }
;   __device__ __forceinline__ void operator()(const f32x4 (&acc)[2][2][4][2], const pg8::Unit& u, int wr, int wc, int fr, int fq) const {
;     ...
;         for (int ai = 0; ai < 2; ++ai)
; #pragma unroll
;           for (int m = 0; m < 4; ++m) {
;             const int fc = row0 + ai * 128 + m * 16; const int order = fc >> 11, dir = (fc >> 10) & 1, c = fc & 1023;
;             const float dl = dmin + (dmax - dmin) * ((float)c * (1.0f / 1023.0f));
;             float v[8]; float dk = __expf(-(float)p0 * tinv * dl); const float dstep = __expf(-tinv * dl);
; #pragma unroll
;             for (int e = 0; e < 8; ++e) { v[e] = acc[ai][bj][m][e >> 2][e & 3] * dk; dk *= dstep; }
;             u16* base = G + (size_t)(order * 1024 + c) * (size_t)(2 * L);
;             u32x4 o;
;             if (dir == 0) { o.x = pk2(v[7], v[6]); o.y = pk2(v[5], v[4]); o.z = pk2(v[3], v[2]); o.w = pk2(v[1], v[0]); *(u32x4*)(base + (L - 8 - p0)) = o; }
;             else { o.x = pk2(v[0], v[1]); o.y = pk2(v[2], v[3]); o.z = pk2(v[4], v[5]); o.w = pk2(v[6], v[7]); *(u32x4*)(base + (L + p0)) = o; }
.LBB0_334:
	v_mul_f32_e32 v35, v106, v82
	v_mul_f32_e32 v35, 0x3fb8aa3b, v35
	v_exp_f32_e32 v40, v35
	v_mul_f32_e64 v35, v106, -v79
	v_mul_f32_e32 v35, 0x3fb8aa3b, v35
	v_exp_f32_e32 v42, v35
	v_lshlrev_b64 v[36:37], v70, v[102:103]
	v_lshl_add_u64 v[36:37], v[36:37], 1, v[64:65]
	v_cvt_pk_bf16_f32 v35, v38, v39
	v_lshl_add_u64 v[36:37], v[44:45], 1, v[36:37]
	v_mul_f32_e32 v41, v42, v40
	global_store_dwordx4 v[36:37], v[32:35], off
	s_nop 1
	v_pk_mul_f32 v[32:33], v[40:41], v[28:29]
	v_mul_f32_e32 v28, v42, v41
	v_mul_f32_e32 v29, v42, v28
	v_pk_mul_f32 v[30:31], v[28:29], v[30:31]
	v_mul_f32_e32 v28, v42, v29
	v_mul_f32_e32 v29, v42, v28
	v_pk_mul_f32 v[34:35], v[28:29], v[24:25]
	v_mul_f32_e32 v24, v42, v29
	v_mul_f32_e32 v25, v42, v24
	v_pk_mul_f32 v[28:29], v[24:25], v[26:27]
	s_and_saveexec_b64 s[0:1], s[10:11]
	s_xor_b64 s[0:1], exec, s[0:1]
	v_cvt_pk_bf16_f32 v24, v32, v33
	v_cvt_pk_bf16_f32 v25, v30, v31
	v_cvt_pk_bf16_f32 v26, v34, v35
	s_or_saveexec_b64 s[0:1], s[0:1]
	v_mov_b64_e32 v[36:37], v[60:61]
	s_xor_b64 exec, exec, s[0:1]
	v_pk_mov_b32 v[24:25], v[28:29], v[28:29] op_sel:[1,0]
	v_pk_mov_b32 v[26:27], v[34:35], v[34:35] op_sel:[1,0]
	v_cvt_pk_bf16_f32 v24, v24, v25
	v_cvt_pk_bf16_f32 v25, v26, v27
	v_pk_mov_b32 v[26:27], v[30:31], v[30:31] op_sel:[1,0]
	v_mov_b64_e32 v[36:37], v[62:63]
	v_cvt_pk_bf16_f32 v26, v26, v27
	v_mov_b32_e32 v28, v33
	v_mov_b32_e32 v29, v32
	s_or_b64 exec, exec, s[0:1]
	v_mul_f32_e32 v27, v82, v98
	v_mul_f32_e32 v27, 0x3fb8aa3b, v27
	v_exp_f32_e32 v32, v27
	v_mul_f32_e64 v27, v98, -v79
	v_mul_f32_e32 v27, 0x3fb8aa3b, v27
	v_exp_f32_e32 v34, v27
	v_lshlrev_b64 v[30:31], v70, v[94:95]
	v_lshl_add_u64 v[30:31], v[30:31], 1, v[64:65]
	v_cvt_pk_bf16_f32 v27, v28, v29
	v_lshl_add_u64 v[28:29], v[36:37], 1, v[30:31]
	v_mul_f32_e32 v33, v34, v32
	global_store_dwordx4 v[28:29], v[24:27], off
	s_nop 1
	v_pk_mul_f32 v[24:25], v[32:33], v[20:21]
	v_mul_f32_e32 v20, v34, v33
	v_mul_f32_e32 v21, v34, v20
	v_pk_mul_f32 v[22:23], v[20:21], v[22:23]
	v_mul_f32_e32 v20, v34, v21
	v_mul_f32_e32 v21, v34, v20
	v_pk_mul_f32 v[26:27], v[20:21], v[16:17]
	v_mul_f32_e32 v16, v34, v21
	v_mul_f32_e32 v17, v34, v16
	v_pk_mul_f32 v[20:21], v[16:17], v[18:19]
	s_and_saveexec_b64 s[0:1], s[10:11]
	s_xor_b64 s[0:1], exec, s[0:1]
	v_cvt_pk_bf16_f32 v16, v24, v25
	v_cvt_pk_bf16_f32 v17, v22, v23
	v_cvt_pk_bf16_f32 v18, v26, v27
	s_or_saveexec_b64 s[0:1], s[0:1]
	v_mov_b64_e32 v[28:29], v[60:61]
	s_xor_b64 exec, exec, s[0:1]
	v_pk_mov_b32 v[16:17], v[20:21], v[20:21] op_sel:[1,0]
	v_pk_mov_b32 v[18:19], v[26:27], v[26:27] op_sel:[1,0]
	v_cvt_pk_bf16_f32 v16, v16, v17
	v_cvt_pk_bf16_f32 v17, v18, v19
	v_pk_mov_b32 v[18:19], v[22:23], v[22:23] op_sel:[1,0]
	v_mov_b64_e32 v[28:29], v[62:63]
	v_cvt_pk_bf16_f32 v18, v18, v19
	v_mov_b32_e32 v20, v25
	v_mov_b32_e32 v21, v24
	s_or_b64 exec, exec, s[0:1]
	v_mul_f32_e32 v19, v82, v90
	v_mul_f32_e32 v19, 0x3fb8aa3b, v19
	v_exp_f32_e32 v24, v19
	v_mul_f32_e64 v19, v90, -v79
	v_mul_f32_e32 v19, 0x3fb8aa3b, v19
	v_exp_f32_e32 v26, v19
	v_lshlrev_b64 v[22:23], v70, v[86:87]
	v_lshl_add_u64 v[22:23], v[22:23], 1, v[64:65]
	v_cvt_pk_bf16_f32 v19, v20, v21
	v_lshl_add_u64 v[20:21], v[28:29], 1, v[22:23]
	v_mul_f32_e32 v25, v26, v24
	global_store_dwordx4 v[20:21], v[16:19], off
	s_nop 1
	v_pk_mul_f32 v[16:17], v[24:25], v[12:13]
	v_mul_f32_e32 v12, v26, v25
	v_mul_f32_e32 v13, v26, v12
	v_pk_mul_f32 v[14:15], v[12:13], v[14:15]
	v_mul_f32_e32 v12, v26, v13
	v_mul_f32_e32 v13, v26, v12
	v_pk_mul_f32 v[18:19], v[12:13], v[8:9]
	v_mul_f32_e32 v8, v26, v13
	v_mul_f32_e32 v9, v26, v8
	v_pk_mul_f32 v[12:13], v[8:9], v[10:11]
	s_and_saveexec_b64 s[0:1], s[10:11]
	s_xor_b64 s[0:1], exec, s[0:1]
	v_cvt_pk_bf16_f32 v8, v16, v17
	v_cvt_pk_bf16_f32 v9, v14, v15
	v_cvt_pk_bf16_f32 v10, v18, v19
	s_or_saveexec_b64 s[0:1], s[0:1]
	v_mov_b64_e32 v[20:21], v[60:61]
	s_xor_b64 exec, exec, s[0:1]
	v_pk_mov_b32 v[8:9], v[12:13], v[12:13] op_sel:[1,0]
	v_pk_mov_b32 v[10:11], v[18:19], v[18:19] op_sel:[1,0]
	v_cvt_pk_bf16_f32 v8, v8, v9
	v_cvt_pk_bf16_f32 v9, v10, v11
	v_pk_mov_b32 v[10:11], v[14:15], v[14:15] op_sel:[1,0]
	v_mov_b64_e32 v[20:21], v[62:63]
	v_cvt_pk_bf16_f32 v10, v10, v11
	v_mov_b32_e32 v12, v17
	v_mov_b32_e32 v13, v16
	s_or_b64 exec, exec, s[0:1]
	v_mul_f32_e32 v11, v82, v78
	v_mul_f32_e32 v11, 0x3fb8aa3b, v11
	v_exp_f32_e32 v16, v11
	v_mul_f32_e64 v11, v78, -v79
	v_mul_f32_e32 v11, 0x3fb8aa3b, v11
	v_exp_f32_e32 v18, v11
	v_lshlrev_b64 v[14:15], v70, v[76:77]
	v_lshl_add_u64 v[14:15], v[14:15], 1, v[64:65]
	v_cvt_pk_bf16_f32 v11, v12, v13
	v_lshl_add_u64 v[12:13], v[20:21], 1, v[14:15]
	v_mul_f32_e32 v17, v18, v16
	global_store_dwordx4 v[12:13], v[8:11], off
	v_pk_mul_f32 v[4:5], v[16:17], v[4:5]
	s_nop 0
	v_mul_f32_e32 v10, v18, v17
	v_mul_f32_e32 v11, v18, v10
	v_pk_mul_f32 v[8:9], v[10:11], v[6:7]
	v_mul_f32_e32 v6, v18, v11
	v_mul_f32_e32 v7, v18, v6
	v_pk_mul_f32 v[10:11], v[6:7], v[0:1]
	v_mul_f32_e32 v0, v18, v7
	v_mul_f32_e32 v1, v18, v0
	v_pk_mul_f32 v[6:7], v[0:1], v[2:3]
	s_and_saveexec_b64 s[0:1], s[10:11]
	s_xor_b64 s[0:1], exec, s[0:1]
	v_cvt_pk_bf16_f32 v0, v4, v5
	v_cvt_pk_bf16_f32 v1, v8, v9
	v_cvt_pk_bf16_f32 v2, v10, v11
	s_andn2_saveexec_b64 s[0:1], s[0:1]
	s_cbranch_execz .LBB0_49
	v_pk_mov_b32 v[0:1], v[6:7], v[6:7] op_sel:[1,0]
	v_pk_mov_b32 v[2:3], v[10:11], v[10:11] op_sel:[1,0]
	v_cvt_pk_bf16_f32 v0, v0, v1
	v_cvt_pk_bf16_f32 v1, v2, v3
	v_pk_mov_b32 v[2:3], v[8:9], v[8:9] op_sel:[1,0]
	v_mov_b64_e32 v[60:61], v[62:63]
	v_cvt_pk_bf16_f32 v2, v2, v3
	v_mov_b32_e32 v6, v5
	v_mov_b32_e32 v7, v4
	s_branch .LBB0_49

; #define LAS __attribute__((address_space(3)))
; __device__ __forceinline__ unsigned pk2(float lo, float hi) { const f32x2_t f = {lo, hi}; const bf16x2_t b = __builtin_convertvector(f, bf16x2_t); return __builtin_bit_cast(unsigned, b); }
; __device__ __forceinline__ void attn_item(const Params& P, int slice, int item, LAS unsigned char* lds) {
;     ...
;   const float inv = 1.0f / den;
;   if (h == 0) ((float*)(ws + O_LSE))[((size_t)(gi * 4 + g)) * TS + b * L + r * M + mq] = mx + __logf(den);
;   __syncthreads();
;   stage_kv(qkv + 3072 + head * 128, b, L, dil, r, m0, M, img, nullptr, ht);
;   __syncthreads();
;   f32x16 oa[4];
; #pragma unroll
;   for (int dt = 0; dt < 4; ++dt)
; #pragma unroll
;     for (int i = 0; i < 16; ++i) oa[dt][i] = 0.f;
;   const int i16 = lane & 15, q4 = i16 >> 2, p4 = i16 & 3, blk = (lane >> 4) & 1;
; #pragma unroll
;   for (int kt = 0; kt < 5; ++kt)
; #pragma unroll
;     for (int s = 0; s < 2; ++s) {
;       u32x4 pb; pb.x = pk2(sc[kt][8 * s + 0] * inv, sc[kt][8 * s + 1] * inv); pb.y = pk2(sc[kt][8 * s + 2] * inv, sc[kt][8 * s + 3] * inv);
;       pb.z = pk2(sc[kt][8 * s + 4] * inv, sc[kt][8 * s + 5] * inv); pb.w = pk2(sc[kt][8 * s + 6] * inv, sc[kt][8 * s + 7] * inv);
;       const bf16x8 bfr = __builtin_bit_cast(bf16x8, pb);
;       const LAS unsigned char* vp = img + (32 * wq + 32 * kt + 16 * s + 4 * h + q4) * KROW + 2 * (16 * blk + 4 * p4);
; #pragma unroll
;       for (int dt = 0; dt < 4; ++dt) {
;         const s16x4 lo = __builtin_amdgcn_ds_read_tr16_b64_v4i16((LAS s16x4*)(vp + 64 * dt));
;         const s16x4 hi4 = __builtin_amdgcn_ds_read_tr16_b64_v4i16((LAS s16x4*)(vp + 64 * dt + 8 * KROW));
;         const bf16x8 a = __builtin_shufflevector(lo, hi4, 0, 1, 2, 3, 4, 5, 6, 7);
;         oa[dt] = __builtin_amdgcn_mfma_f32_32x32x16_bf16(a, bfr, oa[dt], 0, 0, 0);
;       }
.LBB0_380:
	s_or_b64 exec, exec, s[0:1]
	v_div_scale_f32 v0, s[0:1], v65, v65, 1.0
	v_rcp_f32_e32 v2, v0
	v_div_scale_f32 v3, vcc, 1.0, v65, 1.0
	s_ashr_i32 s83, s82, 31
	v_fma_f32 v5, -v0, v2, 1.0
	v_fmac_f32_e32 v2, v5, v2
	v_mul_f32_e32 v5, v3, v2
	v_fma_f32 v8, -v0, v5, v3
	v_fmac_f32_e32 v5, v8, v2
	v_fma_f32 v0, -v0, v5, v3
	v_div_fmas_f32 v0, v0, v2, v5
	v_div_fixup_f32 v80, v0, v65, 1.0
	v_mov_b32_e32 v5, v1
	v_bfe_u32 v0, v107, 2, 2
	v_and_b32_e32 v1, 16, v107
	v_lshlrev_b32_e32 v2, 2, v107
	v_or3_b32 v0, v0, v168, s72
	v_and_or_b32 v1, v2, 12, v1
	v_lshlrev_b32_e32 v1, 1, v1
	v_mul_u32_u24_e32 v0, 0x110, v0
	v_add3_u32 v152, s64, v1, v0
	ds_write_b128 v154, v[4:7] offset:65280
	s_waitcnt lgkmcnt(0)
	s_barrier
	ds_read_b64_tr_b16 v[0:1], v152
	ds_read_b64_tr_b16 v[2:3], v152 offset:2176
	v_pk_mul_f32 v[4:5], v[76:77], v[80:81] op_sel_hi:[1,0]
	v_pk_mul_f32 v[64:65], v[66:67], v[80:81] op_sel_hi:[1,0]
	v_cvt_pk_bf16_f32 v16, v4, v5
	v_pk_mul_f32 v[4:5], v[78:79], v[80:81] op_sel_hi:[1,0]
	v_pk_mul_f32 v[66:67], v[68:69], v[80:81] op_sel_hi:[1,0]
	v_cvt_pk_bf16_f32 v17, v4, v5
	v_pk_mul_f32 v[4:5], v[84:85], v[80:81] op_sel_hi:[1,0]
	v_cvt_pk_bf16_f32 v64, v64, v65
	v_cvt_pk_bf16_f32 v18, v4, v5
	v_pk_mul_f32 v[4:5], v[90:91], v[80:81] op_sel_hi:[1,0]
	v_cvt_pk_bf16_f32 v65, v66, v67
	v_cvt_pk_bf16_f32 v19, v4, v5
	v_pk_mul_f32 v[66:67], v[70:71], v[80:81] op_sel_hi:[1,0]
	v_pk_mul_f32 v[68:69], v[74:75], v[80:81] op_sel_hi:[1,0]
	s_waitcnt lgkmcnt(0)
	v_mfma_f32_32x32x16_bf16 v[48:63], v[0:3], v[16:19], 0
	ds_read_b64_tr_b16 v[0:1], v152 offset:64
	ds_read_b64_tr_b16 v[2:3], v152 offset:2240
	v_cvt_pk_bf16_f32 v66, v66, v67
	v_cvt_pk_bf16_f32 v67, v68, v69
	s_lshl_b64 s[0:1], s[82:83], 24
	v_ashrrev_i32_e32 v107, 31, v106
	s_add_u32 s0, s4, s0
	s_addc_u32 s1, s5, s1
	s_waitcnt lgkmcnt(0)
	v_mfma_f32_32x32x16_bf16 v[32:47], v[0:3], v[16:19], 0
	ds_read_b64_tr_b16 v[0:1], v152 offset:128
	ds_read_b64_tr_b16 v[2:3], v152 offset:2304
	ds_read_b64_tr_b16 v[20:21], v152 offset:192
	ds_read_b64_tr_b16 v[22:23], v152 offset:2368
	ds_read_b64_tr_b16 v[76:77], v152 offset:4352
	ds_read_b64_tr_b16 v[78:79], v152 offset:6528
	ds_read_b64_tr_b16 v[68:69], v152 offset:4416
	ds_read_b64_tr_b16 v[70:71], v152 offset:6592
	s_lshl_b32 s64, s3, 8
	s_waitcnt lgkmcnt(6)
	v_mfma_f32_32x32x16_bf16 v[0:15], v[0:3], v[16:19], 0
	s_waitcnt lgkmcnt(0)
	v_mfma_f32_32x32x16_bf16 v[32:47], v[68:71], v[64:67], v[32:47]
	ds_read_b64_tr_b16 v[68:69], v152 offset:4480
	ds_read_b64_tr_b16 v[70:71], v152 offset:6656
	v_mfma_f32_32x32x16_bf16 v[16:31], v[20:23], v[16:19], 0
	s_waitcnt lgkmcnt(0)
	v_mfma_f32_32x32x16_bf16 v[0:15], v[68:71], v[64:67], v[0:15]
	ds_read_b64_tr_b16 v[68:69], v152 offset:4544
	ds_read_b64_tr_b16 v[70:71], v152 offset:6720
	v_mfma_f32_32x32x16_bf16 v[48:63], v[76:79], v[64:67], v[48:63]
	s_waitcnt lgkmcnt(0)
	v_mfma_f32_32x32x16_bf16 v[16:31], v[68:71], v[64:67], v[16:31]
	ds_read_b64_tr_b16 v[64:65], v152 offset:8704
	ds_read_b64_tr_b16 v[66:67], v152 offset:10880
	v_mul_f32_e64 v68, v72, v80
	v_mul_f32_e64 v69, v73, v80
	v_mul_f32_e64 v70, v82, v80
	v_mul_f32_e64 v71, v83, v80
	v_cvt_pk_bf16_f32 v68, v68, v69
	v_cvt_pk_bf16_f32 v69, v70, v71
	v_pk_mul_f32 v[70:71], v[86:87], v[80:81] op_sel_hi:[1,0]
	v_pk_mul_f32 v[72:73], v[92:93], v[80:81] op_sel_hi:[1,0]
	v_cvt_pk_bf16_f32 v70, v70, v71
	v_cvt_pk_bf16_f32 v71, v72, v73
	v_pk_mul_f32 v[72:73], v[102:103], v[80:81] op_sel_hi:[1,0]
	s_waitcnt lgkmcnt(0)
	v_mfma_f32_32x32x16_bf16 v[48:63], v[64:67], v[68:71], v[48:63]
	ds_read_b64_tr_b16 v[64:65], v152 offset:8768
	ds_read_b64_tr_b16 v[66:67], v152 offset:10944
	s_waitcnt lgkmcnt(0)
	v_mfma_f32_32x32x16_bf16 v[32:47], v[64:67], v[68:71], v[32:47]
	ds_read_b64_tr_b16 v[64:65], v152 offset:8832
	ds_read_b64_tr_b16 v[66:67], v152 offset:11008
	s_waitcnt lgkmcnt(0)
	v_mfma_f32_32x32x16_bf16 v[0:15], v[64:67], v[68:71], v[0:15]
	ds_read_b64_tr_b16 v[64:65], v152 offset:8896
	ds_read_b64_tr_b16 v[66:67], v152 offset:11072
	s_waitcnt lgkmcnt(0)
	v_mfma_f32_32x32x16_bf16 v[16:31], v[64:67], v[68:71], v[16:31]
	ds_read_b64_tr_b16 v[64:65], v152 offset:13056
	ds_read_b64_tr_b16 v[66:67], v152 offset:15232
	v_mul_f32_e64 v68, v88, v80
	v_mul_f32_e64 v69, v89, v80
	v_mul_f32_e64 v70, v94, v80
	v_mul_f32_e64 v71, v95, v80
	v_cvt_pk_bf16_f32 v68, v68, v69
	v_cvt_pk_bf16_f32 v69, v70, v71
	v_pk_mul_f32 v[70:71], v[96:97], v[80:81] op_sel_hi:[1,0]
	s_nop 0
	v_cvt_pk_bf16_f32 v70, v70, v71
	v_cvt_pk_bf16_f32 v71, v72, v73
	v_pk_mul_f32 v[72:73], v[112:113], v[80:81] op_sel_hi:[1,0]
	s_waitcnt lgkmcnt(0)
	v_mfma_f32_32x32x16_bf16 v[48:63], v[64:67], v[68:71], v[48:63]
	ds_read_b64_tr_b16 v[64:65], v152 offset:13120
	ds_read_b64_tr_b16 v[66:67], v152 offset:15296
	s_waitcnt lgkmcnt(0)
	v_mfma_f32_32x32x16_bf16 v[32:47], v[64:67], v[68:71], v[32:47]
	ds_read_b64_tr_b16 v[64:65], v152 offset:13184
	ds_read_b64_tr_b16 v[66:67], v152 offset:15360
	s_waitcnt lgkmcnt(0)
	v_mfma_f32_32x32x16_bf16 v[0:15], v[64:67], v[68:71], v[0:15]
	ds_read_b64_tr_b16 v[64:65], v152 offset:13248
	ds_read_b64_tr_b16 v[66:67], v152 offset:15424
	s_waitcnt lgkmcnt(0)
	v_mfma_f32_32x32x16_bf16 v[16:31], v[64:67], v[68:71], v[16:31]
	ds_read_b64_tr_b16 v[64:65], v152 offset:17408
	ds_read_b64_tr_b16 v[66:67], v152 offset:19584
	v_mul_f32_e64 v68, v100, v80
	v_mul_f32_e64 v69, v101, v80
	v_mul_f32_e64 v70, v104, v80
	v_mul_f32_e64 v71, v105, v80
	v_cvt_pk_bf16_f32 v68, v68, v69
	v_cvt_pk_bf16_f32 v69, v70, v71
	v_pk_mul_f32 v[70:71], v[108:109], v[80:81] op_sel_hi:[1,0]
	s_nop 0
	v_cvt_pk_bf16_f32 v70, v70, v71
	v_cvt_pk_bf16_f32 v71, v72, v73
	s_waitcnt lgkmcnt(0)
; #define LAS __attribute__((address_space(3)))
; __device__ __forceinline__ unsigned pk2(float lo, float hi) { const f32x2_t f = {lo, hi}; const bf16x2_t b = __builtin_convertvector(f, bf16x2_t); return __builtin_bit_cast(unsigned, b); }
; __device__ __forceinline__ void attn_item(const Params& P, int slice, int item, LAS unsigned char* lds) {
;     ...
; #pragma unroll
;   for (int kt = 0; kt < 5; ++kt)
; #pragma unroll
;     for (int s = 0; s < 2; ++s) {
;       u32x4 pb; pb.x = pk2(sc[kt][8 * s + 0] * inv, sc[kt][8 * s + 1] * inv); pb.y = pk2(sc[kt][8 * s + 2] * inv, sc[kt][8 * s + 3] * inv);
;       pb.z = pk2(sc[kt][8 * s + 4] * inv, sc[kt][8 * s + 5] * inv); pb.w = pk2(sc[kt][8 * s + 6] * inv, sc[kt][8 * s + 7] * inv);
;       const bf16x8 bfr = __builtin_bit_cast(bf16x8, pb);
;       const LAS unsigned char* vp = img + (32 * wq + 32 * kt + 16 * s + 4 * h + q4) * KROW + 2 * (16 * blk + 4 * p4);
; #pragma unroll
;       for (int dt = 0; dt < 4; ++dt) {
;         const s16x4 lo = __builtin_amdgcn_ds_read_tr16_b64_v4i16((LAS s16x4*)(vp + 64 * dt));
;         const s16x4 hi4 = __builtin_amdgcn_ds_read_tr16_b64_v4i16((LAS s16x4*)(vp + 64 * dt + 8 * KROW));
;         const bf16x8 a = __builtin_shufflevector(lo, hi4, 0, 1, 2, 3, 4, 5, 6, 7);
;         oa[dt] = __builtin_amdgcn_mfma_f32_32x32x16_bf16(a, bfr, oa[dt], 0, 0, 0);
;       }
	s_nop 0
	v_mfma_f32_32x32x16_bf16 v[48:63], v[64:67], v[68:71], v[48:63]
	ds_read_b64_tr_b16 v[64:65], v152 offset:17472
	ds_read_b64_tr_b16 v[66:67], v152 offset:19648
	s_waitcnt lgkmcnt(0)
	v_mfma_f32_32x32x16_bf16 v[32:47], v[64:67], v[68:71], v[32:47]
	ds_read_b64_tr_b16 v[64:65], v152 offset:17536
	ds_read_b64_tr_b16 v[66:67], v152 offset:19712
	ds_read_b64_tr_b16 v[72:73], v152 offset:17600
	ds_read_b64_tr_b16 v[74:75], v152 offset:19776
	ds_read_b64_tr_b16 v[76:77], v152 offset:21760
	ds_read_b64_tr_b16 v[78:79], v152 offset:23936
	s_waitcnt lgkmcnt(4)
	v_mfma_f32_32x32x16_bf16 v[0:15], v[64:67], v[68:71], v[0:15]
	v_mul_f32_e64 v64, v110, v80
	v_mul_f32_e64 v65, v111, v80
	v_mul_f32_e64 v66, v114, v80
	v_mul_f32_e64 v67, v115, v80
	v_cvt_pk_bf16_f32 v64, v64, v65
	v_cvt_pk_bf16_f32 v65, v66, v67
	v_pk_mul_f32 v[66:67], v[116:117], v[80:81] op_sel_hi:[1,0]
	s_nop 0
	v_cvt_pk_bf16_f32 v66, v66, v67
	s_waitcnt lgkmcnt(2)
	v_mfma_f32_32x32x16_bf16 v[16:31], v[72:75], v[68:71], v[16:31]
	v_mul_f32_e64 v68, v120, v80
	v_mul_f32_e64 v69, v121, v80
	v_cvt_pk_bf16_f32 v67, v68, v69
	ds_read_b64_tr_b16 v[68:69], v152 offset:21824
	ds_read_b64_tr_b16 v[70:71], v152 offset:24000
	ds_read_b64_tr_b16 v[72:73], v152 offset:21888
	s_waitcnt lgkmcnt(1)
	v_mfma_f32_32x32x16_bf16 v[32:47], v[68:71], v[64:67], v[32:47]
	ds_read_b64_tr_b16 v[74:75], v152 offset:24064
	ds_read_b64_tr_b16 v[68:69], v152 offset:21952
	ds_read_b64_tr_b16 v[70:71], v152 offset:24128
	v_mfma_f32_32x32x16_bf16 v[48:63], v[76:79], v[64:67], v[48:63]
	ds_read_b64_tr_b16 v[76:77], v152 offset:26112
	ds_read_b64_tr_b16 v[78:79], v152 offset:28288
	s_waitcnt lgkmcnt(4)
	v_mfma_f32_32x32x16_bf16 v[0:15], v[72:75], v[64:67], v[0:15]
	v_mul_f32_e64 v72, v118, v80
	v_mul_f32_e64 v73, v119, v80
	v_cvt_pk_bf16_f32 v72, v72, v73
	s_waitcnt lgkmcnt(2)
	v_mfma_f32_32x32x16_bf16 v[16:31], v[68:71], v[64:67], v[16:31]
	v_mul_f32_e64 v64, v122, v80
	v_mul_f32_e64 v65, v123, v80
	ds_read_b64_tr_b16 v[66:67], v152 offset:28352
	v_cvt_pk_bf16_f32 v73, v64, v65
	v_mul_f32_e64 v64, v124, v80
	v_mul_f32_e64 v65, v125, v80
	v_cvt_pk_bf16_f32 v74, v64, v65
	v_pk_mul_f32 v[64:65], v[128:129], v[80:81] op_sel_hi:[1,0]
	s_nop 0
	v_cvt_pk_bf16_f32 v75, v64, v65
	ds_read_b64_tr_b16 v[64:65], v152 offset:26176
	s_waitcnt lgkmcnt(2)
	v_mfma_f32_32x32x16_bf16 v[48:63], v[76:79], v[72:75], v[48:63]
	ds_read_b64_tr_b16 v[68:69], v152 offset:26240
	ds_read_b64_tr_b16 v[70:71], v152 offset:28416
	ds_read_b64_tr_b16 v[76:77], v152 offset:26304
	ds_read_b64_tr_b16 v[78:79], v152 offset:28480
	s_waitcnt lgkmcnt(2)
	v_mfma_f32_32x32x16_bf16 v[0:15], v[68:71], v[72:75], v[0:15]
	v_mul_f32_e64 v70, v138, v80
	v_mul_f32_e64 v71, v139, v80
	v_mfma_f32_32x32x16_bf16 v[32:47], v[64:67], v[72:75], v[32:47]
	v_mul_f32_e64 v64, v126, v80
	v_mul_f32_e64 v65, v127, v80
	ds_read_b64_tr_b16 v[66:67], v152 offset:30464
	ds_read_b64_tr_b16 v[68:69], v152 offset:32640
	ds_read_b64_tr_b16 v[82:83], v152 offset:30528
	ds_read_b64_tr_b16 v[84:85], v152 offset:32704
	ds_read_b64_tr_b16 v[94:95], v152 offset:30592
	ds_read_b64_tr_b16 v[96:97], v152 offset:32768
	v_cvt_pk_bf16_f32 v86, v64, v65
	v_pk_mul_f32 v[64:65], v[130:131], v[80:81] op_sel_hi:[1,0]
	s_nop 0
	v_cvt_pk_bf16_f32 v87, v64, v65
	v_pk_mul_f32 v[64:65], v[132:133], v[80:81] op_sel_hi:[1,0]
	s_waitcnt lgkmcnt(6)
	v_mfma_f32_32x32x16_bf16 v[16:31], v[76:79], v[72:75], v[16:31]
	v_cvt_pk_bf16_f32 v88, v64, v65
	v_mul_f32_e64 v64, v136, v80
	v_mul_f32_e64 v65, v137, v80
	ds_read_b64_tr_b16 v[76:77], v152 offset:30656
	ds_read_b64_tr_b16 v[78:79], v152 offset:32832
	v_cvt_pk_bf16_f32 v89, v64, v65
	v_pk_mul_f32 v[64:65], v[134:135], v[80:81] op_sel_hi:[1,0]
	ds_read_b64_tr_b16 v[102:103], v152 offset:34816
	ds_read_b64_tr_b16 v[104:105], v152 offset:36992
	ds_read_b64_tr_b16 v[90:91], v152 offset:34880
	ds_read_b64_tr_b16 v[92:93], v152 offset:37056
	v_cvt_pk_bf16_f32 v64, v64, v65
	s_waitcnt lgkmcnt(6)
; #define LAS __attribute__((address_space(3)))
; __device__ __forceinline__ unsigned pk2(float lo, float hi) { const f32x2_t f = {lo, hi}; const bf16x2_t b = __builtin_convertvector(f, bf16x2_t); return __builtin_bit_cast(unsigned, b); }
; __device__ __forceinline__ void attn_item(const Params& P, int slice, int item, LAS unsigned char* lds) {
;     ...
; #pragma unroll
;   for (int kt = 0; kt < 5; ++kt)
; #pragma unroll
;     for (int s = 0; s < 2; ++s) {
;       u32x4 pb; pb.x = pk2(sc[kt][8 * s + 0] * inv, sc[kt][8 * s + 1] * inv); pb.y = pk2(sc[kt][8 * s + 2] * inv, sc[kt][8 * s + 3] * inv);
;       pb.z = pk2(sc[kt][8 * s + 4] * inv, sc[kt][8 * s + 5] * inv); pb.w = pk2(sc[kt][8 * s + 6] * inv, sc[kt][8 * s + 7] * inv);
;       const bf16x8 bfr = __builtin_bit_cast(bf16x8, pb);
;       const LAS unsigned char* vp = img + (32 * wq + 32 * kt + 16 * s + 4 * h + q4) * KROW + 2 * (16 * blk + 4 * p4);
; #pragma unroll
;       for (int dt = 0; dt < 4; ++dt) {
;         const s16x4 lo = __builtin_amdgcn_ds_read_tr16_b64_v4i16((LAS s16x4*)(vp + 64 * dt));
;         const s16x4 hi4 = __builtin_amdgcn_ds_read_tr16_b64_v4i16((LAS s16x4*)(vp + 64 * dt + 8 * KROW));
;         const bf16x8 a = __builtin_shufflevector(lo, hi4, 0, 1, 2, 3, 4, 5, 6, 7);
;         oa[dt] = __builtin_amdgcn_mfma_f32_32x32x16_bf16(a, bfr, oa[dt], 0, 0, 0);
;       }
;     }
;   u16* o3 = (u16*)(ws + O_O3) + ((size_t)gi * TS + tokq) * 512 + g * 128;
; #pragma unroll
;   for (int dt = 0; dt < 4; ++dt)
; #pragma unroll
;     for (int g4 = 0; g4 < 4; ++g4) {
;       u32x2 o; o.x = pk2(oa[dt][4 * g4], oa[dt][4 * g4 + 1]); o.y = pk2(oa[dt][4 * g4 + 2], oa[dt][4 * g4 + 3]);
;       *(u32x2*)(o3 + 32 * dt + 8 * g4 + 4 * h) = o;
;     }
	v_mfma_f32_32x32x16_bf16 v[0:15], v[94:97], v[86:89], v[0:15]
	v_cvt_pk_bf16_f32 v65, v70, v71
	v_mul_f32_e64 v70, v140, v80
	v_mul_f32_e64 v71, v141, v80
	v_mul_f32_e64 v94, v150, v80
	v_mul_f32_e64 v95, v151, v80
	v_mfma_f32_32x32x16_bf16 v[48:63], v[66:69], v[86:89], v[48:63]
	v_mul_f32_e64 v68, v144, v80
	v_mul_f32_e64 v69, v145, v80
	v_cvt_pk_bf16_f32 v66, v70, v71
	v_cvt_pk_bf16_f32 v67, v68, v69
	v_mul_f32_e64 v68, v142, v80
	v_mul_f32_e64 v69, v143, v80
	v_pk_mul_f32 v[70:71], v[146:147], v[80:81] op_sel_hi:[1,0]
	v_cvt_pk_bf16_f32 v68, v68, v69
	v_cvt_pk_bf16_f32 v69, v70, v71
	v_mfma_f32_32x32x16_bf16 v[32:47], v[82:85], v[86:89], v[32:47]
	ds_read_b64_tr_b16 v[82:83], v152 offset:34944
	ds_read_b64_tr_b16 v[84:85], v152 offset:37120
	ds_read_b64_tr_b16 v[72:73], v152 offset:35008
	ds_read_b64_tr_b16 v[74:75], v152 offset:37184
	v_mul_f32_e64 v70, v148, v80
	v_mul_f32_e64 v71, v149, v80
	ds_read_b64_tr_b16 v[98:99], v152 offset:39168
	ds_read_b64_tr_b16 v[100:101], v152 offset:41344
	v_cvt_pk_bf16_f32 v70, v70, v71
	v_cvt_pk_bf16_f32 v71, v94, v95
	v_lshlrev_b32_e32 v80, 1, v168
	s_waitcnt lgkmcnt(10)
	v_mfma_f32_32x32x16_bf16 v[16:31], v[76:79], v[86:89], v[16:31]
	ds_read_b64_tr_b16 v[94:95], v152 offset:39232
	ds_read_b64_tr_b16 v[96:97], v152 offset:41408
	ds_read_b64_tr_b16 v[86:87], v152 offset:39296
	ds_read_b64_tr_b16 v[88:89], v152 offset:41472
	ds_read_b64_tr_b16 v[76:77], v152 offset:39360
	ds_read_b64_tr_b16 v[78:79], v152 offset:41536
	s_waitcnt lgkmcnt(10)
	v_mfma_f32_32x32x16_bf16 v[0:15], v[82:85], v[64:67], v[0:15]
	v_mfma_f32_32x32x16_bf16 v[48:63], v[102:105], v[64:67], v[48:63]
	v_lshlrev_b64 v[102:103], 10, v[106:107]
	v_lshl_add_u64 v[102:103], s[0:1], 0, v[102:103]
	v_lshl_add_u64 v[102:103], v[102:103], 0, s[64:65]
	s_mov_b64 s[0:1], 0x2d852000
	v_mfma_f32_32x32x16_bf16 v[32:47], v[90:93], v[64:67], v[32:47]
	s_waitcnt lgkmcnt(8)
	v_mfma_f32_32x32x16_bf16 v[16:31], v[72:75], v[64:67], v[16:31]
	s_waitcnt lgkmcnt(2)
	v_mfma_f32_32x32x16_bf16 v[0:15], v[86:89], v[68:71], v[0:15]
	v_mfma_f32_32x32x16_bf16 v[48:63], v[98:101], v[68:71], v[48:63]
	v_lshl_add_u64 v[98:99], v[102:103], 0, v[80:81]
	v_lshl_add_u64 v[100:101], v[98:99], 0, s[0:1]
	s_nop 8
	v_cvt_pk_bf16_f32 v0, v0, v1
	v_cvt_pk_bf16_f32 v1, v2, v3
	global_store_dwordx2 v[100:101], v[0:1], off offset:128
	v_cvt_pk_bf16_f32 v0, v4, v5
	v_cvt_pk_bf16_f32 v1, v6, v7
	v_mfma_f32_32x32x16_bf16 v[32:47], v[94:97], v[68:71], v[32:47]
	s_mov_b32 s0, 0x2d852000
	global_store_dwordx2 v[100:101], v[0:1], off offset:144
	v_cvt_pk_bf16_f32 v0, v8, v9
	v_cvt_pk_bf16_f32 v1, v10, v11
	v_cvt_pk_bf16_f32 v48, v48, v49
	v_cvt_pk_bf16_f32 v49, v50, v51
	v_add_co_u32_e32 v50, vcc, s0, v98
	s_waitcnt lgkmcnt(0)
	v_mfma_f32_32x32x16_bf16 v[16:31], v[76:79], v[68:71], v[16:31]
	global_store_dwordx2 v[100:101], v[0:1], off offset:160
	v_cvt_pk_bf16_f32 v0, v12, v13
	v_cvt_pk_bf16_f32 v1, v14, v15
	v_addc_co_u32_e32 v51, vcc, 0, v99, vcc
	v_cvt_pk_bf16_f32 v32, v32, v33
	v_cvt_pk_bf16_f32 v33, v34, v35
	global_store_dwordx2 v[100:101], v[0:1], off offset:176
	s_nop 4
	v_cvt_pk_bf16_f32 v0, v16, v17
	v_cvt_pk_bf16_f32 v1, v18, v19
	global_store_dwordx2 v[50:51], v[48:49], off
	v_cvt_pk_bf16_f32 v48, v52, v53
	v_cvt_pk_bf16_f32 v49, v54, v55
	global_store_dwordx2 v[100:101], v[32:33], off offset:64
	v_cvt_pk_bf16_f32 v32, v36, v37
	v_cvt_pk_bf16_f32 v33, v38, v39
	global_store_dwordx2 v[100:101], v[0:1], off offset:192
	v_cvt_pk_bf16_f32 v0, v20, v21
	v_cvt_pk_bf16_f32 v1, v22, v23
	global_store_dwordx2 v[100:101], v[48:49], off offset:16
	v_cvt_pk_bf16_f32 v48, v56, v57
	v_cvt_pk_bf16_f32 v49, v58, v59
	global_store_dwordx2 v[100:101], v[32:33], off offset:80
	v_cvt_pk_bf16_f32 v32, v40, v41
	v_cvt_pk_bf16_f32 v33, v42, v43
	global_store_dwordx2 v[100:101], v[0:1], off offset:208
	v_cvt_pk_bf16_f32 v0, v24, v25
	v_cvt_pk_bf16_f32 v1, v26, v27
	global_store_dwordx2 v[100:101], v[48:49], off offset:32
	v_cvt_pk_bf16_f32 v48, v60, v61
	v_cvt_pk_bf16_f32 v49, v62, v63
	global_store_dwordx2 v[100:101], v[32:33], off offset:96
	v_cvt_pk_bf16_f32 v32, v44, v45
	v_cvt_pk_bf16_f32 v33, v46, v47
	global_store_dwordx2 v[100:101], v[0:1], off offset:224
	v_cvt_pk_bf16_f32 v0, v28, v29
	v_cvt_pk_bf16_f32 v1, v30, v31
	global_store_dwordx2 v[100:101], v[48:49], off offset:48
	global_store_dwordx2 v[100:101], v[32:33], off offset:112
	global_store_dwordx2 v[100:101], v[0:1], off offset:240
	s_waitcnt lgkmcnt(0)
	s_barrier

; #define LAS __attribute__((address_space(3)))
; __device__ __forceinline__ float lo16(unsigned v) { return __uint_as_float(v << 16); }
; __device__ __forceinline__ float hi16(unsigned v) { return __uint_as_float(v & 0xffff0000u); }
; __device__ __forceinline__ void attn_item(const Params& P, int slice, int item, LAS unsigned char* lds) {
;     ...
;   LAS float* bl = (LAS float*)(lds + 2 * KHALF + half * 1024);
;   stage_kv(qkv + 1536 + head * 128, b, L, dil, r, m0, M, img, P.in[I_GK], ht);
;   if (ht < 129) bl[ht] = ((const float*)(ws + O_BIAS))[head * 129 + ht];
;   const int mq = m0 + 32 * wq + qn, tokq = b * L + mq * dil + r;
;   bf16x8 Qf[8];
;   {
;     u32x4 qv[8]; float s = 0.f;
; #pragma unroll
;     for (int ks = 0; ks < 8; ++ks) { qv[ks] = *(const u32x4*)(qkv + (size_t)tokq * 4608 + head * 128 + 16 * ks + 8 * h);
;       const float f0 = lo16(qv[ks].x), f1 = hi16(qv[ks].x), f2 = lo16(qv[ks].y), f3 = hi16(qv[ks].y), f4 = lo16(qv[ks].z), f5 = hi16(qv[ks].z), f6 = lo16(qv[ks].w), f7 = hi16(qv[ks].w);
;       s += f0 * f0 + f1 * f1 + f2 * f2 + f3 * f3 + f4 * f4 + f5 * f5 + f6 * f6 + f7 * f7; }
.LBB0_656:
	s_lshl_b32 s76, s76, 10
	v_and_b32_e32 v0, 0xff, v107
	s_add_i32 s76, s76, 0
	s_movk_i32 s77, 0x81
	s_add_i32 s76, s76, 0x22000
	v_cmp_gt_u32_e32 vcc, s77, v0
	ds_write_b128 v154, v[4:7] offset:65280
	s_and_saveexec_b64 s[92:93], vcc
	s_cbranch_execz .LBB0_658
	s_mul_i32 s77, s84, 0x81
	v_add_u32_e32 v2, s77, v0
	v_ashrrev_i32_e32 v3, 31, v2
	v_lshl_add_u64 v[2:3], v[2:3], 2, s[4:5]
	v_add_co_u32_e32 v2, vcc, 0x16850000, v2
	v_lshl_add_u32 v0, v0, 2, s76
	s_nop 0
	v_addc_co_u32_e32 v3, vcc, 0, v3, vcc
	global_load_dword v1, v[2:3], off
	s_waitcnt vmcnt(0) lgkmcnt(0)
	ds_write_b32 v0, v1
.LBB0_658:
	s_or_b64 exec, exec, s[92:93]
	s_lshr_b32 s72, s72, 1
	v_and_b32_e32 v102, 31, v107
	s_and_b32 s72, s72, 0x60
	v_or_b32_e32 v68, s72, v102
	v_or_b32_e32 v169, s74, v68
	v_lshlrev_b32_e32 v0, s73, v169
	v_add_u32_e32 v106, s75, v0
	v_mov_b64_e32 v[0:1], s[4:5]
	v_bfe_u32 v103, v107, 5, 1
	v_mad_i64_i32 v[0:1], s[74:75], v106, s31, v[0:1]
	v_lshl_add_u64 v[0:1], s[0:1], 1, v[0:1]
	v_lshlrev_b32_e32 v36, 4, v103
	v_mov_b32_e32 v37, v81
	v_lshl_add_u64 v[38:39], v[0:1], 0, v[36:37]
	s_mov_b64 s[0:1], 0x16852000
	v_lshl_add_u64 v[40:41], v[38:39], 0, s[0:1]
	global_load_dwordx4 v[46:49], v[40:41], off offset:192
	global_load_dwordx4 v[56:59], v[40:41], off offset:160
	global_load_dwordx4 v[70:73], v[40:41], off offset:128
	global_load_dwordx4 v[74:77], v[40:41], off offset:224
	v_and_b32_e32 v0, 64, v225
	v_xor_b32_e32 v37, 32, v225
	v_add_u32_e32 v42, 64, v0
	v_and_b32_e32 v69, 32, v107
	v_cmp_lt_i32_e32 vcc, v37, v42
	s_mov_b32 s0, 0x16852000
	global_load_dwordx4 v[28:31], v69, s[46:47] offset:16
	global_load_dwordx4 v[32:35], v69, s[46:47]
	global_load_dwordx4 v[20:23], v69, s[46:47] offset:80
	global_load_dwordx4 v[24:27], v69, s[46:47] offset:64
	global_load_dwordx4 v[12:15], v69, s[46:47] offset:144
	global_load_dwordx4 v[16:19], v69, s[46:47] offset:128
	global_load_dwordx4 v[4:7], v69, s[46:47] offset:208
	global_load_dwordx4 v[8:11], v69, s[46:47] offset:192
	global_load_dwordx4 v[0:3], v69, s[46:47] offset:256
	v_cndmask_b32_e32 v37, v225, v37, vcc
	v_add_co_u32_e32 v38, vcc, s0, v38
	global_load_dwordx4 v[82:85], v[40:41], off offset:96
	s_nop 0
	v_addc_co_u32_e32 v39, vcc, 0, v39, vcc
	global_load_dwordx4 v[86:89], v[40:41], off offset:32
	global_load_dwordx4 v[90:93], v[40:41], off offset:64
	global_load_dwordx4 v[94:97], v[38:39], off
	v_lshlrev_b32_e32 v170, 2, v37
	s_mov_b32 s0, 0x800000
	v_lshlrev_b32_e32 v168, 2, v103
	s_add_i32 s71, s71, s72
	s_cmp_gt_i32 s71, -1
	s_waitcnt vmcnt(0) lgkmcnt(0)
	v_and_b32_e32 v45, 0xffff0000, v46
	v_lshlrev_b32_e32 v50, 16, v59
	v_and_b32_e32 v51, 0xffff0000, v59
	v_lshlrev_b32_e32 v54, 16, v58
	v_and_b32_e32 v55, 0xffff0000, v58
	v_lshlrev_b32_e32 v58, 16, v57
	v_and_b32_e32 v59, 0xffff0000, v57
	v_and_b32_e32 v57, 0xffff0000, v74
	v_lshlrev_b32_e32 v44, 16, v46
	v_lshlrev_b32_e32 v60, 16, v56
	v_and_b32_e32 v61, 0xffff0000, v56
	v_lshlrev_b32_e32 v56, 16, v74
	v_mov_b32_e32 v110, v45
	v_mov_b32_e32 v111, v57
	v_lshlrev_b32_e32 v42, 16, v47
	v_and_b32_e32 v67, 0xffff0000, v70
	v_lshlrev_b32_e32 v52, 16, v75
	v_mov_b32_e32 v108, v44
	v_mov_b32_e32 v109, v56
	v_pk_mul_f32 v[110:111], v[110:111], v[110:111]
	v_and_b32_e32 v43, 0xffff0000, v47
	v_lshlrev_b32_e32 v66, 16, v70
	v_and_b32_e32 v53, 0xffff0000, v75
	v_mov_b32_e32 v78, v42
	v_mov_b32_e32 v79, v52
	v_pk_fma_f32 v[108:109], v[108:109], v[108:109], v[110:111]
	v_mov_b32_e32 v112, v67
	v_mov_b32_e32 v113, v61
	v_lshlrev_b32_e32 v40, 16, v48
	v_and_b32_e32 v41, 0xffff0000, v48
	v_lshlrev_b32_e32 v64, 16, v71
	v_lshlrev_b32_e32 v48, 16, v76
	v_mov_b32_e32 v104, v43
	v_mov_b32_e32 v105, v53
	v_pk_fma_f32 v[78:79], v[78:79], v[78:79], v[108:109]
	v_mov_b32_e32 v110, v66
	v_mov_b32_e32 v111, v60
	v_pk_mul_f32 v[112:113], v[112:113], v[112:113]
	v_lshlrev_b32_e32 v38, 16, v49
	v_and_b32_e32 v39, 0xffff0000, v49
	v_and_b32_e32 v65, 0xffff0000, v71
	v_and_b32_e32 v49, 0xffff0000, v76
	v_mov_b32_e32 v74, v40
	v_mov_b32_e32 v75, v48
	v_pk_fma_f32 v[78:79], v[104:105], v[104:105], v[78:79]
	v_mov_b32_e32 v104, v64
	v_mov_b32_e32 v105, v58
	v_pk_fma_f32 v[110:111], v[110:111], v[110:111], v[112:113]
	v_lshlrev_b32_e32 v100, 16, v72
	v_lshlrev_b32_e32 v46, 16, v77
	v_and_b32_e32 v47, 0xffff0000, v77
	v_mov_b32_e32 v76, v41
	v_mov_b32_e32 v77, v49
	v_pk_fma_f32 v[74:75], v[74:75], v[74:75], v[78:79]
	v_mov_b32_e32 v108, v65
	v_mov_b32_e32 v109, v59
	v_pk_fma_f32 v[104:105], v[104:105], v[104:105], v[110:111]
	v_pk_fma_f32 v[74:75], v[76:77], v[76:77], v[74:75]
	v_mov_b32_e32 v76, v100
	v_mov_b32_e32 v77, v54
	v_pk_fma_f32 v[104:105], v[108:109], v[108:109], v[104:105]
	v_and_b32_e32 v101, 0xffff0000, v72
	v_pk_fma_f32 v[76:77], v[76:77], v[76:77], v[104:105]
	v_and_b32_e32 v105, 0xffff0000, v82
	v_and_b32_e32 v141, 0xffff0000, v90
	v_mov_b32_e32 v70, v38
	v_mov_b32_e32 v71, v46
	v_mov_b32_e32 v78, v101
	v_mov_b32_e32 v79, v55
	v_lshlrev_b32_e32 v104, 16, v82
	v_lshlrev_b32_e32 v140, 16, v90
	v_mov_b32_e32 v116, v141
	v_mov_b32_e32 v117, v105
	v_lshlrev_b32_e32 v62, 16, v73
	v_and_b32_e32 v63, 0xffff0000, v73
	v_mov_b32_e32 v72, v39
	v_mov_b32_e32 v73, v47
	v_pk_fma_f32 v[70:71], v[70:71], v[70:71], v[74:75]
	v_pk_fma_f32 v[76:77], v[78:79], v[78:79], v[76:77]
	v_lshlrev_b32_e32 v78, 16, v83
	v_lshlrev_b32_e32 v138, 16, v92
	v_and_b32_e32 v139, 0xffff0000, v92
	v_lshlrev_b32_e32 v92, 16, v91
	v_mov_b32_e32 v114, v140
	v_mov_b32_e32 v115, v104
	v_pk_mul_f32 v[116:117], v[116:117], v[116:117]
	v_pk_fma_f32 v[70:71], v[72:73], v[72:73], v[70:71]
	v_mov_b32_e32 v72, v62
	v_mov_b32_e32 v73, v50
	v_and_b32_e32 v79, 0xffff0000, v83
	v_lshlrev_b32_e32 v136, 16, v93
; #define LAS __attribute__((address_space(3)))
; __device__ __forceinline__ unsigned pk2(float lo, float hi) { const f32x2_t f = {lo, hi}; const bf16x2_t b = __builtin_convertvector(f, bf16x2_t); return __builtin_bit_cast(unsigned, b); }
; __device__ __forceinline__ float lo16(unsigned v) { return __uint_as_float(v << 16); }
; __device__ __forceinline__ float hi16(unsigned v) { return __uint_as_float(v & 0xffff0000u); }
; __device__ __forceinline__ void attn_item(const Params& P, int slice, int item, LAS unsigned char* lds) {
;     ...
;     for (int ks = 0; ks < 8; ++ks) { qv[ks] = *(const u32x4*)(qkv + (size_t)tokq * 4608 + head * 128 + 16 * ks + 8 * h);
;       const float f0 = lo16(qv[ks].x), f1 = hi16(qv[ks].x), f2 = lo16(qv[ks].y), f3 = hi16(qv[ks].y), f4 = lo16(qv[ks].z), f5 = hi16(qv[ks].z), f6 = lo16(qv[ks].w), f7 = hi16(qv[ks].w);
;       s += f0 * f0 + f1 * f1 + f2 * f2 + f3 * f3 + f4 * f4 + f5 * f5 + f6 * f6 + f7 * f7; }
;     s += __shfl_xor(s, 32);
;     const float rs = rsqrtf(s * (1.0f / 128.0f) + 1e-6f) * 0.08838834764831845f;
;     const float* gq = P.in[I_GQ];
; #pragma unroll
;     for (int ks = 0; ks < 8; ++ks) {
;       const f32x4 g0 = *(const f32x4*)(gq + 16 * ks + 8 * h), g1 = *(const f32x4*)(gq + 16 * ks + 8 * h + 4);
;       u32x4 o; o.x = pk2(lo16(qv[ks].x) * rs * g0[0], hi16(qv[ks].x) * rs * g0[1]); o.y = pk2(lo16(qv[ks].y) * rs * g0[2], hi16(qv[ks].y) * rs * g0[3]);
;       o.z = pk2(lo16(qv[ks].z) * rs * g1[0], hi16(qv[ks].z) * rs * g1[1]); o.w = pk2(lo16(qv[ks].w) * rs * g1[2], hi16(qv[ks].w) * rs * g1[3]);
;       Qf[ks] = __builtin_bit_cast(bf16x8, o);
;     }
;   }
;   __syncthreads();
;   f32x16 sc[5];
; #pragma unroll
;   for (int kt = 0; kt < 5; ++kt) {
; #pragma unroll
;     for (int i = 0; i < 16; ++i) sc[kt][i] = 0.f;
;     const LAS unsigned char* kp = img + (32 * wq + 32 * kt + qn) * KROW + 16 * h;
; #pragma unroll
;     for (int ks = 0; ks < 8; ++ks) { const bf16x8 a = *(const LAS bf16x8*)(kp + 32 * ks); sc[kt] = __builtin_amdgcn_mfma_f32_32x32x16_bf16(a, Qf[ks], sc[kt], 0, 0, 0); }
	v_and_b32_e32 v137, 0xffff0000, v93
	v_and_b32_e32 v93, 0xffff0000, v91
	v_mov_b32_e32 v110, v92
	v_mov_b32_e32 v111, v78
	v_pk_fma_f32 v[114:115], v[114:115], v[114:115], v[116:117]
	v_pk_fma_f32 v[72:73], v[72:73], v[72:73], v[76:77]
	v_lshlrev_b32_e32 v76, 16, v84
	v_mov_b32_e32 v112, v93
	v_mov_b32_e32 v113, v79
	v_pk_fma_f32 v[110:111], v[110:111], v[110:111], v[114:115]
	v_mov_b32_e32 v74, v63
	v_mov_b32_e32 v75, v51
	v_and_b32_e32 v77, 0xffff0000, v84
	v_mov_b32_e32 v90, v138
	v_mov_b32_e32 v91, v76
	v_pk_fma_f32 v[110:111], v[112:113], v[112:113], v[110:111]
	v_pk_fma_f32 v[72:73], v[74:75], v[74:75], v[72:73]
	v_lshlrev_b32_e32 v74, 16, v85
	v_mov_b32_e32 v108, v139
	v_mov_b32_e32 v109, v77
	v_pk_fma_f32 v[90:91], v[90:91], v[90:91], v[110:111]
	v_and_b32_e32 v75, 0xffff0000, v85
	v_mov_b32_e32 v82, v136
	v_mov_b32_e32 v83, v74
	v_pk_fma_f32 v[90:91], v[108:109], v[108:109], v[90:91]
	v_and_b32_e32 v145, 0xffff0000, v86
	v_and_b32_e32 v147, 0xffff0000, v94
	v_mov_b32_e32 v84, v137
	v_mov_b32_e32 v85, v75
	v_pk_fma_f32 v[82:83], v[82:83], v[82:83], v[90:91]
	v_lshlrev_b32_e32 v144, 16, v86
	v_lshlrev_b32_e32 v146, 16, v94
	v_mov_b32_e32 v120, v147
	v_mov_b32_e32 v121, v145
	v_pk_fma_f32 v[82:83], v[84:85], v[84:85], v[82:83]
	v_lshlrev_b32_e32 v142, 16, v88
	v_and_b32_e32 v143, 0xffff0000, v88
	v_lshlrev_b32_e32 v88, 16, v87
	v_lshlrev_b32_e32 v84, 16, v96
	v_and_b32_e32 v85, 0xffff0000, v96
	v_lshlrev_b32_e32 v96, 16, v95
	v_mov_b32_e32 v118, v146
	v_mov_b32_e32 v119, v144
	v_pk_mul_f32 v[120:121], v[120:121], v[120:121]
	v_lshlrev_b32_e32 v90, 16, v89
	v_and_b32_e32 v91, 0xffff0000, v89
	v_and_b32_e32 v89, 0xffff0000, v87
	v_lshlrev_b32_e32 v86, 16, v97
	v_and_b32_e32 v87, 0xffff0000, v97
	v_and_b32_e32 v97, 0xffff0000, v95
	v_mov_b32_e32 v114, v96
	v_mov_b32_e32 v115, v88
	v_pk_fma_f32 v[118:119], v[118:119], v[118:119], v[120:121]
	v_mov_b32_e32 v116, v97
	v_mov_b32_e32 v117, v89
	v_pk_fma_f32 v[114:115], v[114:115], v[114:115], v[118:119]
	v_mov_b32_e32 v110, v84
	v_mov_b32_e32 v111, v142
	v_pk_fma_f32 v[114:115], v[116:117], v[116:117], v[114:115]
	v_mov_b32_e32 v112, v85
	v_mov_b32_e32 v113, v143
	v_pk_fma_f32 v[110:111], v[110:111], v[110:111], v[114:115]
	v_mov_b32_e32 v94, v86
	v_mov_b32_e32 v95, v90
	v_pk_fma_f32 v[110:111], v[112:113], v[112:113], v[110:111]
	v_mov_b32_e32 v108, v87
	v_mov_b32_e32 v109, v91
	v_pk_fma_f32 v[94:95], v[94:95], v[94:95], v[110:111]
	s_nop 0
	v_pk_fma_f32 v[94:95], v[108:109], v[108:109], v[94:95]
	global_load_dwordx4 v[108:111], v69, s[46:47] offset:272
	global_load_dwordx4 v[112:115], v69, s[46:47] offset:336
	global_load_dwordx4 v[116:119], v69, s[46:47] offset:320
	v_add_f32_e32 v37, v94, v95
	v_add_f32_e32 v37, v37, v82
	v_add_f32_e32 v37, v37, v83
	v_add_f32_e32 v37, v37, v72
	v_add_f32_e32 v37, v37, v73
	v_add_f32_e32 v37, v37, v70
	v_add_f32_e32 v37, v37, v71
	ds_bpermute_b32 v70, v170, v37
	global_load_dwordx4 v[120:123], v69, s[46:47] offset:400
	global_load_dwordx4 v[124:127], v69, s[46:47] offset:384
	global_load_dwordx4 v[128:131], v69, s[46:47] offset:464
	global_load_dwordx4 v[132:135], v69, s[46:47] offset:448
	s_waitcnt lgkmcnt(0)
	s_barrier
	v_add_f32_e32 v37, v37, v70
	v_fmamk_f32 v37, v37, 0x3c000000, v218
	v_mul_f32_e32 v70, 0x4b800000, v37
	v_cmp_gt_f32_e32 vcc, s0, v37
	s_movk_i32 s0, 0x81
	s_nop 0
	v_cndmask_b32_e32 v37, v37, v70, vcc
	v_rsq_f32_e32 v37, v37
	s_nop 0
	v_mul_f32_e32 v69, 0x45800000, v37
	v_cndmask_b32_e32 v37, v37, v69, vcc
	v_mul_f32_e32 v148, 0x3db504f3, v37
	v_pk_mul_f32 v[70:71], v[148:149], v[146:147] op_sel_hi:[0,1]
	v_pk_mul_f32 v[32:33], v[32:33], v[70:71]
	s_nop 0
	v_cvt_pk_bf16_f32 v82, v32, v33
	v_pk_mul_f32 v[32:33], v[148:149], v[96:97] op_sel_hi:[0,1]
	v_pk_mul_f32 v[32:33], v[34:35], v[32:33]
	s_nop 0
	v_cvt_pk_bf16_f32 v83, v32, v33
	v_pk_mul_f32 v[32:33], v[148:149], v[84:85] op_sel_hi:[0,1]
	v_pk_mul_f32 v[28:29], v[28:29], v[32:33]
	s_nop 0
	v_cvt_pk_bf16_f32 v84, v28, v29
	v_pk_mul_f32 v[28:29], v[148:149], v[86:87] op_sel_hi:[0,1]
	v_pk_mul_f32 v[28:29], v[30:31], v[28:29]
	s_nop 0
	v_cvt_pk_bf16_f32 v85, v28, v29
	v_pk_mul_f32 v[28:29], v[148:149], v[144:145] op_sel_hi:[0,1]
	v_pk_mul_f32 v[24:25], v[24:25], v[28:29]
	s_nop 0
	v_cvt_pk_bf16_f32 v86, v24, v25
	v_pk_mul_f32 v[24:25], v[148:149], v[88:89] op_sel_hi:[0,1]
	v_pk_mul_f32 v[24:25], v[26:27], v[24:25]
	s_nop 0
	v_cvt_pk_bf16_f32 v87, v24, v25
	v_pk_mul_f32 v[24:25], v[148:149], v[142:143] op_sel_hi:[0,1]
	v_pk_mul_f32 v[20:21], v[20:21], v[24:25]
	s_nop 0
	v_cvt_pk_bf16_f32 v88, v20, v21
	v_pk_mul_f32 v[20:21], v[148:149], v[90:91] op_sel_hi:[0,1]
	v_pk_mul_f32 v[20:21], v[22:23], v[20:21]
	s_nop 0
	v_cvt_pk_bf16_f32 v89, v20, v21
	v_pk_mul_f32 v[20:21], v[148:149], v[140:141] op_sel_hi:[0,1]
	v_pk_mul_f32 v[16:17], v[16:17], v[20:21]
	s_nop 0
	v_cvt_pk_bf16_f32 v90, v16, v17
	v_pk_mul_f32 v[16:17], v[148:149], v[92:93] op_sel_hi:[0,1]
	v_pk_mul_f32 v[16:17], v[18:19], v[16:17]
	s_nop 0
	v_cvt_pk_bf16_f32 v91, v16, v17
	v_pk_mul_f32 v[16:17], v[148:149], v[138:139] op_sel_hi:[0,1]
	v_pk_mul_f32 v[12:13], v[12:13], v[16:17]
	s_nop 0
	v_cvt_pk_bf16_f32 v92, v12, v13
	v_pk_mul_f32 v[12:13], v[148:149], v[136:137] op_sel_hi:[0,1]
	v_pk_mul_f32 v[12:13], v[14:15], v[12:13]
	s_nop 0
	v_cvt_pk_bf16_f32 v93, v12, v13
	v_pk_mul_f32 v[12:13], v[148:149], v[104:105] op_sel_hi:[0,1]
	v_pk_mul_f32 v[8:9], v[8:9], v[12:13]
	s_nop 0
	v_cvt_pk_bf16_f32 v94, v8, v9
	v_pk_mul_f32 v[8:9], v[148:149], v[78:79] op_sel_hi:[0,1]
	v_pk_mul_f32 v[8:9], v[10:11], v[8:9]
	s_nop 0
	v_cvt_pk_bf16_f32 v95, v8, v9
	v_pk_mul_f32 v[8:9], v[148:149], v[76:77] op_sel_hi:[0,1]
	v_pk_mul_f32 v[4:5], v[4:5], v[8:9]
	v_mul_u32_u24_e32 v8, 0x110, v68
	v_add3_u32 v104, s64, v36, v8
	ds_read_b128 v[8:11], v104
	v_cvt_pk_bf16_f32 v96, v4, v5
	v_pk_mul_f32 v[4:5], v[148:149], v[74:75] op_sel_hi:[0,1]
	v_pk_mul_f32 v[4:5], v[6:7], v[4:5]
	s_nop 0
	v_cvt_pk_bf16_f32 v97, v4, v5
	v_pk_mul_f32 v[4:5], v[148:149], v[66:67] op_sel_hi:[0,1]
	v_pk_mul_f32 v[0:1], v[0:1], v[4:5]
	s_nop 0
	v_cvt_pk_bf16_f32 v136, v0, v1
	v_pk_mul_f32 v[0:1], v[148:149], v[64:65] op_sel_hi:[0,1]
	v_pk_mul_f32 v[4:5], v[2:3], v[0:1]
	ds_read_b128 v[0:3], v104 offset:32
	s_waitcnt lgkmcnt(1)
; #define LAS __attribute__((address_space(3)))
; __device__ __forceinline__ unsigned pk2(float lo, float hi) { const f32x2_t f = {lo, hi}; const bf16x2_t b = __builtin_convertvector(f, bf16x2_t); return __builtin_bit_cast(unsigned, b); }
; __device__ __forceinline__ float lo16(unsigned v) { return __uint_as_float(v << 16); }
; __device__ __forceinline__ float hi16(unsigned v) { return __uint_as_float(v & 0xffff0000u); }
; __device__ __forceinline__ void attn_item(const Params& P, int slice, int item, LAS unsigned char* lds) {
;     ...
;     for (int ks = 0; ks < 8; ++ks) {
;       const f32x4 g0 = *(const f32x4*)(gq + 16 * ks + 8 * h), g1 = *(const f32x4*)(gq + 16 * ks + 8 * h + 4);
;       u32x4 o; o.x = pk2(lo16(qv[ks].x) * rs * g0[0], hi16(qv[ks].x) * rs * g0[1]); o.y = pk2(lo16(qv[ks].y) * rs * g0[2], hi16(qv[ks].y) * rs * g0[3]);
;       o.z = pk2(lo16(qv[ks].z) * rs * g1[0], hi16(qv[ks].z) * rs * g1[1]); o.w = pk2(lo16(qv[ks].w) * rs * g1[2], hi16(qv[ks].w) * rs * g1[3]);
;       Qf[ks] = __builtin_bit_cast(bf16x8, o);
;     }
;   }
;   __syncthreads();
;   f32x16 sc[5];
; #pragma unroll
;   for (int kt = 0; kt < 5; ++kt) {
; #pragma unroll
;     for (int i = 0; i < 16; ++i) sc[kt][i] = 0.f;
;     const LAS unsigned char* kp = img + (32 * wq + 32 * kt + qn) * KROW + 16 * h;
; #pragma unroll
;     for (int ks = 0; ks < 8; ++ks) { const bf16x8 a = *(const LAS bf16x8*)(kp + 32 * ks); sc[kt] = __builtin_amdgcn_mfma_f32_32x32x16_bf16(a, Qf[ks], sc[kt], 0, 0, 0); }
	v_mfma_f32_32x32x16_bf16 v[64:79], v[8:11], v[82:85], 0
	v_cvt_pk_bf16_f32 v137, v4, v5
	v_mul_f32_e64 v4, v148, v100
	v_mul_f32_e64 v5, v148, v101
	s_waitcnt vmcnt(6)
	v_mul_f32_e64 v4, v108, v4
	v_mul_f32_e64 v5, v109, v5
	v_cvt_pk_bf16_f32 v138, v4, v5
	v_pk_mul_f32 v[4:5], v[148:149], v[62:63] op_sel_hi:[0,1]
	v_pk_mul_f32 v[8:9], v[110:111], v[4:5]
	ds_read_b128 v[4:7], v104 offset:64
	s_waitcnt lgkmcnt(1)
	v_mfma_f32_32x32x16_bf16 v[64:79], v[0:3], v[86:89], v[64:79]
	v_mul_f32_e64 v0, v148, v60
	v_mul_f32_e64 v1, v148, v61
	s_waitcnt vmcnt(4)
	v_mul_f32_e64 v0, v116, v0
	v_mul_f32_e64 v1, v117, v1
	v_cvt_pk_bf16_f32 v139, v8, v9
	v_cvt_pk_bf16_f32 v108, v0, v1
	v_pk_mul_f32 v[0:1], v[148:149], v[58:59] op_sel_hi:[0,1]
	v_pk_mul_f32 v[8:9], v[118:119], v[0:1]
	ds_read_b128 v[0:3], v104 offset:96
	s_waitcnt lgkmcnt(1)
	v_mfma_f32_32x32x16_bf16 v[64:79], v[4:7], v[90:93], v[64:79]
	v_mul_f32_e64 v4, v148, v54
	v_mul_f32_e64 v5, v148, v55
	v_mul_f32_e64 v4, v112, v4
	v_mul_f32_e64 v5, v113, v5
	v_cvt_pk_bf16_f32 v109, v8, v9
	v_cvt_pk_bf16_f32 v110, v4, v5
	v_pk_mul_f32 v[4:5], v[148:149], v[50:51] op_sel_hi:[0,1]
	v_pk_mul_f32 v[8:9], v[114:115], v[4:5]
	ds_read_b128 v[4:7], v104 offset:128
	s_waitcnt lgkmcnt(1)
	v_mfma_f32_32x32x16_bf16 v[64:79], v[0:3], v[94:97], v[64:79]
	v_mul_f32_e64 v0, v148, v44
	v_mul_f32_e64 v1, v148, v45
	s_waitcnt vmcnt(2)
	v_mul_f32_e64 v0, v124, v0
	v_mul_f32_e64 v1, v125, v1
	v_cvt_pk_bf16_f32 v111, v8, v9
	v_cvt_pk_bf16_f32 v112, v0, v1
	v_pk_mul_f32 v[0:1], v[148:149], v[42:43] op_sel_hi:[0,1]
	v_pk_mul_f32 v[8:9], v[126:127], v[0:1]
	ds_read_b128 v[0:3], v104 offset:160
	s_waitcnt lgkmcnt(1)
	v_mfma_f32_32x32x16_bf16 v[64:79], v[4:7], v[136:139], v[64:79]
	v_mul_f32_e64 v4, v148, v40
	v_mul_f32_e64 v5, v148, v41
	v_mul_f32_e64 v4, v120, v4
	v_mul_f32_e64 v5, v121, v5
	v_cvt_pk_bf16_f32 v113, v8, v9
	v_cvt_pk_bf16_f32 v114, v4, v5
	v_pk_mul_f32 v[4:5], v[148:149], v[38:39] op_sel_hi:[0,1]
	v_pk_mul_f32 v[8:9], v[122:123], v[4:5]
	ds_read_b128 v[4:7], v104 offset:192
	s_waitcnt lgkmcnt(1)
	v_mfma_f32_32x32x16_bf16 v[64:79], v[0:3], v[108:111], v[64:79]
	v_mul_f32_e64 v0, v148, v56
	v_mul_f32_e64 v1, v148, v57
	s_waitcnt vmcnt(0)
	v_mul_f32_e64 v0, v132, v0
	v_mul_f32_e64 v1, v133, v1
	v_cvt_pk_bf16_f32 v115, v8, v9
	v_cvt_pk_bf16_f32 v116, v0, v1
	v_pk_mul_f32 v[0:1], v[148:149], v[52:53] op_sel_hi:[0,1]
	v_pk_mul_f32 v[8:9], v[134:135], v[0:1]
	ds_read_b128 v[0:3], v104 offset:224
	s_waitcnt lgkmcnt(1)
	v_mfma_f32_32x32x16_bf16 v[64:79], v[4:7], v[112:115], v[64:79]
	v_mul_f32_e64 v4, v148, v48
	v_mul_f32_e64 v5, v148, v49
	v_mul_f32_e64 v4, v128, v4
	v_mul_f32_e64 v5, v129, v5
	v_cvt_pk_bf16_f32 v117, v8, v9
	v_cvt_pk_bf16_f32 v118, v4, v5
	v_pk_mul_f32 v[4:5], v[148:149], v[46:47] op_sel_hi:[0,1]
	v_pk_mul_f32 v[4:5], v[130:131], v[4:5]
	s_nop 0
	v_cvt_pk_bf16_f32 v119, v4, v5
	s_waitcnt lgkmcnt(0)
	s_nop 0
	v_mfma_f32_32x32x16_bf16 v[64:79], v[0:3], v[116:119], v[64:79]
	ds_read_b128 v[0:3], v104 offset:8704
	ds_read_b128 v[4:7], v104 offset:8736
	s_waitcnt lgkmcnt(1)
	v_mfma_f32_32x32x16_bf16 v[48:63], v[0:3], v[82:85], 0
	s_waitcnt lgkmcnt(0)
	v_mfma_f32_32x32x16_bf16 v[48:63], v[4:7], v[86:89], v[48:63]
	ds_read_b128 v[0:3], v104 offset:8768
	ds_read_b128 v[4:7], v104 offset:8800
	s_waitcnt lgkmcnt(1)
	v_mfma_f32_32x32x16_bf16 v[48:63], v[0:3], v[90:93], v[48:63]
	s_waitcnt lgkmcnt(0)
	v_mfma_f32_32x32x16_bf16 v[48:63], v[4:7], v[94:97], v[48:63]
	ds_read_b128 v[0:3], v104 offset:8832
	ds_read_b128 v[4:7], v104 offset:8864
	s_waitcnt lgkmcnt(1)
	v_mfma_f32_32x32x16_bf16 v[48:63], v[0:3], v[136:139], v[48:63]
	s_waitcnt lgkmcnt(0)
; #define LAS __attribute__((address_space(3)))
; __device__ __forceinline__ void attn_item(const Params& P, int slice, int item, LAS unsigned char* lds) {
;     ...
;   for (int kt = 0; kt < 5; ++kt) {
; #pragma unroll
;     for (int i = 0; i < 16; ++i) sc[kt][i] = 0.f;
;     const LAS unsigned char* kp = img + (32 * wq + 32 * kt + qn) * KROW + 16 * h;
; #pragma unroll
;     for (int ks = 0; ks < 8; ++ks) { const bf16x8 a = *(const LAS bf16x8*)(kp + 32 * ks); sc[kt] = __builtin_amdgcn_mfma_f32_32x32x16_bf16(a, Qf[ks], sc[kt], 0, 0, 0); }
;   }
;   float mx = -3.0e38f;
; #pragma unroll
;   for (int kt = 0; kt < 5; ++kt)
; #pragma unroll
;     for (int i = 0; i < 16; ++i) {
;       const int keyl = 32 * kt + (i & 3) + 8 * (i >> 2) + 4 * h; const int delta = keyl - 64 - qn; const int km = m0 - 64 + 32 * wq + keyl;
;       const bool valid = (delta >= -64) && (delta <= 64) && (km >= 0) && (km < M);
;       int bi = delta + 64; bi = bi < 0 ? 0 : (bi > 128 ? 128 : bi);
;       const float sv = valid ? sc[kt][i] + bl[bi] : -1e30f;
	v_mfma_f32_32x32x16_bf16 v[48:63], v[4:7], v[108:111], v[48:63]
	ds_read_b128 v[0:3], v104 offset:8896
	ds_read_b128 v[4:7], v104 offset:8928
	s_waitcnt lgkmcnt(1)
	v_mfma_f32_32x32x16_bf16 v[48:63], v[0:3], v[112:115], v[48:63]
	s_waitcnt lgkmcnt(0)
	v_mfma_f32_32x32x16_bf16 v[48:63], v[4:7], v[116:119], v[48:63]
	ds_read_b128 v[0:3], v104 offset:17408
	ds_read_b128 v[4:7], v104 offset:17440
	s_waitcnt lgkmcnt(1)
	v_mfma_f32_32x32x16_bf16 v[32:47], v[0:3], v[82:85], 0
	s_waitcnt lgkmcnt(0)
	v_mfma_f32_32x32x16_bf16 v[32:47], v[4:7], v[86:89], v[32:47]
	ds_read_b128 v[0:3], v104 offset:17472
	ds_read_b128 v[4:7], v104 offset:17504
	s_waitcnt lgkmcnt(1)
	v_mfma_f32_32x32x16_bf16 v[32:47], v[0:3], v[90:93], v[32:47]
	s_waitcnt lgkmcnt(0)
	v_mfma_f32_32x32x16_bf16 v[32:47], v[4:7], v[94:97], v[32:47]
	ds_read_b128 v[0:3], v104 offset:17536
	ds_read_b128 v[4:7], v104 offset:17568
	s_waitcnt lgkmcnt(1)
	v_mfma_f32_32x32x16_bf16 v[32:47], v[0:3], v[136:139], v[32:47]
	s_waitcnt lgkmcnt(0)
	v_mfma_f32_32x32x16_bf16 v[32:47], v[4:7], v[108:111], v[32:47]
	ds_read_b128 v[0:3], v104 offset:17600
	ds_read_b128 v[4:7], v104 offset:17632
	s_waitcnt lgkmcnt(1)
	v_mfma_f32_32x32x16_bf16 v[32:47], v[0:3], v[112:115], v[32:47]
	s_waitcnt lgkmcnt(0)
	v_mfma_f32_32x32x16_bf16 v[32:47], v[4:7], v[116:119], v[32:47]
	ds_read_b128 v[0:3], v104 offset:26112
	ds_read_b128 v[4:7], v104 offset:26144
	s_waitcnt lgkmcnt(1)
	v_mfma_f32_32x32x16_bf16 v[16:31], v[0:3], v[82:85], 0
	s_waitcnt lgkmcnt(0)
	v_mfma_f32_32x32x16_bf16 v[16:31], v[4:7], v[86:89], v[16:31]
	ds_read_b128 v[0:3], v104 offset:26176
	ds_read_b128 v[4:7], v104 offset:26208
	s_waitcnt lgkmcnt(1)
	v_mfma_f32_32x32x16_bf16 v[16:31], v[0:3], v[90:93], v[16:31]
	s_waitcnt lgkmcnt(0)
	v_mfma_f32_32x32x16_bf16 v[16:31], v[4:7], v[94:97], v[16:31]
	ds_read_b128 v[0:3], v104 offset:26240
	ds_read_b128 v[4:7], v104 offset:26272
	s_waitcnt lgkmcnt(1)
	v_mfma_f32_32x32x16_bf16 v[16:31], v[0:3], v[136:139], v[16:31]
	s_waitcnt lgkmcnt(0)
	v_mfma_f32_32x32x16_bf16 v[16:31], v[4:7], v[108:111], v[16:31]
	ds_read_b128 v[0:3], v104 offset:26304
	ds_read_b128 v[4:7], v104 offset:26336
	s_waitcnt lgkmcnt(1)
	v_mfma_f32_32x32x16_bf16 v[16:31], v[0:3], v[112:115], v[16:31]
	ds_read_b128 v[0:3], v104 offset:34816
	ds_read_b128 v[120:123], v104 offset:34848
	s_waitcnt lgkmcnt(2)
	v_mfma_f32_32x32x16_bf16 v[16:31], v[4:7], v[116:119], v[16:31]
	s_waitcnt lgkmcnt(1)
	v_mfma_f32_32x32x16_bf16 v[0:15], v[0:3], v[82:85], 0
	s_waitcnt lgkmcnt(0)
	v_mfma_f32_32x32x16_bf16 v[0:15], v[120:123], v[86:89], v[0:15]
	ds_read_b128 v[82:85], v104 offset:34880
	ds_read_b128 v[86:89], v104 offset:34912
	s_waitcnt lgkmcnt(1)
	v_mfma_f32_32x32x16_bf16 v[0:15], v[82:85], v[90:93], v[0:15]
	s_waitcnt lgkmcnt(0)
	v_mfma_f32_32x32x16_bf16 v[0:15], v[86:89], v[94:97], v[0:15]
	ds_read_b128 v[82:85], v104 offset:34944
	ds_read_b128 v[86:89], v104 offset:34976
	s_waitcnt lgkmcnt(1)
	v_mfma_f32_32x32x16_bf16 v[0:15], v[82:85], v[136:139], v[0:15]
	s_waitcnt lgkmcnt(0)
	v_mfma_f32_32x32x16_bf16 v[0:15], v[86:89], v[108:111], v[0:15]
	ds_read_b128 v[82:85], v104 offset:35008
	ds_read_b128 v[86:89], v104 offset:35040
	s_waitcnt lgkmcnt(1)
	v_mfma_f32_32x32x16_bf16 v[0:15], v[82:85], v[112:115], v[0:15]
	v_sub_u32_e32 v84, v168, v102
	v_or_b32_e32 v82, s71, v168
	v_cmp_gt_u32_e32 vcc, s0, v84
	s_cselect_b64 s[0:1], -1, 0
	s_and_b64 s[74:75], vcc, s[0:1]
	v_cmp_gt_i32_e32 vcc, s68, v82
	s_and_b64 s[74:75], s[74:75], vcc
	s_waitcnt lgkmcnt(0)
	v_mfma_f32_32x32x16_bf16 v[0:15], v[86:89], v[116:119], v[0:15]
	v_mov_b32_e32 v82, 0xf149f2ca
	v_mov_b32_e32 v83, 0xf149f2ca
	s_and_saveexec_b64 s[92:93], s[74:75]
	s_cbranch_execz .LBB0_660
	v_lshl_add_u32 v83, v84, 2, s76
	ds_read_b32 v83, v83
	s_waitcnt lgkmcnt(0)
	v_add_f32_e32 v83, v64, v83

; __device__ __forceinline__ void attn_item(const Params& P, int slice, int item, LAS unsigned char* lds) {
;     ...
;   float mx = -3.0e38f;
; #pragma unroll
;   for (int kt = 0; kt < 5; ++kt)
; #pragma unroll
;     for (int i = 0; i < 16; ++i) {
;       const int keyl = 32 * kt + (i & 3) + 8 * (i >> 2) + 4 * h; const int delta = keyl - 64 - qn; const int km = m0 - 64 + 32 * wq + keyl;
;       const bool valid = (delta >= -64) && (delta <= 64) && (km >= 0) && (km < M);
;       int bi = delta + 64; bi = bi < 0 ? 0 : (bi > 128 ? 128 : bi);
;       const float sv = valid ? sc[kt][i] + bl[bi] : -1e30f;
;       sc[kt][i] = sv; mx = fmaxf(mx, sv);
;     }
;   mx = fmaxf(mx, __shfl_xor(mx, 32));
;   float den = 0.f;
; #pragma unroll
;   for (int kt = 0; kt < 5; ++kt)
; #pragma unroll
;     for (int i = 0; i < 16; ++i) { const float pe = __expf(sc[kt][i] - mx); sc[kt][i] = pe; den += pe; }
;   den += __shfl_xor(den, 32);
.LBB0_818:
	s_or_b64 exec, exec, s[0:1]
	s_mov_b32 s0, 0xff61b1e6
	v_max3_f32 v14, v83, s0, v82
	v_max3_f32 v14, v14, v65, v64
	v_max3_f32 v14, v14, v67, v66
	v_max3_f32 v14, v14, v69, v68
	v_max3_f32 v14, v14, v71, v70
	v_max3_f32 v14, v14, v73, v72
	v_max3_f32 v14, v14, v75, v74
	v_max3_f32 v14, v14, v87, v86
	v_max3_f32 v14, v14, v89, v88
	v_max3_f32 v14, v14, v49, v48
	v_max3_f32 v14, v14, v51, v50
	v_max3_f32 v14, v14, v53, v52
	v_max3_f32 v14, v14, v55, v54
	v_max3_f32 v14, v14, v57, v56
	v_max3_f32 v14, v14, v59, v58
	v_max3_f32 v14, v14, v61, v60
	v_max3_f32 v14, v14, v63, v62
	v_max3_f32 v14, v14, v33, v32
	v_max3_f32 v14, v14, v35, v34
	v_max3_f32 v14, v14, v37, v36
	v_max3_f32 v14, v14, v39, v38
	v_max3_f32 v14, v14, v41, v40
	v_max3_f32 v14, v14, v43, v42
	v_max3_f32 v14, v14, v45, v44
	v_max3_f32 v14, v14, v47, v46
	v_max3_f32 v14, v14, v17, v16
	v_max3_f32 v14, v14, v19, v18
	v_max3_f32 v14, v14, v21, v20
	v_max3_f32 v14, v14, v23, v22
	v_max3_f32 v14, v14, v25, v24
	v_max3_f32 v14, v14, v27, v26
	v_max3_f32 v14, v14, v29, v28
	v_max3_f32 v14, v14, v31, v30
	v_max3_f32 v14, v14, v1, v0
	v_max3_f32 v14, v14, v3, v2
	v_max3_f32 v14, v14, v5, v4
	v_max3_f32 v14, v14, v7, v6
	v_max3_f32 v14, v14, v9, v8
	v_max3_f32 v14, v14, v11, v10
	v_max3_f32 v14, v14, v13, v12
	ds_bpermute_b32 v15, v170, v14
	s_waitcnt lgkmcnt(0)
	v_max_f32_e32 v15, v15, v15
	v_max_f32_e32 v14, v14, v15
	v_sub_f32_e32 v15, v83, v14
	v_sub_f32_e32 v76, v82, v14
	v_sub_f32_e32 v65, v65, v14
	v_mul_f32_e32 v15, 0x3fb8aa3b, v15
	v_mul_f32_e32 v77, 0x3fb8aa3b, v76
	v_exp_f32_e32 v76, v15
	v_mul_f32_e32 v15, 0x3fb8aa3b, v65
	v_exp_f32_e32 v78, v15
	v_sub_f32_e32 v15, v64, v14
	v_sub_f32_e32 v64, v67, v14
	v_mul_f32_e32 v64, 0x3fb8aa3b, v64
	v_exp_f32_e32 v84, v64
	v_sub_f32_e32 v64, v66, v14
	v_mul_f32_e32 v64, 0x3fb8aa3b, v64
	v_exp_f32_e32 v85, v64
	v_sub_f32_e32 v64, v69, v14
	v_mul_f32_e32 v64, 0x3fb8aa3b, v64
	v_exp_f32_e32 v90, v64
	v_sub_f32_e32 v64, v68, v14
	v_mul_f32_e32 v64, 0x3fb8aa3b, v64
	v_exp_f32_e32 v91, v64
	v_sub_f32_e32 v64, v71, v14
	v_mul_f32_e32 v64, 0x3fb8aa3b, v64
	v_exp_f32_e32 v66, v64
	v_sub_f32_e32 v64, v70, v14
	v_mul_f32_e32 v64, 0x3fb8aa3b, v64
	v_exp_f32_e32 v67, v64
	v_sub_f32_e32 v64, v73, v14
	v_mul_f32_e32 v64, 0x3fb8aa3b, v64
	v_exp_f32_e32 v68, v64
	v_sub_f32_e32 v64, v72, v14
	v_mul_f32_e32 v64, 0x3fb8aa3b, v64
	v_exp_f32_e32 v77, v77
	v_exp_f32_e32 v69, v64
	v_sub_f32_e32 v64, v75, v14
	v_mul_f32_e32 v15, 0x3fb8aa3b, v15
	v_mul_f32_e32 v64, 0x3fb8aa3b, v64
	v_exp_f32_e32 v79, v15
	v_exp_f32_e32 v70, v64
	v_sub_f32_e32 v64, v74, v14
	v_sub_f32_e32 v48, v48, v14
	v_add_f32_e32 v15, 0, v76
	v_mul_f32_e32 v64, 0x3fb8aa3b, v64
	v_mul_f32_e32 v48, 0x3fb8aa3b, v48
	v_add_f32_e32 v15, v77, v15
	v_exp_f32_e32 v71, v64
	v_sub_f32_e32 v64, v87, v14
	v_exp_f32_e32 v83, v48
	v_sub_f32_e32 v48, v51, v14
	v_add_f32_e32 v15, v78, v15
	v_mul_f32_e32 v64, 0x3fb8aa3b, v64
	v_mul_f32_e32 v48, 0x3fb8aa3b, v48
	v_add_f32_e32 v15, v79, v15
	v_exp_f32_e32 v74, v64
	v_sub_f32_e32 v64, v86, v14
	v_exp_f32_e32 v86, v48
	v_sub_f32_e32 v48, v50, v14
	v_add_f32_e32 v15, v84, v15
	v_mul_f32_e32 v48, 0x3fb8aa3b, v48
	v_add_f32_e32 v15, v85, v15
	v_exp_f32_e32 v87, v48
	v_sub_f32_e32 v48, v53, v14
	v_add_f32_e32 v15, v90, v15
	v_mul_f32_e32 v48, 0x3fb8aa3b, v48
	v_add_f32_e32 v15, v91, v15
	v_exp_f32_e32 v92, v48
	v_sub_f32_e32 v48, v52, v14
	v_add_f32_e32 v15, v66, v15
	v_mul_f32_e32 v64, 0x3fb8aa3b, v64
	v_mul_f32_e32 v48, 0x3fb8aa3b, v48
	v_add_f32_e32 v15, v67, v15
	v_exp_f32_e32 v75, v64
	v_sub_f32_e32 v64, v89, v14
	v_exp_f32_e32 v93, v48
	v_sub_f32_e32 v48, v55, v14
	v_add_f32_e32 v15, v68, v15
	v_mul_f32_e32 v64, 0x3fb8aa3b, v64
	v_mul_f32_e32 v48, 0x3fb8aa3b, v48
	v_add_f32_e32 v15, v69, v15
	v_exp_f32_e32 v72, v64
	v_sub_f32_e32 v64, v88, v14
	v_exp_f32_e32 v88, v48
	v_sub_f32_e32 v48, v54, v14
	v_add_f32_e32 v15, v70, v15
	v_mul_f32_e32 v64, 0x3fb8aa3b, v64
	v_sub_f32_e32 v49, v49, v14
	v_mul_f32_e32 v48, 0x3fb8aa3b, v48
	v_add_f32_e32 v15, v71, v15
	v_exp_f32_e32 v73, v64
	v_mul_f32_e32 v49, 0x3fb8aa3b, v49
	v_exp_f32_e32 v89, v48
	v_sub_f32_e32 v48, v57, v14
	v_add_f32_e32 v15, v74, v15
	v_exp_f32_e32 v82, v49
	v_mul_f32_e32 v48, 0x3fb8aa3b, v48
	v_add_f32_e32 v15, v75, v15
	v_exp_f32_e32 v94, v48
	v_sub_f32_e32 v48, v56, v14
	v_sub_f32_e32 v32, v32, v14
	v_add_f32_e32 v15, v72, v15
	v_mul_f32_e32 v48, 0x3fb8aa3b, v48
	v_mul_f32_e32 v32, 0x3fb8aa3b, v32
	v_add_f32_e32 v15, v73, v15
	v_exp_f32_e32 v95, v48
	v_sub_f32_e32 v48, v59, v14
	v_exp_f32_e32 v105, v32
	v_sub_f32_e32 v32, v35, v14
	v_add_f32_e32 v15, v82, v15
	v_mul_f32_e32 v48, 0x3fb8aa3b, v48
	v_mul_f32_e32 v32, 0x3fb8aa3b, v32
	v_add_f32_e32 v15, v83, v15
	v_exp_f32_e32 v96, v48
	v_sub_f32_e32 v48, v58, v14
	v_exp_f32_e32 v108, v32
	v_sub_f32_e32 v32, v34, v14
	v_add_f32_e32 v15, v86, v15
	v_mul_f32_e32 v48, 0x3fb8aa3b, v48
	v_mul_f32_e32 v32, 0x3fb8aa3b, v32
	v_add_f32_e32 v15, v87, v15
	v_exp_f32_e32 v97, v48
	v_sub_f32_e32 v48, v61, v14
	v_exp_f32_e32 v109, v32
	v_sub_f32_e32 v32, v37, v14
	v_add_f32_e32 v15, v92, v15
	v_mul_f32_e32 v48, 0x3fb8aa3b, v48
	v_mul_f32_e32 v32, 0x3fb8aa3b, v32
	v_add_f32_e32 v15, v93, v15
	v_exp_f32_e32 v102, v48
	v_sub_f32_e32 v48, v60, v14
	v_exp_f32_e32 v112, v32
	v_sub_f32_e32 v32, v36, v14
	v_add_f32_e32 v15, v88, v15
	v_mul_f32_e32 v48, 0x3fb8aa3b, v48
	v_mul_f32_e32 v32, 0x3fb8aa3b, v32
	v_add_f32_e32 v15, v89, v15
	v_exp_f32_e32 v103, v48
	v_sub_f32_e32 v48, v63, v14
	v_exp_f32_e32 v113, v32
	v_sub_f32_e32 v32, v39, v14
	v_add_f32_e32 v15, v94, v15
	v_mul_f32_e32 v48, 0x3fb8aa3b, v48
	v_mul_f32_e32 v32, 0x3fb8aa3b, v32
	v_add_f32_e32 v15, v95, v15
; __device__ __forceinline__ void attn_item(const Params& P, int slice, int item, LAS unsigned char* lds) {
;     ...
;   float den = 0.f;
; #pragma unroll
;   for (int kt = 0; kt < 5; ++kt)
; #pragma unroll
;     for (int i = 0; i < 16; ++i) { const float pe = __expf(sc[kt][i] - mx); sc[kt][i] = pe; den += pe; }
;   den += __shfl_xor(den, 32);
;   const float inv = 1.0f / den;
;   if (h == 0) ((float*)(ws + O_LSE))[((size_t)(gi * 4 + g)) * TS + b * L + r * M + mq] = mx + __logf(den);
	v_exp_f32_e32 v100, v48
	v_sub_f32_e32 v48, v62, v14
	v_exp_f32_e32 v110, v32
	v_sub_f32_e32 v32, v38, v14
	v_add_f32_e32 v15, v96, v15
	v_mul_f32_e32 v48, 0x3fb8aa3b, v48
	v_sub_f32_e32 v33, v33, v14
	v_mul_f32_e32 v32, 0x3fb8aa3b, v32
	v_add_f32_e32 v15, v97, v15
	v_exp_f32_e32 v101, v48
	v_mul_f32_e32 v33, 0x3fb8aa3b, v33
	v_exp_f32_e32 v111, v32
	v_sub_f32_e32 v32, v41, v14
	v_add_f32_e32 v15, v102, v15
	v_exp_f32_e32 v104, v33
	v_mul_f32_e32 v32, 0x3fb8aa3b, v32
	v_add_f32_e32 v15, v103, v15
	v_exp_f32_e32 v114, v32
	v_sub_f32_e32 v32, v40, v14
	v_sub_f32_e32 v16, v16, v14
	v_add_f32_e32 v15, v100, v15
	v_mul_f32_e32 v32, 0x3fb8aa3b, v32
	v_mul_f32_e32 v16, 0x3fb8aa3b, v16
	v_add_f32_e32 v15, v101, v15
	v_exp_f32_e32 v115, v32
	v_sub_f32_e32 v32, v43, v14
	v_exp_f32_e32 v123, v16
	v_sub_f32_e32 v16, v19, v14
	v_add_f32_e32 v15, v104, v15
	v_mul_f32_e32 v32, 0x3fb8aa3b, v32
	v_mul_f32_e32 v16, 0x3fb8aa3b, v16
	v_add_f32_e32 v15, v105, v15
	v_exp_f32_e32 v116, v32
	v_sub_f32_e32 v32, v42, v14
	v_exp_f32_e32 v124, v16
	v_sub_f32_e32 v16, v18, v14
	v_add_f32_e32 v15, v108, v15
	v_mul_f32_e32 v32, 0x3fb8aa3b, v32
	v_mul_f32_e32 v16, 0x3fb8aa3b, v16
	v_add_f32_e32 v15, v109, v15
	v_exp_f32_e32 v117, v32
	v_sub_f32_e32 v32, v45, v14
	v_exp_f32_e32 v125, v16
	v_sub_f32_e32 v16, v21, v14
	v_add_f32_e32 v15, v112, v15
	v_mul_f32_e32 v32, 0x3fb8aa3b, v32
	v_mul_f32_e32 v16, 0x3fb8aa3b, v16
	v_add_f32_e32 v15, v113, v15
	v_exp_f32_e32 v120, v32
	v_sub_f32_e32 v32, v44, v14
	v_exp_f32_e32 v128, v16
	v_sub_f32_e32 v16, v20, v14
	v_add_f32_e32 v15, v110, v15
	v_mul_f32_e32 v32, 0x3fb8aa3b, v32
	v_mul_f32_e32 v16, 0x3fb8aa3b, v16
	v_add_f32_e32 v15, v111, v15
	v_exp_f32_e32 v121, v32
	v_sub_f32_e32 v32, v47, v14
	v_exp_f32_e32 v129, v16
	v_sub_f32_e32 v16, v23, v14
	v_add_f32_e32 v15, v114, v15
	v_mul_f32_e32 v32, 0x3fb8aa3b, v32
	v_mul_f32_e32 v16, 0x3fb8aa3b, v16
	v_add_f32_e32 v15, v115, v15
	v_exp_f32_e32 v118, v32
	v_sub_f32_e32 v32, v46, v14
	v_exp_f32_e32 v126, v16
	v_sub_f32_e32 v16, v22, v14
	v_add_f32_e32 v15, v116, v15
	v_mul_f32_e32 v32, 0x3fb8aa3b, v32
	v_sub_f32_e32 v17, v17, v14
	v_mul_f32_e32 v16, 0x3fb8aa3b, v16
	v_add_f32_e32 v15, v117, v15
	v_exp_f32_e32 v119, v32
	v_mul_f32_e32 v17, 0x3fb8aa3b, v17
	v_exp_f32_e32 v127, v16
	v_sub_f32_e32 v16, v25, v14
	v_add_f32_e32 v15, v120, v15
	v_exp_f32_e32 v122, v17
	v_mul_f32_e32 v16, 0x3fb8aa3b, v16
	v_add_f32_e32 v15, v121, v15
	v_exp_f32_e32 v130, v16
	v_sub_f32_e32 v16, v24, v14
	v_add_f32_e32 v15, v118, v15
	v_mul_f32_e32 v16, 0x3fb8aa3b, v16
	v_add_f32_e32 v15, v119, v15
	v_exp_f32_e32 v131, v16
	v_sub_f32_e32 v16, v27, v14
	v_sub_f32_e32 v1, v1, v14
	v_add_f32_e32 v15, v122, v15
	v_mul_f32_e32 v16, 0x3fb8aa3b, v16
	v_mul_f32_e32 v1, 0x3fb8aa3b, v1
	v_add_f32_e32 v15, v123, v15
	v_exp_f32_e32 v132, v16
	v_sub_f32_e32 v16, v26, v14
	v_exp_f32_e32 v138, v1
	v_sub_f32_e32 v1, v3, v14
	v_add_f32_e32 v15, v124, v15
	v_mul_f32_e32 v16, 0x3fb8aa3b, v16
	v_mul_f32_e32 v1, 0x3fb8aa3b, v1
	v_add_f32_e32 v15, v125, v15
	v_exp_f32_e32 v133, v16
	v_sub_f32_e32 v16, v29, v14
	v_exp_f32_e32 v140, v1
	v_sub_f32_e32 v1, v2, v14
	v_add_f32_e32 v15, v128, v15
	v_mul_f32_e32 v16, 0x3fb8aa3b, v16
	v_mul_f32_e32 v1, 0x3fb8aa3b, v1
	v_add_f32_e32 v15, v129, v15
	v_exp_f32_e32 v136, v16
	v_sub_f32_e32 v16, v28, v14
	v_exp_f32_e32 v141, v1
	v_sub_f32_e32 v1, v5, v14
	v_add_f32_e32 v15, v126, v15
	v_mul_f32_e32 v16, 0x3fb8aa3b, v16
	v_mul_f32_e32 v1, 0x3fb8aa3b, v1
	v_add_f32_e32 v15, v127, v15
	v_exp_f32_e32 v137, v16
	v_sub_f32_e32 v16, v31, v14
	v_exp_f32_e32 v144, v1
	v_sub_f32_e32 v1, v4, v14
	v_add_f32_e32 v15, v130, v15
	v_mul_f32_e32 v16, 0x3fb8aa3b, v16
	v_mul_f32_e32 v1, 0x3fb8aa3b, v1
	v_add_f32_e32 v15, v131, v15
	v_exp_f32_e32 v134, v16
	v_sub_f32_e32 v16, v30, v14
	v_exp_f32_e32 v145, v1
	v_sub_f32_e32 v1, v7, v14
	v_add_f32_e32 v15, v132, v15
	v_mul_f32_e32 v16, 0x3fb8aa3b, v16
	v_mul_f32_e32 v1, 0x3fb8aa3b, v1
	v_add_f32_e32 v15, v133, v15
	v_exp_f32_e32 v135, v16
	v_sub_f32_e32 v0, v0, v14
	v_exp_f32_e32 v142, v1
	v_sub_f32_e32 v1, v6, v14
	v_add_f32_e32 v15, v136, v15
	v_mul_f32_e32 v0, 0x3fb8aa3b, v0
	v_mul_f32_e32 v1, 0x3fb8aa3b, v1
	v_add_f32_e32 v15, v137, v15
	v_exp_f32_e32 v139, v0
	v_exp_f32_e32 v143, v1
	v_sub_f32_e32 v1, v9, v14
	v_add_f32_e32 v0, v134, v15
	v_mul_f32_e32 v1, 0x3fb8aa3b, v1
	v_add_f32_e32 v0, v135, v0
	v_exp_f32_e32 v146, v1
	v_sub_f32_e32 v1, v8, v14
	v_add_f32_e32 v0, v138, v0
	v_mul_f32_e32 v1, 0x3fb8aa3b, v1
	v_add_f32_e32 v0, v139, v0
	v_exp_f32_e32 v147, v1
	v_sub_f32_e32 v1, v11, v14
	v_add_f32_e32 v0, v140, v0
	v_mul_f32_e32 v1, 0x3fb8aa3b, v1
	v_add_f32_e32 v0, v141, v0
	v_exp_f32_e32 v148, v1
	v_sub_f32_e32 v1, v10, v14
	v_add_f32_e32 v0, v144, v0
	v_mul_f32_e32 v1, 0x3fb8aa3b, v1
	v_add_f32_e32 v0, v145, v0
	v_exp_f32_e32 v149, v1
	v_sub_f32_e32 v1, v13, v14
	v_add_f32_e32 v0, v142, v0
	v_mul_f32_e32 v1, 0x3fb8aa3b, v1
	v_add_f32_e32 v0, v143, v0
	v_exp_f32_e32 v150, v1
	v_sub_f32_e32 v1, v12, v14
	v_add_f32_e32 v0, v146, v0
	v_mul_f32_e32 v1, 0x3fb8aa3b, v1
	v_add_f32_e32 v0, v147, v0
	v_exp_f32_e32 v151, v1
	v_add_f32_e32 v0, v148, v0
	v_add_f32_e32 v0, v149, v0
	v_add_f32_e32 v0, v150, v0
	v_add_f32_e32 v0, v151, v0
	ds_bpermute_b32 v1, v170, v0
	v_and_b32_e32 v2, 63, v107
	v_cmp_gt_u32_e32 vcc, 32, v2
	s_waitcnt lgkmcnt(0)
	v_add_f32_e32 v65, v0, v1
	s_and_saveexec_b64 s[0:1], vcc
	s_cbranch_execz .LBB0_820
	s_mov_b32 s31, 0x800000
	v_cmp_gt_f32_e32 vcc, s31, v65
	s_mov_b32 s71, 0x3f317217
	v_mov_b32_e32 v1, 0x41b17218
	v_cndmask_b32_e64 v0, 0, 32, vcc
	v_ldexp_f32 v0, v65, v0
	v_log_f32_e32 v0, v0
	s_mov_b32 s74, s84
	s_ashr_i32 s75, s84, 31
	v_cndmask_b32_e32 v1, 0, v1, vcc
	v_mul_f32_e32 v2, 0x3f317217, v0
	v_fma_f32 v2, v0, s71, -v2
	s_mov_b32 s71, 0x7f800000
	v_cmp_lt_f32_e64 vcc, |v0|, s71
	s_mul_i32 s71, s69, s68
	s_lshl_b64 s[68:69], s[74:75], 16
	s_add_u32 s68, s4, s68
	v_fmac_f32_e32 v2, 0x3377d1cf, v0
	s_addc_u32 s69, s5, s69
	s_lshl_b32 s70, s70, 2
	v_fmac_f32_e32 v2, 0x3f317217, v0
	s_add_u32 s68, s68, s70
	v_cndmask_b32_e32 v0, v0, v2, vcc
	s_addc_u32 s69, s69, 0
	s_lshl_b32 s70, s71, 2
	v_sub_f32_e32 v0, v0, v1
	s_add_u32 s68, s68, s70
	v_add_f32_e32 v2, v14, v0
	s_addc_u32 s69, s69, 0
	v_lshlrev_b32_e32 v0, 2, v169
	v_mov_b32_e32 v1, v81
	v_lshl_add_u64 v[0:1], s[68:69], 0, v[0:1]
	v_add_co_u32_e32 v0, vcc, 0x30852000, v0
	s_nop 1
	v_addc_co_u32_e32 v1, vcc, 0, v1, vcc
	global_store_dword v[0:1], v2, off

; #define LAUNDER_V(x) asm volatile("" : "+v"(x))
; __device__ __forceinline__ void phase_prep(const Params& P, LAS unsigned char* lds) {
;     ...
;     for (int i = bid * 512 + tid; i < 4096 * 24; i += G * 512) { const int n = i / 24, c = i % 24; unsigned z0 = 0u; LAUNDER_V(z0); *(u32x4*)((u16*)(ws + O_W4) + (size_t)n * 256 + 64 + 8 * c) = (u32x4){z0, z0, z0, z0}; }
.LBB0_891:
	s_mov_b32 s3, 0x2aaaaaab
	v_mul_hi_i32 v3, v1, s3
	v_lshrrev_b32_e32 v5, 31, v3
	v_ashrrev_i32_e32 v3, 2, v3
	v_add_u32_e32 v1, s73, v1
	s_mov_b32 s3, 0x17fff
	v_add_u32_e32 v8, v3, v5
	v_cmp_lt_i32_e32 vcc, s3, v1
	v_ashrrev_i32_e32 v9, 31, v8
	s_movk_i32 s3, 0xff40
	v_mad_u64_u32 v[10:11], s[8:9], v8, s3, v[2:3]
	v_lshlrev_b64 v[8:9], 9, v[8:9]
	v_ashrrev_i32_e32 v11, 31, v10
	v_lshl_add_u64 v[8:9], s[4:5], 0, v[8:9]
	v_lshl_add_u64 v[8:9], v[10:11], 1, v[8:9]
	v_mov_b32_e32 v4, v81
	s_or_b64 s[6:7], vcc, s[6:7]
	v_add_co_u32_e32 v8, vcc, 0x2800000, v8
	v_add_u32_e32 v2, s2, v2
	v_mov_b32_e32 v5, v4
	v_mov_b32_e32 v6, v4
	v_mov_b32_e32 v7, v4
	v_addc_co_u32_e32 v9, vcc, 0, v9, vcc
	global_store_dwordx4 v[8:9], v[4:7], off offset:128
	s_andn2_b64 exec, exec, s[6:7]
	s_cbranch_execnz .LBB0_891

; #define LAS __attribute__((address_space(3)))
; __device__ __forceinline__ unsigned pk2(float lo, float hi) { const f32x2_t f = {lo, hi}; const bf16x2_t b = __builtin_convertvector(f, bf16x2_t); return __builtin_bit_cast(unsigned, b); }
; __device__ __forceinline__ void transpose_tile(const float* W, int K, int N, u16* WT, int ldo, const float* g, int tile, LAS float* scr) {
;     ...
;   { const int n = tid >> 3, c = tid & 7; const LAS float* s = scr + (8 * c) * 65 + n;
;     u32x4 o; o.x = pk2(s[0], s[65]); o.y = pk2(s[130], s[195]); o.z = pk2(s[260], s[325]); o.w = pk2(s[390], s[455]);
;     *(u32x4*)(WT + (size_t)(n0 + n) * ldo + k0 + 8 * c) = o; }
;   __syncthreads();
.LBB0_894:
	v_ashrrev_i32_e32 v10, 3, v1
	v_lshlrev_b32_e32 v1, 3, v1
	v_and_b32_e32 v1, 56, v1
	v_mul_u32_u24_e32 v2, 0x104, v1
	v_lshlrev_b32_e32 v3, 2, v10
	v_add3_u32 v6, 0, v2, v3
	s_waitcnt lgkmcnt(0)
	s_barrier
	ds_read2_b32 v[2:3], v6 offset1:65
	ds_read2_b32 v[4:5], v6 offset0:130 offset1:195
	v_add_u32_e32 v8, 0x400, v6
	ds_read2_b32 v[6:7], v8 offset0:4 offset1:69
	ds_read2_b32 v[8:9], v8 offset0:134 offset1:199
	s_add_u32 s0, s4, s8
	s_waitcnt lgkmcnt(3)
	v_cvt_pk_bf16_f32 v2, v2, v3
	s_waitcnt lgkmcnt(2)
	v_cvt_pk_bf16_f32 v3, v4, v5
	s_waitcnt lgkmcnt(1)
	v_cvt_pk_bf16_f32 v4, v6, v7
	v_add_u32_e32 v6, s14, v10
	v_ashrrev_i32_e32 v7, 31, v6
	s_waitcnt lgkmcnt(0)
	v_cvt_pk_bf16_f32 v5, v8, v9
	v_mul_lo_u32 v8, s6, v7
	v_mul_lo_u32 v9, s7, v6
	v_mad_u64_u32 v[6:7], s[6:7], s6, v6, 0
	s_addc_u32 s1, s5, s9
	v_add3_u32 v7, v7, v8, v9
	v_lshl_add_u64 v[6:7], v[6:7], 1, s[0:1]
	s_ashr_i32 s13, s12, 31
	v_readlane_b32 s0, v253, 6
	v_lshl_add_u64 v[6:7], s[12:13], 1, v[6:7]
	v_lshlrev_b32_e32 v80, 1, v1
	s_add_i32 s2, s2, s0
	v_lshl_add_u64 v[6:7], v[6:7], 0, v[80:81]
	s_cmpk_gt_i32 s2, 0x143f
	global_store_dwordx4 v[6:7], v[2:5], off
	s_waitcnt lgkmcnt(0)
	s_barrier
	s_cbranch_scc1 .LBB0_889

; __device__ __forceinline__ void phase_prep(const Params& P, LAS unsigned char* lds) {
;     ...
;     for (int chunk = bid; chunk < TALL / 32; chunk += G) {
; #pragma unroll 1
;       for (int rr = 0; rr < 4; ++rr) {
;         const int row = chunk * 32 + wave * 4 + rr;
;         const float* src = row < 65536 ? P.in[I_XP] + (size_t)row * DM : P.in[I_XS] + (size_t)(row - 65536) * DM;
;         f32x4 v[4]; float s = 0.f;
; #pragma unroll
;         for (int j = 0; j < 4; ++j) { v[j] = *(const f32x4*)(src + 4 * lane + 256 * j); s += v[j][0] * v[j][0] + v[j][1] * v[j][1] + v[j][2] * v[j][2] + v[j][3] * v[j][3]; }
; #pragma unroll
;         for (int o = 1; o < 64; o <<= 1) s += __shfl_xor(s, o);
.LBB0_935:
	s_nop 0
	v_readfirstlane_b32 s0, v4
	v_readlane_b32 s10, v253, 16
	v_readlane_b32 s11, v253, 17
	s_nop 0
	s_cmp_gt_u32 s0, 0xffff
	s_cselect_b32 s10, s10, s36
	s_cselect_b32 s11, s11, s37
	v_mov_b32_e32 v8, v4
	v_ashrrev_i32_e32 v9, 31, v4
	v_lshlrev_b64 v[10:11], 12, v[8:9]
	v_lshl_add_u64 v[10:11], s[10:11], 0, v[10:11]
	v_lshl_add_u64 v[10:11], v[10:11], 0, v[80:81]
	v_mov_b32_e32 v98, 0x1000
	v_mov_b32_e32 v99, 0
	v_lshl_add_u64 v[92:93], v[98:99], 0, v[10:11]
	v_lshl_add_u64 v[94:95], v[98:99], 0, v[92:93]
	v_lshl_add_u64 v[96:97], v[98:99], 0, v[94:95]
	global_load_dwordx4 v[100:103], v[10:11], off
	global_load_dwordx4 v[104:107], v[10:11], off offset:1024
	global_load_dwordx4 v[108:111], v[10:11], off offset:2048
	global_load_dwordx4 v[112:115], v[10:11], off offset:3072
	global_load_dwordx4 v[116:119], v[92:93], off
	global_load_dwordx4 v[120:123], v[92:93], off offset:1024
	global_load_dwordx4 v[124:127], v[92:93], off offset:2048
	global_load_dwordx4 v[128:131], v[92:93], off offset:3072
	global_load_dwordx4 v[132:135], v[94:95], off
	global_load_dwordx4 v[136:139], v[94:95], off offset:1024
	global_load_dwordx4 v[140:143], v[94:95], off offset:2048
	global_load_dwordx4 v[144:147], v[94:95], off offset:3072
	global_load_dwordx4 v[148:151], v[96:97], off
	global_load_dwordx4 v[152:155], v[96:97], off offset:1024
	global_load_dwordx4 v[156:159], v[96:97], off offset:2048
	global_load_dwordx4 v[160:163], v[96:97], off offset:3072
	s_waitcnt vmcnt(12)
	v_mul_f32_e32 v164, v101, v101
	v_mul_f32_e32 v168, v105, v105
	v_mul_f32_e32 v172, v109, v109
	v_fmac_f32_e32 v164, v100, v100
	v_fmac_f32_e32 v168, v104, v104
	v_mul_f32_e32 v176, v113, v113
	v_fmac_f32_e32 v172, v108, v108
	v_fmac_f32_e32 v164, v102, v102
	v_fmac_f32_e32 v168, v106, v106
	v_fmac_f32_e32 v176, v112, v112
	v_fmac_f32_e32 v172, v110, v110
	v_fmac_f32_e32 v164, v103, v103
	v_fmac_f32_e32 v168, v107, v107
	v_fmac_f32_e32 v176, v114, v114
	v_fmac_f32_e32 v172, v111, v111
	v_add_f32_e32 v164, v164, v168
	v_fmac_f32_e32 v176, v115, v115
	v_add_f32_e32 v164, v164, v172
	v_add_f32_e32 v164, v164, v176
	s_waitcnt vmcnt(8)
	v_mul_f32_e32 v165, v117, v117
	v_mul_f32_e32 v169, v121, v121
	v_mul_f32_e32 v173, v125, v125
	v_fmac_f32_e32 v165, v116, v116
	v_fmac_f32_e32 v169, v120, v120
	v_mul_f32_e32 v177, v129, v129
	v_fmac_f32_e32 v173, v124, v124
	v_fmac_f32_e32 v165, v118, v118
	v_fmac_f32_e32 v169, v122, v122
	v_fmac_f32_e32 v177, v128, v128
	v_fmac_f32_e32 v173, v126, v126
	v_fmac_f32_e32 v165, v119, v119
	v_fmac_f32_e32 v169, v123, v123
	v_fmac_f32_e32 v177, v130, v130
	v_fmac_f32_e32 v173, v127, v127
	v_add_f32_e32 v165, v165, v169
	v_fmac_f32_e32 v177, v131, v131
	v_add_f32_e32 v165, v165, v173
	v_add_f32_e32 v165, v165, v177
	s_waitcnt vmcnt(4)
	v_mul_f32_e32 v166, v133, v133
	v_mul_f32_e32 v170, v137, v137
	v_mul_f32_e32 v174, v141, v141
	v_fmac_f32_e32 v166, v132, v132
	v_fmac_f32_e32 v170, v136, v136
	v_mul_f32_e32 v178, v145, v145
	v_fmac_f32_e32 v174, v140, v140
	v_fmac_f32_e32 v166, v134, v134
	v_fmac_f32_e32 v170, v138, v138
	v_fmac_f32_e32 v178, v144, v144
	v_fmac_f32_e32 v174, v142, v142
	v_fmac_f32_e32 v166, v135, v135
	v_fmac_f32_e32 v170, v139, v139
	v_fmac_f32_e32 v178, v146, v146
	v_fmac_f32_e32 v174, v143, v143
	v_add_f32_e32 v166, v166, v170
	v_fmac_f32_e32 v178, v147, v147
	v_add_f32_e32 v166, v166, v174
	v_add_f32_e32 v166, v166, v178
	s_waitcnt vmcnt(0)
	v_mul_f32_e32 v167, v149, v149
	v_mul_f32_e32 v171, v153, v153
	v_mul_f32_e32 v175, v157, v157
	v_fmac_f32_e32 v167, v148, v148
	v_fmac_f32_e32 v171, v152, v152
	v_mul_f32_e32 v179, v161, v161
	v_fmac_f32_e32 v175, v156, v156
	v_fmac_f32_e32 v167, v150, v150
	v_fmac_f32_e32 v171, v154, v154
	v_fmac_f32_e32 v179, v160, v160
	v_fmac_f32_e32 v175, v158, v158
	v_fmac_f32_e32 v167, v151, v151
	v_fmac_f32_e32 v171, v155, v155
	v_fmac_f32_e32 v179, v162, v162
	v_fmac_f32_e32 v175, v159, v159
	v_add_f32_e32 v167, v167, v171
	v_fmac_f32_e32 v179, v163, v163
	v_add_f32_e32 v167, v167, v175
	v_add_f32_e32 v167, v167, v179
	ds_bpermute_b32 v180, v16, v164
	ds_bpermute_b32 v181, v16, v165
	ds_bpermute_b32 v182, v16, v166
	ds_bpermute_b32 v183, v16, v167
	s_waitcnt lgkmcnt(0)
	v_add_f32_e32 v164, v164, v180
	v_add_f32_e32 v165, v165, v181
	v_add_f32_e32 v166, v166, v182
	v_add_f32_e32 v167, v167, v183
	ds_bpermute_b32 v180, v17, v164
	ds_bpermute_b32 v181, v17, v165
	ds_bpermute_b32 v182, v17, v166
	ds_bpermute_b32 v183, v17, v167
	s_waitcnt lgkmcnt(0)
	v_add_f32_e32 v164, v164, v180
	v_add_f32_e32 v165, v165, v181
	v_add_f32_e32 v166, v166, v182
	v_add_f32_e32 v167, v167, v183
	ds_bpermute_b32 v180, v18, v164
	ds_bpermute_b32 v181, v18, v165
	ds_bpermute_b32 v182, v18, v166
	ds_bpermute_b32 v183, v18, v167
	s_waitcnt lgkmcnt(0)
; __device__ __forceinline__ unsigned pk2(float lo, float hi) { const f32x2_t f = {lo, hi}; const bf16x2_t b = __builtin_convertvector(f, bf16x2_t); return __builtin_bit_cast(unsigned, b); }
; __device__ __forceinline__ void phase_prep(const Params& P, LAS unsigned char* lds) {
;     ...
;         for (int o = 1; o < 64; o <<= 1) s += __shfl_xor(s, o);
; #pragma unroll
;         for (int j = 0; j < 4; ++j) { u32x2 o; o.x = pk2(v[j][0], v[j][1]); o.y = pk2(v[j][2], v[j][3]); *(u32x2*)(xb + (size_t)row * DM + 4 * lane + 256 * j) = o; }
;         if (lane == 0) rstd1[row] = rsqrtf(s * (1.0f / 1024.0f) + 1e-6f);
	v_add_f32_e32 v164, v164, v180
	v_add_f32_e32 v165, v165, v181
	v_add_f32_e32 v166, v166, v182
	v_add_f32_e32 v167, v167, v183
	ds_bpermute_b32 v180, v19, v164
	ds_bpermute_b32 v181, v19, v165
	ds_bpermute_b32 v182, v19, v166
	ds_bpermute_b32 v183, v19, v167
	s_waitcnt lgkmcnt(0)
	v_add_f32_e32 v164, v164, v180
	v_add_f32_e32 v165, v165, v181
	v_add_f32_e32 v166, v166, v182
	v_add_f32_e32 v167, v167, v183
	ds_bpermute_b32 v180, v20, v164
	ds_bpermute_b32 v181, v20, v165
	ds_bpermute_b32 v182, v20, v166
	ds_bpermute_b32 v183, v20, v167
	s_waitcnt lgkmcnt(0)
	v_add_f32_e32 v164, v164, v180
	v_add_f32_e32 v165, v165, v181
	v_add_f32_e32 v166, v166, v182
	v_add_f32_e32 v167, v167, v183
	ds_bpermute_b32 v180, v21, v164
	ds_bpermute_b32 v181, v21, v165
	ds_bpermute_b32 v182, v21, v166
	ds_bpermute_b32 v183, v21, v167
	s_waitcnt lgkmcnt(0)
	v_add_f32_e32 v164, v164, v180
	v_add_f32_e32 v165, v165, v181
	v_add_f32_e32 v166, v166, v182
	v_add_f32_e32 v167, v167, v183
	v_lshlrev_b64 v[12:13], 11, v[8:9]
	v_lshl_add_u64 v[40:41], v[2:3], 0, v[12:13]
	v_lshl_add_u64 v[42:43], v[98:99], 0, v[40:41]
	v_cvt_pk_bf16_f32 v184, v100, v101
	v_cvt_pk_bf16_f32 v185, v102, v103
	v_cvt_pk_bf16_f32 v186, v104, v105
	v_cvt_pk_bf16_f32 v187, v106, v107
	v_cvt_pk_bf16_f32 v188, v108, v109
	v_cvt_pk_bf16_f32 v189, v110, v111
	v_cvt_pk_bf16_f32 v190, v112, v113
	v_cvt_pk_bf16_f32 v191, v114, v115
	v_cvt_pk_bf16_f32 v192, v116, v117
	v_cvt_pk_bf16_f32 v193, v118, v119
	v_cvt_pk_bf16_f32 v194, v120, v121
	v_cvt_pk_bf16_f32 v195, v122, v123
	v_cvt_pk_bf16_f32 v196, v124, v125
	v_cvt_pk_bf16_f32 v197, v126, v127
	v_cvt_pk_bf16_f32 v198, v128, v129
	v_cvt_pk_bf16_f32 v199, v130, v131
	v_cvt_pk_bf16_f32 v200, v132, v133
	v_cvt_pk_bf16_f32 v201, v134, v135
	v_cvt_pk_bf16_f32 v202, v136, v137
	v_cvt_pk_bf16_f32 v203, v138, v139
	v_cvt_pk_bf16_f32 v204, v140, v141
	v_cvt_pk_bf16_f32 v205, v142, v143
	v_cvt_pk_bf16_f32 v206, v144, v145
	v_cvt_pk_bf16_f32 v207, v146, v147
	v_cvt_pk_bf16_f32 v84, v148, v149
	v_cvt_pk_bf16_f32 v85, v150, v151
	v_cvt_pk_bf16_f32 v86, v152, v153
	v_cvt_pk_bf16_f32 v87, v154, v155
	v_cvt_pk_bf16_f32 v88, v156, v157
	v_cvt_pk_bf16_f32 v89, v158, v159
	v_cvt_pk_bf16_f32 v90, v160, v161
	v_cvt_pk_bf16_f32 v91, v162, v163
	global_store_dwordx2 v[40:41], v[184:185], off
	global_store_dwordx2 v[40:41], v[186:187], off offset:512
	global_store_dwordx2 v[40:41], v[188:189], off offset:1024
	global_store_dwordx2 v[40:41], v[190:191], off offset:1536
	global_store_dwordx2 v[40:41], v[192:193], off offset:2048
	global_store_dwordx2 v[40:41], v[194:195], off offset:2560
	global_store_dwordx2 v[40:41], v[196:197], off offset:3072
	global_store_dwordx2 v[40:41], v[198:199], off offset:3584
	global_store_dwordx2 v[42:43], v[200:201], off
	global_store_dwordx2 v[42:43], v[202:203], off offset:512
	global_store_dwordx2 v[42:43], v[204:205], off offset:1024
	global_store_dwordx2 v[42:43], v[206:207], off offset:1536
	global_store_dwordx2 v[42:43], v[84:85], off offset:2048
	global_store_dwordx2 v[42:43], v[86:87], off offset:2560
	global_store_dwordx2 v[42:43], v[88:89], off offset:3072
	global_store_dwordx2 v[42:43], v[90:91], off offset:3584
	s_and_saveexec_b64 s[10:11], vcc
	v_lshl_add_u64 v[12:13], v[8:9], 2, s[6:7]
	v_fmamk_f32 v164, v164, 0x3a800000, v218
	v_mul_f32_e32 v180, 0x4b800000, v164
	v_cmp_gt_f32_e64 s[0:1], s71, v164
	s_nop 1
	v_cndmask_b32_e64 v164, v164, v180, s[0:1]
	v_rsq_f32_e32 v164, v164
	s_nop 0
	v_mul_f32_e32 v180, 0x45800000, v164
	v_cndmask_b32_e64 v164, v164, v180, s[0:1]
	global_store_dword v[12:13], v164, off
	v_fmamk_f32 v165, v165, 0x3a800000, v218
	v_mul_f32_e32 v181, 0x4b800000, v165
	v_cmp_gt_f32_e64 s[0:1], s71, v165
	s_nop 1
	v_cndmask_b32_e64 v165, v165, v181, s[0:1]
	v_rsq_f32_e32 v165, v165
	s_nop 0
	v_mul_f32_e32 v181, 0x45800000, v165
	v_cndmask_b32_e64 v165, v165, v181, s[0:1]
	global_store_dword v[12:13], v165, off offset:4
	v_fmamk_f32 v166, v166, 0x3a800000, v218
	v_mul_f32_e32 v182, 0x4b800000, v166
	v_cmp_gt_f32_e64 s[0:1], s71, v166
	s_nop 1
	v_cndmask_b32_e64 v166, v166, v182, s[0:1]
	v_rsq_f32_e32 v166, v166
	s_nop 0
	v_mul_f32_e32 v182, 0x45800000, v166
	v_cndmask_b32_e64 v166, v166, v182, s[0:1]
	global_store_dword v[12:13], v166, off offset:8
	v_fmamk_f32 v167, v167, 0x3a800000, v218
	v_mul_f32_e32 v183, 0x4b800000, v167
	v_cmp_gt_f32_e64 s[0:1], s71, v167
	s_nop 1
	v_cndmask_b32_e64 v167, v167, v183, s[0:1]
	v_rsq_f32_e32 v167, v167
	s_nop 0
	v_mul_f32_e32 v183, 0x45800000, v167
	v_cndmask_b32_e64 v167, v167, v183, s[0:1]
	global_store_dword v[12:13], v167, off offset:12
	s_or_b64 exec, exec, s[10:11]
	s_branch .LBB0_934

; __device__ __forceinline__ void phase_prep(const Params& P, LAS unsigned char* lds) {
;     ...
;   if (bid == 0) {
;     float* bt = (float*)(ws + O_BIAS);
;     for (int i = tid; i < 12 * 129; i += 512) {
;       const int h = i / 129, e = i % 129, delta = e - 64, gi = h >> 2, dil = 1 << (2 * gi), rel = delta * dil;
;       const int side = rel > 0 ? 16 : 0, n = rel < 0 ? -rel : rel;
;       int bucket;
;       if (n < 8) bucket = n; else { int lg = 8 + (int)(__log2f((float)n * 0.125f) * (8.0f / 7.0f)); bucket = lg < 15 ? lg : 15; }
;       bt[i] = P.in[I_RELB][(side + bucket) * 12 + h];
;     }
;   }
.LBB0_946:
	s_mov_b32 s2, 0xfe03f81
	v_mul_hi_i32 v1, v4, s2
	v_lshrrev_b32_e32 v5, 31, v1
	v_ashrrev_i32_e32 v1, 3, v1
	v_add_u32_e32 v6, v1, v5
	s_movk_i32 s2, 0xff7f
	v_mad_u64_u32 v[8:9], s[2:3], v6, s2, v[4:5]
	v_ashrrev_i32_e32 v1, 1, v6
	v_and_b32_e32 v1, -2, v1
	s_movk_i32 s2, 0xffc0
	v_add_lshl_u32 v1, v8, s2, v1
	v_sub_u32_e32 v7, 0, v1
	v_max_i32_e32 v1, v1, v7
	v_cvt_f32_u32_e32 v7, v1
	v_cmp_lt_i32_e32 vcc, 64, v8
	v_mul_f32_e32 v7, 0x3e000000, v7
	v_log_f32_e32 v7, v7
	v_cndmask_b32_e64 v5, 0, 16, vcc
	v_cmp_gt_u32_e32 vcc, 8, v1
	v_mul_f32_e32 v7, 0x3f924925, v7
	v_cvt_i32_f32_e32 v7, v7
	v_min_i32_e32 v7, 7, v7
	v_add_u32_e32 v7, 8, v7
	v_cndmask_b32_e32 v1, v7, v1, vcc
	v_add_u32_e32 v1, v1, v5
	v_mad_u64_u32 v[6:7], s[2:3], v1, 12, v[6:7]
	v_ashrrev_i32_e32 v7, 31, v6
	v_lshl_add_u64 v[6:7], v[6:7], 2, s[40:41]
	global_load_dword v1, v[6:7], off
	s_movk_i32 s2, 0x40b
	v_add_u32_e32 v5, 0x200, v4
	v_cmp_lt_i32_e32 vcc, s2, v4
	s_mov_b64 s[2:3], 0x800
	s_or_b64 s[6:7], vcc, s[6:7]
	v_mov_b32_e32 v4, v5
	s_waitcnt vmcnt(0)
	global_store_dword v[2:3], v1, off
	v_lshl_add_u64 v[2:3], v[2:3], 0, s[2:3]
	s_andn2_b64 exec, exec, s[6:7]
	s_cbranch_execnz .LBB0_946

; __device__ __forceinline__ unsigned pk2(float lo, float hi) { const f32x2_t f = {lo, hi}; const bf16x2_t b = __builtin_convertvector(f, bf16x2_t); return __builtin_bit_cast(unsigned, b); }
; __device__ __forceinline__ void phase_prep(const Params& P, LAS unsigned char* lds) {
;     ...
;       { float a = b3;
; _Pragma("unroll 4")
;         for (int k = 0; k < 64; ++k) a += hb[pp * 64 + k] * w3[k * 64 + j]; const float v = psin(fr * a);
;         u16* d = h3 + (size_t)r * 256; d[j] = (u16)(pk2(v, 0.f) & 0xffffu); d[64 + j] = 0; d[128 + j] = 0; d[192 + j] = 0; }
;       __syncthreads();
.LBB0_965:
	global_load_dword v23, v[10:11], off offset:-512
	global_load_dword v28, v[10:11], off offset:-256
	global_load_dword v29, v[10:11], off
	global_load_dword v30, v[10:11], off offset:256
	v_add_u32_e32 v24, s0, v21
	ds_read_b128 v[24:27], v24
	s_add_i32 s0, s0, 16
	v_lshl_add_u64 v[10:11], v[10:11], 0, s[96:97]
	s_cmpk_eq_i32 s0, 0x100
	s_waitcnt vmcnt(3) lgkmcnt(0)
	v_fmac_f32_e32 v9, v24, v23
	s_waitcnt vmcnt(2)
	v_fmac_f32_e32 v9, v25, v28
	s_waitcnt vmcnt(1)
	v_fmac_f32_e32 v9, v26, v29
	s_waitcnt vmcnt(0)
	v_fmac_f32_e32 v9, v27, v30
	s_cbranch_scc0 .LBB0_965
	v_mul_f32_e32 v9, v12, v9
	v_mul_f32_e32 v10, 0.15915494, v9
	v_rndne_f32_e32 v10, v10
	v_fmac_f32_e32 v9, 0xc0c90000, v10
	v_fmac_f32_e32 v9, 0xbafdaa22, v10
	v_mul_f32_e32 v9, 0.5, v9
	v_mul_f32_e32 v10, v9, v9
	v_fmamk_f32 v11, v10, 0xb2d7322b, v222
	v_fmaak_f32 v11, v10, v11, 0xb9500d01
	v_fmaak_f32 v11, v10, v11, 0x3c088888
	v_fmaak_f32 v11, v10, v11, 0xbe2aaaab
	v_fma_f32 v11, v10, v11, 1.0
	v_mul_f32_e32 v9, v9, v11
	v_fmamk_f32 v11, v10, 0x310f76c8, v223
	v_fmaak_f32 v11, v10, v11, 0x37d00d01
	v_fmaak_f32 v11, v10, v11, 0xbab60b61
	v_fmaak_f32 v11, v10, v11, 0x3d2aaaab
	v_fma_f32 v11, v10, v11, -0.5
	v_fma_f32 v10, v10, v11, 1.0
	v_add_f32_e32 v9, v9, v9
	v_mul_f32_e32 v10, v9, v10
	v_ashrrev_i32_e32 v9, 31, v8
	v_cvt_pk_bf16_f32 v10, v10, s0
	v_readlane_b32 s0, v253, 6
	v_lshlrev_b64 v[8:9], 9, v[8:9]
	s_add_i32 s2, s2, s0
	v_lshl_add_u64 v[8:9], v[2:3], 0, v[8:9]
	s_cmpk_gt_i32 s2, 0x8ff
	global_store_short v[8:9], v10, off
	global_store_short v[8:9], v81, off offset:128
	global_store_short v[8:9], v81, off offset:256
	global_store_short v[8:9], v81, off offset:384
	s_waitcnt lgkmcnt(0)
	s_barrier
	s_cbranch_scc0 .LBB0_950
